# hoisted serialized epilogue loads (residual R in P8/P12, rstd sums in P7/P10/P13) with counted waits; nt on once-read f32 weight/x loads
# speedup vs baseline: 1.0254x; 1.0168x over previous
.LBB0_24:
	v_mov_b32_e32 v3, 0
	v_lshlrev_b32_e32 v2, 2, v1
	v_mov_b32_e32 v4, v3
	v_mov_b32_e32 v5, v3
	v_and_b32_e32 v167, 60, v2
	s_lshl_b32 s22, s25, 6
	v_mov_b32_e32 v2, v3
	v_mov_b64_e32 v[64:65], v[4:5]
	v_mov_b64_e32 v[60:61], v[4:5]
	v_mov_b64_e32 v[56:57], v[4:5]
	v_mov_b64_e32 v[52:53], v[4:5]
	v_mov_b64_e32 v[48:49], v[4:5]
	v_mov_b64_e32 v[44:45], v[4:5]
	v_mov_b64_e32 v[40:41], v[4:5]
	v_mov_b64_e32 v[36:37], v[4:5]
	v_mov_b64_e32 v[32:33], v[4:5]
	v_mov_b64_e32 v[28:29], v[4:5]
	v_mov_b64_e32 v[24:25], v[4:5]
	v_mov_b64_e32 v[20:21], v[4:5]
	v_mov_b64_e32 v[16:17], v[4:5]
	v_mov_b64_e32 v[12:13], v[4:5]
	v_mov_b64_e32 v[8:9], v[4:5]
	v_mov_b64_e32 v[68:69], v[4:5]
	v_or_b32_e32 v141, 1, v134
	v_or_b32_e32 v143, 8, v139
	v_or_b32_e32 v145, 9, v134
	v_or_b32_e32 v147, 16, v139
	v_or_b32_e32 v149, 17, v134
	v_or_b32_e32 v151, 24, v139
	v_or_b32_e32 v158, 25, v134
	v_or_b32_e32 v159, 32, v139
	v_or_b32_e32 v160, 33, v134
	v_or_b32_e32 v161, 40, v139
	v_or_b32_e32 v162, 41, v134
	v_or_b32_e32 v163, 48, v139
	v_or_b32_e32 v164, 49, v134
	v_or_b32_e32 v165, 56, v139
	v_or_b32_e32 v166, 57, v134
	s_add_i32 s24, s24, s31
	s_ashr_i32 s23, s22, 31
	v_cmp_gt_u32_e32 vcc, s36, v167
	v_lshlrev_b32_e32 v136, 2, v167
	v_mov_b64_e32 v[62:63], v[2:3]
	v_mov_b64_e32 v[58:59], v[2:3]
	v_mov_b64_e32 v[54:55], v[2:3]
	v_mov_b64_e32 v[50:51], v[2:3]
	v_mov_b64_e32 v[46:47], v[2:3]
	v_mov_b64_e32 v[42:43], v[2:3]
	v_mov_b64_e32 v[38:39], v[2:3]
	v_mov_b64_e32 v[34:35], v[2:3]
	v_mov_b64_e32 v[30:31], v[2:3]
	v_mov_b64_e32 v[26:27], v[2:3]
	v_mov_b64_e32 v[22:23], v[2:3]
	v_mov_b64_e32 v[18:19], v[2:3]
	v_mov_b64_e32 v[14:15], v[2:3]
	v_mov_b64_e32 v[10:11], v[2:3]
	v_mov_b64_e32 v[6:7], v[2:3]
	v_mov_b64_e32 v[66:67], v[2:3]
	s_and_saveexec_b64 s[26:27], vcc
	s_cbranch_execz .LBB0_26
	s_mul_i32 s25, s10, s23
	s_mul_hi_u32 s31, s10, s22
	s_add_i32 s25, s31, s25
	s_mul_i32 s11, s11, s22
	s_add_i32 s35, s25, s11
	s_mul_i32 s34, s10, s22
	s_lshl_b64 s[34:35], s[34:35], 2
	s_waitcnt lgkmcnt(0)
	s_add_u32 s11, s14, s34
	s_addc_u32 s31, s15, s35
	s_ashr_i32 s25, s24, 31
	s_lshl_b64 s[14:15], s[24:25], 2
	s_add_u32 s14, s11, s14
	v_mul_u32_u24_e32 v2, s10, v139
	s_addc_u32 s15, s31, s15
	v_lshlrev_b32_e32 v2, 2, v2
	v_lshl_add_u64 v[4:5], s[14:15], 0, v[2:3]
	v_mul_u32_u24_e32 v2, s10, v141
	v_lshlrev_b32_e32 v2, 2, v2
	v_mov_b32_e32 v137, v3
	v_lshl_add_u64 v[6:7], s[14:15], 0, v[2:3]
	v_mul_u32_u24_e32 v2, s10, v143
	v_lshl_add_u64 v[4:5], v[4:5], 0, v[136:137]
	v_lshlrev_b32_e32 v2, 2, v2
	v_lshl_add_u64 v[14:15], v[6:7], 0, v[136:137]
	global_load_dwordx4 v[6:9], v[4:5], off nt
	global_load_dwordx4 v[10:13], v[14:15], off nt
	v_lshl_add_u64 v[4:5], s[14:15], 0, v[2:3]
	v_mul_u32_u24_e32 v2, s10, v145
	v_lshlrev_b32_e32 v2, 2, v2
	v_lshl_add_u64 v[14:15], s[14:15], 0, v[2:3]
	v_mul_u32_u24_e32 v2, s10, v147
	v_lshl_add_u64 v[4:5], v[4:5], 0, v[136:137]
	v_lshlrev_b32_e32 v2, 2, v2
	v_lshl_add_u64 v[22:23], v[14:15], 0, v[136:137]
	global_load_dwordx4 v[14:17], v[4:5], off nt
	global_load_dwordx4 v[18:21], v[22:23], off nt
	v_lshl_add_u64 v[4:5], s[14:15], 0, v[2:3]
	v_mul_u32_u24_e32 v2, s10, v149
	v_lshlrev_b32_e32 v2, 2, v2
	v_lshl_add_u64 v[22:23], s[14:15], 0, v[2:3]
	v_mul_u32_u24_e32 v2, s10, v151
	v_lshl_add_u64 v[4:5], v[4:5], 0, v[136:137]
	v_lshlrev_b32_e32 v2, 2, v2
	v_lshl_add_u64 v[30:31], v[22:23], 0, v[136:137]
	global_load_dwordx4 v[22:25], v[4:5], off nt
	global_load_dwordx4 v[26:29], v[30:31], off nt
	v_lshl_add_u64 v[4:5], s[14:15], 0, v[2:3]
	v_mul_u32_u24_e32 v2, s10, v158
	v_lshlrev_b32_e32 v2, 2, v2
	v_lshl_add_u64 v[30:31], s[14:15], 0, v[2:3]
	v_mul_u32_u24_e32 v2, s10, v159
	v_lshl_add_u64 v[4:5], v[4:5], 0, v[136:137]
	v_lshlrev_b32_e32 v2, 2, v2
	v_lshl_add_u64 v[38:39], v[30:31], 0, v[136:137]
	global_load_dwordx4 v[30:33], v[4:5], off nt
	global_load_dwordx4 v[34:37], v[38:39], off nt
	v_lshl_add_u64 v[4:5], s[14:15], 0, v[2:3]
	v_mul_u32_u24_e32 v2, s10, v160
	v_lshlrev_b32_e32 v2, 2, v2
	v_lshl_add_u64 v[38:39], s[14:15], 0, v[2:3]
	v_mul_u32_u24_e32 v2, s10, v161
	v_lshl_add_u64 v[4:5], v[4:5], 0, v[136:137]
	v_lshlrev_b32_e32 v2, 2, v2
	v_lshl_add_u64 v[46:47], v[38:39], 0, v[136:137]
	global_load_dwordx4 v[38:41], v[4:5], off nt
	global_load_dwordx4 v[42:45], v[46:47], off nt
	v_lshl_add_u64 v[4:5], s[14:15], 0, v[2:3]
	v_mul_u32_u24_e32 v2, s10, v162
	v_lshlrev_b32_e32 v2, 2, v2
	v_lshl_add_u64 v[46:47], s[14:15], 0, v[2:3]
	v_mul_u32_u24_e32 v2, s10, v163
	v_lshl_add_u64 v[4:5], v[4:5], 0, v[136:137]
	v_lshlrev_b32_e32 v2, 2, v2
	v_lshl_add_u64 v[54:55], v[46:47], 0, v[136:137]
	global_load_dwordx4 v[46:49], v[4:5], off nt
	global_load_dwordx4 v[50:53], v[54:55], off nt
	v_lshl_add_u64 v[4:5], s[14:15], 0, v[2:3]
	v_mul_u32_u24_e32 v2, s10, v164
	v_lshlrev_b32_e32 v2, 2, v2
	v_lshl_add_u64 v[54:55], s[14:15], 0, v[2:3]
	v_mul_u32_u24_e32 v2, s10, v165
	v_lshl_add_u64 v[4:5], v[4:5], 0, v[136:137]
	v_lshlrev_b32_e32 v2, 2, v2
	v_lshl_add_u64 v[62:63], v[54:55], 0, v[136:137]
	global_load_dwordx4 v[54:57], v[4:5], off nt
	global_load_dwordx4 v[58:61], v[62:63], off nt
	v_lshl_add_u64 v[4:5], s[14:15], 0, v[2:3]
	v_mul_u32_u24_e32 v2, s10, v166
	v_lshlrev_b32_e32 v2, 2, v2
	v_lshl_add_u64 v[4:5], v[4:5], 0, v[136:137]
	v_lshl_add_u64 v[62:63], s[14:15], 0, v[2:3]
	v_lshl_add_u64 v[70:71], v[62:63], 0, v[136:137]
	global_load_dwordx4 v[62:65], v[4:5], off nt
	global_load_dwordx4 v[66:69], v[70:71], off nt

.LBB0_57:
	s_waitcnt lgkmcnt(0)
	s_add_u32 s26, s10, s24
	s_addc_u32 s27, s11, s25
	s_add_i32 s30, s30, s42
	s_cmpk_lt_i32 s30, 0x400
	s_cselect_b64 s[24:25], -1, 0
	s_lshl_b32 s34, s31, 6
	s_ashr_i32 s35, s34, 31
	s_lshl_b64 s[10:11], s[34:35], 2
	s_add_u32 s10, s12, s10
	s_addc_u32 s11, s13, s11
	s_cmp_lg_u64 s[12:13], 0
	s_cselect_b32 s11, s11, 0
	s_cselect_b32 s10, s10, 0
	s_ashr_i32 s31, s33, 31
	s_and_b64 s[12:13], s[28:29], exec
	s_cselect_b32 s12, 0, s33
	s_cselect_b32 s13, 0, s31
	s_mul_i32 s13, s13, s37
	s_mul_hi_u32 s28, s12, s37
	s_add_i32 s13, s28, s13
	s_mul_i32 s12, s12, s37
	s_lshl_b64 s[12:13], s[12:13], 1
	s_add_u32 s26, s26, s12
	s_addc_u32 s27, s27, s13
	s_lshl_b64 s[12:13], s[34:35], 1
	s_add_u32 s12, s26, s12
	s_addc_u32 s13, s27, s13
	v_cmp_gt_u32_e32 vcc, s39, v167
	v_mov_b32_e32 v73, 0
	v_mov_b32_e32 v72, 0
	v_mov_b32_e32 v71, 0
	v_mov_b32_e32 v70, 0
	v_mov_b32_e32 v77, 0
	v_mov_b32_e32 v76, 0
	v_mov_b32_e32 v75, 0
	v_mov_b32_e32 v74, 0
	v_mov_b32_e32 v81, 0
	v_mov_b32_e32 v80, 0
	v_mov_b32_e32 v79, 0
	v_mov_b32_e32 v78, 0
	v_mov_b32_e32 v85, 0
	v_mov_b32_e32 v84, 0
	v_mov_b32_e32 v83, 0
	v_mov_b32_e32 v82, 0
	v_mov_b32_e32 v89, 0
	v_mov_b32_e32 v88, 0
	v_mov_b32_e32 v87, 0
	v_mov_b32_e32 v86, 0
	v_mov_b32_e32 v93, 0
	v_mov_b32_e32 v92, 0
	v_mov_b32_e32 v91, 0
	v_mov_b32_e32 v90, 0
	v_mov_b32_e32 v97, 0
	v_mov_b32_e32 v96, 0
	v_mov_b32_e32 v95, 0
	v_mov_b32_e32 v94, 0
	v_mov_b32_e32 v101, 0
	v_mov_b32_e32 v100, 0
	v_mov_b32_e32 v99, 0
	v_mov_b32_e32 v98, 0
	v_mov_b32_e32 v105, 0
	v_mov_b32_e32 v104, 0
	v_mov_b32_e32 v103, 0
	v_mov_b32_e32 v102, 0
	v_mov_b32_e32 v109, 0
	v_mov_b32_e32 v108, 0
	v_mov_b32_e32 v107, 0
	v_mov_b32_e32 v106, 0
	v_mov_b32_e32 v113, 0
	v_mov_b32_e32 v112, 0
	v_mov_b32_e32 v111, 0
	v_mov_b32_e32 v110, 0
	v_mov_b32_e32 v117, 0
	v_mov_b32_e32 v116, 0
	v_mov_b32_e32 v115, 0
	v_mov_b32_e32 v114, 0
	v_mov_b32_e32 v121, 0
	v_mov_b32_e32 v120, 0
	v_mov_b32_e32 v119, 0
	v_mov_b32_e32 v118, 0
	v_mov_b32_e32 v125, 0
	v_mov_b32_e32 v124, 0
	v_mov_b32_e32 v123, 0
	v_mov_b32_e32 v122, 0
	v_mov_b32_e32 v129, 0
	v_mov_b32_e32 v128, 0
	v_mov_b32_e32 v127, 0
	v_mov_b32_e32 v126, 0
	v_mov_b32_e32 v133, 0
	v_mov_b32_e32 v132, 0
	v_mov_b32_e32 v131, 0
	v_mov_b32_e32 v130, 0
	s_and_saveexec_b64 s[26:27], vcc
	s_cbranch_execz .LBB0_59
	s_mul_i32 s28, s20, s35
	s_mul_hi_u32 s29, s20, s34
	s_add_i32 s28, s29, s28
	s_mul_i32 s21, s21, s34
	s_add_i32 s29, s28, s21
	s_mul_i32 s28, s20, s34
	s_lshl_b64 s[28:29], s[28:29], 2
	s_add_u32 s21, s22, s28
	s_addc_u32 s28, s23, s29
	s_ashr_i32 s31, s30, 31
	s_lshl_b64 s[22:23], s[30:31], 2
	s_add_u32 s22, s21, s22
	v_mul_u32_u24_e32 v70, s20, v139
	s_addc_u32 s23, s28, s23
	v_lshlrev_b32_e32 v70, 2, v70
	v_mov_b32_e32 v71, v3
	v_lshl_add_u64 v[70:71], s[22:23], 0, v[70:71]
	v_mov_b32_e32 v137, v3
	v_lshl_add_u64 v[78:79], v[70:71], 0, v[136:137]
	v_mul_u32_u24_e32 v70, s20, v141
	v_lshlrev_b32_e32 v70, 2, v70
	v_mov_b32_e32 v71, v3
	v_lshl_add_u64 v[70:71], s[22:23], 0, v[70:71]
	v_lshl_add_u64 v[80:81], v[70:71], 0, v[136:137]
	global_load_dwordx4 v[70:73], v[78:79], off nt
	global_load_dwordx4 v[74:77], v[80:81], off nt
	v_mul_u32_u24_e32 v78, s20, v143
	v_lshlrev_b32_e32 v78, 2, v78
	v_mov_b32_e32 v79, v3
	v_lshl_add_u64 v[78:79], s[22:23], 0, v[78:79]
	v_lshl_add_u64 v[86:87], v[78:79], 0, v[136:137]
	v_mul_u32_u24_e32 v78, s20, v145
	v_lshlrev_b32_e32 v78, 2, v78
	v_mov_b32_e32 v79, v3
	v_lshl_add_u64 v[78:79], s[22:23], 0, v[78:79]
	v_lshl_add_u64 v[88:89], v[78:79], 0, v[136:137]
	global_load_dwordx4 v[78:81], v[86:87], off nt
	global_load_dwordx4 v[82:85], v[88:89], off nt
	v_mul_u32_u24_e32 v86, s20, v147
	v_mul_u32_u24_e32 v88, s20, v149
	v_mul_u32_u24_e32 v94, s20, v151
	v_mul_u32_u24_e32 v96, s20, v158
	v_mul_u32_u24_e32 v102, s20, v159
	v_mul_u32_u24_e32 v104, s20, v160
	v_mul_u32_u24_e32 v110, s20, v161
	v_mul_u32_u24_e32 v112, s20, v162
	v_mul_u32_u24_e32 v118, s20, v163
	v_mul_u32_u24_e32 v120, s20, v164
	v_mul_u32_u24_e32 v126, s20, v165
	v_mul_u32_u24_e32 v128, s20, v166
	v_lshlrev_b32_e32 v86, 2, v86
	v_mov_b32_e32 v87, v3
	v_lshlrev_b32_e32 v88, 2, v88
	v_mov_b32_e32 v89, v3
	v_lshlrev_b32_e32 v94, 2, v94
	v_mov_b32_e32 v95, v3
	v_lshlrev_b32_e32 v96, 2, v96
	v_mov_b32_e32 v97, v3
	v_lshlrev_b32_e32 v102, 2, v102
	v_mov_b32_e32 v103, v3
	v_lshlrev_b32_e32 v104, 2, v104
	v_mov_b32_e32 v105, v3
	v_lshlrev_b32_e32 v110, 2, v110
	v_mov_b32_e32 v111, v3
	v_lshlrev_b32_e32 v112, 2, v112
	v_mov_b32_e32 v113, v3
	v_lshlrev_b32_e32 v118, 2, v118
	v_mov_b32_e32 v119, v3
	v_lshlrev_b32_e32 v120, 2, v120
	v_mov_b32_e32 v121, v3
	v_lshlrev_b32_e32 v126, 2, v126
	v_mov_b32_e32 v127, v3
	v_lshlrev_b32_e32 v128, 2, v128
	v_mov_b32_e32 v129, v3
	v_lshl_add_u64 v[86:87], s[22:23], 0, v[86:87]
	v_lshl_add_u64 v[88:89], s[22:23], 0, v[88:89]
	v_lshl_add_u64 v[94:95], s[22:23], 0, v[94:95]
	v_lshl_add_u64 v[96:97], s[22:23], 0, v[96:97]
	v_lshl_add_u64 v[102:103], s[22:23], 0, v[102:103]
	v_lshl_add_u64 v[104:105], s[22:23], 0, v[104:105]
	v_lshl_add_u64 v[110:111], s[22:23], 0, v[110:111]
	v_lshl_add_u64 v[112:113], s[22:23], 0, v[112:113]
	v_lshl_add_u64 v[118:119], s[22:23], 0, v[118:119]
	v_lshl_add_u64 v[120:121], s[22:23], 0, v[120:121]
	v_lshl_add_u64 v[126:127], s[22:23], 0, v[126:127]
	v_lshl_add_u64 v[128:129], s[22:23], 0, v[128:129]
	v_lshl_add_u64 v[86:87], v[86:87], 0, v[136:137]
	v_lshl_add_u64 v[90:91], v[88:89], 0, v[136:137]
	v_lshl_add_u64 v[94:95], v[94:95], 0, v[136:137]
	v_lshl_add_u64 v[98:99], v[96:97], 0, v[136:137]
	v_lshl_add_u64 v[102:103], v[102:103], 0, v[136:137]
	v_lshl_add_u64 v[106:107], v[104:105], 0, v[136:137]
	v_lshl_add_u64 v[110:111], v[110:111], 0, v[136:137]
	v_lshl_add_u64 v[114:115], v[112:113], 0, v[136:137]
	v_lshl_add_u64 v[118:119], v[118:119], 0, v[136:137]
	v_lshl_add_u64 v[122:123], v[120:121], 0, v[136:137]
	v_lshl_add_u64 v[126:127], v[126:127], 0, v[136:137]
	v_lshl_add_u64 v[130:131], v[128:129], 0, v[136:137]
	global_load_dwordx4 v[86:89], v[86:87], off nt
	s_nop 0
	global_load_dwordx4 v[90:93], v[90:91], off nt
	s_nop 0
	global_load_dwordx4 v[94:97], v[94:95], off nt
	s_nop 0
	global_load_dwordx4 v[98:101], v[98:99], off nt
	s_nop 0
	global_load_dwordx4 v[102:105], v[102:103], off nt
	s_nop 0
	global_load_dwordx4 v[106:109], v[106:107], off nt
	s_nop 0
	global_load_dwordx4 v[110:113], v[110:111], off nt
	s_nop 0
	global_load_dwordx4 v[114:117], v[114:115], off nt
	s_nop 0
	global_load_dwordx4 v[118:121], v[118:119], off nt
	s_nop 0
	global_load_dwordx4 v[122:125], v[122:123], off nt
	s_nop 0
	global_load_dwordx4 v[126:129], v[126:127], off nt
	s_nop 0
	global_load_dwordx4 v[130:133], v[130:131], off nt

.LBB0_117:
	s_waitcnt lgkmcnt(0)
	s_add_u32 s26, s6, s24
	s_addc_u32 s27, s7, s25
	s_add_i32 s30, s30, s42
	s_cmpk_lt_i32 s30, 0x400
	s_cselect_b64 s[24:25], -1, 0
	s_lshl_b32 s34, s31, 6
	s_ashr_i32 s35, s34, 31
	s_lshl_b64 s[6:7], s[34:35], 2
	s_add_u32 s6, s8, s6
	s_addc_u32 s7, s9, s7
	s_cmp_lg_u64 s[8:9], 0
	s_cselect_b32 s7, s7, 0
	s_cselect_b32 s6, s6, 0
	s_ashr_i32 s31, s33, 31
	s_and_b64 s[8:9], s[28:29], exec
	s_cselect_b32 s8, 0, s33
	s_cselect_b32 s9, 0, s31
	s_mul_i32 s9, s9, s19
	s_mul_hi_u32 s28, s8, s19
	s_add_i32 s9, s28, s9
	s_mul_i32 s8, s8, s19
	s_lshl_b64 s[8:9], s[8:9], 1
	s_add_u32 s26, s26, s8
	s_addc_u32 s27, s27, s9
	s_lshl_b64 s[8:9], s[34:35], 1
	v_mov_b32_e32 v8, v3
	v_mov_b32_e32 v9, v3
	s_add_u32 s8, s26, s8
	v_mov_b32_e32 v6, v3
	v_mov_b32_e32 v7, v3
	v_mov_b64_e32 v[12:13], v[8:9]
	v_mov_b64_e32 v[16:17], v[8:9]
	v_mov_b64_e32 v[20:21], v[8:9]
	v_mov_b64_e32 v[24:25], v[8:9]
	v_mov_b64_e32 v[28:29], v[8:9]
	v_mov_b64_e32 v[32:33], v[8:9]
	v_mov_b64_e32 v[36:37], v[8:9]
	v_mov_b64_e32 v[40:41], v[8:9]
	v_mov_b64_e32 v[44:45], v[8:9]
	v_mov_b64_e32 v[48:49], v[8:9]
	v_mov_b64_e32 v[52:53], v[8:9]
	v_mov_b64_e32 v[56:57], v[8:9]
	v_mov_b64_e32 v[60:61], v[8:9]
	v_mov_b64_e32 v[64:65], v[8:9]
	v_mov_b64_e32 v[68:69], v[8:9]
	s_addc_u32 s9, s27, s9
	v_cmp_gt_u32_e32 vcc, s36, v167
	v_mov_b64_e32 v[10:11], v[6:7]
	v_mov_b64_e32 v[14:15], v[6:7]
	v_mov_b64_e32 v[18:19], v[6:7]
	v_mov_b64_e32 v[22:23], v[6:7]
	v_mov_b64_e32 v[26:27], v[6:7]
	v_mov_b64_e32 v[30:31], v[6:7]
	v_mov_b64_e32 v[34:35], v[6:7]
	v_mov_b64_e32 v[38:39], v[6:7]
	v_mov_b64_e32 v[42:43], v[6:7]
	v_mov_b64_e32 v[46:47], v[6:7]
	v_mov_b64_e32 v[50:51], v[6:7]
	v_mov_b64_e32 v[54:55], v[6:7]
	v_mov_b64_e32 v[58:59], v[6:7]
	v_mov_b64_e32 v[62:63], v[6:7]
	v_mov_b64_e32 v[66:67], v[6:7]
	s_and_saveexec_b64 s[26:27], vcc
	s_cbranch_execz .LBB0_119
	s_mul_i32 s28, s20, s35
	s_mul_hi_u32 s29, s20, s34
	s_add_i32 s28, s29, s28
	s_mul_i32 s21, s21, s34
	s_add_i32 s29, s28, s21
	s_mul_i32 s28, s20, s34
	s_lshl_b64 s[28:29], s[28:29], 2
	s_add_u32 s21, s22, s28
	s_addc_u32 s28, s23, s29
	s_ashr_i32 s31, s30, 31
	s_lshl_b64 s[22:23], s[30:31], 2
	s_add_u32 s22, s21, s22
	v_mul_u32_u24_e32 v6, s20, v139
	s_addc_u32 s23, s28, s23
	v_lshlrev_b32_e32 v6, 2, v6
	v_mov_b32_e32 v7, v3
	v_lshl_add_u64 v[6:7], s[22:23], 0, v[6:7]
	v_mov_b32_e32 v137, v3
	v_lshl_add_u64 v[14:15], v[6:7], 0, v[136:137]
	v_mul_u32_u24_e32 v6, s20, v141
	v_lshlrev_b32_e32 v6, 2, v6
	v_mov_b32_e32 v7, v3
	v_lshl_add_u64 v[6:7], s[22:23], 0, v[6:7]
	v_lshl_add_u64 v[16:17], v[6:7], 0, v[136:137]
	global_load_dwordx4 v[6:9], v[14:15], off nt
	global_load_dwordx4 v[10:13], v[16:17], off nt
	v_mul_u32_u24_e32 v14, s20, v143
	v_lshlrev_b32_e32 v14, 2, v14
	v_mov_b32_e32 v15, v3
	v_lshl_add_u64 v[14:15], s[22:23], 0, v[14:15]
	v_lshl_add_u64 v[22:23], v[14:15], 0, v[136:137]
	v_mul_u32_u24_e32 v14, s20, v145
	v_lshlrev_b32_e32 v14, 2, v14
	v_mov_b32_e32 v15, v3
	v_lshl_add_u64 v[14:15], s[22:23], 0, v[14:15]
	v_lshl_add_u64 v[24:25], v[14:15], 0, v[136:137]
	global_load_dwordx4 v[14:17], v[22:23], off nt
	global_load_dwordx4 v[18:21], v[24:25], off nt
	v_mul_u32_u24_e32 v22, s20, v147
	v_mul_u32_u24_e32 v24, s20, v149
	v_mul_u32_u24_e32 v30, s20, v151
	v_mul_u32_u24_e32 v32, s20, v158
	v_mul_u32_u24_e32 v38, s20, v159
	v_mul_u32_u24_e32 v40, s20, v160
	v_mul_u32_u24_e32 v46, s20, v161
	v_mul_u32_u24_e32 v48, s20, v162
	v_mul_u32_u24_e32 v54, s20, v163
	v_mul_u32_u24_e32 v56, s20, v164
	v_mul_u32_u24_e32 v62, s20, v165
	v_mul_u32_u24_e32 v64, s20, v166
	v_lshlrev_b32_e32 v22, 2, v22
	v_mov_b32_e32 v23, v3
	v_lshlrev_b32_e32 v24, 2, v24
	v_mov_b32_e32 v25, v3
	v_lshlrev_b32_e32 v30, 2, v30
	v_mov_b32_e32 v31, v3
	v_lshlrev_b32_e32 v32, 2, v32
	v_mov_b32_e32 v33, v3
	v_lshlrev_b32_e32 v38, 2, v38
	v_mov_b32_e32 v39, v3
	v_lshlrev_b32_e32 v40, 2, v40
	v_mov_b32_e32 v41, v3
	v_lshlrev_b32_e32 v46, 2, v46
	v_mov_b32_e32 v47, v3
	v_lshlrev_b32_e32 v48, 2, v48
	v_mov_b32_e32 v49, v3
	v_lshlrev_b32_e32 v54, 2, v54
	v_mov_b32_e32 v55, v3
	v_lshlrev_b32_e32 v56, 2, v56
	v_mov_b32_e32 v57, v3
	v_lshlrev_b32_e32 v62, 2, v62
	v_mov_b32_e32 v63, v3
	v_lshlrev_b32_e32 v64, 2, v64
	v_mov_b32_e32 v65, v3
	v_lshl_add_u64 v[22:23], s[22:23], 0, v[22:23]
	v_lshl_add_u64 v[24:25], s[22:23], 0, v[24:25]
	v_lshl_add_u64 v[30:31], s[22:23], 0, v[30:31]
	v_lshl_add_u64 v[32:33], s[22:23], 0, v[32:33]
	v_lshl_add_u64 v[38:39], s[22:23], 0, v[38:39]
	v_lshl_add_u64 v[40:41], s[22:23], 0, v[40:41]
	v_lshl_add_u64 v[46:47], s[22:23], 0, v[46:47]
	v_lshl_add_u64 v[48:49], s[22:23], 0, v[48:49]
	v_lshl_add_u64 v[54:55], s[22:23], 0, v[54:55]
	v_lshl_add_u64 v[56:57], s[22:23], 0, v[56:57]
	v_lshl_add_u64 v[62:63], s[22:23], 0, v[62:63]
	v_lshl_add_u64 v[64:65], s[22:23], 0, v[64:65]
	v_lshl_add_u64 v[22:23], v[22:23], 0, v[136:137]
	v_lshl_add_u64 v[26:27], v[24:25], 0, v[136:137]
	v_lshl_add_u64 v[30:31], v[30:31], 0, v[136:137]
	v_lshl_add_u64 v[34:35], v[32:33], 0, v[136:137]
	v_lshl_add_u64 v[38:39], v[38:39], 0, v[136:137]
	v_lshl_add_u64 v[42:43], v[40:41], 0, v[136:137]
	v_lshl_add_u64 v[46:47], v[46:47], 0, v[136:137]
	v_lshl_add_u64 v[50:51], v[48:49], 0, v[136:137]
	v_lshl_add_u64 v[54:55], v[54:55], 0, v[136:137]
	v_lshl_add_u64 v[58:59], v[56:57], 0, v[136:137]
	v_lshl_add_u64 v[62:63], v[62:63], 0, v[136:137]
	v_lshl_add_u64 v[66:67], v[64:65], 0, v[136:137]
	global_load_dwordx4 v[22:25], v[22:23], off nt
	s_nop 0
	global_load_dwordx4 v[26:29], v[26:27], off nt
	s_nop 0
	global_load_dwordx4 v[30:33], v[30:31], off nt
	s_nop 0
	global_load_dwordx4 v[34:37], v[34:35], off nt
	s_nop 0
	global_load_dwordx4 v[38:41], v[38:39], off nt
	s_nop 0
	global_load_dwordx4 v[42:45], v[42:43], off nt
	s_nop 0
	global_load_dwordx4 v[46:49], v[46:47], off nt
	s_nop 0
	global_load_dwordx4 v[50:53], v[50:51], off nt
	s_nop 0
	global_load_dwordx4 v[54:57], v[54:55], off nt
	s_nop 0
	global_load_dwordx4 v[58:61], v[58:59], off nt
	s_nop 0
	global_load_dwordx4 v[62:65], v[62:63], off nt
	s_nop 0
	global_load_dwordx4 v[66:69], v[66:67], off nt

.LBB0_156:
	v_ashrrev_i32_e32 v12, 2, v7
	v_mad_i64_i32 v[8:9], s[22:23], v12, s12, v[4:5]
	v_lshl_add_u64 v[8:9], v[8:9], 0, v[2:3]
	v_ashrrev_i32_e32 v13, 31, v12
	v_add_co_u32_e32 v8, vcc, 0x6000, v8
	v_lshl_add_u64 v[10:11], v[12:13], 2, s[8:9]
	s_nop 0
	v_addc_co_u32_e32 v9, vcc, 0, v9, vcc
	global_load_dword v14, v[10:11], off
	v_and_b32_e32 v13, 0xffffc00, v7
	global_load_dwordx4 v[8:11], v[8:9], off nt
	v_lshlrev_b32_e32 v12, 8, v12
	v_and_or_b32 v12, v12, s13, v13
	v_and_b32_e32 v15, 0x3f0, v7
	v_add_u32_e32 v16, 0x200, v7
	v_cmp_lt_i32_e32 vcc, s19, v7
	v_lshlrev_b32_e32 v12, 4, v12
	s_or_b64 s[10:11], vcc, s[10:11]
	v_mov_b32_e32 v7, v16
	v_add3_u32 v12, v6, v15, v12
	s_waitcnt vmcnt(0)
	v_pk_mul_f32 v[10:11], v[10:11], v[14:15] op_sel_hi:[1,0]
	v_pk_mul_f32 v[8:9], v[8:9], v[14:15] op_sel_hi:[1,0]
	ds_write_b128 v12, v[8:11]
	s_andn2_b64 exec, exec, s[10:11]
	s_cbranch_execnz .LBB0_156
	s_or_b64 exec, exec, s[10:11]
.LBB0_158:
	s_or_b64 exec, exec, s[6:7]
	s_cmpk_lt_i32 s18, 0x2000
	s_waitcnt lgkmcnt(0)
	s_barrier
	s_cbranch_scc0 .LBB0_163
	s_ashr_i32 s19, s18, 31
	s_waitcnt vmcnt(10)
	v_lshlrev_b32_e32 v34, 4, v1
	v_mov_b32_e32 v35, 0
	s_lshl_b64 s[6:7], s[18:19], 13
	s_waitcnt vmcnt(2)
	v_lshl_add_u64 v[66:67], s[4:5], 0, v[34:35]
	s_add_u32 s4, s4, s6
	s_addc_u32 s5, s5, s7
	v_mbcnt_lo_u32_b32 v19, -1, 0
	v_lshl_add_u64 v[2:3], s[4:5], 0, v[34:35]
	v_mbcnt_hi_u32_b32 v19, -1, v19
	v_add_co_u32_e32 v36, vcc, 0x1000, v2
	v_and_b32_e32 v20, 64, v19
	s_nop 0
	v_addc_co_u32_e32 v37, vcc, 0, v3, vcc
	v_add_u32_e32 v20, 64, v20
	v_xor_b32_e32 v21, 1, v19
	v_cmp_lt_i32_e32 vcc, v21, v20
	global_load_dwordx4 v[14:17], v34, s[4:5] offset:3072 nt
	global_load_dwordx4 v[10:13], v34, s[4:5] offset:2048 nt
	global_load_dwordx4 v[6:9], v34, s[4:5] offset:1024 nt
	global_load_dwordx4 v[2:5], v34, s[4:5] nt
	v_cndmask_b32_e32 v21, v19, v21, vcc
	v_lshlrev_b32_e32 v74, 2, v21
	v_xor_b32_e32 v21, 2, v19
	v_cmp_lt_i32_e32 vcc, v21, v20
	v_cmp_eq_u32_e64 s[12:13], 0, v18
	s_lshl_b64 s[22:23], s[18:19], 6
	v_cndmask_b32_e32 v21, v19, v21, vcc
	v_lshlrev_b32_e32 v75, 2, v21
	v_xor_b32_e32 v21, 4, v19
	v_cmp_lt_i32_e32 vcc, v21, v20
	s_add_u32 s20, s20, s22
	v_add_u32_e32 v80, 0, v34
	v_cndmask_b32_e32 v21, v19, v21, vcc
	v_lshlrev_b32_e32 v76, 2, v21
	v_xor_b32_e32 v21, 8, v19
	v_cmp_lt_i32_e32 vcc, v21, v20
	v_and_b32_e32 v34, 60, v1
	s_addc_u32 s21, s21, s23
	v_cndmask_b32_e32 v21, v19, v21, vcc
	v_lshlrev_b32_e32 v77, 2, v21
	v_xor_b32_e32 v21, 16, v19
	v_cmp_lt_i32_e32 vcc, v21, v20
	s_ashr_i32 s47, s46, 31
	s_lshl_b64 s[22:23], s[18:19], 12
	v_cndmask_b32_e32 v21, v19, v21, vcc
	v_lshlrev_b32_e32 v78, 2, v21
	v_xor_b32_e32 v21, 32, v19
	v_cmp_lt_i32_e32 vcc, v21, v20
	s_movk_i32 s26, 0x1000
	v_cmp_gt_u32_e64 s[4:5], 32, v1
	v_cndmask_b32_e32 v19, v19, v21, vcc
	v_lshlrev_b32_e32 v79, 2, v19
	v_and_b32_e32 v19, 16, v135
	v_cmp_eq_u32_e64 s[6:7], 0, v19
	v_and_b32_e32 v19, 8, v135
	v_cmp_eq_u32_e64 s[8:9], 0, v19
	v_and_b32_e32 v19, 4, v135
	v_cmp_eq_u32_e64 s[10:11], 0, v19
	global_load_dwordx4 v[30:33], v[36:37], off offset:3072 nt
	global_load_dwordx4 v[26:29], v[36:37], off offset:2048 nt
	global_load_dwordx4 v[22:25], v[36:37], off offset:1024 nt
	global_load_dwordx4 v[18:21], v[36:37], off nt
	v_lshl_add_u64 v[36:37], s[20:21], 0, v[34:35]
	s_mov_b64 s[20:21], 0x17700000
	v_lshl_add_u64 v[68:69], v[36:37], 0, s[20:21]
	s_lshl_b64 s[20:21], s[46:47], 6
	s_add_u32 s14, s14, s22
	v_lshlrev_b32_e32 v34, 3, v1
	s_addc_u32 s15, s15, s23
	v_lshl_add_u64 v[34:35], s[14:15], 0, v[34:35]
	s_mov_b64 s[14:15], 0xc600000
	v_add_u32_e32 v81, 0x10000, v80
	v_add_u32_e32 v82, 0x10400, v80
	v_add_u32_e32 v83, 0x10800, v80
	v_add_u32_e32 v84, 0x10c00, v80
	v_add_u32_e32 v85, 0x11000, v80
	v_add_u32_e32 v86, 0x11400, v80
	v_add_u32_e32 v87, 0x11800, v80
	v_add_u32_e32 v88, 0x11c00, v80
	v_add_u32_e32 v89, 0x12000, v80
	v_add_u32_e32 v90, 0x12400, v80
	v_add_u32_e32 v91, 0x12800, v80
	v_add_u32_e32 v92, 0x12c00, v80
	v_add_u32_e32 v93, 0x13000, v80
	v_add_u32_e32 v94, 0x13400, v80
	v_add_u32_e32 v95, 0x13800, v80
	v_add_u32_e32 v96, 0x13c00, v80
	v_add_u32_e32 v97, 0x14000, v80
	v_add_u32_e32 v98, 0x14400, v80
	v_add_u32_e32 v99, 0x14800, v80
	v_add_u32_e32 v100, 0x14c00, v80
	v_add_u32_e32 v101, 0x15000, v80
	v_add_u32_e32 v102, 0x15400, v80
	v_add_u32_e32 v103, 0x15800, v80
	v_add_u32_e32 v104, 0x15c00, v80
	v_add_u32_e32 v105, 0x16000, v80
	v_add_u32_e32 v106, 0x16400, v80
	v_add_u32_e32 v107, 0x16800, v80
	v_add_u32_e32 v108, 0x16c00, v80
	v_add_u32_e32 v1, 0x17000, v80
	v_lshl_add_u64 v[70:71], v[34:35], 0, s[14:15]
	s_lshl_b64 s[22:23], s[46:47], 12
	s_mov_b32 s19, 0xf800000
	v_add_u32_e32 v109, 0x17400, v80
	v_add_u32_e32 v110, 0x17800, v80
	v_add_u32_e32 v111, 0x17c00, v80
	v_add_u32_e32 v112, 0x18000, v80
	v_add_u32_e32 v113, 0x18400, v80
	v_add_u32_e32 v114, 0x18800, v80
	v_add_u32_e32 v115, 0x18c00, v80
	v_add_u32_e32 v116, 0x19000, v80
	v_add_u32_e32 v117, 0x19400, v80
	v_add_u32_e32 v118, 0x19800, v80
	v_add_u32_e32 v119, 0x19c00, v80
	v_add_u32_e32 v120, 0x1a000, v80
	v_add_u32_e32 v121, 0x1a400, v80
	v_add_u32_e32 v122, 0x1a800, v80
	v_add_u32_e32 v123, 0x1ac00, v80
	v_add_u32_e32 v124, 0x1b000, v80
	v_add_u32_e32 v125, 0x1b400, v80
	v_add_u32_e32 v126, 0x1b800, v80
	v_add_u32_e32 v127, 0x1bc00, v80
	v_add_u32_e32 v128, 0x1c000, v80
	v_add_u32_e32 v129, 0x1c400, v80
	v_add_u32_e32 v130, 0x1c800, v80
	v_add_u32_e32 v131, 0x1cc00, v80
	v_add_u32_e32 v132, 0x1d000, v80
	v_add_u32_e32 v133, 0x1d400, v80
	v_add_u32_e32 v134, 0x1d800, v80
	v_add_u32_e32 v135, 0x1dc00, v80
	v_add_u32_e32 v136, 0x1e000, v80
	v_add_u32_e32 v137, 0x1e400, v80
	v_add_u32_e32 v138, 0x1e800, v80
	v_add_u32_e32 v139, 0x1ec00, v80
	v_add_u32_e32 v140, 0x1f000, v80
	v_add_u32_e32 v141, 0x1f400, v80
	v_add_u32_e32 v142, 0x1f800, v80
	v_add_u32_e32 v143, 0x1fc00, v80
	v_mov_b32_e32 v144, 0x358637bd
	v_mov_b32_e32 v145, 0x260
	s_branch .LBB0_161

.LBB0_161:
	s_waitcnt vmcnt(5)
	v_mov_b64_e32 v[60:61], v[8:9]
	v_mov_b64_e32 v[58:59], v[6:7]
	s_waitcnt vmcnt(4)
	v_mov_b64_e32 v[64:65], v[4:5]
	v_mov_b64_e32 v[56:57], v[12:13]
	v_mov_b64_e32 v[62:63], v[2:3]
	v_mul_f32_e32 v4, v59, v59
	v_mul_f32_e32 v5, v61, v61
	v_mov_b64_e32 v[54:55], v[10:11]
	v_fmac_f32_e32 v4, v58, v58
	v_fmac_f32_e32 v5, v60, v60
	v_mov_b64_e32 v[52:53], v[16:17]
	v_add_f32_e32 v4, v4, v5
	v_mul_f32_e32 v5, v55, v55
	v_mul_f32_e32 v6, v57, v57
	v_mov_b64_e32 v[50:51], v[14:15]
	v_fmac_f32_e32 v5, v54, v54
	v_fmac_f32_e32 v6, v56, v56
	s_waitcnt vmcnt(0)
	v_mov_b64_e32 v[48:49], v[20:21]
	v_add_f32_e32 v5, v5, v6
	v_mul_f32_e32 v6, v51, v51
	v_mul_f32_e32 v7, v53, v53
	v_mov_b64_e32 v[46:47], v[18:19]
	v_fmac_f32_e32 v6, v50, v50
	v_fmac_f32_e32 v7, v52, v52
	v_mov_b64_e32 v[44:45], v[24:25]
	v_mul_f32_e32 v2, v63, v63
	v_mul_f32_e32 v3, v65, v65
	v_add_f32_e32 v6, v6, v7
	v_mul_f32_e32 v7, v47, v47
	v_mul_f32_e32 v8, v49, v49
	v_mov_b64_e32 v[42:43], v[22:23]
	v_fmac_f32_e32 v3, v64, v64
	v_fmac_f32_e32 v7, v46, v46
	v_fmac_f32_e32 v8, v48, v48
	v_fmac_f32_e32 v2, v62, v62
	v_mov_b64_e32 v[40:41], v[28:29]
	v_add_f32_e32 v7, v7, v8
	v_mul_f32_e32 v8, v43, v43
	v_mul_f32_e32 v9, v45, v45
	v_add_f32_e32 v2, v2, v3
	v_mov_b64_e32 v[38:39], v[26:27]
	v_fmac_f32_e32 v8, v42, v42
	v_fmac_f32_e32 v9, v44, v44
	v_add_f32_e32 v2, v2, v4
	s_waitcnt lgkmcnt(0)
	v_mov_b64_e32 v[36:37], v[32:33]
	v_add_f32_e32 v8, v8, v9
	v_mul_f32_e32 v9, v39, v39
	v_mul_f32_e32 v10, v41, v41
	v_add_f32_e32 v2, v2, v5
	v_mov_b64_e32 v[34:35], v[30:31]
	v_fmac_f32_e32 v9, v38, v38
	v_fmac_f32_e32 v10, v40, v40
	v_add_f32_e32 v2, v2, v6
	v_add_f32_e32 v9, v9, v10
	v_mul_f32_e32 v10, v35, v35
	v_mul_f32_e32 v11, v37, v37
	v_add_f32_e32 v2, v2, v7
	v_fmac_f32_e32 v10, v34, v34
	v_fmac_f32_e32 v11, v36, v36
	v_add_f32_e32 v2, v2, v8
	v_add_f32_e32 v10, v10, v11
	v_add_f32_e32 v2, v2, v9
	v_add_f32_e32 v2, v2, v10
	ds_bpermute_b32 v3, v74, v2
	s_mov_b32 s14, s18
	s_add_i32 s18, s18, s46
	s_cmpk_gt_i32 s18, 0x1fff
	s_cselect_b64 s[24:25], -1, 0
	s_waitcnt lgkmcnt(0)
	v_add_f32_e32 v2, v2, v3
	ds_bpermute_b32 v3, v75, v2
	s_cmpk_lt_i32 s18, 0x2000
	s_cselect_b32 s14, s18, s14
	s_ashr_i32 s15, s14, 31
	s_lshl_b64 s[14:15], s[14:15], 13
	s_waitcnt lgkmcnt(0)
	v_add_f32_e32 v2, v2, v3
	ds_bpermute_b32 v3, v76, v2
	v_lshl_add_u64 v[18:19], v[66:67], 0, s[14:15]
	v_add_co_u32_e64 v30, s[14:15], s26, v18
	s_waitcnt lgkmcnt(0)
	v_add_f32_e32 v2, v2, v3
	ds_bpermute_b32 v3, v77, v2
	v_addc_co_u32_e64 v31, s[14:15], 0, v19, s[14:15]
	s_waitcnt lgkmcnt(0)
	v_add_f32_e32 v2, v2, v3
	ds_bpermute_b32 v3, v78, v2
	s_waitcnt lgkmcnt(0)
	v_add_f32_e32 v20, v2, v3
	ds_bpermute_b32 v21, v79, v20
	global_load_dwordx4 v[2:5], v[18:19], off nt
	global_load_dwordx4 v[6:9], v[18:19], off offset:1024 nt
	global_load_dwordx4 v[10:13], v[18:19], off offset:2048 nt
	global_load_dwordx4 v[14:17], v[18:19], off offset:3072 nt
	s_waitcnt lgkmcnt(0)
	v_add_f32_e32 v20, v20, v21
	v_fmamk_f32 v20, v20, 0x3a000000, v144
	v_mul_f32_e32 v21, 0x4f800000, v20
	v_cmp_gt_f32_e32 vcc, s19, v20
	s_nop 1
	v_cndmask_b32_e32 v20, v20, v21, vcc
	v_sqrt_f32_e32 v21, v20
	s_nop 0
	v_add_u32_e32 v18, -1, v21
	v_fma_f32 v19, -v18, v21, v20
	v_cmp_ge_f32_e64 s[14:15], 0, v19
	v_add_u32_e32 v19, 1, v21
	s_nop 0
	v_cndmask_b32_e64 v18, v21, v18, s[14:15]
	v_fma_f32 v21, -v19, v21, v20
	v_cmp_lt_f32_e64 s[14:15], 0, v21
	s_nop 1
	v_cndmask_b32_e64 v18, v18, v19, s[14:15]
	v_mul_f32_e32 v19, 0x37800000, v18
	v_cndmask_b32_e32 v18, v18, v19, vcc
	v_cmp_class_f32_e32 vcc, v20, v145
	s_nop 1
	v_cndmask_b32_e32 v72, v18, v20, vcc
	v_div_scale_f32 v73, s[14:15], v72, v72, 1.0
	v_rcp_f32_e32 v146, v73
	global_load_dwordx4 v[18:21], v[30:31], off nt
	global_load_dwordx4 v[22:25], v[30:31], off offset:1024 nt
	global_load_dwordx4 v[26:29], v[30:31], off offset:2048 nt
	s_nop 0
	global_load_dwordx4 v[30:33], v[30:31], off offset:3072 nt
	v_fma_f32 v147, -v73, v146, 1.0
	v_fmac_f32_e32 v146, v147, v146
	v_div_scale_f32 v147, vcc, 1.0, v72, 1.0
	v_mul_f32_e32 v148, v147, v146
	v_fma_f32 v149, -v73, v148, v147
	v_fmac_f32_e32 v148, v149, v146
	v_fma_f32 v73, -v73, v148, v147
	v_div_fmas_f32 v73, v73, v146, v148
	v_div_fixup_f32 v146, v73, v72, 1.0
	v_mul_f32_e32 v72, v62, v146
	v_mul_f32_e32 v73, v63, v146
	v_cvt_pk_bf16_f32 v72, v72, v73
	v_mul_f32_e32 v73, v64, v146
	v_mul_f32_e32 v147, v65, v146
	v_cvt_pk_bf16_f32 v73, v73, v147
	global_store_dwordx2 v[70:71], v[72:73], off
	v_mul_f32_e32 v72, v58, v146
	v_mul_f32_e32 v73, v59, v146
	v_cvt_pk_bf16_f32 v72, v72, v73
	v_mul_f32_e32 v73, v60, v146
	v_mul_f32_e32 v147, v61, v146
	v_cvt_pk_bf16_f32 v73, v73, v147
	global_store_dwordx2 v[70:71], v[72:73], off offset:512
	v_mul_f32_e32 v72, v54, v146
	v_mul_f32_e32 v73, v55, v146
	v_cvt_pk_bf16_f32 v72, v72, v73
	v_mul_f32_e32 v73, v56, v146
	v_mul_f32_e32 v147, v57, v146
	v_cvt_pk_bf16_f32 v73, v73, v147
	global_store_dwordx2 v[70:71], v[72:73], off offset:1024
	v_mul_f32_e32 v72, v50, v146
	v_mul_f32_e32 v73, v51, v146
	v_cvt_pk_bf16_f32 v72, v72, v73
	v_mul_f32_e32 v73, v52, v146
	v_mul_f32_e32 v147, v53, v146
	v_cvt_pk_bf16_f32 v73, v73, v147
	global_store_dwordx2 v[70:71], v[72:73], off offset:1536
	v_mul_f32_e32 v72, v46, v146
	v_mul_f32_e32 v73, v47, v146
	v_cvt_pk_bf16_f32 v72, v72, v73
	v_mul_f32_e32 v73, v48, v146
	v_mul_f32_e32 v147, v49, v146
	v_cvt_pk_bf16_f32 v73, v73, v147
	global_store_dwordx2 v[70:71], v[72:73], off offset:2048
	v_mul_f32_e32 v72, v42, v146
	v_mul_f32_e32 v73, v43, v146
	v_cvt_pk_bf16_f32 v72, v72, v73
	v_mul_f32_e32 v73, v44, v146
	v_mul_f32_e32 v147, v45, v146
	v_cvt_pk_bf16_f32 v73, v73, v147
	global_store_dwordx2 v[70:71], v[72:73], off offset:2560
	v_mul_f32_e32 v72, v38, v146
	v_mul_f32_e32 v73, v39, v146
	v_cvt_pk_bf16_f32 v72, v72, v73
	v_mul_f32_e32 v73, v40, v146
	v_mul_f32_e32 v147, v41, v146
	v_cvt_pk_bf16_f32 v73, v73, v147
	global_store_dwordx2 v[70:71], v[72:73], off offset:3072
	v_mul_f32_e32 v72, v34, v146
	v_mul_f32_e32 v73, v35, v146
	v_cvt_pk_bf16_f32 v72, v72, v73
	v_mul_f32_e32 v73, v36, v146
	v_mul_f32_e32 v147, v37, v146
	v_cvt_pk_bf16_f32 v73, v73, v147
	ds_read_b128 v[148:151], v80
	ds_read_b128 v[152:155], v80 offset:1024
	ds_read_b128 v[156:159], v80 offset:2048
	global_store_dwordx2 v[70:71], v[72:73], off offset:3584
	s_waitcnt lgkmcnt(2)
	v_pk_fma_f32 v[160:161], v[62:63], v[148:149], 0 op_sel_hi:[0,1,0]
	v_pk_fma_f32 v[162:163], v[62:63], v[150:151], 0 op_sel_hi:[0,1,0]
	ds_read_b128 v[148:151], v80 offset:3072
	s_waitcnt lgkmcnt(2)
	v_pk_fma_f32 v[164:165], v[62:63], v[152:153], 0 op_sel_hi:[0,1,0]
	v_pk_fma_f32 v[166:167], v[62:63], v[154:155], 0 op_sel_hi:[0,1,0]
	s_waitcnt lgkmcnt(1)
	v_pk_fma_f32 v[168:169], v[62:63], v[156:157], 0 op_sel_hi:[0,1,0]
	ds_read_b128 v[152:155], v80 offset:4096
	v_pk_fma_f32 v[170:171], v[62:63], v[158:159], 0 op_sel_hi:[0,1,0]
	ds_read_b128 v[156:159], v80 offset:5120
	s_waitcnt lgkmcnt(2)
	v_pk_fma_f32 v[172:173], v[62:63], v[148:149], 0 op_sel_hi:[0,1,0]
	v_pk_fma_f32 v[174:175], v[62:63], v[150:151], 0 op_sel_hi:[0,1,0]
	ds_read_b128 v[148:151], v80 offset:6144
	s_waitcnt lgkmcnt(2)
	v_pk_fma_f32 v[162:163], v[62:63], v[154:155], v[162:163] op_sel:[1,0,0]
	v_pk_fma_f32 v[160:161], v[62:63], v[152:153], v[160:161] op_sel:[1,0,0]
	s_waitcnt lgkmcnt(1)
	v_pk_fma_f32 v[166:167], v[62:63], v[158:159], v[166:167] op_sel:[1,0,0]
	ds_read_b128 v[152:155], v80 offset:7168
	v_pk_fma_f32 v[164:165], v[62:63], v[156:157], v[164:165] op_sel:[1,0,0]
	ds_read_b128 v[156:159], v80 offset:8192
	s_waitcnt lgkmcnt(2)
	v_pk_fma_f32 v[170:171], v[62:63], v[150:151], v[170:171] op_sel:[1,0,0]
	v_pk_fma_f32 v[168:169], v[62:63], v[148:149], v[168:169] op_sel:[1,0,0]
	ds_read_b128 v[148:151], v80 offset:9216
	s_waitcnt lgkmcnt(2)
	v_pk_fma_f32 v[174:175], v[62:63], v[154:155], v[174:175] op_sel:[1,0,0]
	v_pk_fma_f32 v[62:63], v[62:63], v[152:153], v[172:173] op_sel:[1,0,0]
	s_waitcnt lgkmcnt(1)
	v_pk_fma_f32 v[160:161], v[64:65], v[156:157], v[160:161] op_sel_hi:[0,1,1]
	ds_read_b128 v[152:155], v80 offset:10240
	v_pk_fma_f32 v[162:163], v[64:65], v[158:159], v[162:163] op_sel_hi:[0,1,1]
	ds_read_b128 v[156:159], v80 offset:11264
	s_waitcnt lgkmcnt(2)
	v_pk_fma_f32 v[164:165], v[64:65], v[148:149], v[164:165] op_sel_hi:[0,1,1]
	v_pk_fma_f32 v[166:167], v[64:65], v[150:151], v[166:167] op_sel_hi:[0,1,1]
	ds_read_b128 v[148:151], v80 offset:12288
	s_waitcnt lgkmcnt(2)
	v_pk_fma_f32 v[168:169], v[64:65], v[152:153], v[168:169] op_sel_hi:[0,1,1]
	v_pk_fma_f32 v[170:171], v[64:65], v[154:155], v[170:171] op_sel_hi:[0,1,1]
	s_waitcnt lgkmcnt(1)
	v_pk_fma_f32 v[156:157], v[64:65], v[156:157], v[62:63] op_sel_hi:[0,1,1]
	v_pk_fma_f32 v[158:159], v[64:65], v[158:159], v[174:175] op_sel_hi:[0,1,1]
	ds_read_b128 v[152:155], v80 offset:13312
	v_mov_b32_e32 v172, v65
	ds_read_b128 v[62:65], v80 offset:14336
	s_waitcnt lgkmcnt(2)
	v_pk_fma_f32 v[162:163], v[172:173], v[150:151], v[162:163] op_sel_hi:[0,1,1]
	v_pk_fma_f32 v[160:161], v[172:173], v[148:149], v[160:161] op_sel_hi:[0,1,1]
	ds_read_b128 v[148:151], v80 offset:15360
	s_waitcnt lgkmcnt(2)
	v_pk_fma_f32 v[166:167], v[172:173], v[154:155], v[166:167] op_sel_hi:[0,1,1]
	v_pk_fma_f32 v[164:165], v[172:173], v[152:153], v[164:165] op_sel_hi:[0,1,1]
	s_waitcnt lgkmcnt(1)
	v_pk_fma_f32 v[170:171], v[172:173], v[64:65], v[170:171] op_sel_hi:[0,1,1]
	ds_read_b128 v[152:155], v80 offset:16384
	v_pk_fma_f32 v[168:169], v[172:173], v[62:63], v[168:169] op_sel_hi:[0,1,1]
	ds_read_b128 v[62:65], v80 offset:17408
	s_waitcnt lgkmcnt(2)
	v_pk_fma_f32 v[158:159], v[172:173], v[150:151], v[158:159] op_sel_hi:[0,1,1]
	v_pk_fma_f32 v[156:157], v[172:173], v[148:149], v[156:157] op_sel_hi:[0,1,1]
	ds_read_b128 v[148:151], v80 offset:18432
	s_waitcnt lgkmcnt(2)
	v_pk_fma_f32 v[160:161], v[58:59], v[152:153], v[160:161] op_sel_hi:[0,1,1]
	v_pk_fma_f32 v[162:163], v[58:59], v[154:155], v[162:163] op_sel_hi:[0,1,1]
	s_waitcnt lgkmcnt(1)
	v_pk_fma_f32 v[164:165], v[58:59], v[62:63], v[164:165] op_sel_hi:[0,1,1]
	ds_read_b128 v[152:155], v80 offset:19456
	v_pk_fma_f32 v[166:167], v[58:59], v[64:65], v[166:167] op_sel_hi:[0,1,1]
	ds_read_b128 v[62:65], v80 offset:20480
	s_waitcnt lgkmcnt(2)
	v_pk_fma_f32 v[168:169], v[58:59], v[148:149], v[168:169] op_sel_hi:[0,1,1]
	v_pk_fma_f32 v[170:171], v[58:59], v[150:151], v[170:171] op_sel_hi:[0,1,1]
	ds_read_b128 v[148:151], v80 offset:21504
	s_waitcnt lgkmcnt(2)
	v_pk_fma_f32 v[156:157], v[58:59], v[152:153], v[156:157] op_sel_hi:[0,1,1]
	v_pk_fma_f32 v[158:159], v[58:59], v[154:155], v[158:159] op_sel_hi:[0,1,1]
	s_waitcnt lgkmcnt(1)
	v_pk_fma_f32 v[162:163], v[58:59], v[64:65], v[162:163] op_sel:[1,0,0]
	ds_read_b128 v[152:155], v80 offset:22528
	v_pk_fma_f32 v[160:161], v[58:59], v[62:63], v[160:161] op_sel:[1,0,0]
	ds_read_b128 v[62:65], v80 offset:23552
	s_waitcnt lgkmcnt(2)
	v_pk_fma_f32 v[166:167], v[58:59], v[150:151], v[166:167] op_sel:[1,0,0]
	v_pk_fma_f32 v[164:165], v[58:59], v[148:149], v[164:165] op_sel:[1,0,0]
	ds_read_b128 v[148:151], v80 offset:24576
	s_waitcnt lgkmcnt(2)
	v_pk_fma_f32 v[170:171], v[58:59], v[154:155], v[170:171] op_sel:[1,0,0]
	v_pk_fma_f32 v[168:169], v[58:59], v[152:153], v[168:169] op_sel:[1,0,0]
	s_waitcnt lgkmcnt(1)
	v_pk_fma_f32 v[158:159], v[58:59], v[64:65], v[158:159] op_sel:[1,0,0]
	ds_read_b128 v[152:155], v80 offset:25600
	v_pk_fma_f32 v[58:59], v[58:59], v[62:63], v[156:157] op_sel:[1,0,0]
	ds_read_b128 v[62:65], v80 offset:26624
	s_waitcnt lgkmcnt(2)
	v_pk_fma_f32 v[156:157], v[60:61], v[148:149], v[160:161] op_sel_hi:[0,1,1]
	v_pk_fma_f32 v[160:161], v[60:61], v[150:151], v[162:163] op_sel_hi:[0,1,1]
	ds_read_b128 v[148:151], v80 offset:27648
	s_waitcnt lgkmcnt(2)
	v_pk_fma_f32 v[152:153], v[60:61], v[152:153], v[164:165] op_sel_hi:[0,1,1]
	s_waitcnt lgkmcnt(1)
	v_pk_fma_f32 v[162:163], v[60:61], v[62:63], v[168:169] op_sel_hi:[0,1,1]
	v_pk_fma_f32 v[164:165], v[60:61], v[64:65], v[170:171] op_sel_hi:[0,1,1]
	ds_read_b128 v[62:65], v80 offset:28672
	v_pk_fma_f32 v[154:155], v[60:61], v[154:155], v[166:167] op_sel_hi:[0,1,1]
	s_waitcnt lgkmcnt(1)
	v_pk_fma_f32 v[166:167], v[60:61], v[148:149], v[58:59] op_sel_hi:[0,1,1]
	v_pk_fma_f32 v[158:159], v[60:61], v[150:151], v[158:159] op_sel_hi:[0,1,1]
	ds_read_b128 v[148:151], v80 offset:29696
	v_mov_b32_e32 v168, v61
	ds_read_b128 v[58:61], v80 offset:30720
	s_waitcnt lgkmcnt(2)
	v_pk_fma_f32 v[160:161], v[168:169], v[64:65], v[160:161] op_sel_hi:[0,1,1]
	v_pk_fma_f32 v[156:157], v[168:169], v[62:63], v[156:157] op_sel_hi:[0,1,1]
	ds_read_b128 v[62:65], v80 offset:31744
	s_waitcnt lgkmcnt(2)
	v_pk_fma_f32 v[154:155], v[168:169], v[150:151], v[154:155] op_sel_hi:[0,1,1]
	v_pk_fma_f32 v[152:153], v[168:169], v[148:149], v[152:153] op_sel_hi:[0,1,1]
	s_waitcnt lgkmcnt(1)
	v_pk_fma_f32 v[164:165], v[168:169], v[60:61], v[164:165] op_sel_hi:[0,1,1]
	ds_read_b128 v[148:151], v80 offset:32768
	v_pk_fma_f32 v[162:163], v[168:169], v[58:59], v[162:163] op_sel_hi:[0,1,1]
	ds_read_b128 v[58:61], v80 offset:33792
	s_waitcnt lgkmcnt(2)
	v_pk_fma_f32 v[158:159], v[168:169], v[64:65], v[158:159] op_sel_hi:[0,1,1]
	v_pk_fma_f32 v[166:167], v[168:169], v[62:63], v[166:167] op_sel_hi:[0,1,1]
	ds_read_b128 v[62:65], v80 offset:34816
	s_waitcnt lgkmcnt(2)
	v_pk_fma_f32 v[156:157], v[54:55], v[148:149], v[156:157] op_sel_hi:[0,1,1]
	v_pk_fma_f32 v[160:161], v[54:55], v[150:151], v[160:161] op_sel_hi:[0,1,1]
	s_waitcnt lgkmcnt(1)
	v_pk_fma_f32 v[152:153], v[54:55], v[58:59], v[152:153] op_sel_hi:[0,1,1]
	ds_read_b128 v[148:151], v80 offset:35840
	v_pk_fma_f32 v[154:155], v[54:55], v[60:61], v[154:155] op_sel_hi:[0,1,1]
	ds_read_b128 v[58:61], v80 offset:36864
	s_waitcnt lgkmcnt(2)
	v_pk_fma_f32 v[162:163], v[54:55], v[62:63], v[162:163] op_sel_hi:[0,1,1]
	v_pk_fma_f32 v[164:165], v[54:55], v[64:65], v[164:165] op_sel_hi:[0,1,1]
	ds_read_b128 v[62:65], v80 offset:37888
	s_waitcnt lgkmcnt(2)
	v_pk_fma_f32 v[166:167], v[54:55], v[148:149], v[166:167] op_sel_hi:[0,1,1]
	v_pk_fma_f32 v[158:159], v[54:55], v[150:151], v[158:159] op_sel_hi:[0,1,1]
	s_waitcnt lgkmcnt(1)
	v_pk_fma_f32 v[160:161], v[54:55], v[60:61], v[160:161] op_sel:[1,0,0]
	ds_read_b128 v[148:151], v80 offset:38912
	v_pk_fma_f32 v[156:157], v[54:55], v[58:59], v[156:157] op_sel:[1,0,0]
	ds_read_b128 v[58:61], v80 offset:39936
	s_waitcnt lgkmcnt(2)
	v_pk_fma_f32 v[154:155], v[54:55], v[64:65], v[154:155] op_sel:[1,0,0]
	v_pk_fma_f32 v[152:153], v[54:55], v[62:63], v[152:153] op_sel:[1,0,0]
	ds_read_b128 v[62:65], v80 offset:40960
	s_waitcnt lgkmcnt(2)
	v_pk_fma_f32 v[164:165], v[54:55], v[150:151], v[164:165] op_sel:[1,0,0]
	v_pk_fma_f32 v[162:163], v[54:55], v[148:149], v[162:163] op_sel:[1,0,0]
	s_waitcnt lgkmcnt(1)
	v_pk_fma_f32 v[158:159], v[54:55], v[60:61], v[158:159] op_sel:[1,0,0]
	ds_read_b128 v[148:151], v80 offset:41984
	v_pk_fma_f32 v[54:55], v[54:55], v[58:59], v[166:167] op_sel:[1,0,0]
	ds_read_b128 v[58:61], v80 offset:43008
	s_waitcnt lgkmcnt(2)
	v_pk_fma_f32 v[156:157], v[56:57], v[62:63], v[156:157] op_sel_hi:[0,1,1]
	v_pk_fma_f32 v[160:161], v[56:57], v[64:65], v[160:161] op_sel_hi:[0,1,1]
	ds_read_b128 v[62:65], v80 offset:44032
	s_waitcnt lgkmcnt(2)
	v_pk_fma_f32 v[148:149], v[56:57], v[148:149], v[152:153] op_sel_hi:[0,1,1]
	v_pk_fma_f32 v[150:151], v[56:57], v[150:151], v[154:155] op_sel_hi:[0,1,1]
	s_waitcnt lgkmcnt(1)
	v_pk_fma_f32 v[152:153], v[56:57], v[58:59], v[162:163] op_sel_hi:[0,1,1]
	v_pk_fma_f32 v[154:155], v[56:57], v[60:61], v[164:165] op_sel_hi:[0,1,1]
	ds_read_b128 v[58:61], v80 offset:45056
	s_waitcnt lgkmcnt(1)
	v_pk_fma_f32 v[162:163], v[56:57], v[62:63], v[54:55] op_sel_hi:[0,1,1]
	v_pk_fma_f32 v[158:159], v[56:57], v[64:65], v[158:159] op_sel_hi:[0,1,1]
	ds_read_b128 v[62:65], v80 offset:46080
	v_mov_b32_e32 v164, v57
	ds_read_b128 v[54:57], v80 offset:47104
	s_waitcnt lgkmcnt(2)
	v_pk_fma_f32 v[160:161], v[164:165], v[60:61], v[160:161] op_sel_hi:[0,1,1]
	v_pk_fma_f32 v[156:157], v[164:165], v[58:59], v[156:157] op_sel_hi:[0,1,1]
	ds_read_b128 v[58:61], v80 offset:48128
	s_waitcnt lgkmcnt(2)
	v_pk_fma_f32 v[150:151], v[164:165], v[64:65], v[150:151] op_sel_hi:[0,1,1]
	v_pk_fma_f32 v[148:149], v[164:165], v[62:63], v[148:149] op_sel_hi:[0,1,1]
	s_waitcnt lgkmcnt(1)
	v_pk_fma_f32 v[154:155], v[164:165], v[56:57], v[154:155] op_sel_hi:[0,1,1]
	ds_read_b128 v[62:65], v80 offset:49152
	v_pk_fma_f32 v[152:153], v[164:165], v[54:55], v[152:153] op_sel_hi:[0,1,1]
	ds_read_b128 v[54:57], v80 offset:50176
	s_waitcnt lgkmcnt(2)
	v_pk_fma_f32 v[158:159], v[164:165], v[60:61], v[158:159] op_sel_hi:[0,1,1]
	v_pk_fma_f32 v[162:163], v[164:165], v[58:59], v[162:163] op_sel_hi:[0,1,1]
	ds_read_b128 v[58:61], v80 offset:51200
	s_waitcnt lgkmcnt(2)
	v_pk_fma_f32 v[156:157], v[50:51], v[62:63], v[156:157] op_sel_hi:[0,1,1]
	v_pk_fma_f32 v[160:161], v[50:51], v[64:65], v[160:161] op_sel_hi:[0,1,1]
	s_waitcnt lgkmcnt(1)
	v_pk_fma_f32 v[148:149], v[50:51], v[54:55], v[148:149] op_sel_hi:[0,1,1]
	ds_read_b128 v[62:65], v80 offset:52224
	v_pk_fma_f32 v[150:151], v[50:51], v[56:57], v[150:151] op_sel_hi:[0,1,1]
	ds_read_b128 v[54:57], v80 offset:53248
	s_waitcnt lgkmcnt(2)
	v_pk_fma_f32 v[152:153], v[50:51], v[58:59], v[152:153] op_sel_hi:[0,1,1]
	v_pk_fma_f32 v[154:155], v[50:51], v[60:61], v[154:155] op_sel_hi:[0,1,1]
	ds_read_b128 v[58:61], v80 offset:54272
	s_waitcnt lgkmcnt(2)
	v_pk_fma_f32 v[162:163], v[50:51], v[62:63], v[162:163] op_sel_hi:[0,1,1]
	v_pk_fma_f32 v[158:159], v[50:51], v[64:65], v[158:159] op_sel_hi:[0,1,1]
	s_waitcnt lgkmcnt(1)
	v_pk_fma_f32 v[160:161], v[50:51], v[56:57], v[160:161] op_sel:[1,0,0]
	ds_read_b128 v[62:65], v80 offset:55296
	v_pk_fma_f32 v[156:157], v[50:51], v[54:55], v[156:157] op_sel:[1,0,0]
	ds_read_b128 v[54:57], v80 offset:56320
	s_waitcnt lgkmcnt(2)
	v_pk_fma_f32 v[150:151], v[50:51], v[60:61], v[150:151] op_sel:[1,0,0]
	v_pk_fma_f32 v[148:149], v[50:51], v[58:59], v[148:149] op_sel:[1,0,0]
	ds_read_b128 v[58:61], v80 offset:57344
	s_waitcnt lgkmcnt(2)
	v_pk_fma_f32 v[154:155], v[50:51], v[64:65], v[154:155] op_sel:[1,0,0]
	v_pk_fma_f32 v[152:153], v[50:51], v[62:63], v[152:153] op_sel:[1,0,0]
	s_waitcnt lgkmcnt(1)
	v_pk_fma_f32 v[158:159], v[50:51], v[56:57], v[158:159] op_sel:[1,0,0]
	ds_read_b128 v[62:65], v80 offset:58368
	v_pk_fma_f32 v[50:51], v[50:51], v[54:55], v[162:163] op_sel:[1,0,0]
	ds_read_b128 v[54:57], v80 offset:59392
	s_waitcnt lgkmcnt(2)
	v_pk_fma_f32 v[156:157], v[52:53], v[58:59], v[156:157] op_sel_hi:[0,1,1]
	v_pk_fma_f32 v[160:161], v[52:53], v[60:61], v[160:161] op_sel_hi:[0,1,1]
	ds_read_b128 v[58:61], v80 offset:60416
	s_waitcnt lgkmcnt(2)
	v_pk_fma_f32 v[62:63], v[52:53], v[62:63], v[148:149] op_sel_hi:[0,1,1]
	v_pk_fma_f32 v[64:65], v[52:53], v[64:65], v[150:151] op_sel_hi:[0,1,1]
	s_waitcnt lgkmcnt(1)
	v_pk_fma_f32 v[148:149], v[52:53], v[54:55], v[152:153] op_sel_hi:[0,1,1]
	v_pk_fma_f32 v[150:151], v[52:53], v[56:57], v[154:155] op_sel_hi:[0,1,1]
	ds_read_b128 v[54:57], v80 offset:61440
	s_waitcnt lgkmcnt(1)
	v_pk_fma_f32 v[154:155], v[52:53], v[60:61], v[158:159] op_sel_hi:[0,1,1]
	v_mov_b32_e32 v158, v53
	v_pk_fma_f32 v[152:153], v[52:53], v[58:59], v[50:51] op_sel_hi:[0,1,1]
	ds_read_b128 v[58:61], v80 offset:62464
	s_waitcnt lgkmcnt(1)
	v_pk_fma_f32 v[160:161], v[158:159], v[56:57], v[160:161] op_sel_hi:[0,1,1]
	ds_read_b128 v[50:53], v80 offset:63488
	v_pk_fma_f32 v[156:157], v[158:159], v[54:55], v[156:157] op_sel_hi:[0,1,1]
	ds_read_b128 v[54:57], v80 offset:64512
	s_waitcnt lgkmcnt(2)
	v_pk_fma_f32 v[64:65], v[158:159], v[60:61], v[64:65] op_sel_hi:[0,1,1]
	v_pk_fma_f32 v[62:63], v[158:159], v[58:59], v[62:63] op_sel_hi:[0,1,1]
	s_waitcnt lgkmcnt(1)
	v_pk_fma_f32 v[150:151], v[158:159], v[52:53], v[150:151] op_sel_hi:[0,1,1]
	ds_read_b128 v[58:61], v81
	v_pk_fma_f32 v[148:149], v[158:159], v[50:51], v[148:149] op_sel_hi:[0,1,1]
	s_waitcnt lgkmcnt(1)
	v_pk_fma_f32 v[154:155], v[158:159], v[56:57], v[154:155] op_sel_hi:[0,1,1]
	ds_read_b128 v[50:53], v82
	v_pk_fma_f32 v[152:153], v[158:159], v[54:55], v[152:153] op_sel_hi:[0,1,1]
	ds_read_b128 v[54:57], v83
	s_waitcnt lgkmcnt(2)
	v_pk_fma_f32 v[156:157], v[46:47], v[58:59], v[156:157] op_sel_hi:[0,1,1]
	v_pk_fma_f32 v[158:159], v[46:47], v[60:61], v[160:161] op_sel_hi:[0,1,1]
	s_waitcnt lgkmcnt(1)
	v_pk_fma_f32 v[62:63], v[46:47], v[50:51], v[62:63] op_sel_hi:[0,1,1]
	ds_read_b128 v[58:61], v84
	v_pk_fma_f32 v[64:65], v[46:47], v[52:53], v[64:65] op_sel_hi:[0,1,1]
	s_waitcnt lgkmcnt(1)
	v_pk_fma_f32 v[148:149], v[46:47], v[54:55], v[148:149] op_sel_hi:[0,1,1]
	ds_read_b128 v[50:53], v85
	v_pk_fma_f32 v[150:151], v[46:47], v[56:57], v[150:151] op_sel_hi:[0,1,1]
	ds_read_b128 v[54:57], v86
	s_waitcnt lgkmcnt(2)
	v_pk_fma_f32 v[152:153], v[46:47], v[58:59], v[152:153] op_sel_hi:[0,1,1]
	v_pk_fma_f32 v[154:155], v[46:47], v[60:61], v[154:155] op_sel_hi:[0,1,1]
	s_waitcnt lgkmcnt(1)
	v_pk_fma_f32 v[158:159], v[46:47], v[52:53], v[158:159] op_sel:[1,0,0]
	ds_read_b128 v[58:61], v87
	v_pk_fma_f32 v[156:157], v[46:47], v[50:51], v[156:157] op_sel:[1,0,0]
	s_waitcnt lgkmcnt(1)
	v_pk_fma_f32 v[64:65], v[46:47], v[56:57], v[64:65] op_sel:[1,0,0]
	ds_read_b128 v[50:53], v88
	v_pk_fma_f32 v[62:63], v[46:47], v[54:55], v[62:63] op_sel:[1,0,0]
	ds_read_b128 v[54:57], v89
	s_waitcnt lgkmcnt(2)
	v_pk_fma_f32 v[150:151], v[46:47], v[60:61], v[150:151] op_sel:[1,0,0]
	v_pk_fma_f32 v[148:149], v[46:47], v[58:59], v[148:149] op_sel:[1,0,0]
	s_waitcnt lgkmcnt(1)
	v_pk_fma_f32 v[154:155], v[46:47], v[52:53], v[154:155] op_sel:[1,0,0]
	ds_read_b128 v[58:61], v90
	v_pk_fma_f32 v[46:47], v[46:47], v[50:51], v[152:153] op_sel:[1,0,0]
	s_waitcnt lgkmcnt(1)
	v_pk_fma_f32 v[152:153], v[48:49], v[54:55], v[156:157] op_sel_hi:[0,1,1]
	ds_read_b128 v[50:53], v91
	v_pk_fma_f32 v[156:157], v[48:49], v[56:57], v[158:159] op_sel_hi:[0,1,1]
	ds_read_b128 v[54:57], v92
	s_waitcnt lgkmcnt(2)
	v_pk_fma_f32 v[58:59], v[48:49], v[58:59], v[62:63] op_sel_hi:[0,1,1]
	v_pk_fma_f32 v[60:61], v[48:49], v[60:61], v[64:65] op_sel_hi:[0,1,1]
	s_waitcnt lgkmcnt(1)
	v_pk_fma_f32 v[62:63], v[48:49], v[50:51], v[148:149] op_sel_hi:[0,1,1]
	v_pk_fma_f32 v[64:65], v[48:49], v[52:53], v[150:151] op_sel_hi:[0,1,1]
	ds_read_b128 v[50:53], v93
	s_waitcnt lgkmcnt(1)
	v_pk_fma_f32 v[148:149], v[48:49], v[54:55], v[46:47] op_sel_hi:[0,1,1]
	v_pk_fma_f32 v[150:151], v[48:49], v[56:57], v[154:155] op_sel_hi:[0,1,1]
	ds_read_b128 v[54:57], v94
	v_mov_b32_e32 v154, v49
	ds_read_b128 v[46:49], v95
	s_waitcnt lgkmcnt(2)
	v_pk_fma_f32 v[156:157], v[154:155], v[52:53], v[156:157] op_sel_hi:[0,1,1]
	v_pk_fma_f32 v[152:153], v[154:155], v[50:51], v[152:153] op_sel_hi:[0,1,1]
	s_waitcnt lgkmcnt(1)
	v_pk_fma_f32 v[60:61], v[154:155], v[56:57], v[60:61] op_sel_hi:[0,1,1]
	ds_read_b128 v[50:53], v96
	v_pk_fma_f32 v[58:59], v[154:155], v[54:55], v[58:59] op_sel_hi:[0,1,1]
	s_waitcnt lgkmcnt(1)
	v_pk_fma_f32 v[64:65], v[154:155], v[48:49], v[64:65] op_sel_hi:[0,1,1]
	ds_read_b128 v[54:57], v97
	v_pk_fma_f32 v[62:63], v[154:155], v[46:47], v[62:63] op_sel_hi:[0,1,1]
	ds_read_b128 v[46:49], v98
	s_waitcnt lgkmcnt(2)
	v_pk_fma_f32 v[150:151], v[154:155], v[52:53], v[150:151] op_sel_hi:[0,1,1]
	v_pk_fma_f32 v[148:149], v[154:155], v[50:51], v[148:149] op_sel_hi:[0,1,1]
	s_waitcnt lgkmcnt(1)
	v_pk_fma_f32 v[152:153], v[42:43], v[54:55], v[152:153] op_sel_hi:[0,1,1]
	ds_read_b128 v[50:53], v99
	v_pk_fma_f32 v[154:155], v[42:43], v[56:57], v[156:157] op_sel_hi:[0,1,1]
	s_waitcnt lgkmcnt(1)
	v_pk_fma_f32 v[58:59], v[42:43], v[46:47], v[58:59] op_sel_hi:[0,1,1]
	ds_read_b128 v[54:57], v100
	v_pk_fma_f32 v[60:61], v[42:43], v[48:49], v[60:61] op_sel_hi:[0,1,1]
	ds_read_b128 v[46:49], v101
	s_waitcnt lgkmcnt(2)
	v_pk_fma_f32 v[62:63], v[42:43], v[50:51], v[62:63] op_sel_hi:[0,1,1]
	v_pk_fma_f32 v[64:65], v[42:43], v[52:53], v[64:65] op_sel_hi:[0,1,1]
	s_waitcnt lgkmcnt(1)
	v_pk_fma_f32 v[148:149], v[42:43], v[54:55], v[148:149] op_sel_hi:[0,1,1]
	ds_read_b128 v[50:53], v102
	v_pk_fma_f32 v[150:151], v[42:43], v[56:57], v[150:151] op_sel_hi:[0,1,1]
	s_waitcnt lgkmcnt(1)
	v_pk_fma_f32 v[154:155], v[42:43], v[48:49], v[154:155] op_sel:[1,0,0]
	ds_read_b128 v[54:57], v103
	v_pk_fma_f32 v[152:153], v[42:43], v[46:47], v[152:153] op_sel:[1,0,0]
	ds_read_b128 v[46:49], v104
	s_waitcnt lgkmcnt(2)
	v_pk_fma_f32 v[60:61], v[42:43], v[52:53], v[60:61] op_sel:[1,0,0]
	v_pk_fma_f32 v[58:59], v[42:43], v[50:51], v[58:59] op_sel:[1,0,0]
	s_waitcnt lgkmcnt(1)
	v_pk_fma_f32 v[64:65], v[42:43], v[56:57], v[64:65] op_sel:[1,0,0]
	ds_read_b128 v[50:53], v105
	v_pk_fma_f32 v[62:63], v[42:43], v[54:55], v[62:63] op_sel:[1,0,0]
	s_waitcnt lgkmcnt(1)
	v_pk_fma_f32 v[150:151], v[42:43], v[48:49], v[150:151] op_sel:[1,0,0]
	ds_read_b128 v[54:57], v106
	v_pk_fma_f32 v[42:43], v[42:43], v[46:47], v[148:149] op_sel:[1,0,0]
	ds_read_b128 v[46:49], v107
	s_waitcnt lgkmcnt(1)
	v_pk_fma_f32 v[54:55], v[44:45], v[54:55], v[58:59] op_sel_hi:[0,1,1]
	v_pk_fma_f32 v[56:57], v[44:45], v[56:57], v[60:61] op_sel_hi:[0,1,1]
	s_waitcnt lgkmcnt(0)
	v_pk_fma_f32 v[58:59], v[44:45], v[46:47], v[62:63] op_sel_hi:[0,1,1]
	v_pk_fma_f32 v[60:61], v[44:45], v[48:49], v[64:65] op_sel_hi:[0,1,1]
	ds_read_b128 v[46:49], v1
	v_pk_fma_f32 v[148:149], v[44:45], v[50:51], v[152:153] op_sel_hi:[0,1,1]
	v_pk_fma_f32 v[152:153], v[44:45], v[52:53], v[154:155] op_sel_hi:[0,1,1]
	ds_read_b128 v[50:53], v108
	s_waitcnt lgkmcnt(0)
	v_pk_fma_f32 v[64:65], v[44:45], v[52:53], v[150:151] op_sel_hi:[0,1,1]
	v_mov_b32_e32 v150, v45
	v_pk_fma_f32 v[62:63], v[44:45], v[50:51], v[42:43] op_sel_hi:[0,1,1]
	ds_read_b128 v[50:53], v109
	ds_read_b128 v[42:45], v110
	v_pk_fma_f32 v[152:153], v[150:151], v[48:49], v[152:153] op_sel_hi:[0,1,1]
	v_pk_fma_f32 v[148:149], v[150:151], v[46:47], v[148:149] op_sel_hi:[0,1,1]
	ds_read_b128 v[46:49], v111
	s_waitcnt lgkmcnt(2)
	v_pk_fma_f32 v[56:57], v[150:151], v[52:53], v[56:57] op_sel_hi:[0,1,1]
	v_pk_fma_f32 v[54:55], v[150:151], v[50:51], v[54:55] op_sel_hi:[0,1,1]
	s_waitcnt lgkmcnt(1)
	v_pk_fma_f32 v[60:61], v[150:151], v[44:45], v[60:61] op_sel_hi:[0,1,1]
	ds_read_b128 v[50:53], v112
	v_pk_fma_f32 v[58:59], v[150:151], v[42:43], v[58:59] op_sel_hi:[0,1,1]
	s_waitcnt lgkmcnt(1)
	v_pk_fma_f32 v[64:65], v[150:151], v[48:49], v[64:65] op_sel_hi:[0,1,1]
	ds_read_b128 v[42:45], v113
	v_pk_fma_f32 v[62:63], v[150:151], v[46:47], v[62:63] op_sel_hi:[0,1,1]
	ds_read_b128 v[46:49], v114
	s_waitcnt lgkmcnt(2)
	v_pk_fma_f32 v[148:149], v[38:39], v[50:51], v[148:149] op_sel_hi:[0,1,1]
	v_pk_fma_f32 v[150:151], v[38:39], v[52:53], v[152:153] op_sel_hi:[0,1,1]
	s_waitcnt lgkmcnt(1)
	v_pk_fma_f32 v[54:55], v[38:39], v[42:43], v[54:55] op_sel_hi:[0,1,1]
	ds_read_b128 v[50:53], v115
	v_pk_fma_f32 v[56:57], v[38:39], v[44:45], v[56:57] op_sel_hi:[0,1,1]
	s_waitcnt lgkmcnt(1)
	v_pk_fma_f32 v[58:59], v[38:39], v[46:47], v[58:59] op_sel_hi:[0,1,1]
	ds_read_b128 v[42:45], v116
	v_pk_fma_f32 v[60:61], v[38:39], v[48:49], v[60:61] op_sel_hi:[0,1,1]
	ds_read_b128 v[46:49], v117
	s_waitcnt lgkmcnt(2)
	v_pk_fma_f32 v[62:63], v[38:39], v[50:51], v[62:63] op_sel_hi:[0,1,1]
	v_pk_fma_f32 v[64:65], v[38:39], v[52:53], v[64:65] op_sel_hi:[0,1,1]
	s_waitcnt lgkmcnt(1)
	v_pk_fma_f32 v[150:151], v[38:39], v[44:45], v[150:151] op_sel:[1,0,0]
	ds_read_b128 v[50:53], v118
	v_pk_fma_f32 v[148:149], v[38:39], v[42:43], v[148:149] op_sel:[1,0,0]
	s_waitcnt lgkmcnt(1)
	v_pk_fma_f32 v[56:57], v[38:39], v[48:49], v[56:57] op_sel:[1,0,0]
	ds_read_b128 v[42:45], v119
	v_pk_fma_f32 v[54:55], v[38:39], v[46:47], v[54:55] op_sel:[1,0,0]
	ds_read_b128 v[46:49], v120
	s_waitcnt lgkmcnt(2)
	v_pk_fma_f32 v[60:61], v[38:39], v[52:53], v[60:61] op_sel:[1,0,0]
	v_pk_fma_f32 v[58:59], v[38:39], v[50:51], v[58:59] op_sel:[1,0,0]
	s_waitcnt lgkmcnt(1)
	v_pk_fma_f32 v[64:65], v[38:39], v[44:45], v[64:65] op_sel:[1,0,0]
	ds_read_b128 v[50:53], v121
	v_pk_fma_f32 v[38:39], v[38:39], v[42:43], v[62:63] op_sel:[1,0,0]
	s_waitcnt lgkmcnt(1)
	v_pk_fma_f32 v[62:63], v[40:41], v[46:47], v[148:149] op_sel_hi:[0,1,1]
	ds_read_b128 v[42:45], v122
	v_pk_fma_f32 v[148:149], v[40:41], v[48:49], v[150:151] op_sel_hi:[0,1,1]
	ds_read_b128 v[46:49], v123
	s_waitcnt lgkmcnt(2)
	v_pk_fma_f32 v[50:51], v[40:41], v[50:51], v[54:55] op_sel_hi:[0,1,1]
	v_pk_fma_f32 v[52:53], v[40:41], v[52:53], v[56:57] op_sel_hi:[0,1,1]
	s_waitcnt lgkmcnt(1)
	v_pk_fma_f32 v[54:55], v[40:41], v[42:43], v[58:59] op_sel_hi:[0,1,1]
	v_pk_fma_f32 v[56:57], v[40:41], v[44:45], v[60:61] op_sel_hi:[0,1,1]
	ds_read_b128 v[42:45], v124
	s_waitcnt lgkmcnt(1)
	v_pk_fma_f32 v[58:59], v[40:41], v[46:47], v[38:39] op_sel_hi:[0,1,1]
	v_pk_fma_f32 v[60:61], v[40:41], v[48:49], v[64:65] op_sel_hi:[0,1,1]
	ds_read_b128 v[46:49], v125
	v_mov_b32_e32 v64, v41
	ds_read_b128 v[38:41], v126
	s_waitcnt lgkmcnt(2)
	v_pk_fma_f32 v[148:149], v[64:65], v[44:45], v[148:149] op_sel_hi:[0,1,1]
	v_pk_fma_f32 v[62:63], v[64:65], v[42:43], v[62:63] op_sel_hi:[0,1,1]
	s_waitcnt lgkmcnt(1)
	v_pk_fma_f32 v[52:53], v[64:65], v[48:49], v[52:53] op_sel_hi:[0,1,1]
	ds_read_b128 v[42:45], v127
	v_pk_fma_f32 v[50:51], v[64:65], v[46:47], v[50:51] op_sel_hi:[0,1,1]
	s_waitcnt lgkmcnt(1)
	v_pk_fma_f32 v[56:57], v[64:65], v[40:41], v[56:57] op_sel_hi:[0,1,1]
	ds_read_b128 v[46:49], v128
	v_pk_fma_f32 v[54:55], v[64:65], v[38:39], v[54:55] op_sel_hi:[0,1,1]
	ds_read_b128 v[38:41], v129
	s_waitcnt lgkmcnt(2)
	v_pk_fma_f32 v[60:61], v[64:65], v[44:45], v[60:61] op_sel_hi:[0,1,1]
	v_pk_fma_f32 v[58:59], v[64:65], v[42:43], v[58:59] op_sel_hi:[0,1,1]
	s_waitcnt lgkmcnt(1)
	v_pk_fma_f32 v[62:63], v[34:35], v[46:47], v[62:63] op_sel_hi:[0,1,1]
	ds_read_b128 v[42:45], v130
	v_pk_fma_f32 v[64:65], v[34:35], v[48:49], v[148:149] op_sel_hi:[0,1,1]
	s_waitcnt lgkmcnt(1)
	v_pk_fma_f32 v[50:51], v[34:35], v[38:39], v[50:51] op_sel_hi:[0,1,1]
	ds_read_b128 v[46:49], v131
	v_pk_fma_f32 v[52:53], v[34:35], v[40:41], v[52:53] op_sel_hi:[0,1,1]
	ds_read_b128 v[38:41], v132
	s_waitcnt lgkmcnt(2)
	v_pk_fma_f32 v[54:55], v[34:35], v[42:43], v[54:55] op_sel_hi:[0,1,1]
	v_pk_fma_f32 v[56:57], v[34:35], v[44:45], v[56:57] op_sel_hi:[0,1,1]
	s_waitcnt lgkmcnt(1)
	v_pk_fma_f32 v[58:59], v[34:35], v[46:47], v[58:59] op_sel_hi:[0,1,1]
	ds_read_b128 v[42:45], v133
	v_pk_fma_f32 v[60:61], v[34:35], v[48:49], v[60:61] op_sel_hi:[0,1,1]
	s_waitcnt lgkmcnt(1)
	v_pk_fma_f32 v[64:65], v[34:35], v[40:41], v[64:65] op_sel:[1,0,0]
	ds_read_b128 v[46:49], v134
	v_pk_fma_f32 v[62:63], v[34:35], v[38:39], v[62:63] op_sel:[1,0,0]
	ds_read_b128 v[38:41], v135
	s_waitcnt lgkmcnt(2)
	v_pk_fma_f32 v[52:53], v[34:35], v[44:45], v[52:53] op_sel:[1,0,0]
	v_pk_fma_f32 v[50:51], v[34:35], v[42:43], v[50:51] op_sel:[1,0,0]
	s_waitcnt lgkmcnt(1)
	v_pk_fma_f32 v[56:57], v[34:35], v[48:49], v[56:57] op_sel:[1,0,0]
	ds_read_b128 v[42:45], v136
	v_pk_fma_f32 v[54:55], v[34:35], v[46:47], v[54:55] op_sel:[1,0,0]
	s_waitcnt lgkmcnt(1)
	v_pk_fma_f32 v[60:61], v[34:35], v[40:41], v[60:61] op_sel:[1,0,0]
	ds_read_b128 v[46:49], v137
	v_pk_fma_f32 v[34:35], v[34:35], v[38:39], v[58:59] op_sel:[1,0,0]
	ds_read_b128 v[38:41], v138
	s_waitcnt lgkmcnt(2)
	v_pk_fma_f32 v[58:59], v[36:37], v[42:43], v[62:63] op_sel_hi:[0,1,1]
	v_pk_fma_f32 v[62:63], v[36:37], v[44:45], v[64:65] op_sel_hi:[0,1,1]
	ds_read_b128 v[42:45], v139
	s_waitcnt lgkmcnt(2)
	v_pk_fma_f32 v[48:49], v[36:37], v[48:49], v[52:53] op_sel_hi:[0,1,1]
	s_waitcnt lgkmcnt(1)
	v_pk_fma_f32 v[52:53], v[36:37], v[38:39], v[54:55] op_sel_hi:[0,1,1]
	v_pk_fma_f32 v[54:55], v[36:37], v[40:41], v[56:57] op_sel_hi:[0,1,1]
	ds_read_b128 v[38:41], v140
	v_mov_b32_e32 v64, v37
	v_pk_fma_f32 v[50:51], v[36:37], v[46:47], v[50:51] op_sel_hi:[0,1,1]
	s_waitcnt lgkmcnt(1)
	v_pk_fma_f32 v[56:57], v[36:37], v[42:43], v[34:35] op_sel_hi:[0,1,1]
	v_pk_fma_f32 v[60:61], v[36:37], v[44:45], v[60:61] op_sel_hi:[0,1,1]
	ds_read_b128 v[34:37], v141
	s_waitcnt lgkmcnt(1)
	v_pk_fma_f32 v[62:63], v[64:65], v[40:41], v[62:63] op_sel_hi:[0,1,1]
	ds_read_b128 v[40:43], v142
	v_pk_fma_f32 v[38:39], v[64:65], v[38:39], v[58:59] op_sel_hi:[0,1,1]
	ds_read_b128 v[44:47], v143
	s_waitcnt lgkmcnt(2)
	v_pk_fma_f32 v[36:37], v[64:65], v[36:37], v[48:49] op_sel_hi:[0,1,1]
	v_pk_fma_f32 v[34:35], v[64:65], v[34:35], v[50:51] op_sel_hi:[0,1,1]
	s_waitcnt lgkmcnt(1)
	v_pk_fma_f32 v[40:41], v[64:65], v[40:41], v[52:53] op_sel_hi:[0,1,1]
	v_cndmask_b32_e64 v48, v40, v38, s[4:5]
	v_cndmask_b32_e64 v38, v38, v40, s[4:5]
	v_cndmask_b32_e64 v40, v39, v41, s[4:5]
	ds_bpermute_b32 v40, v79, v40
	v_pk_fma_f32 v[42:43], v[64:65], v[42:43], v[54:55] op_sel_hi:[0,1,1]
	s_waitcnt lgkmcnt(1)
	v_pk_fma_f32 v[44:45], v[64:65], v[44:45], v[56:57] op_sel_hi:[0,1,1]
	v_cndmask_b32_e64 v39, v41, v39, s[4:5]
	v_cndmask_b32_e64 v49, v62, v42, s[4:5]
	s_waitcnt lgkmcnt(0)
	v_add_f32_e32 v39, v39, v40
	v_cndmask_b32_e64 v40, v42, v62, s[4:5]
	v_cndmask_b32_e64 v41, v43, v63, s[4:5]
	v_cndmask_b32_e64 v42, v63, v43, s[4:5]
	v_cndmask_b32_e64 v43, v34, v44, s[4:5]
	ds_bpermute_b32 v38, v79, v38
	ds_bpermute_b32 v42, v79, v42
	ds_bpermute_b32 v43, v79, v43
	v_pk_fma_f32 v[46:47], v[64:65], v[46:47], v[60:61] op_sel_hi:[0,1,1]
	v_cndmask_b32_e64 v34, v44, v34, s[4:5]
	s_waitcnt lgkmcnt(2)
	v_add_f32_e32 v38, v48, v38
	v_cndmask_b32_e64 v48, v35, v45, s[4:5]
	s_waitcnt lgkmcnt(1)
	v_add_f32_e32 v41, v41, v42
	s_waitcnt lgkmcnt(0)
	v_add_f32_e32 v34, v34, v43
	v_cndmask_b32_e64 v42, v46, v36, s[4:5]
	v_cndmask_b32_e64 v36, v36, v46, s[4:5]
	v_cndmask_b32_e64 v43, v37, v47, s[4:5]
	ds_bpermute_b32 v49, v79, v49
	ds_bpermute_b32 v48, v79, v48
	ds_bpermute_b32 v36, v79, v36
	ds_bpermute_b32 v43, v79, v43
	v_cndmask_b32_e64 v35, v45, v35, s[4:5]
	v_cndmask_b32_e64 v37, v47, v37, s[4:5]
	s_waitcnt lgkmcnt(3)
	v_add_f32_e32 v40, v40, v49
	s_waitcnt lgkmcnt(2)
	v_add_f32_e32 v35, v35, v48
	s_waitcnt lgkmcnt(1)
	v_add_f32_e32 v36, v42, v36
	s_waitcnt lgkmcnt(0)
	v_add_f32_e32 v37, v37, v43
	v_cndmask_b32_e64 v44, v38, v34, s[6:7]
	v_cndmask_b32_e64 v34, v34, v38, s[6:7]
	v_cndmask_b32_e64 v38, v35, v39, s[6:7]
	v_cndmask_b32_e64 v35, v39, v35, s[6:7]
	v_cndmask_b32_e64 v39, v40, v36, s[6:7]
	v_cndmask_b32_e64 v42, v41, v37, s[6:7]
	ds_bpermute_b32 v44, v78, v44
	ds_bpermute_b32 v35, v78, v35
	ds_bpermute_b32 v39, v78, v39
	ds_bpermute_b32 v42, v78, v42
	v_cndmask_b32_e64 v36, v36, v40, s[6:7]
	v_cndmask_b32_e64 v37, v37, v41, s[6:7]
	s_waitcnt lgkmcnt(3)
	v_add_f32_e32 v34, v34, v44
	s_waitcnt lgkmcnt(2)
	v_add_f32_e32 v35, v38, v35
	s_waitcnt lgkmcnt(1)
	v_add_f32_e32 v36, v36, v39
	s_waitcnt lgkmcnt(0)
	v_add_f32_e32 v37, v37, v42
	v_cndmask_b32_e64 v38, v34, v36, s[8:9]
	v_cndmask_b32_e64 v39, v35, v37, s[8:9]
	ds_bpermute_b32 v38, v77, v38
	ds_bpermute_b32 v39, v77, v39
	v_cndmask_b32_e64 v34, v36, v34, s[8:9]
	v_cndmask_b32_e64 v35, v37, v35, s[8:9]
	s_waitcnt lgkmcnt(1)
	v_add_f32_e32 v34, v34, v38
	s_waitcnt lgkmcnt(0)
	v_add_f32_e32 v35, v35, v39
	v_cndmask_b32_e64 v36, v34, v35, s[10:11]
	ds_bpermute_b32 v36, v76, v36
	v_cndmask_b32_e64 v34, v35, v34, s[10:11]
	s_waitcnt lgkmcnt(0)
	v_add_f32_e32 v34, v34, v36
	ds_bpermute_b32 v35, v75, v34
	s_waitcnt lgkmcnt(0)
	v_add_f32_e32 v34, v34, v35
	ds_bpermute_b32 v35, v74, v34
	s_and_saveexec_b64 s[14:15], s[12:13]
	s_cbranch_execz .LBB0_160
	s_waitcnt lgkmcnt(0)
	v_add_f32_e32 v34, v34, v35
	v_mul_f32_e32 v34, v146, v34
	global_store_dword v[68:69], v34, off
	s_branch .LBB0_160

.LBB0_673:
	ds_read_b128 v[144:147], v153
	ds_read_b128 v[158:161], v153 offset:1024
	ds_read_b128 v[162:165], v153 offset:2048
	ds_read_b128 v[166:169], v153 offset:3072
	ds_read_b128 v[170:173], v154
	ds_read_b128 v[174:177], v154 offset:1024
	ds_read_b128 v[178:181], v154 offset:2048
	ds_read_b128 v[182:185], v154 offset:3072
	s_add_u32 s33, s30, 0xfff80080
	s_addc_u32 s34, s31, -1
	s_cmp_eq_u32 s69, 28
	s_cselect_b32 s37, s25, s34
	s_cselect_b32 s36, s65, s33
	s_cselect_b32 s35, s23, s68
	s_cselect_b32 s34, s66, s67
	v_lshl_add_u64 v[148:149], s[30:31], 0, v[136:137]
	s_add_i32 m0, s48, 0xc000
	ds_read_b128 v[186:189], v155
	ds_read_b128 v[194:197], v155 offset:1024
	ds_read_b128 v[198:201], v155 offset:2048
	ds_read_b128 v[202:205], v155 offset:3072
	ds_read_b128 v[206:209], v155 offset:4096
	ds_read_b128 v[210:213], v155 offset:5120
	ds_read_b128 v[214:217], v155 offset:6144
	ds_read_b128 v[218:221], v155 offset:7168
	global_load_lds_dwordx4 v[148:149], off
	v_lshl_add_u64 v[148:149], s[30:31], 0, v[138:139]
	s_add_i32 m0, s48, 0xe000
	s_nop 0
	global_load_lds_dwordx4 v[148:149], off
	s_waitcnt vmcnt(8)
	s_waitcnt lgkmcnt(0)
	s_barrier
	s_setprio 1
	s_waitcnt lgkmcnt(0)
	v_mfma_f32_16x16x32_bf16 v[116:119], v[144:147], v[186:189], v[116:119]
	v_mfma_f32_16x16x32_bf16 v[112:115], v[162:165], v[186:189], v[112:115]
	v_mfma_f32_16x16x32_bf16 v[100:103], v[144:147], v[198:201], v[100:103]
	v_mfma_f32_16x16x32_bf16 v[96:99], v[162:165], v[198:201], v[96:99]
	v_mfma_f32_16x16x32_bf16 v[84:87], v[144:147], v[206:209], v[84:87]
	v_mfma_f32_16x16x32_bf16 v[80:83], v[162:165], v[206:209], v[80:83]
	v_mfma_f32_16x16x32_bf16 v[68:71], v[144:147], v[214:217], v[68:71]
	v_mfma_f32_16x16x32_bf16 v[64:67], v[162:165], v[214:217], v[64:67]
	v_mfma_f32_16x16x32_bf16 v[116:119], v[158:161], v[194:197], v[116:119]
	v_mfma_f32_16x16x32_bf16 v[112:115], v[166:169], v[194:197], v[112:115]
	v_mfma_f32_16x16x32_bf16 v[100:103], v[158:161], v[202:205], v[100:103]
	v_mfma_f32_16x16x32_bf16 v[96:99], v[166:169], v[202:205], v[96:99]
	v_mfma_f32_16x16x32_bf16 v[84:87], v[158:161], v[210:213], v[84:87]
	v_mfma_f32_16x16x32_bf16 v[80:83], v[166:169], v[210:213], v[80:83]
	v_mfma_f32_16x16x32_bf16 v[68:71], v[158:161], v[218:221], v[68:71]
	v_mfma_f32_16x16x32_bf16 v[64:67], v[166:169], v[218:221], v[64:67]
	s_setprio 0
	s_setprio 1
	v_mfma_f32_16x16x32_bf16 v[124:127], v[170:173], v[186:189], v[124:127]
	v_mfma_f32_16x16x32_bf16 v[120:123], v[178:181], v[186:189], v[120:123]
	v_mfma_f32_16x16x32_bf16 v[108:111], v[170:173], v[198:201], v[108:111]
	v_mfma_f32_16x16x32_bf16 v[104:107], v[178:181], v[198:201], v[104:107]
	v_mfma_f32_16x16x32_bf16 v[92:95], v[170:173], v[206:209], v[92:95]
	v_mfma_f32_16x16x32_bf16 v[88:91], v[178:181], v[206:209], v[88:91]
	v_mfma_f32_16x16x32_bf16 v[76:79], v[170:173], v[214:217], v[76:79]
	v_mfma_f32_16x16x32_bf16 v[72:75], v[178:181], v[214:217], v[72:75]
	v_mfma_f32_16x16x32_bf16 v[124:127], v[174:177], v[194:197], v[124:127]
	v_mfma_f32_16x16x32_bf16 v[120:123], v[182:185], v[194:197], v[120:123]
	v_mfma_f32_16x16x32_bf16 v[108:111], v[174:177], v[202:205], v[108:111]
	v_mfma_f32_16x16x32_bf16 v[104:107], v[182:185], v[202:205], v[104:107]
	v_mfma_f32_16x16x32_bf16 v[92:95], v[174:177], v[210:213], v[92:95]
	v_mfma_f32_16x16x32_bf16 v[88:91], v[182:185], v[210:213], v[88:91]
	v_mfma_f32_16x16x32_bf16 v[76:79], v[174:177], v[218:221], v[76:79]
	v_mfma_f32_16x16x32_bf16 v[72:75], v[182:185], v[218:221], v[72:75]
	s_setprio 0
	s_barrier
	s_add_i32 s33, s61, s42
	v_lshl_add_u64 v[148:149], s[34:35], 0, v[132:133]
	s_mov_b32 m0, s33
	ds_read_b128 v[186:189], v155 offset:16384
	ds_read_b128 v[194:197], v155 offset:17408
	ds_read_b128 v[198:201], v155 offset:18432
	ds_read_b128 v[202:205], v155 offset:19456
	ds_read_b128 v[206:209], v155 offset:20480
	ds_read_b128 v[210:213], v155 offset:21504
	ds_read_b128 v[214:217], v155 offset:22528
	ds_read_b128 v[218:221], v155 offset:23552
	global_load_lds_dwordx4 v[148:149], off
	s_add_i32 m0, s33, 0x2000
	s_add_u32 s54, s34, 0x80000
	v_lshl_add_u64 v[190:191], s[34:35], 0, v[128:129]
	s_addc_u32 s55, s35, 0
	s_add_i32 s33, s62, s42
	global_load_lds_dwordx4 v[190:191], off
	v_lshl_add_u64 v[222:223], s[54:55], 0, v[132:133]
	s_mov_b32 m0, s33
	v_lshl_add_u64 v[224:225], s[36:37], 0, v[130:131]
	global_load_lds_dwordx4 v[222:223], off
	v_lshl_add_u64 v[222:223], s[54:55], 0, v[128:129]
	s_add_i32 m0, s33, 0x2000
	s_nop 0
	global_load_lds_dwordx4 v[222:223], off
	v_lshl_add_u64 v[222:223], s[36:37], 0, v[134:135]
	s_mov_b32 m0, s48
	s_nop 0
	global_load_lds_dwordx4 v[222:223], off
	s_mov_b32 m0, s49
	s_nop 0
	global_load_lds_dwordx4 v[224:225], off
	s_waitcnt vmcnt(8)
	s_waitcnt lgkmcnt(0)
	s_barrier
	s_setprio 1
	s_waitcnt lgkmcnt(0)
	v_mfma_f32_16x16x32_bf16 v[52:55], v[144:147], v[186:189], v[52:55]
	v_mfma_f32_16x16x32_bf16 v[48:51], v[162:165], v[186:189], v[48:51]
	v_mfma_f32_16x16x32_bf16 v[36:39], v[144:147], v[198:201], v[36:39]
	v_mfma_f32_16x16x32_bf16 v[32:35], v[162:165], v[198:201], v[32:35]
	v_mfma_f32_16x16x32_bf16 v[20:23], v[144:147], v[206:209], v[20:23]
	v_mfma_f32_16x16x32_bf16 v[16:19], v[162:165], v[206:209], v[16:19]
	v_mfma_f32_16x16x32_bf16 v[4:7], v[144:147], v[214:217], v[4:7]
	v_mfma_f32_16x16x32_bf16 v[0:3], v[162:165], v[214:217], v[0:3]
	v_mfma_f32_16x16x32_bf16 v[52:55], v[158:161], v[194:197], v[52:55]
	v_mfma_f32_16x16x32_bf16 v[48:51], v[166:169], v[194:197], v[48:51]
	v_mfma_f32_16x16x32_bf16 v[36:39], v[158:161], v[202:205], v[36:39]
	v_mfma_f32_16x16x32_bf16 v[32:35], v[166:169], v[202:205], v[32:35]
	v_mfma_f32_16x16x32_bf16 v[20:23], v[158:161], v[210:213], v[20:23]
	v_mfma_f32_16x16x32_bf16 v[16:19], v[166:169], v[210:213], v[16:19]
	v_mfma_f32_16x16x32_bf16 v[4:7], v[158:161], v[218:221], v[4:7]
	v_mfma_f32_16x16x32_bf16 v[0:3], v[166:169], v[218:221], v[0:3]
	s_setprio 0
	s_setprio 1
	v_mfma_f32_16x16x32_bf16 v[60:63], v[170:173], v[186:189], v[60:63]
	v_mfma_f32_16x16x32_bf16 v[56:59], v[178:181], v[186:189], v[56:59]
	v_mfma_f32_16x16x32_bf16 v[44:47], v[170:173], v[198:201], v[44:47]
	v_mfma_f32_16x16x32_bf16 v[40:43], v[178:181], v[198:201], v[40:43]
	v_mfma_f32_16x16x32_bf16 v[28:31], v[170:173], v[206:209], v[28:31]
	v_mfma_f32_16x16x32_bf16 v[24:27], v[178:181], v[206:209], v[24:27]
	v_mfma_f32_16x16x32_bf16 v[12:15], v[170:173], v[214:217], v[12:15]
	v_mfma_f32_16x16x32_bf16 v[8:11], v[178:181], v[214:217], v[8:11]
	v_mfma_f32_16x16x32_bf16 v[60:63], v[174:177], v[194:197], v[60:63]
	v_mfma_f32_16x16x32_bf16 v[56:59], v[182:185], v[194:197], v[56:59]
	v_mfma_f32_16x16x32_bf16 v[44:47], v[174:177], v[202:205], v[44:47]
	v_mfma_f32_16x16x32_bf16 v[40:43], v[182:185], v[202:205], v[40:43]
	v_mfma_f32_16x16x32_bf16 v[28:31], v[174:177], v[210:213], v[28:31]
	v_mfma_f32_16x16x32_bf16 v[24:27], v[182:185], v[210:213], v[24:27]
	v_mfma_f32_16x16x32_bf16 v[12:15], v[174:177], v[218:221], v[12:15]
	v_mfma_f32_16x16x32_bf16 v[8:11], v[182:185], v[218:221], v[8:11]
	s_setprio 0
	s_barrier
	s_add_i32 s33, 0, 0x18000
	s_add_i32 s54, 0, 0x1c000
	v_add_u32_e32 v166, s33, v151
	v_add_u32_e32 v182, s54, v151
	ds_read_b128 v[144:147], v166
	ds_read_b128 v[158:161], v166 offset:1024
	ds_read_b128 v[162:165], v166 offset:2048
	ds_read_b128 v[166:169], v166 offset:3072
	ds_read_b128 v[170:173], v182
	ds_read_b128 v[174:177], v182 offset:1024
	ds_read_b128 v[178:181], v182 offset:2048
	ds_read_b128 v[182:185], v182 offset:3072
	s_add_u32 s36, s36, 0x80000
	s_addc_u32 s37, s37, 0
	s_mov_b32 m0, s50
	v_lshl_add_u64 v[226:227], s[36:37], 0, v[134:135]
	ds_read_b128 v[186:189], v155 offset:32768
	ds_read_b128 v[194:197], v155 offset:33792
	ds_read_b128 v[198:201], v155 offset:34816
	ds_read_b128 v[202:205], v155 offset:35840
	ds_read_b128 v[206:209], v155 offset:36864
	ds_read_b128 v[210:213], v155 offset:37888
	ds_read_b128 v[214:217], v155 offset:38912
	ds_read_b128 v[218:221], v155 offset:39936
	global_load_lds_dwordx4 v[226:227], off
	v_lshl_add_u64 v[226:227], s[36:37], 0, v[130:131]
	s_mov_b32 m0, s51
	s_nop 0
	global_load_lds_dwordx4 v[226:227], off
	s_waitcnt vmcnt(8)
	s_waitcnt lgkmcnt(0)
	s_barrier
	s_setprio 1
	s_waitcnt lgkmcnt(0)
	v_mfma_f32_16x16x32_bf16 v[116:119], v[144:147], v[186:189], v[116:119]
	v_mfma_f32_16x16x32_bf16 v[112:115], v[162:165], v[186:189], v[112:115]
	v_mfma_f32_16x16x32_bf16 v[100:103], v[144:147], v[198:201], v[100:103]
	v_mfma_f32_16x16x32_bf16 v[96:99], v[162:165], v[198:201], v[96:99]
	v_mfma_f32_16x16x32_bf16 v[84:87], v[144:147], v[206:209], v[84:87]
	v_mfma_f32_16x16x32_bf16 v[80:83], v[162:165], v[206:209], v[80:83]
	v_mfma_f32_16x16x32_bf16 v[68:71], v[144:147], v[214:217], v[68:71]
	v_mfma_f32_16x16x32_bf16 v[64:67], v[162:165], v[214:217], v[64:67]
	v_mfma_f32_16x16x32_bf16 v[116:119], v[158:161], v[194:197], v[116:119]
	v_mfma_f32_16x16x32_bf16 v[112:115], v[166:169], v[194:197], v[112:115]
	v_mfma_f32_16x16x32_bf16 v[100:103], v[158:161], v[202:205], v[100:103]
	v_mfma_f32_16x16x32_bf16 v[96:99], v[166:169], v[202:205], v[96:99]
	v_mfma_f32_16x16x32_bf16 v[84:87], v[158:161], v[210:213], v[84:87]
	v_mfma_f32_16x16x32_bf16 v[80:83], v[166:169], v[210:213], v[80:83]
	v_mfma_f32_16x16x32_bf16 v[68:71], v[158:161], v[218:221], v[68:71]
	v_mfma_f32_16x16x32_bf16 v[64:67], v[166:169], v[218:221], v[64:67]
	s_setprio 0
	s_setprio 1
	v_mfma_f32_16x16x32_bf16 v[124:127], v[170:173], v[186:189], v[124:127]
	v_mfma_f32_16x16x32_bf16 v[120:123], v[178:181], v[186:189], v[120:123]
	v_mfma_f32_16x16x32_bf16 v[108:111], v[170:173], v[198:201], v[108:111]
	v_mfma_f32_16x16x32_bf16 v[104:107], v[178:181], v[198:201], v[104:107]
	v_mfma_f32_16x16x32_bf16 v[92:95], v[170:173], v[206:209], v[92:95]
	v_mfma_f32_16x16x32_bf16 v[88:91], v[178:181], v[206:209], v[88:91]
	v_mfma_f32_16x16x32_bf16 v[76:79], v[170:173], v[214:217], v[76:79]
	v_mfma_f32_16x16x32_bf16 v[72:75], v[178:181], v[214:217], v[72:75]
	v_mfma_f32_16x16x32_bf16 v[124:127], v[174:177], v[194:197], v[124:127]
	v_mfma_f32_16x16x32_bf16 v[120:123], v[182:185], v[194:197], v[120:123]
	v_mfma_f32_16x16x32_bf16 v[108:111], v[174:177], v[202:205], v[108:111]
	v_mfma_f32_16x16x32_bf16 v[104:107], v[182:185], v[202:205], v[104:107]
	v_mfma_f32_16x16x32_bf16 v[92:95], v[174:177], v[210:213], v[92:95]
	v_mfma_f32_16x16x32_bf16 v[88:91], v[182:185], v[210:213], v[88:91]
	v_mfma_f32_16x16x32_bf16 v[76:79], v[174:177], v[218:221], v[76:79]
	v_mfma_f32_16x16x32_bf16 v[72:75], v[182:185], v[218:221], v[72:75]
	s_setprio 0
	s_barrier
	s_add_i32 s33, s33, s42
	v_lshl_add_u64 v[148:149], v[148:149], 0, s[18:19]
	s_mov_b32 m0, s33
	ds_read_b128 v[186:189], v155 offset:49152
	ds_read_b128 v[194:197], v155 offset:50176
	ds_read_b128 v[198:201], v155 offset:51200
	ds_read_b128 v[202:205], v155 offset:52224
	ds_read_b128 v[206:209], v155 offset:53248
	ds_read_b128 v[210:213], v155 offset:54272
	ds_read_b128 v[214:217], v155 offset:55296
	ds_read_b128 v[218:221], v155 offset:56320
	global_load_lds_dwordx4 v[148:149], off
	s_add_i32 m0, s33, 0x2000
	s_add_u32 s34, s34, 0x80080
	v_lshl_add_u64 v[148:149], v[190:191], 0, s[18:19]
	s_addc_u32 s35, s35, 0
	s_add_i32 s33, s54, s42
	global_load_lds_dwordx4 v[148:149], off
	v_lshl_add_u64 v[148:149], s[34:35], 0, v[132:133]
	s_mov_b32 m0, s33
	s_nop 0
	global_load_lds_dwordx4 v[148:149], off
	v_lshl_add_u64 v[148:149], s[34:35], 0, v[128:129]
	s_add_i32 m0, s33, 0x2000
	s_nop 0
	global_load_lds_dwordx4 v[148:149], off
	v_lshl_add_u64 v[148:149], v[222:223], 0, s[18:19]
	s_mov_b32 m0, s59
	s_nop 0
	global_load_lds_dwordx4 v[148:149], off
	v_lshl_add_u64 v[148:149], v[224:225], 0, s[18:19]
	s_mov_b32 m0, s60
	s_nop 0
	global_load_lds_dwordx4 v[148:149], off
	s_waitcnt vmcnt(8)
	s_waitcnt lgkmcnt(0)
	s_barrier
	s_setprio 1
	s_waitcnt lgkmcnt(0)
	v_mfma_f32_16x16x32_bf16 v[52:55], v[144:147], v[186:189], v[52:55]
	v_mfma_f32_16x16x32_bf16 v[48:51], v[162:165], v[186:189], v[48:51]
	v_mfma_f32_16x16x32_bf16 v[36:39], v[144:147], v[198:201], v[36:39]
	v_mfma_f32_16x16x32_bf16 v[32:35], v[162:165], v[198:201], v[32:35]
	v_mfma_f32_16x16x32_bf16 v[20:23], v[144:147], v[206:209], v[20:23]
	v_mfma_f32_16x16x32_bf16 v[16:19], v[162:165], v[206:209], v[16:19]
	v_mfma_f32_16x16x32_bf16 v[4:7], v[144:147], v[214:217], v[4:7]
	v_mfma_f32_16x16x32_bf16 v[0:3], v[162:165], v[214:217], v[0:3]
	v_mfma_f32_16x16x32_bf16 v[52:55], v[158:161], v[194:197], v[52:55]
	v_mfma_f32_16x16x32_bf16 v[48:51], v[166:169], v[194:197], v[48:51]
	v_mfma_f32_16x16x32_bf16 v[36:39], v[158:161], v[202:205], v[36:39]
	v_mfma_f32_16x16x32_bf16 v[32:35], v[166:169], v[202:205], v[32:35]
	v_mfma_f32_16x16x32_bf16 v[20:23], v[158:161], v[210:213], v[20:23]
	v_mfma_f32_16x16x32_bf16 v[16:19], v[166:169], v[210:213], v[16:19]
	v_mfma_f32_16x16x32_bf16 v[4:7], v[158:161], v[218:221], v[4:7]
	v_mfma_f32_16x16x32_bf16 v[0:3], v[166:169], v[218:221], v[0:3]
	s_setprio 0
	s_setprio 1
	v_mfma_f32_16x16x32_bf16 v[60:63], v[170:173], v[186:189], v[60:63]
	v_mfma_f32_16x16x32_bf16 v[56:59], v[178:181], v[186:189], v[56:59]
	v_mfma_f32_16x16x32_bf16 v[44:47], v[170:173], v[198:201], v[44:47]
	v_mfma_f32_16x16x32_bf16 v[40:43], v[178:181], v[198:201], v[40:43]
	v_mfma_f32_16x16x32_bf16 v[28:31], v[170:173], v[206:209], v[28:31]
	v_mfma_f32_16x16x32_bf16 v[24:27], v[178:181], v[206:209], v[24:27]
	v_mfma_f32_16x16x32_bf16 v[12:15], v[170:173], v[214:217], v[12:15]
	v_mfma_f32_16x16x32_bf16 v[8:11], v[178:181], v[214:217], v[8:11]
	v_mfma_f32_16x16x32_bf16 v[60:63], v[174:177], v[194:197], v[60:63]
	v_mfma_f32_16x16x32_bf16 v[56:59], v[182:185], v[194:197], v[56:59]
	v_mfma_f32_16x16x32_bf16 v[44:47], v[174:177], v[202:205], v[44:47]
	v_mfma_f32_16x16x32_bf16 v[40:43], v[182:185], v[202:205], v[40:43]
	v_mfma_f32_16x16x32_bf16 v[28:31], v[174:177], v[210:213], v[28:31]
	v_mfma_f32_16x16x32_bf16 v[24:27], v[182:185], v[210:213], v[24:27]
	v_mfma_f32_16x16x32_bf16 v[12:15], v[174:177], v[218:221], v[12:15]
	v_mfma_f32_16x16x32_bf16 v[8:11], v[182:185], v[218:221], v[8:11]
	s_setprio 0
	s_barrier
	s_add_i32 s69, s69, 2
	s_add_u32 s30, s30, 0x100
	s_addc_u32 s31, s31, 0
	s_add_u32 s67, s67, 0x100
	s_addc_u32 s68, s68, 0
	s_cmp_gt_u32 s69, 29
	s_cbranch_scc0 .LBB0_673
	v_lshl_add_u32 v144, s8, 8, v150
	v_ashrrev_i32_e32 v145, 31, v144
	v_lshl_add_u64 v[148:149], v[144:145], 2, s[16:17]
	global_load_dword v172, v[148:149], off
	global_load_dword v173, v[148:149], off offset:64
	global_load_dword v174, v[148:149], off offset:128
	global_load_dword v175, v[148:149], off offset:192
	global_load_dword v176, v[148:149], off offset:512
	global_load_dword v177, v[148:149], off offset:576
	global_load_dword v178, v[148:149], off offset:640
	global_load_dword v179, v[148:149], off offset:704
	s_and_b64 vcc, exec, s[20:21]
	s_cbranch_vccz .LBB0_676
	s_barrier
.LBB0_676:
	s_nop 0
	v_mov_b32_e32 v160, v124
	v_mov_b32_e32 v124, v126
	v_mov_b32_e32 v126, v120
	v_mov_b32_e32 v161, v116
	v_mov_b32_e32 v116, v125
	v_mov_b32_e32 v125, v118
	v_mov_b32_e32 v118, v127
	v_mov_b32_e32 v127, v112
	v_mov_b32_e32 v112, v121
	v_lshl_or_b32 v158, s9, 7, v152
	v_ashrrev_i32_e32 v159, 31, v158
	v_mov_b64_e32 v[146:147], s[12:13]
	v_mov_b32_e32 v162, v122
	v_mov_b32_e32 v163, v114
	v_mov_b32_e32 v114, v123
	v_mad_i64_i32 v[122:123], s[8:9], v144, s63, v[146:147]
	v_or_b32_e32 v164, 16, v144
	v_ashrrev_i32_e32 v165, 31, v164
	s_waitcnt vmcnt(7)
	v_mov_b32_e32 v145, v172
	v_fmamk_f32 v120, v145, 0x3a000000, v156
	v_mul_f32_e32 v121, 0x4f800000, v120
	v_cmp_gt_f32_e32 vcc, s64, v120
	s_nop 1
	v_cndmask_b32_e32 v145, v120, v121, vcc
	v_sqrt_f32_e32 v166, v145
	v_lshlrev_b64 v[120:121], 1, v[158:159]
	v_lshl_add_u64 v[122:123], v[122:123], 0, v[120:121]
	v_add_u32_e32 v158, -1, v166
	v_add_u32_e32 v159, 1, v166
	v_fma_f32 v167, -v158, v166, v145
	v_fma_f32 v168, -v159, v166, v145
	v_cmp_ge_f32_e64 s[8:9], 0, v167
	s_nop 1
	v_cndmask_b32_e64 v158, v166, v158, s[8:9]
	v_cmp_lt_f32_e64 s[8:9], 0, v168
	s_nop 1
	v_cndmask_b32_e64 v158, v158, v159, s[8:9]
	v_mul_f32_e32 v159, 0x37800000, v158
	v_cndmask_b32_e32 v158, v158, v159, vcc
	v_cmp_class_f32_e32 vcc, v145, v157
	s_nop 1
	v_cndmask_b32_e32 v145, v158, v145, vcc
	v_div_scale_f32 v166, s[8:9], v145, v145, 1.0
	v_rcp_f32_e32 v167, v166
	v_lshl_add_u64 v[158:159], v[164:165], 2, s[16:17]
	v_div_scale_f32 v165, vcc, 1.0, v145, 1.0
	v_fma_f32 v168, -v166, v167, 1.0
	v_fmac_f32_e32 v167, v168, v167
	v_mul_f32_e32 v168, v165, v167
	v_fma_f32 v169, -v166, v168, v165
	v_fmac_f32_e32 v168, v169, v167
	v_fma_f32 v165, -v166, v168, v165
	v_div_fmas_f32 v165, v165, v167, v168
	v_div_fixup_f32 v166, v165, v145, 1.0
	v_pk_mul_f32 v[114:115], v[114:115], v[166:167] op_sel_hi:[1,0]
	v_pk_mul_f32 v[160:161], v[160:161], v[166:167] op_sel_hi:[1,0]
	v_pk_mul_f32 v[116:117], v[116:117], v[166:167] op_sel_hi:[1,0]
	v_pk_mul_f32 v[124:125], v[124:125], v[166:167] op_sel_hi:[1,0]
	v_pk_mul_f32 v[118:119], v[118:119], v[166:167] op_sel_hi:[1,0]
	v_pk_mul_f32 v[126:127], v[126:127], v[166:167] op_sel_hi:[1,0]
	v_pk_mul_f32 v[112:113], v[112:113], v[166:167] op_sel_hi:[1,0]
	v_pk_mul_f32 v[162:163], v[162:163], v[166:167] op_sel_hi:[1,0]
	v_mul_f32_e32 v171, 0xbfb8aa3b, v115
	v_mul_f32_e32 v145, 0xbfb8aa3b, v161
	v_mul_f32_e32 v165, 0xbfb8aa3b, v117
	v_mul_f32_e32 v166, 0xbfb8aa3b, v125
	v_mul_f32_e32 v167, 0xbfb8aa3b, v119
	v_mul_f32_e32 v168, 0xbfb8aa3b, v127
	v_mul_f32_e32 v169, 0xbfb8aa3b, v113
	v_mul_f32_e32 v170, 0xbfb8aa3b, v163
	v_exp_f32_e32 v171, v171
	v_exp_f32_e32 v145, v145
	v_exp_f32_e32 v165, v165
	v_exp_f32_e32 v166, v166
	v_exp_f32_e32 v167, v167
	v_exp_f32_e32 v168, v168
	v_exp_f32_e32 v169, v169
	v_exp_f32_e32 v170, v170
	v_add_f32_e32 v171, 1.0, v171
	v_add_f32_e32 v145, 1.0, v145
	v_add_f32_e32 v165, 1.0, v165
	v_add_f32_e32 v166, 1.0, v166
	v_add_f32_e32 v167, 1.0, v167
	v_add_f32_e32 v168, 1.0, v168
	v_add_f32_e32 v169, 1.0, v169
	v_add_f32_e32 v170, 1.0, v170
	v_rcp_f32_e32 v171, v171
	v_rcp_f32_e32 v145, v145
	v_rcp_f32_e32 v165, v165
	v_rcp_f32_e32 v166, v166
	v_rcp_f32_e32 v167, v167
	v_rcp_f32_e32 v168, v168
	v_rcp_f32_e32 v169, v169
	v_rcp_f32_e32 v170, v170
	v_mul_f32_e32 v115, v115, v171
	v_mul_f32_e32 v145, v161, v145
	v_mul_f32_e32 v117, v117, v165
	v_mul_f32_e32 v125, v125, v166
	v_mul_f32_e32 v119, v119, v167
	v_mul_f32_e32 v127, v127, v168
	v_mul_f32_e32 v113, v113, v169
	v_mul_f32_e32 v161, v163, v170
	v_mul_f32_e32 v115, v114, v115
	v_mul_f32_e32 v145, v160, v145
	v_mul_f32_e32 v116, v116, v117
	v_mul_f32_e32 v117, v124, v125
	v_mul_f32_e32 v118, v118, v119
	v_mul_f32_e32 v119, v126, v127
	v_mul_f32_e32 v124, v112, v113
	v_mul_f32_e32 v125, v162, v161
	v_cvt_pk_bf16_f32 v112, v145, v116
	v_cvt_pk_bf16_f32 v113, v117, v118
	v_cvt_pk_bf16_f32 v114, v119, v124
	v_cvt_pk_bf16_f32 v115, v125, v115
	global_store_dwordx4 v[122:123], v[112:115], off
	s_nop 0
	s_nop 0
	v_mov_b32_e32 v113, v100
	v_mov_b32_e32 v100, v109
	v_mov_b32_e32 v109, v102
	v_mov_b32_e32 v102, v111
	v_mov_b32_e32 v111, v96
	v_mov_b32_e32 v96, v105
	v_mov_b32_e32 v105, v98
	v_mov_b32_e32 v98, v107
	v_mov_b32_e32 v112, v108
	v_mov_b32_e32 v108, v110
	v_mov_b32_e32 v110, v104
	v_mov_b32_e32 v104, v106
	v_or_b32_e32 v106, 32, v144
	s_waitcnt vmcnt(7)
	v_mov_b32_e32 v114, v173
	v_fmamk_f32 v107, v114, 0x3a000000, v156
	v_mul_f32_e32 v114, 0x4f800000, v107
	v_cmp_gt_f32_e32 vcc, s64, v107
	s_nop 1
	v_cndmask_b32_e32 v116, v107, v114, vcc
	v_sqrt_f32_e32 v117, v116
	v_mad_i64_i32 v[114:115], s[8:9], v164, s63, v[146:147]
	v_ashrrev_i32_e32 v107, 31, v106
	v_add_u32_e32 v118, -1, v117
	v_add_u32_e32 v119, 1, v117
	v_fma_f32 v122, -v118, v117, v116
	v_fma_f32 v123, -v119, v117, v116
	v_cmp_ge_f32_e64 s[8:9], 0, v122
	v_lshl_add_u64 v[114:115], v[114:115], 0, v[120:121]
	s_nop 0
	v_cndmask_b32_e64 v117, v117, v118, s[8:9]
	v_cmp_lt_f32_e64 s[8:9], 0, v123
	s_nop 1
	v_cndmask_b32_e64 v117, v117, v119, s[8:9]
	v_mul_f32_e32 v118, 0x37800000, v117
	v_cndmask_b32_e32 v117, v117, v118, vcc
	v_cmp_class_f32_e32 vcc, v116, v157
	s_nop 1
	v_cndmask_b32_e32 v118, v117, v116, vcc
	v_div_scale_f32 v119, s[8:9], v118, v118, 1.0
	v_rcp_f32_e32 v122, v119
	v_lshl_add_u64 v[116:117], v[106:107], 2, s[16:17]
	v_div_scale_f32 v107, vcc, 1.0, v118, 1.0
	v_fma_f32 v123, -v119, v122, 1.0
	v_fmac_f32_e32 v122, v123, v122
	v_mul_f32_e32 v123, v107, v122
	v_fma_f32 v124, -v119, v123, v107
	v_fmac_f32_e32 v123, v124, v122
	v_fma_f32 v107, -v119, v123, v107
	v_div_fmas_f32 v107, v107, v122, v123
	v_div_fixup_f32 v118, v107, v118, 1.0
	v_pk_mul_f32 v[98:99], v[98:99], v[118:119] op_sel_hi:[1,0]
	v_pk_mul_f32 v[112:113], v[112:113], v[118:119] op_sel_hi:[1,0]
	v_pk_mul_f32 v[100:101], v[100:101], v[118:119] op_sel_hi:[1,0]
	v_pk_mul_f32 v[108:109], v[108:109], v[118:119] op_sel_hi:[1,0]
	v_pk_mul_f32 v[102:103], v[102:103], v[118:119] op_sel_hi:[1,0]
	v_pk_mul_f32 v[110:111], v[110:111], v[118:119] op_sel_hi:[1,0]
	v_pk_mul_f32 v[96:97], v[96:97], v[118:119] op_sel_hi:[1,0]
	v_pk_mul_f32 v[104:105], v[104:105], v[118:119] op_sel_hi:[1,0]
	v_mul_f32_e32 v126, 0xbfb8aa3b, v99
	v_mul_f32_e32 v107, 0xbfb8aa3b, v113
	v_mul_f32_e32 v118, 0xbfb8aa3b, v101
	v_mul_f32_e32 v119, 0xbfb8aa3b, v109
	v_mul_f32_e32 v122, 0xbfb8aa3b, v103
	v_mul_f32_e32 v123, 0xbfb8aa3b, v111
	v_mul_f32_e32 v124, 0xbfb8aa3b, v97
	v_mul_f32_e32 v125, 0xbfb8aa3b, v105
	v_exp_f32_e32 v126, v126
	v_exp_f32_e32 v107, v107
	v_exp_f32_e32 v118, v118
	v_exp_f32_e32 v119, v119
	v_exp_f32_e32 v122, v122
	v_exp_f32_e32 v123, v123
	v_exp_f32_e32 v124, v124
	v_exp_f32_e32 v125, v125
	v_add_f32_e32 v126, 1.0, v126
	v_add_f32_e32 v107, 1.0, v107
	v_add_f32_e32 v118, 1.0, v118
	v_add_f32_e32 v119, 1.0, v119
	v_add_f32_e32 v122, 1.0, v122
	v_add_f32_e32 v123, 1.0, v123
	v_add_f32_e32 v124, 1.0, v124
	v_add_f32_e32 v125, 1.0, v125
	v_rcp_f32_e32 v126, v126
	v_rcp_f32_e32 v107, v107
	v_rcp_f32_e32 v118, v118
	v_rcp_f32_e32 v119, v119
	v_rcp_f32_e32 v122, v122
	v_rcp_f32_e32 v123, v123
	v_rcp_f32_e32 v124, v124
	v_rcp_f32_e32 v125, v125
	v_mul_f32_e32 v99, v99, v126
	v_mul_f32_e32 v107, v113, v107
	v_mul_f32_e32 v101, v101, v118
	v_mul_f32_e32 v109, v109, v119
	v_mul_f32_e32 v103, v103, v122
	v_mul_f32_e32 v111, v111, v123
	v_mul_f32_e32 v97, v97, v124
	v_mul_f32_e32 v105, v105, v125
	v_mul_f32_e32 v99, v98, v99
	v_mul_f32_e32 v107, v112, v107
	v_mul_f32_e32 v100, v100, v101
	v_mul_f32_e32 v101, v108, v109
	v_mul_f32_e32 v102, v102, v103
	v_mul_f32_e32 v103, v110, v111
	v_mul_f32_e32 v108, v96, v97
	v_mul_f32_e32 v104, v104, v105
	v_cvt_pk_bf16_f32 v96, v107, v100
	v_cvt_pk_bf16_f32 v97, v101, v102
	v_cvt_pk_bf16_f32 v98, v103, v108
	v_cvt_pk_bf16_f32 v99, v104, v99
	global_store_dwordx4 v[114:115], v[96:99], off
	s_nop 0
	s_nop 0
	v_mov_b32_e32 v97, v84
	v_mov_b32_e32 v84, v93
	v_mov_b32_e32 v93, v86
	v_mov_b32_e32 v86, v95
	v_mov_b32_e32 v95, v80
	v_mov_b32_e32 v80, v89
	v_mov_b32_e32 v89, v82
	v_mov_b32_e32 v82, v91
	v_mov_b32_e32 v96, v92
	v_mov_b32_e32 v92, v94
	v_mov_b32_e32 v94, v88
	v_mov_b32_e32 v88, v90
	v_or_b32_e32 v90, 48, v144
	s_waitcnt vmcnt(7)
	v_mov_b32_e32 v98, v174
	v_fmamk_f32 v91, v98, 0x3a000000, v156
	v_mul_f32_e32 v98, 0x4f800000, v91
	v_cmp_gt_f32_e32 vcc, s64, v91
	s_nop 1
	v_cndmask_b32_e32 v100, v91, v98, vcc
	v_sqrt_f32_e32 v101, v100
	v_mad_i64_i32 v[98:99], s[8:9], v106, s63, v[146:147]
	v_ashrrev_i32_e32 v91, 31, v90
	v_add_u32_e32 v102, -1, v101
	v_add_u32_e32 v103, 1, v101
	v_fma_f32 v104, -v102, v101, v100
	v_fma_f32 v105, -v103, v101, v100
	v_cmp_ge_f32_e64 s[8:9], 0, v104
	v_lshl_add_u64 v[98:99], v[98:99], 0, v[120:121]
	s_nop 0
	v_cndmask_b32_e64 v101, v101, v102, s[8:9]
	v_cmp_lt_f32_e64 s[8:9], 0, v105
	s_nop 1
	v_cndmask_b32_e64 v101, v101, v103, s[8:9]
	v_mul_f32_e32 v102, 0x37800000, v101
	v_cndmask_b32_e32 v101, v101, v102, vcc
	v_cmp_class_f32_e32 vcc, v100, v157
	s_nop 1
	v_cndmask_b32_e32 v102, v101, v100, vcc
	v_div_scale_f32 v103, s[8:9], v102, v102, 1.0
	v_rcp_f32_e32 v104, v103
	v_lshl_add_u64 v[100:101], v[90:91], 2, s[16:17]
	v_div_scale_f32 v91, vcc, 1.0, v102, 1.0
	v_fma_f32 v105, -v103, v104, 1.0
	v_fmac_f32_e32 v104, v105, v104
	v_mul_f32_e32 v105, v91, v104
	v_fma_f32 v106, -v103, v105, v91
	v_fmac_f32_e32 v105, v106, v104
	v_fma_f32 v91, -v103, v105, v91
	v_div_fmas_f32 v91, v91, v104, v105
	v_div_fixup_f32 v102, v91, v102, 1.0
	v_pk_mul_f32 v[82:83], v[82:83], v[102:103] op_sel_hi:[1,0]
	v_pk_mul_f32 v[96:97], v[96:97], v[102:103] op_sel_hi:[1,0]
	v_pk_mul_f32 v[84:85], v[84:85], v[102:103] op_sel_hi:[1,0]
	v_pk_mul_f32 v[92:93], v[92:93], v[102:103] op_sel_hi:[1,0]
	v_pk_mul_f32 v[86:87], v[86:87], v[102:103] op_sel_hi:[1,0]
	v_pk_mul_f32 v[94:95], v[94:95], v[102:103] op_sel_hi:[1,0]
	v_pk_mul_f32 v[80:81], v[80:81], v[102:103] op_sel_hi:[1,0]
	v_pk_mul_f32 v[88:89], v[88:89], v[102:103] op_sel_hi:[1,0]
	v_mul_f32_e32 v108, 0xbfb8aa3b, v83
	v_mul_f32_e32 v91, 0xbfb8aa3b, v97
	v_mul_f32_e32 v102, 0xbfb8aa3b, v85
	v_mul_f32_e32 v103, 0xbfb8aa3b, v93
	v_mul_f32_e32 v104, 0xbfb8aa3b, v87
	v_mul_f32_e32 v105, 0xbfb8aa3b, v95
	v_mul_f32_e32 v106, 0xbfb8aa3b, v81
	v_mul_f32_e32 v107, 0xbfb8aa3b, v89
	v_exp_f32_e32 v108, v108
	v_exp_f32_e32 v91, v91
	v_exp_f32_e32 v102, v102
	v_exp_f32_e32 v103, v103
	v_exp_f32_e32 v104, v104
	v_exp_f32_e32 v105, v105
	v_exp_f32_e32 v106, v106
	v_exp_f32_e32 v107, v107
	v_add_f32_e32 v108, 1.0, v108
	v_add_f32_e32 v91, 1.0, v91
	v_add_f32_e32 v102, 1.0, v102
	v_add_f32_e32 v103, 1.0, v103
	v_add_f32_e32 v104, 1.0, v104
	v_add_f32_e32 v105, 1.0, v105
	v_add_f32_e32 v106, 1.0, v106
	v_add_f32_e32 v107, 1.0, v107
	v_rcp_f32_e32 v108, v108
	v_rcp_f32_e32 v91, v91
	v_rcp_f32_e32 v102, v102
	v_rcp_f32_e32 v103, v103
	v_rcp_f32_e32 v104, v104
	v_rcp_f32_e32 v105, v105
	v_rcp_f32_e32 v106, v106
	v_rcp_f32_e32 v107, v107
	v_mul_f32_e32 v83, v83, v108
	v_mul_f32_e32 v91, v97, v91
	v_mul_f32_e32 v85, v85, v102
	v_mul_f32_e32 v93, v93, v103
	v_mul_f32_e32 v87, v87, v104
	v_mul_f32_e32 v95, v95, v105
	v_mul_f32_e32 v81, v81, v106
	v_mul_f32_e32 v89, v89, v107
	v_mul_f32_e32 v83, v82, v83
	v_mul_f32_e32 v91, v96, v91
	v_mul_f32_e32 v84, v84, v85
	v_mul_f32_e32 v85, v92, v93
	v_mul_f32_e32 v86, v86, v87
	v_mul_f32_e32 v87, v94, v95
	v_mul_f32_e32 v92, v80, v81
	v_mul_f32_e32 v88, v88, v89
	v_cvt_pk_bf16_f32 v80, v91, v84
	v_cvt_pk_bf16_f32 v81, v85, v86
	v_cvt_pk_bf16_f32 v82, v87, v92
	v_cvt_pk_bf16_f32 v83, v88, v83
	global_store_dwordx4 v[98:99], v[80:83], off
	s_nop 0
	s_nop 0
	v_mov_b32_e32 v81, v68
	v_mov_b32_e32 v68, v77
	v_mov_b32_e32 v77, v70
	v_mov_b32_e32 v70, v79
	v_mov_b32_e32 v79, v64
	v_mov_b32_e32 v64, v73
	v_mov_b32_e32 v73, v66
	v_mov_b32_e32 v80, v76
	v_mov_b32_e32 v76, v78
	v_mov_b32_e32 v78, v72
	v_mov_b32_e32 v72, v74
	s_waitcnt vmcnt(7)
	v_mov_b32_e32 v82, v175
	v_fmamk_f32 v66, v82, 0x3a000000, v156
	v_mul_f32_e32 v74, 0x4f800000, v66
	v_cmp_gt_f32_e32 vcc, s64, v66
	s_nop 1
	v_cndmask_b32_e32 v82, v66, v74, vcc
	v_sqrt_f32_e32 v83, v82
	v_mov_b32_e32 v66, v75
	v_mad_i64_i32 v[74:75], s[8:9], v90, s63, v[146:147]
	v_add_u32_e32 v84, -1, v83
	v_add_u32_e32 v85, 1, v83
	v_fma_f32 v86, -v84, v83, v82
	v_fma_f32 v87, -v85, v83, v82
	v_cmp_ge_f32_e64 s[8:9], 0, v86
	v_lshl_add_u64 v[74:75], v[74:75], 0, v[120:121]
	s_nop 0
	v_cndmask_b32_e64 v83, v83, v84, s[8:9]
	v_cmp_lt_f32_e64 s[8:9], 0, v87
	s_nop 1
	v_cndmask_b32_e64 v83, v83, v85, s[8:9]
	v_mul_f32_e32 v84, 0x37800000, v83
	v_cndmask_b32_e32 v83, v83, v84, vcc
	v_cmp_class_f32_e32 vcc, v82, v157
	s_nop 1
	v_cndmask_b32_e32 v82, v83, v82, vcc
	v_div_scale_f32 v83, s[8:9], v82, v82, 1.0
	v_rcp_f32_e32 v84, v83
	v_div_scale_f32 v85, vcc, 1.0, v82, 1.0
	v_fma_f32 v86, -v83, v84, 1.0
	v_fmac_f32_e32 v84, v86, v84
	v_mul_f32_e32 v86, v85, v84
	v_fma_f32 v87, -v83, v86, v85
	v_fmac_f32_e32 v86, v87, v84
	v_fma_f32 v83, -v83, v86, v85
	v_div_fmas_f32 v83, v83, v84, v86
	v_div_fixup_f32 v82, v83, v82, 1.0
	v_pk_mul_f32 v[66:67], v[66:67], v[82:83] op_sel_hi:[1,0]
	v_pk_mul_f32 v[80:81], v[80:81], v[82:83] op_sel_hi:[1,0]
	v_pk_mul_f32 v[68:69], v[68:69], v[82:83] op_sel_hi:[1,0]
	v_pk_mul_f32 v[76:77], v[76:77], v[82:83] op_sel_hi:[1,0]
	v_pk_mul_f32 v[70:71], v[70:71], v[82:83] op_sel_hi:[1,0]
	v_pk_mul_f32 v[78:79], v[78:79], v[82:83] op_sel_hi:[1,0]
	v_pk_mul_f32 v[64:65], v[64:65], v[82:83] op_sel_hi:[1,0]
	v_pk_mul_f32 v[72:73], v[72:73], v[82:83] op_sel_hi:[1,0]
	v_mul_f32_e32 v89, 0xbfb8aa3b, v67
	v_mul_f32_e32 v82, 0xbfb8aa3b, v81
	v_mul_f32_e32 v83, 0xbfb8aa3b, v69
	v_mul_f32_e32 v84, 0xbfb8aa3b, v77
	v_mul_f32_e32 v85, 0xbfb8aa3b, v71
	v_mul_f32_e32 v86, 0xbfb8aa3b, v79
	v_mul_f32_e32 v87, 0xbfb8aa3b, v65
	v_mul_f32_e32 v88, 0xbfb8aa3b, v73
	v_exp_f32_e32 v89, v89
	v_exp_f32_e32 v82, v82
	v_exp_f32_e32 v83, v83
	v_exp_f32_e32 v84, v84
	v_exp_f32_e32 v85, v85
	v_exp_f32_e32 v86, v86
	v_exp_f32_e32 v87, v87
	v_exp_f32_e32 v88, v88
	v_add_f32_e32 v89, 1.0, v89
	v_add_f32_e32 v82, 1.0, v82
	v_add_f32_e32 v83, 1.0, v83
	v_add_f32_e32 v84, 1.0, v84
	v_add_f32_e32 v85, 1.0, v85
	v_add_f32_e32 v86, 1.0, v86
	v_add_f32_e32 v87, 1.0, v87
	v_add_f32_e32 v88, 1.0, v88
	v_rcp_f32_e32 v89, v89
	v_rcp_f32_e32 v82, v82
	v_rcp_f32_e32 v83, v83
	v_rcp_f32_e32 v84, v84
	v_rcp_f32_e32 v85, v85
	v_rcp_f32_e32 v86, v86
	v_rcp_f32_e32 v87, v87
	v_rcp_f32_e32 v88, v88
	v_mul_f32_e32 v67, v67, v89
	v_mul_f32_e32 v81, v81, v82
	v_mul_f32_e32 v69, v69, v83
	v_mul_f32_e32 v77, v77, v84
	v_mul_f32_e32 v71, v71, v85
	v_mul_f32_e32 v79, v79, v86
	v_mul_f32_e32 v65, v65, v87
	v_mul_f32_e32 v73, v73, v88
	v_mul_f32_e32 v67, v66, v67
	v_mul_f32_e32 v80, v80, v81
	v_mul_f32_e32 v68, v68, v69
	v_mul_f32_e32 v69, v76, v77
	v_mul_f32_e32 v70, v70, v71
	v_mul_f32_e32 v71, v78, v79
	v_mul_f32_e32 v76, v64, v65
	v_mul_f32_e32 v72, v72, v73
	v_cvt_pk_bf16_f32 v64, v80, v68
	v_cvt_pk_bf16_f32 v65, v69, v70
	v_cvt_pk_bf16_f32 v66, v71, v76
	v_cvt_pk_bf16_f32 v67, v72, v67
	global_store_dwordx4 v[74:75], v[64:67], off
	s_nop 0
	s_nop 0
	v_mov_b32_e32 v64, v60
	v_mov_b32_e32 v60, v62
	v_mov_b32_e32 v62, v56
	v_mov_b32_e32 v56, v58
	v_mov_b32_e32 v65, v52
	v_mov_b32_e32 v52, v61
	v_mov_b32_e32 v61, v54
	v_mov_b32_e32 v54, v63
	v_mov_b32_e32 v63, v48
	v_mov_b32_e32 v48, v57
	v_mov_b32_e32 v57, v50
	v_mov_b32_e32 v50, v59
	s_waitcnt vmcnt(7)
	v_mov_b32_e32 v66, v176
	v_fmamk_f32 v58, v66, 0x3a000000, v156
	v_mul_f32_e32 v59, 0x4f800000, v58
	v_cmp_gt_f32_e32 vcc, s64, v58
	s_nop 1
	v_cndmask_b32_e32 v66, v58, v59, vcc
	v_sqrt_f32_e32 v67, v66
	v_add_u32_e32 v58, 0x80, v144
	v_mad_i64_i32 v[58:59], s[8:9], v58, s63, v[146:147]
	v_add_u32_e32 v68, -1, v67
	v_add_u32_e32 v69, 1, v67
	v_fma_f32 v70, -v68, v67, v66
	v_fma_f32 v71, -v69, v67, v66
	v_cmp_ge_f32_e64 s[8:9], 0, v70
	v_lshl_add_u64 v[58:59], v[58:59], 0, v[120:121]
	s_nop 0
	v_cndmask_b32_e64 v67, v67, v68, s[8:9]
	v_cmp_lt_f32_e64 s[8:9], 0, v71
	s_nop 1
	v_cndmask_b32_e64 v67, v67, v69, s[8:9]
	v_mul_f32_e32 v68, 0x37800000, v67
	v_cndmask_b32_e32 v67, v67, v68, vcc
	v_cmp_class_f32_e32 vcc, v66, v157
	s_nop 1
	v_cndmask_b32_e32 v66, v67, v66, vcc
	v_div_scale_f32 v67, s[8:9], v66, v66, 1.0
	v_rcp_f32_e32 v68, v67
	v_div_scale_f32 v69, vcc, 1.0, v66, 1.0
	v_fma_f32 v70, -v67, v68, 1.0
	v_fmac_f32_e32 v68, v70, v68
	v_mul_f32_e32 v70, v69, v68
	v_fma_f32 v71, -v67, v70, v69
	v_fmac_f32_e32 v70, v71, v68
	v_fma_f32 v67, -v67, v70, v69
	v_div_fmas_f32 v67, v67, v68, v70
	v_div_fixup_f32 v66, v67, v66, 1.0
	v_pk_mul_f32 v[50:51], v[50:51], v[66:67] op_sel_hi:[1,0]
	v_pk_mul_f32 v[64:65], v[64:65], v[66:67] op_sel_hi:[1,0]
	v_pk_mul_f32 v[52:53], v[52:53], v[66:67] op_sel_hi:[1,0]
	v_pk_mul_f32 v[60:61], v[60:61], v[66:67] op_sel_hi:[1,0]
	v_pk_mul_f32 v[54:55], v[54:55], v[66:67] op_sel_hi:[1,0]
	v_pk_mul_f32 v[62:63], v[62:63], v[66:67] op_sel_hi:[1,0]
	v_pk_mul_f32 v[48:49], v[48:49], v[66:67] op_sel_hi:[1,0]
	v_pk_mul_f32 v[56:57], v[56:57], v[66:67] op_sel_hi:[1,0]
	v_mul_f32_e32 v73, 0xbfb8aa3b, v51
	v_mul_f32_e32 v66, 0xbfb8aa3b, v65
	v_mul_f32_e32 v67, 0xbfb8aa3b, v53
	v_mul_f32_e32 v68, 0xbfb8aa3b, v61
	v_mul_f32_e32 v69, 0xbfb8aa3b, v55
	v_mul_f32_e32 v70, 0xbfb8aa3b, v63
	v_mul_f32_e32 v71, 0xbfb8aa3b, v49
	v_mul_f32_e32 v72, 0xbfb8aa3b, v57
	v_exp_f32_e32 v73, v73
	v_exp_f32_e32 v66, v66
	v_exp_f32_e32 v67, v67
	v_exp_f32_e32 v68, v68
	v_exp_f32_e32 v69, v69
	v_exp_f32_e32 v70, v70
	v_exp_f32_e32 v71, v71
	v_exp_f32_e32 v72, v72
	v_add_f32_e32 v73, 1.0, v73
	v_add_f32_e32 v66, 1.0, v66
	v_add_f32_e32 v67, 1.0, v67
	v_add_f32_e32 v68, 1.0, v68
	v_add_f32_e32 v69, 1.0, v69
	v_add_f32_e32 v70, 1.0, v70
	v_add_f32_e32 v71, 1.0, v71
	v_add_f32_e32 v72, 1.0, v72
	v_rcp_f32_e32 v73, v73
	v_rcp_f32_e32 v66, v66
	v_rcp_f32_e32 v67, v67
	v_rcp_f32_e32 v68, v68
	v_rcp_f32_e32 v69, v69
	v_rcp_f32_e32 v70, v70
	v_rcp_f32_e32 v71, v71
	v_rcp_f32_e32 v72, v72
	v_mul_f32_e32 v51, v51, v73
	v_mul_f32_e32 v65, v65, v66
	v_mul_f32_e32 v53, v53, v67
	v_mul_f32_e32 v61, v61, v68
	v_mul_f32_e32 v55, v55, v69
	v_mul_f32_e32 v63, v63, v70
	v_mul_f32_e32 v49, v49, v71
	v_mul_f32_e32 v57, v57, v72
	v_mul_f32_e32 v51, v50, v51
	v_mul_f32_e32 v64, v64, v65
	v_mul_f32_e32 v52, v52, v53
	v_mul_f32_e32 v53, v60, v61
	v_mul_f32_e32 v54, v54, v55
	v_mul_f32_e32 v55, v62, v63
	v_mul_f32_e32 v60, v48, v49
	v_mul_f32_e32 v56, v56, v57
	v_cvt_pk_bf16_f32 v48, v64, v52
	v_cvt_pk_bf16_f32 v49, v53, v54
	v_cvt_pk_bf16_f32 v50, v55, v60
	v_cvt_pk_bf16_f32 v51, v56, v51
	global_store_dwordx4 v[58:59], v[48:51], off
	s_nop 0
	s_nop 0
	v_mov_b32_e32 v48, v44
	v_mov_b32_e32 v44, v46
	v_mov_b32_e32 v46, v40
	v_mov_b32_e32 v40, v42
	v_mov_b32_e32 v49, v36
	v_mov_b32_e32 v36, v45
	v_mov_b32_e32 v45, v38
	v_mov_b32_e32 v38, v47
	v_mov_b32_e32 v47, v32
	v_mov_b32_e32 v32, v41
	v_mov_b32_e32 v41, v34
	v_mov_b32_e32 v34, v43
	s_waitcnt vmcnt(7)
	v_mov_b32_e32 v50, v177
	v_fmamk_f32 v42, v50, 0x3a000000, v156
	v_mul_f32_e32 v43, 0x4f800000, v42
	v_cmp_gt_f32_e32 vcc, s64, v42
	s_nop 1
	v_cndmask_b32_e32 v50, v42, v43, vcc
	v_sqrt_f32_e32 v51, v50
	v_add_u32_e32 v42, 0x90, v144
	v_mad_i64_i32 v[42:43], s[8:9], v42, s63, v[146:147]
	v_add_u32_e32 v52, -1, v51
	v_add_u32_e32 v53, 1, v51
	v_fma_f32 v54, -v52, v51, v50
	v_fma_f32 v55, -v53, v51, v50
	v_cmp_ge_f32_e64 s[8:9], 0, v54
	v_lshl_add_u64 v[42:43], v[42:43], 0, v[120:121]
	s_nop 0
	v_cndmask_b32_e64 v51, v51, v52, s[8:9]
	v_cmp_lt_f32_e64 s[8:9], 0, v55
	s_nop 1
	v_cndmask_b32_e64 v51, v51, v53, s[8:9]
	v_mul_f32_e32 v52, 0x37800000, v51
	v_cndmask_b32_e32 v51, v51, v52, vcc
	v_cmp_class_f32_e32 vcc, v50, v157
	s_nop 1
	v_cndmask_b32_e32 v50, v51, v50, vcc
	v_div_scale_f32 v51, s[8:9], v50, v50, 1.0
	v_rcp_f32_e32 v52, v51
	v_div_scale_f32 v53, vcc, 1.0, v50, 1.0
	v_fma_f32 v54, -v51, v52, 1.0
	v_fmac_f32_e32 v52, v54, v52
	v_mul_f32_e32 v54, v53, v52
	v_fma_f32 v55, -v51, v54, v53
	v_fmac_f32_e32 v54, v55, v52
	v_fma_f32 v51, -v51, v54, v53
	v_div_fmas_f32 v51, v51, v52, v54
	v_div_fixup_f32 v50, v51, v50, 1.0
	v_pk_mul_f32 v[34:35], v[34:35], v[50:51] op_sel_hi:[1,0]
	v_pk_mul_f32 v[48:49], v[48:49], v[50:51] op_sel_hi:[1,0]
	v_pk_mul_f32 v[36:37], v[36:37], v[50:51] op_sel_hi:[1,0]
	v_pk_mul_f32 v[44:45], v[44:45], v[50:51] op_sel_hi:[1,0]
	v_pk_mul_f32 v[38:39], v[38:39], v[50:51] op_sel_hi:[1,0]
	v_pk_mul_f32 v[46:47], v[46:47], v[50:51] op_sel_hi:[1,0]
	v_pk_mul_f32 v[32:33], v[32:33], v[50:51] op_sel_hi:[1,0]
	v_pk_mul_f32 v[40:41], v[40:41], v[50:51] op_sel_hi:[1,0]
	v_mul_f32_e32 v57, 0xbfb8aa3b, v35
	v_mul_f32_e32 v50, 0xbfb8aa3b, v49
	v_mul_f32_e32 v51, 0xbfb8aa3b, v37
	v_mul_f32_e32 v52, 0xbfb8aa3b, v45
	v_mul_f32_e32 v53, 0xbfb8aa3b, v39
	v_mul_f32_e32 v54, 0xbfb8aa3b, v47
	v_mul_f32_e32 v55, 0xbfb8aa3b, v33
	v_mul_f32_e32 v56, 0xbfb8aa3b, v41
	v_exp_f32_e32 v57, v57
	v_exp_f32_e32 v50, v50
	v_exp_f32_e32 v51, v51
	v_exp_f32_e32 v52, v52
	v_exp_f32_e32 v53, v53
	v_exp_f32_e32 v54, v54
	v_exp_f32_e32 v55, v55
	v_exp_f32_e32 v56, v56
	v_add_f32_e32 v57, 1.0, v57
	v_add_f32_e32 v50, 1.0, v50
	v_add_f32_e32 v51, 1.0, v51
	v_add_f32_e32 v52, 1.0, v52
	v_add_f32_e32 v53, 1.0, v53
	v_add_f32_e32 v54, 1.0, v54
	v_add_f32_e32 v55, 1.0, v55
	v_add_f32_e32 v56, 1.0, v56
	v_rcp_f32_e32 v57, v57
	v_rcp_f32_e32 v50, v50
	v_rcp_f32_e32 v51, v51
	v_rcp_f32_e32 v52, v52
	v_rcp_f32_e32 v53, v53
	v_rcp_f32_e32 v54, v54
	v_rcp_f32_e32 v55, v55
	v_rcp_f32_e32 v56, v56
	v_mul_f32_e32 v35, v35, v57
	v_mul_f32_e32 v49, v49, v50
	v_mul_f32_e32 v37, v37, v51
	v_mul_f32_e32 v45, v45, v52
	v_mul_f32_e32 v39, v39, v53
	v_mul_f32_e32 v47, v47, v54
	v_mul_f32_e32 v33, v33, v55
	v_mul_f32_e32 v41, v41, v56
	v_mul_f32_e32 v35, v34, v35
	v_mul_f32_e32 v48, v48, v49
	v_mul_f32_e32 v36, v36, v37
	v_mul_f32_e32 v37, v44, v45
	v_mul_f32_e32 v38, v38, v39
	v_mul_f32_e32 v39, v46, v47
	v_mul_f32_e32 v44, v32, v33
	v_mul_f32_e32 v40, v40, v41
	v_cvt_pk_bf16_f32 v32, v48, v36
	v_cvt_pk_bf16_f32 v33, v37, v38
	v_cvt_pk_bf16_f32 v34, v39, v44
	v_cvt_pk_bf16_f32 v35, v40, v35
	global_store_dwordx4 v[42:43], v[32:35], off
	s_nop 0
	s_nop 0
	v_mov_b32_e32 v32, v28
	v_mov_b32_e32 v28, v30
	v_mov_b32_e32 v30, v24
	v_mov_b32_e32 v24, v26
	v_mov_b32_e32 v33, v20
	v_mov_b32_e32 v20, v29
	v_mov_b32_e32 v29, v22
	v_mov_b32_e32 v22, v31
	v_mov_b32_e32 v31, v16
	v_mov_b32_e32 v16, v25
	v_mov_b32_e32 v25, v18
	v_mov_b32_e32 v18, v27
	s_waitcnt vmcnt(7)
	v_mov_b32_e32 v34, v178
	v_fmamk_f32 v26, v34, 0x3a000000, v156
	v_mul_f32_e32 v27, 0x4f800000, v26
	v_cmp_gt_f32_e32 vcc, s64, v26
	s_nop 1
	v_cndmask_b32_e32 v34, v26, v27, vcc
	v_sqrt_f32_e32 v35, v34
	v_add_u32_e32 v26, 0xa0, v144
	v_mad_i64_i32 v[26:27], s[8:9], v26, s63, v[146:147]
	v_add_u32_e32 v36, -1, v35
	v_add_u32_e32 v37, 1, v35
	v_fma_f32 v38, -v36, v35, v34
	v_fma_f32 v39, -v37, v35, v34
	v_cmp_ge_f32_e64 s[8:9], 0, v38
	v_lshl_add_u64 v[26:27], v[26:27], 0, v[120:121]
	s_nop 0
	v_cndmask_b32_e64 v35, v35, v36, s[8:9]
	v_cmp_lt_f32_e64 s[8:9], 0, v39
	s_nop 1
	v_cndmask_b32_e64 v35, v35, v37, s[8:9]
	v_mul_f32_e32 v36, 0x37800000, v35
	v_cndmask_b32_e32 v35, v35, v36, vcc
	v_cmp_class_f32_e32 vcc, v34, v157
	s_nop 1
	v_cndmask_b32_e32 v34, v35, v34, vcc
	v_div_scale_f32 v35, s[8:9], v34, v34, 1.0
	v_rcp_f32_e32 v36, v35
	v_div_scale_f32 v37, vcc, 1.0, v34, 1.0
	v_fma_f32 v38, -v35, v36, 1.0
	v_fmac_f32_e32 v36, v38, v36
	v_mul_f32_e32 v38, v37, v36
	v_fma_f32 v39, -v35, v38, v37
	v_fmac_f32_e32 v38, v39, v36
	v_fma_f32 v35, -v35, v38, v37
	v_div_fmas_f32 v35, v35, v36, v38
	v_div_fixup_f32 v34, v35, v34, 1.0
	v_pk_mul_f32 v[18:19], v[18:19], v[34:35] op_sel_hi:[1,0]
	v_pk_mul_f32 v[32:33], v[32:33], v[34:35] op_sel_hi:[1,0]
	v_pk_mul_f32 v[20:21], v[20:21], v[34:35] op_sel_hi:[1,0]
	v_pk_mul_f32 v[28:29], v[28:29], v[34:35] op_sel_hi:[1,0]
	v_pk_mul_f32 v[22:23], v[22:23], v[34:35] op_sel_hi:[1,0]
	v_pk_mul_f32 v[30:31], v[30:31], v[34:35] op_sel_hi:[1,0]
	v_pk_mul_f32 v[16:17], v[16:17], v[34:35] op_sel_hi:[1,0]
	v_pk_mul_f32 v[24:25], v[24:25], v[34:35] op_sel_hi:[1,0]
	v_mul_f32_e32 v41, 0xbfb8aa3b, v19
	v_mul_f32_e32 v34, 0xbfb8aa3b, v33
	v_mul_f32_e32 v35, 0xbfb8aa3b, v21
	v_mul_f32_e32 v36, 0xbfb8aa3b, v29
	v_mul_f32_e32 v37, 0xbfb8aa3b, v23
	v_mul_f32_e32 v38, 0xbfb8aa3b, v31
	v_mul_f32_e32 v39, 0xbfb8aa3b, v17
	v_mul_f32_e32 v40, 0xbfb8aa3b, v25
	v_exp_f32_e32 v41, v41
	v_exp_f32_e32 v34, v34
	v_exp_f32_e32 v35, v35
	v_exp_f32_e32 v36, v36
	v_exp_f32_e32 v37, v37
	v_exp_f32_e32 v38, v38
	v_exp_f32_e32 v39, v39
	v_exp_f32_e32 v40, v40
	v_add_f32_e32 v41, 1.0, v41
	v_add_f32_e32 v34, 1.0, v34
	v_add_f32_e32 v35, 1.0, v35
	v_add_f32_e32 v36, 1.0, v36
	v_add_f32_e32 v37, 1.0, v37
	v_add_f32_e32 v38, 1.0, v38
	v_add_f32_e32 v39, 1.0, v39
	v_add_f32_e32 v40, 1.0, v40
	v_rcp_f32_e32 v41, v41
	v_rcp_f32_e32 v34, v34
	v_rcp_f32_e32 v35, v35
	v_rcp_f32_e32 v36, v36
	v_rcp_f32_e32 v37, v37
	v_rcp_f32_e32 v38, v38
	v_rcp_f32_e32 v39, v39
	v_rcp_f32_e32 v40, v40
	v_mul_f32_e32 v19, v19, v41
	v_mul_f32_e32 v33, v33, v34
	v_mul_f32_e32 v21, v21, v35
	v_mul_f32_e32 v29, v29, v36
	v_mul_f32_e32 v23, v23, v37
	v_mul_f32_e32 v31, v31, v38
	v_mul_f32_e32 v17, v17, v39
	v_mul_f32_e32 v25, v25, v40
	v_mul_f32_e32 v19, v18, v19
	v_mul_f32_e32 v32, v32, v33
	v_mul_f32_e32 v20, v20, v21
	v_mul_f32_e32 v21, v28, v29
	v_mul_f32_e32 v22, v22, v23
	v_mul_f32_e32 v23, v30, v31
	v_mul_f32_e32 v28, v16, v17
	v_mul_f32_e32 v24, v24, v25
	v_cvt_pk_bf16_f32 v16, v32, v20
	v_cvt_pk_bf16_f32 v17, v21, v22
	v_cvt_pk_bf16_f32 v18, v23, v28
	v_cvt_pk_bf16_f32 v19, v24, v19
	global_store_dwordx4 v[26:27], v[16:19], off
	s_nop 0
	s_nop 0
	v_mov_b32_e32 v17, v4
	v_mov_b32_e32 v4, v13
	v_mov_b32_e32 v13, v6
	v_mov_b32_e32 v6, v15
	v_mov_b32_e32 v15, v0
	v_mov_b32_e32 v0, v9
	v_mov_b32_e32 v9, v2
	v_mov_b32_e32 v2, v11
	v_mov_b32_e32 v16, v12
	v_mov_b32_e32 v12, v14
	v_mov_b32_e32 v14, v8
	v_mov_b32_e32 v8, v10
	v_add_u32_e32 v10, 0xb0, v144
	s_waitcnt vmcnt(7)
	v_mov_b32_e32 v18, v179
	v_fmamk_f32 v11, v18, 0x3a000000, v156
	v_mul_f32_e32 v18, 0x4f800000, v11
	v_cmp_gt_f32_e32 vcc, s64, v11
	s_nop 1
	v_cndmask_b32_e32 v18, v11, v18, vcc
	v_sqrt_f32_e32 v19, v18
	v_mad_i64_i32 v[10:11], s[8:9], v10, s63, v[146:147]
	v_lshl_add_u64 v[10:11], v[10:11], 0, v[120:121]
	v_add_u32_e32 v20, -1, v19
	v_add_u32_e32 v21, 1, v19
	v_fma_f32 v22, -v20, v19, v18
	v_fma_f32 v23, -v21, v19, v18
	v_cmp_ge_f32_e64 s[8:9], 0, v22
	s_nop 1
	v_cndmask_b32_e64 v19, v19, v20, s[8:9]
	v_cmp_lt_f32_e64 s[8:9], 0, v23
	s_nop 1
	v_cndmask_b32_e64 v19, v19, v21, s[8:9]
	v_mul_f32_e32 v20, 0x37800000, v19
	v_cndmask_b32_e32 v19, v19, v20, vcc
	v_cmp_class_f32_e32 vcc, v18, v157
	s_nop 1
	v_cndmask_b32_e32 v18, v19, v18, vcc
	v_div_scale_f32 v19, s[8:9], v18, v18, 1.0
	v_rcp_f32_e32 v20, v19
	v_div_scale_f32 v21, vcc, 1.0, v18, 1.0
	v_fma_f32 v22, -v19, v20, 1.0
	v_fmac_f32_e32 v20, v22, v20
	v_mul_f32_e32 v22, v21, v20
	v_fma_f32 v23, -v19, v22, v21
	v_fmac_f32_e32 v22, v23, v20
	v_fma_f32 v19, -v19, v22, v21
	v_div_fmas_f32 v19, v19, v20, v22
	v_div_fixup_f32 v18, v19, v18, 1.0
	v_pk_mul_f32 v[2:3], v[2:3], v[18:19] op_sel_hi:[1,0]
	v_pk_mul_f32 v[16:17], v[16:17], v[18:19] op_sel_hi:[1,0]
	v_pk_mul_f32 v[4:5], v[4:5], v[18:19] op_sel_hi:[1,0]
	v_pk_mul_f32 v[12:13], v[12:13], v[18:19] op_sel_hi:[1,0]
	v_pk_mul_f32 v[6:7], v[6:7], v[18:19] op_sel_hi:[1,0]
	v_pk_mul_f32 v[14:15], v[14:15], v[18:19] op_sel_hi:[1,0]
	v_pk_mul_f32 v[0:1], v[0:1], v[18:19] op_sel_hi:[1,0]
	v_pk_mul_f32 v[8:9], v[8:9], v[18:19] op_sel_hi:[1,0]
	v_mul_f32_e32 v25, 0xbfb8aa3b, v3
	v_mul_f32_e32 v18, 0xbfb8aa3b, v17
	v_mul_f32_e32 v19, 0xbfb8aa3b, v5
	v_mul_f32_e32 v20, 0xbfb8aa3b, v13
	v_mul_f32_e32 v21, 0xbfb8aa3b, v7
	v_mul_f32_e32 v22, 0xbfb8aa3b, v15
	v_mul_f32_e32 v23, 0xbfb8aa3b, v1
	v_mul_f32_e32 v24, 0xbfb8aa3b, v9
	v_exp_f32_e32 v25, v25
	v_exp_f32_e32 v18, v18
	v_exp_f32_e32 v19, v19
	v_exp_f32_e32 v20, v20
	v_exp_f32_e32 v21, v21
	v_exp_f32_e32 v22, v22
	v_exp_f32_e32 v23, v23
	v_exp_f32_e32 v24, v24
	v_add_f32_e32 v25, 1.0, v25
	v_add_f32_e32 v18, 1.0, v18
	v_add_f32_e32 v19, 1.0, v19
	v_add_f32_e32 v20, 1.0, v20
	v_add_f32_e32 v21, 1.0, v21
	v_add_f32_e32 v22, 1.0, v22
	v_add_f32_e32 v23, 1.0, v23
	v_add_f32_e32 v24, 1.0, v24
	v_rcp_f32_e32 v25, v25
	v_rcp_f32_e32 v18, v18
	v_rcp_f32_e32 v19, v19
	v_rcp_f32_e32 v20, v20
	v_rcp_f32_e32 v21, v21
	v_rcp_f32_e32 v22, v22
	v_rcp_f32_e32 v23, v23
	v_rcp_f32_e32 v24, v24
	v_mul_f32_e32 v3, v3, v25
	s_andn2_b64 vcc, exec, s[6:7]
	v_mul_f32_e32 v17, v17, v18
	v_mul_f32_e32 v5, v5, v19
	v_mul_f32_e32 v13, v13, v20
	v_mul_f32_e32 v7, v7, v21
	v_mul_f32_e32 v15, v15, v22
	v_mul_f32_e32 v1, v1, v23
	v_mul_f32_e32 v9, v9, v24
	v_mul_f32_e32 v3, v2, v3
	s_mov_b64 s[6:7], -1
	v_mul_f32_e32 v16, v16, v17
	v_mul_f32_e32 v4, v4, v5
	v_mul_f32_e32 v5, v12, v13
	v_mul_f32_e32 v6, v6, v7
	v_mul_f32_e32 v7, v14, v15
	v_mul_f32_e32 v12, v0, v1
	v_mul_f32_e32 v8, v8, v9
	v_cvt_pk_bf16_f32 v0, v16, v4
	v_cvt_pk_bf16_f32 v1, v5, v6
	v_cvt_pk_bf16_f32 v2, v7, v12
	v_cvt_pk_bf16_f32 v3, v8, v3
	global_store_dwordx4 v[10:11], v[0:3], off
	s_cbranch_vccnz .LBB0_669
	s_andn2_b64 vcc, exec, s[10:11]
	s_cbranch_vccnz .LBB0_668
	s_barrier
	s_branch .LBB0_668

.LBB0_704:
	s_or_saveexec_b64 s[26:27], s[24:25]
	v_mov_b32_e32 v33, v32
	v_mov_b32_e32 v34, v32
	v_mov_b32_e32 v35, v32
	v_mov_b64_e32 v[58:59], v[34:35]
	v_mov_b64_e32 v[54:55], v[34:35]
	v_mov_b64_e32 v[50:51], v[34:35]
	v_mov_b64_e32 v[46:47], v[34:35]
	v_mov_b64_e32 v[42:43], v[34:35]
	v_mov_b64_e32 v[38:39], v[34:35]
	v_mov_b64_e32 v[28:29], v[32:33]
	v_mov_b64_e32 v[24:25], v[32:33]
	v_mov_b64_e32 v[20:21], v[32:33]
	v_mov_b64_e32 v[16:17], v[32:33]
	v_mov_b64_e32 v[12:13], v[32:33]
	v_mov_b64_e32 v[8:9], v[32:33]
	v_mov_b64_e32 v[4:5], v[32:33]
	v_mov_b64_e32 v[0:1], v[32:33]
	v_mov_b64_e32 v[62:63], v[34:35]
	s_add_i32 s24, s33, s31
	v_mov_b64_e32 v[56:57], v[32:33]
	v_mov_b64_e32 v[52:53], v[32:33]
	v_mov_b64_e32 v[48:49], v[32:33]
	v_mov_b64_e32 v[44:45], v[32:33]
	v_mov_b64_e32 v[40:41], v[32:33]
	v_mov_b64_e32 v[36:37], v[32:33]
	v_mov_b64_e32 v[30:31], v[34:35]
	v_mov_b64_e32 v[26:27], v[34:35]
	v_mov_b64_e32 v[22:23], v[34:35]
	v_mov_b64_e32 v[18:19], v[34:35]
	v_mov_b64_e32 v[14:15], v[34:35]
	v_mov_b64_e32 v[10:11], v[34:35]
	v_mov_b64_e32 v[6:7], v[34:35]
	v_mov_b64_e32 v[2:3], v[34:35]
	v_mov_b64_e32 v[60:61], v[32:33]
	s_xor_b64 exec, exec, s[26:27]
	s_cbranch_execz .LBB0_706
	s_mul_i32 s25, s16, s23
	s_mul_hi_u32 s30, s16, s22
	s_add_i32 s25, s30, s25
	s_mul_i32 s17, s17, s22
	s_add_i32 s31, s25, s17
	s_mul_i32 s30, s16, s22
	s_lshl_b64 s[30:31], s[30:31], 2
	s_waitcnt lgkmcnt(0)
	s_add_u32 s17, s18, s30
	s_addc_u32 s30, s19, s31
	s_ashr_i32 s25, s24, 31
	v_lshrrev_b32_e32 v130, 3, v131
	s_lshl_b64 s[18:19], s[24:25], 2
	v_and_b32_e32 v132, 6, v130
	s_add_u32 s18, s17, s18
	v_mul_u32_u24_e32 v0, s16, v132
	s_addc_u32 s19, s30, s19
	v_mov_b32_e32 v33, 0
	v_lshlrev_b32_e32 v32, 2, v0
	v_lshl_add_u64 v[0:1], s[18:19], 0, v[32:33]
	v_lshlrev_b32_e32 v32, 2, v128
	v_or_b32_e32 v134, 1, v130
	v_lshl_add_u64 v[8:9], v[0:1], 0, v[32:33]
	v_mul_u32_u24_e32 v0, s16, v134
	v_lshlrev_b32_e32 v0, 2, v0
	v_mov_b32_e32 v1, v33
	v_lshl_add_u64 v[0:1], s[18:19], 0, v[0:1]
	v_or_b32_e32 v136, 8, v132
	v_lshl_add_u64 v[10:11], v[0:1], 0, v[32:33]
	global_load_dwordx4 v[0:3], v[8:9], off nt
	global_load_dwordx4 v[4:7], v[10:11], off nt
	v_mul_u32_u24_e32 v8, s16, v136
	v_lshlrev_b32_e32 v8, 2, v8
	v_mov_b32_e32 v9, v33
	v_lshl_add_u64 v[8:9], s[18:19], 0, v[8:9]
	v_or_b32_e32 v138, 9, v130
	v_lshl_add_u64 v[16:17], v[8:9], 0, v[32:33]
	v_mul_u32_u24_e32 v8, s16, v138
	v_lshlrev_b32_e32 v8, 2, v8
	v_mov_b32_e32 v9, v33
	v_lshl_add_u64 v[8:9], s[18:19], 0, v[8:9]
	v_or_b32_e32 v140, 16, v132
	v_lshl_add_u64 v[18:19], v[8:9], 0, v[32:33]
	global_load_dwordx4 v[8:11], v[16:17], off nt
	global_load_dwordx4 v[12:15], v[18:19], off nt
	v_mul_u32_u24_e32 v16, s16, v140
	v_lshlrev_b32_e32 v16, 2, v16
	v_mov_b32_e32 v17, v33
	v_lshl_add_u64 v[16:17], s[18:19], 0, v[16:17]
	v_or_b32_e32 v142, 17, v130
	v_lshl_add_u64 v[24:25], v[16:17], 0, v[32:33]
	v_mul_u32_u24_e32 v16, s16, v142
	v_lshlrev_b32_e32 v16, 2, v16
	v_mov_b32_e32 v17, v33
	v_lshl_add_u64 v[16:17], s[18:19], 0, v[16:17]
	v_or_b32_e32 v144, 24, v132
	v_lshl_add_u64 v[26:27], v[16:17], 0, v[32:33]
	global_load_dwordx4 v[16:19], v[24:25], off nt
	global_load_dwordx4 v[20:23], v[26:27], off nt
	v_mul_u32_u24_e32 v24, s16, v144
	v_lshlrev_b32_e32 v24, 2, v24
	v_mov_b32_e32 v25, v33
	v_lshl_add_u64 v[24:25], s[18:19], 0, v[24:25]
	v_or_b32_e32 v146, 25, v130
	v_lshl_add_u64 v[34:35], v[24:25], 0, v[32:33]
	v_mul_u32_u24_e32 v24, s16, v146
	v_lshlrev_b32_e32 v24, 2, v24
	v_mov_b32_e32 v25, v33
	v_lshl_add_u64 v[24:25], s[18:19], 0, v[24:25]
	v_or_b32_e32 v148, 32, v132
	v_lshl_add_u64 v[36:37], v[24:25], 0, v[32:33]
	global_load_dwordx4 v[24:27], v[34:35], off nt
	global_load_dwordx4 v[28:31], v[36:37], off nt
	v_mul_u32_u24_e32 v34, s16, v148
	v_or_b32_e32 v150, 33, v130
	v_lshlrev_b32_e32 v34, 2, v34
	v_mov_b32_e32 v35, v33
	v_mul_u32_u24_e32 v36, s16, v150
	v_lshl_add_u64 v[34:35], s[18:19], 0, v[34:35]
	v_lshlrev_b32_e32 v36, 2, v36
	v_mov_b32_e32 v37, v33
	v_lshl_add_u64 v[34:35], v[34:35], 0, v[32:33]
	v_lshl_add_u64 v[36:37], s[18:19], 0, v[36:37]
	v_or_b32_e32 v152, 40, v132
	v_lshl_add_u64 v[44:45], v[36:37], 0, v[32:33]
	global_load_dwordx4 v[36:39], v[34:35], off nt
	global_load_dwordx4 v[40:43], v[44:45], off nt
	v_mul_u32_u24_e32 v34, s16, v152
	v_or_b32_e32 v154, 41, v130
	v_lshlrev_b32_e32 v34, 2, v34
	v_mov_b32_e32 v35, v33
	v_mul_u32_u24_e32 v44, s16, v154
	v_lshl_add_u64 v[34:35], s[18:19], 0, v[34:35]
	v_lshlrev_b32_e32 v44, 2, v44
	v_mov_b32_e32 v45, v33
	v_lshl_add_u64 v[34:35], v[34:35], 0, v[32:33]
	v_lshl_add_u64 v[44:45], s[18:19], 0, v[44:45]
	v_or_b32_e32 v156, 48, v132
	v_lshl_add_u64 v[52:53], v[44:45], 0, v[32:33]
	global_load_dwordx4 v[44:47], v[34:35], off nt
	global_load_dwordx4 v[48:51], v[52:53], off nt
	v_mul_u32_u24_e32 v34, s16, v156
	v_or_b32_e32 v158, 49, v130
	v_lshlrev_b32_e32 v34, 2, v34
	v_mov_b32_e32 v35, v33
	v_mul_u32_u24_e32 v52, s16, v158
	v_lshl_add_u64 v[34:35], s[18:19], 0, v[34:35]
	v_lshlrev_b32_e32 v52, 2, v52
	v_mov_b32_e32 v53, v33
	v_lshl_add_u64 v[34:35], v[34:35], 0, v[32:33]
	v_lshl_add_u64 v[52:53], s[18:19], 0, v[52:53]
	v_or_b32_e32 v160, 56, v132
	v_lshl_add_u64 v[60:61], v[52:53], 0, v[32:33]
	global_load_dwordx4 v[52:55], v[34:35], off nt
	global_load_dwordx4 v[56:59], v[60:61], off nt
	v_mul_u32_u24_e32 v34, s16, v160
	v_lshlrev_b32_e32 v34, 2, v34
	v_mov_b32_e32 v35, v33
	v_lshl_add_u64 v[34:35], s[18:19], 0, v[34:35]
	v_or_b32_e32 v162, 57, v130
	s_waitcnt vmcnt(17)
	v_lshl_add_u64 v[64:65], v[34:35], 0, v[32:33]
	v_mul_u32_u24_e32 v34, s16, v162
	v_lshlrev_b32_e32 v34, 2, v34
	v_mov_b32_e32 v35, v33
	v_lshl_add_u64 v[34:35], s[18:19], 0, v[34:35]
	v_lshl_add_u64 v[66:67], v[34:35], 0, v[32:33]
	global_load_dwordx4 v[32:35], v[64:65], off nt
	global_load_dwordx4 v[60:63], v[66:67], off nt

.LBB0_749:
	s_waitcnt lgkmcnt(0)
	s_add_u32 s26, s12, s24
	s_addc_u32 s27, s13, s25
	s_add_i32 s30, s30, s48
	s_cmpk_lt_i32 s30, 0x400
	s_cselect_b64 s[24:25], -1, 0
	s_lshl_b32 s34, s31, 6
	s_ashr_i32 s35, s34, 31
	s_lshl_b64 s[12:13], s[34:35], 2
	s_add_u32 s12, s16, s12
	s_addc_u32 s13, s17, s13
	s_cmp_lg_u64 s[16:17], 0
	s_cselect_b32 s13, s13, 0
	s_cselect_b32 s12, s12, 0
	s_ashr_i32 s31, s33, 31
	s_and_b64 s[16:17], s[28:29], exec
	s_cselect_b32 s16, 0, s33
	s_cselect_b32 s17, 0, s31
	s_mul_i32 s17, s17, s41
	s_mul_hi_u32 s28, s16, s41
	s_add_i32 s17, s28, s17
	s_mul_i32 s16, s16, s41
	s_lshl_b64 s[16:17], s[16:17], 1
	s_add_u32 s26, s26, s16
	s_addc_u32 s27, s27, s17
	s_lshl_b64 s[16:17], s[34:35], 1
	s_add_u32 s16, s26, s16
	s_addc_u32 s17, s27, s17
	v_cmp_gt_u32_e32 vcc, s42, v128
	v_mov_b32_e32 v67, 0
	v_mov_b32_e32 v66, 0
	v_mov_b32_e32 v65, 0
	v_mov_b32_e32 v64, 0
	v_mov_b32_e32 v71, 0
	v_mov_b32_e32 v70, 0
	v_mov_b32_e32 v69, 0
	v_mov_b32_e32 v68, 0
	v_mov_b32_e32 v75, 0
	v_mov_b32_e32 v74, 0
	v_mov_b32_e32 v73, 0
	v_mov_b32_e32 v72, 0
	v_mov_b32_e32 v79, 0
	v_mov_b32_e32 v78, 0
	v_mov_b32_e32 v77, 0
	v_mov_b32_e32 v76, 0
	v_mov_b32_e32 v83, 0
	v_mov_b32_e32 v82, 0
	v_mov_b32_e32 v81, 0
	v_mov_b32_e32 v80, 0
	v_mov_b32_e32 v87, 0
	v_mov_b32_e32 v86, 0
	v_mov_b32_e32 v85, 0
	v_mov_b32_e32 v84, 0
	v_mov_b32_e32 v91, 0
	v_mov_b32_e32 v90, 0
	v_mov_b32_e32 v89, 0
	v_mov_b32_e32 v88, 0
	v_mov_b32_e32 v95, 0
	v_mov_b32_e32 v94, 0
	v_mov_b32_e32 v93, 0
	v_mov_b32_e32 v92, 0
	v_mov_b32_e32 v99, 0
	v_mov_b32_e32 v98, 0
	v_mov_b32_e32 v97, 0
	v_mov_b32_e32 v96, 0
	v_mov_b32_e32 v103, 0
	v_mov_b32_e32 v102, 0
	v_mov_b32_e32 v101, 0
	v_mov_b32_e32 v100, 0
	v_mov_b32_e32 v107, 0
	v_mov_b32_e32 v106, 0
	v_mov_b32_e32 v105, 0
	v_mov_b32_e32 v104, 0
	v_mov_b32_e32 v111, 0
	v_mov_b32_e32 v110, 0
	v_mov_b32_e32 v109, 0
	v_mov_b32_e32 v108, 0
	v_mov_b32_e32 v115, 0
	v_mov_b32_e32 v114, 0
	v_mov_b32_e32 v113, 0
	v_mov_b32_e32 v112, 0
	v_mov_b32_e32 v119, 0
	v_mov_b32_e32 v118, 0
	v_mov_b32_e32 v117, 0
	v_mov_b32_e32 v116, 0
	v_mov_b32_e32 v123, 0
	v_mov_b32_e32 v122, 0
	v_mov_b32_e32 v121, 0
	v_mov_b32_e32 v120, 0
	v_mov_b32_e32 v127, 0
	v_mov_b32_e32 v126, 0
	v_mov_b32_e32 v125, 0
	v_mov_b32_e32 v124, 0
	s_and_saveexec_b64 s[26:27], vcc
	s_cbranch_execz .LBB0_751
	s_mul_i32 s28, s20, s35
	s_mul_hi_u32 s29, s20, s34
	s_add_i32 s28, s29, s28
	s_mul_i32 s21, s21, s34
	s_add_i32 s29, s28, s21
	s_mul_i32 s28, s20, s34
	s_lshl_b64 s[28:29], s[28:29], 2
	s_add_u32 s21, s22, s28
	s_addc_u32 s28, s23, s29
	s_ashr_i32 s31, s30, 31
	s_lshl_b64 s[22:23], s[30:31], 2
	s_add_u32 s22, s21, s22
	s_addc_u32 s23, s28, s23
	v_mul_hi_i32_i24_e32 v65, s20, v132
	v_mul_i32_i24_e32 v64, s20, v132
	v_lshl_add_u64 v[64:65], v[64:65], 2, s[22:23]
	v_lshlrev_b32_e32 v120, 2, v128
	v_mov_b32_e32 v121, v167
	v_lshl_add_u64 v[72:73], v[64:65], 0, v[120:121]
	v_mul_hi_i32_i24_e32 v65, s20, v134
	v_mul_i32_i24_e32 v64, s20, v134
	v_lshl_add_u64 v[64:65], v[64:65], 2, s[22:23]
	v_lshl_add_u64 v[74:75], v[64:65], 0, v[120:121]
	global_load_dwordx4 v[64:67], v[72:73], off nt
	global_load_dwordx4 v[68:71], v[74:75], off nt
	v_mul_hi_i32_i24_e32 v73, s20, v136
	v_mul_i32_i24_e32 v72, s20, v136
	v_mul_hi_i32_i24_e32 v75, s20, v138
	v_mul_i32_i24_e32 v74, s20, v138
	v_mul_hi_i32_i24_e32 v81, s20, v140
	v_mul_i32_i24_e32 v80, s20, v140
	v_mul_hi_i32_i24_e32 v83, s20, v142
	v_mul_i32_i24_e32 v82, s20, v142
	v_mul_hi_i32_i24_e32 v89, s20, v144
	v_mul_i32_i24_e32 v88, s20, v144
	v_mul_hi_i32_i24_e32 v91, s20, v146
	v_mul_i32_i24_e32 v90, s20, v146
	v_mul_hi_i32_i24_e32 v97, s20, v148
	v_mul_i32_i24_e32 v96, s20, v148
	v_mul_hi_i32_i24_e32 v99, s20, v150
	v_mul_i32_i24_e32 v98, s20, v150
	v_mul_hi_i32_i24_e32 v105, s20, v152
	v_mul_i32_i24_e32 v104, s20, v152
	v_mul_hi_i32_i24_e32 v107, s20, v154
	v_mul_i32_i24_e32 v106, s20, v154
	v_mul_hi_i32_i24_e32 v113, s20, v156
	v_mul_i32_i24_e32 v112, s20, v156
	v_mul_hi_i32_i24_e32 v115, s20, v158
	v_mul_i32_i24_e32 v114, s20, v158
	v_mul_hi_i32_i24_e32 v123, s20, v160
	v_mul_i32_i24_e32 v122, s20, v160
	v_mul_hi_i32_i24_e32 v125, s20, v162
	v_mul_i32_i24_e32 v124, s20, v162
	v_lshl_add_u64 v[72:73], v[72:73], 2, s[22:23]
	v_lshl_add_u64 v[74:75], v[74:75], 2, s[22:23]
	v_lshl_add_u64 v[80:81], v[80:81], 2, s[22:23]
	v_lshl_add_u64 v[82:83], v[82:83], 2, s[22:23]
	v_lshl_add_u64 v[88:89], v[88:89], 2, s[22:23]
	v_lshl_add_u64 v[90:91], v[90:91], 2, s[22:23]
	v_lshl_add_u64 v[96:97], v[96:97], 2, s[22:23]
	v_lshl_add_u64 v[98:99], v[98:99], 2, s[22:23]
	v_lshl_add_u64 v[104:105], v[104:105], 2, s[22:23]
	v_lshl_add_u64 v[106:107], v[106:107], 2, s[22:23]
	v_lshl_add_u64 v[112:113], v[112:113], 2, s[22:23]
	v_lshl_add_u64 v[114:115], v[114:115], 2, s[22:23]
	v_lshl_add_u64 v[122:123], v[122:123], 2, s[22:23]
	v_lshl_add_u64 v[124:125], v[124:125], 2, s[22:23]
	v_lshl_add_u64 v[72:73], v[72:73], 0, v[120:121]
	v_lshl_add_u64 v[76:77], v[74:75], 0, v[120:121]
	v_lshl_add_u64 v[80:81], v[80:81], 0, v[120:121]
	v_lshl_add_u64 v[84:85], v[82:83], 0, v[120:121]
	v_lshl_add_u64 v[88:89], v[88:89], 0, v[120:121]
	v_lshl_add_u64 v[92:93], v[90:91], 0, v[120:121]
	v_lshl_add_u64 v[96:97], v[96:97], 0, v[120:121]
	v_lshl_add_u64 v[100:101], v[98:99], 0, v[120:121]
	v_lshl_add_u64 v[104:105], v[104:105], 0, v[120:121]
	v_lshl_add_u64 v[108:109], v[106:107], 0, v[120:121]
	v_lshl_add_u64 v[112:113], v[112:113], 0, v[120:121]
	v_lshl_add_u64 v[116:117], v[114:115], 0, v[120:121]
	v_lshl_add_u64 v[122:123], v[122:123], 0, v[120:121]
	v_lshl_add_u64 v[124:125], v[124:125], 0, v[120:121]
	global_load_dwordx4 v[72:75], v[72:73], off nt
	s_nop 0
	global_load_dwordx4 v[76:79], v[76:77], off nt
	s_nop 0
	global_load_dwordx4 v[80:83], v[80:81], off nt
	s_nop 0
	global_load_dwordx4 v[84:87], v[84:85], off nt
	s_nop 0
	global_load_dwordx4 v[88:91], v[88:89], off nt
	s_nop 0
	global_load_dwordx4 v[92:95], v[92:93], off nt
	s_nop 0
	global_load_dwordx4 v[96:99], v[96:97], off nt
	s_nop 0
	global_load_dwordx4 v[100:103], v[100:101], off nt
	s_nop 0
	global_load_dwordx4 v[104:107], v[104:105], off nt
	s_nop 0
	global_load_dwordx4 v[108:111], v[108:109], off nt
	s_nop 0
	global_load_dwordx4 v[112:115], v[112:113], off nt
	s_nop 0
	global_load_dwordx4 v[116:119], v[116:117], off nt
	s_nop 0
	global_load_dwordx4 v[120:123], v[122:123], off nt
	s_nop 0
	global_load_dwordx4 v[124:127], v[124:125], off nt

.LBB0_822:
	s_waitcnt lgkmcnt(0)
	s_add_u32 s26, s8, s24
	s_addc_u32 s27, s9, s25
	s_add_i32 s30, s30, s48
	s_cmpk_lt_i32 s30, 0x400
	s_cselect_b64 s[24:25], -1, 0
	s_lshl_b32 s34, s31, 6
	s_ashr_i32 s35, s34, 31
	s_lshl_b64 s[8:9], s[34:35], 2
	s_add_u32 s8, s10, s8
	s_addc_u32 s9, s11, s9
	s_cmp_lg_u64 s[10:11], 0
	s_cselect_b32 s9, s9, 0
	s_cselect_b32 s8, s8, 0
	s_ashr_i32 s31, s33, 31
	s_and_b64 s[10:11], s[28:29], exec
	s_cselect_b32 s10, 0, s33
	s_cselect_b32 s11, 0, s31
	s_mul_i32 s11, s11, s37
	s_mul_hi_u32 s28, s10, s37
	s_add_i32 s11, s28, s11
	s_mul_i32 s10, s10, s37
	s_lshl_b64 s[10:11], s[10:11], 1
	s_add_u32 s26, s26, s10
	s_addc_u32 s27, s27, s11
	s_lshl_b64 s[10:11], s[34:35], 1
	v_mov_b32_e32 v2, v167
	v_mov_b32_e32 v3, v167
	s_add_u32 s10, s26, s10
	v_mov_b32_e32 v0, v167
	v_mov_b32_e32 v1, v167
	v_mov_b64_e32 v[6:7], v[2:3]
	v_mov_b64_e32 v[10:11], v[2:3]
	v_mov_b64_e32 v[14:15], v[2:3]
	v_mov_b64_e32 v[18:19], v[2:3]
	v_mov_b64_e32 v[22:23], v[2:3]
	v_mov_b64_e32 v[26:27], v[2:3]
	v_mov_b64_e32 v[30:31], v[2:3]
	v_mov_b64_e32 v[38:39], v[2:3]
	v_mov_b64_e32 v[42:43], v[2:3]
	v_mov_b64_e32 v[46:47], v[2:3]
	v_mov_b64_e32 v[50:51], v[2:3]
	v_mov_b64_e32 v[54:55], v[2:3]
	v_mov_b64_e32 v[58:59], v[2:3]
	v_mov_b64_e32 v[34:35], v[2:3]
	v_mov_b64_e32 v[62:63], v[2:3]
	s_addc_u32 s11, s27, s11
	v_cmp_gt_u32_e32 vcc, s38, v128
	v_mov_b64_e32 v[4:5], v[0:1]
	v_mov_b64_e32 v[8:9], v[0:1]
	v_mov_b64_e32 v[12:13], v[0:1]
	v_mov_b64_e32 v[16:17], v[0:1]
	v_mov_b64_e32 v[20:21], v[0:1]
	v_mov_b64_e32 v[24:25], v[0:1]
	v_mov_b64_e32 v[28:29], v[0:1]
	v_mov_b64_e32 v[36:37], v[0:1]
	v_mov_b64_e32 v[40:41], v[0:1]
	v_mov_b64_e32 v[44:45], v[0:1]
	v_mov_b64_e32 v[48:49], v[0:1]
	v_mov_b64_e32 v[52:53], v[0:1]
	v_mov_b64_e32 v[56:57], v[0:1]
	v_mov_b64_e32 v[32:33], v[0:1]
	v_mov_b64_e32 v[60:61], v[0:1]
	s_and_saveexec_b64 s[26:27], vcc
	s_cbranch_execz .LBB0_824
	s_mul_i32 s28, s20, s35
	s_mul_hi_u32 s29, s20, s34
	s_add_i32 s28, s29, s28
	s_mul_i32 s21, s21, s34
	s_add_i32 s29, s28, s21
	s_mul_i32 s28, s20, s34
	s_lshl_b64 s[28:29], s[28:29], 2
	s_add_u32 s21, s22, s28
	s_addc_u32 s28, s23, s29
	s_ashr_i32 s31, s30, 31
	s_lshl_b64 s[22:23], s[30:31], 2
	s_add_u32 s22, s21, s22
	s_addc_u32 s23, s28, s23
	v_mul_hi_i32_i24_e32 v1, s20, v132
	v_mul_i32_i24_e32 v0, s20, v132
	v_lshl_add_u64 v[0:1], v[0:1], 2, s[22:23]
	v_lshlrev_b32_e32 v32, 2, v128
	v_mov_b32_e32 v33, v167
	v_lshl_add_u64 v[8:9], v[0:1], 0, v[32:33]
	v_mul_hi_i32_i24_e32 v1, s20, v134
	v_mul_i32_i24_e32 v0, s20, v134
	v_lshl_add_u64 v[0:1], v[0:1], 2, s[22:23]
	v_lshl_add_u64 v[10:11], v[0:1], 0, v[32:33]
	global_load_dwordx4 v[0:3], v[8:9], off nt
	global_load_dwordx4 v[4:7], v[10:11], off nt
	v_mul_hi_i32_i24_e32 v9, s20, v136
	v_mul_i32_i24_e32 v8, s20, v136
	v_mul_hi_i32_i24_e32 v11, s20, v138
	v_mul_i32_i24_e32 v10, s20, v138
	v_mul_hi_i32_i24_e32 v17, s20, v140
	v_mul_i32_i24_e32 v16, s20, v140
	v_mul_hi_i32_i24_e32 v19, s20, v142
	v_mul_i32_i24_e32 v18, s20, v142
	v_mul_hi_i32_i24_e32 v25, s20, v144
	v_mul_i32_i24_e32 v24, s20, v144
	v_mul_hi_i32_i24_e32 v27, s20, v146
	v_mul_i32_i24_e32 v26, s20, v146
	v_mul_hi_i32_i24_e32 v35, s20, v148
	v_mul_i32_i24_e32 v34, s20, v148
	v_mul_hi_i32_i24_e32 v37, s20, v150
	v_mul_i32_i24_e32 v36, s20, v150
	v_lshl_add_u64 v[8:9], v[8:9], 2, s[22:23]
	v_lshl_add_u64 v[10:11], v[10:11], 2, s[22:23]
	v_lshl_add_u64 v[16:17], v[16:17], 2, s[22:23]
	v_lshl_add_u64 v[18:19], v[18:19], 2, s[22:23]
	v_lshl_add_u64 v[24:25], v[24:25], 2, s[22:23]
	v_lshl_add_u64 v[26:27], v[26:27], 2, s[22:23]
	v_lshl_add_u64 v[34:35], v[34:35], 2, s[22:23]
	v_lshl_add_u64 v[36:37], v[36:37], 2, s[22:23]
	v_lshl_add_u64 v[8:9], v[8:9], 0, v[32:33]
	v_lshl_add_u64 v[12:13], v[10:11], 0, v[32:33]
	v_lshl_add_u64 v[16:17], v[16:17], 0, v[32:33]
	v_lshl_add_u64 v[20:21], v[18:19], 0, v[32:33]
	v_lshl_add_u64 v[24:25], v[24:25], 0, v[32:33]
	v_lshl_add_u64 v[28:29], v[26:27], 0, v[32:33]
	v_lshl_add_u64 v[34:35], v[34:35], 0, v[32:33]
	v_lshl_add_u64 v[40:41], v[36:37], 0, v[32:33]
	global_load_dwordx4 v[8:11], v[8:9], off nt
	s_nop 0
	global_load_dwordx4 v[12:15], v[12:13], off nt
	s_nop 0
	global_load_dwordx4 v[16:19], v[16:17], off nt
	s_nop 0
	global_load_dwordx4 v[20:23], v[20:21], off nt
	s_nop 0
	global_load_dwordx4 v[24:27], v[24:25], off nt
	s_nop 0
	global_load_dwordx4 v[28:31], v[28:29], off nt
	s_nop 0
	global_load_dwordx4 v[36:39], v[34:35], off nt
	s_nop 0
	global_load_dwordx4 v[40:43], v[40:41], off nt
	v_mul_hi_i32_i24_e32 v35, s20, v152
	v_mul_i32_i24_e32 v34, s20, v152
	v_mul_hi_i32_i24_e32 v45, s20, v154
	v_mul_i32_i24_e32 v44, s20, v154
	v_lshl_add_u64 v[34:35], v[34:35], 2, s[22:23]
	v_lshl_add_u64 v[44:45], v[44:45], 2, s[22:23]
	v_lshl_add_u64 v[34:35], v[34:35], 0, v[32:33]
	v_lshl_add_u64 v[48:49], v[44:45], 0, v[32:33]
	global_load_dwordx4 v[44:47], v[34:35], off nt
	s_nop 0
	global_load_dwordx4 v[48:51], v[48:49], off nt
	v_mul_hi_i32_i24_e32 v35, s20, v156
	v_mul_i32_i24_e32 v34, s20, v156
	v_mul_hi_i32_i24_e32 v53, s20, v158
	v_mul_i32_i24_e32 v52, s20, v158
	v_lshl_add_u64 v[34:35], v[34:35], 2, s[22:23]
	v_lshl_add_u64 v[52:53], v[52:53], 2, s[22:23]
	v_lshl_add_u64 v[34:35], v[34:35], 0, v[32:33]
	v_lshl_add_u64 v[56:57], v[52:53], 0, v[32:33]
	global_load_dwordx4 v[52:55], v[34:35], off nt
	s_nop 0
	global_load_dwordx4 v[56:59], v[56:57], off nt
	v_mul_hi_i32_i24_e32 v35, s20, v160
	v_mul_i32_i24_e32 v34, s20, v160
	v_mul_hi_i32_i24_e32 v61, s20, v162
	v_mul_i32_i24_e32 v60, s20, v162
	v_lshl_add_u64 v[34:35], v[34:35], 2, s[22:23]
	v_lshl_add_u64 v[60:61], v[60:61], 2, s[22:23]
	v_lshl_add_u64 v[34:35], v[34:35], 0, v[32:33]
	v_lshl_add_u64 v[60:61], v[60:61], 0, v[32:33]
	global_load_dwordx4 v[32:35], v[34:35], off nt
	s_nop 0
	global_load_dwordx4 v[60:63], v[60:61], off nt

.LBB0_962:
	s_or_saveexec_b64 s[26:27], s[24:25]
	v_mov_b32_e32 v33, v32
	v_mov_b32_e32 v34, v32
	v_mov_b32_e32 v35, v32
	v_mov_b64_e32 v[58:59], v[34:35]
	v_mov_b64_e32 v[54:55], v[34:35]
	v_mov_b64_e32 v[50:51], v[34:35]
	v_mov_b64_e32 v[46:47], v[34:35]
	v_mov_b64_e32 v[42:43], v[34:35]
	v_mov_b64_e32 v[38:39], v[34:35]
	v_mov_b64_e32 v[28:29], v[32:33]
	v_mov_b64_e32 v[24:25], v[32:33]
	v_mov_b64_e32 v[20:21], v[32:33]
	v_mov_b64_e32 v[16:17], v[32:33]
	v_mov_b64_e32 v[12:13], v[32:33]
	v_mov_b64_e32 v[8:9], v[32:33]
	v_mov_b64_e32 v[4:5], v[32:33]
	v_mov_b64_e32 v[0:1], v[32:33]
	s_waitcnt vmcnt(2)
	v_mov_b64_e32 v[62:63], v[34:35]
	s_add_i32 s24, s33, s31
	v_mov_b64_e32 v[56:57], v[32:33]
	v_mov_b64_e32 v[52:53], v[32:33]
	v_mov_b64_e32 v[48:49], v[32:33]
	v_mov_b64_e32 v[44:45], v[32:33]
	v_mov_b64_e32 v[40:41], v[32:33]
	v_mov_b64_e32 v[36:37], v[32:33]
	v_mov_b64_e32 v[30:31], v[34:35]
	v_mov_b64_e32 v[26:27], v[34:35]
	v_mov_b64_e32 v[22:23], v[34:35]
	v_mov_b64_e32 v[18:19], v[34:35]
	v_mov_b64_e32 v[14:15], v[34:35]
	v_mov_b64_e32 v[10:11], v[34:35]
	v_mov_b64_e32 v[6:7], v[34:35]
	v_mov_b64_e32 v[2:3], v[34:35]
	v_mov_b64_e32 v[60:61], v[32:33]
	s_xor_b64 exec, exec, s[26:27]
	s_cbranch_execz .LBB0_964
	s_mul_i32 s25, s16, s23
	s_mul_hi_u32 s30, s16, s22
	s_add_i32 s25, s30, s25
	s_mul_i32 s17, s17, s22
	s_add_i32 s31, s25, s17
	s_mul_i32 s30, s16, s22
	s_lshl_b64 s[30:31], s[30:31], 2
	s_waitcnt lgkmcnt(0)
	s_add_u32 s17, s18, s30
	s_addc_u32 s30, s19, s31
	s_ashr_i32 s25, s24, 31
	s_lshl_b64 s[18:19], s[24:25], 2
	v_and_b32_e32 v132, 6, v130
	s_add_u32 s18, s17, s18
	v_mul_u32_u24_e32 v0, s16, v132
	s_addc_u32 s19, s30, s19
	v_mov_b32_e32 v33, 0
	v_lshlrev_b32_e32 v32, 2, v0
	v_lshl_add_u64 v[0:1], s[18:19], 0, v[32:33]
	v_lshlrev_b32_e32 v32, 2, v128
	v_or_b32_e32 v134, 1, v130
	v_lshl_add_u64 v[8:9], v[0:1], 0, v[32:33]
	v_mul_u32_u24_e32 v0, s16, v134
	v_lshlrev_b32_e32 v0, 2, v0
	v_mov_b32_e32 v1, v33
	v_lshl_add_u64 v[0:1], s[18:19], 0, v[0:1]
	v_or_b32_e32 v136, 8, v132
	v_lshl_add_u64 v[10:11], v[0:1], 0, v[32:33]
	global_load_dwordx4 v[0:3], v[8:9], off nt
	global_load_dwordx4 v[4:7], v[10:11], off nt
	v_mul_u32_u24_e32 v8, s16, v136
	v_lshlrev_b32_e32 v8, 2, v8
	v_mov_b32_e32 v9, v33
	v_lshl_add_u64 v[8:9], s[18:19], 0, v[8:9]
	v_or_b32_e32 v138, 9, v130
	v_lshl_add_u64 v[16:17], v[8:9], 0, v[32:33]
	v_mul_u32_u24_e32 v8, s16, v138
	v_lshlrev_b32_e32 v8, 2, v8
	v_mov_b32_e32 v9, v33
	v_lshl_add_u64 v[8:9], s[18:19], 0, v[8:9]
	v_or_b32_e32 v140, 16, v132
	v_lshl_add_u64 v[18:19], v[8:9], 0, v[32:33]
	global_load_dwordx4 v[8:11], v[16:17], off nt
	global_load_dwordx4 v[12:15], v[18:19], off nt
	v_mul_u32_u24_e32 v16, s16, v140
	v_lshlrev_b32_e32 v16, 2, v16
	v_mov_b32_e32 v17, v33
	v_lshl_add_u64 v[16:17], s[18:19], 0, v[16:17]
	v_or_b32_e32 v142, 17, v130
	v_lshl_add_u64 v[24:25], v[16:17], 0, v[32:33]
	v_mul_u32_u24_e32 v16, s16, v142
	v_lshlrev_b32_e32 v16, 2, v16
	v_mov_b32_e32 v17, v33
	v_lshl_add_u64 v[16:17], s[18:19], 0, v[16:17]
	v_or_b32_e32 v144, 24, v132
	v_lshl_add_u64 v[26:27], v[16:17], 0, v[32:33]
	global_load_dwordx4 v[16:19], v[24:25], off nt
	global_load_dwordx4 v[20:23], v[26:27], off nt
	v_mul_u32_u24_e32 v24, s16, v144
	v_lshlrev_b32_e32 v24, 2, v24
	v_mov_b32_e32 v25, v33
	v_lshl_add_u64 v[24:25], s[18:19], 0, v[24:25]
	v_or_b32_e32 v146, 25, v130
	v_lshl_add_u64 v[34:35], v[24:25], 0, v[32:33]
	v_mul_u32_u24_e32 v24, s16, v146
	v_lshlrev_b32_e32 v24, 2, v24
	v_mov_b32_e32 v25, v33
	v_lshl_add_u64 v[24:25], s[18:19], 0, v[24:25]
	v_or_b32_e32 v148, 32, v132
	v_lshl_add_u64 v[36:37], v[24:25], 0, v[32:33]
	global_load_dwordx4 v[24:27], v[34:35], off nt
	global_load_dwordx4 v[28:31], v[36:37], off nt
	v_mul_u32_u24_e32 v34, s16, v148
	v_or_b32_e32 v150, 33, v130
	v_lshlrev_b32_e32 v34, 2, v34
	v_mov_b32_e32 v35, v33
	v_mul_u32_u24_e32 v36, s16, v150
	v_lshl_add_u64 v[34:35], s[18:19], 0, v[34:35]
	v_lshlrev_b32_e32 v36, 2, v36
	v_mov_b32_e32 v37, v33
	v_lshl_add_u64 v[34:35], v[34:35], 0, v[32:33]
	v_lshl_add_u64 v[36:37], s[18:19], 0, v[36:37]
	v_or_b32_e32 v152, 40, v132
	v_lshl_add_u64 v[44:45], v[36:37], 0, v[32:33]
	global_load_dwordx4 v[36:39], v[34:35], off nt
	global_load_dwordx4 v[40:43], v[44:45], off nt
	v_mul_u32_u24_e32 v34, s16, v152
	v_or_b32_e32 v154, 41, v130
	v_lshlrev_b32_e32 v34, 2, v34
	v_mov_b32_e32 v35, v33
	v_mul_u32_u24_e32 v44, s16, v154
	v_lshl_add_u64 v[34:35], s[18:19], 0, v[34:35]
	v_lshlrev_b32_e32 v44, 2, v44
	v_mov_b32_e32 v45, v33
	v_lshl_add_u64 v[34:35], v[34:35], 0, v[32:33]
	v_lshl_add_u64 v[44:45], s[18:19], 0, v[44:45]
	v_or_b32_e32 v156, 48, v132
	v_lshl_add_u64 v[52:53], v[44:45], 0, v[32:33]
	global_load_dwordx4 v[44:47], v[34:35], off nt
	global_load_dwordx4 v[48:51], v[52:53], off nt
	v_mul_u32_u24_e32 v34, s16, v156
	v_or_b32_e32 v158, 49, v130
	v_lshlrev_b32_e32 v34, 2, v34
	v_mov_b32_e32 v35, v33
	v_mul_u32_u24_e32 v52, s16, v158
	v_lshl_add_u64 v[34:35], s[18:19], 0, v[34:35]
	v_lshlrev_b32_e32 v52, 2, v52
	v_mov_b32_e32 v53, v33
	v_lshl_add_u64 v[34:35], v[34:35], 0, v[32:33]
	v_lshl_add_u64 v[52:53], s[18:19], 0, v[52:53]
	v_or_b32_e32 v160, 56, v132
	v_lshl_add_u64 v[60:61], v[52:53], 0, v[32:33]
	global_load_dwordx4 v[52:55], v[34:35], off nt
	global_load_dwordx4 v[56:59], v[60:61], off nt
	v_mul_u32_u24_e32 v34, s16, v160
	v_lshlrev_b32_e32 v34, 2, v34
	v_mov_b32_e32 v35, v33
	v_lshl_add_u64 v[34:35], s[18:19], 0, v[34:35]
	v_or_b32_e32 v162, 57, v130
	v_lshl_add_u64 v[64:65], v[34:35], 0, v[32:33]
	v_mul_u32_u24_e32 v34, s16, v162
	v_lshlrev_b32_e32 v34, 2, v34
	v_mov_b32_e32 v35, v33
	v_lshl_add_u64 v[34:35], s[18:19], 0, v[34:35]
	v_lshl_add_u64 v[66:67], v[34:35], 0, v[32:33]
	global_load_dwordx4 v[32:35], v[64:65], off nt
	global_load_dwordx4 v[60:63], v[66:67], off nt

.LBB0_1007:
	s_waitcnt lgkmcnt(0)
	s_add_u32 s26, s12, s24
	s_addc_u32 s27, s13, s25
	s_add_i32 s30, s30, s43
	s_cmpk_lt_i32 s30, 0x400
	s_cselect_b64 s[24:25], -1, 0
	s_lshl_b32 s34, s31, 6
	s_ashr_i32 s35, s34, 31
	s_lshl_b64 s[12:13], s[34:35], 2
	s_add_u32 s12, s16, s12
	s_addc_u32 s13, s17, s13
	s_cmp_lg_u64 s[16:17], 0
	s_cselect_b32 s13, s13, 0
	s_cselect_b32 s12, s12, 0
	s_ashr_i32 s31, s33, 31
	s_and_b64 s[16:17], s[28:29], exec
	s_cselect_b32 s16, 0, s33
	s_cselect_b32 s17, 0, s31
	s_mul_i32 s17, s17, s40
	s_mul_hi_u32 s28, s16, s40
	s_add_i32 s17, s28, s17
	s_mul_i32 s16, s16, s40
	s_lshl_b64 s[16:17], s[16:17], 1
	s_add_u32 s26, s26, s16
	s_addc_u32 s27, s27, s17
	s_lshl_b64 s[16:17], s[34:35], 1
	s_add_u32 s16, s26, s16
	s_addc_u32 s17, s27, s17
	v_cmp_gt_u32_e32 vcc, s41, v128
	v_mov_b32_e32 v67, 0
	v_mov_b32_e32 v66, 0
	v_mov_b32_e32 v65, 0
	v_mov_b32_e32 v64, 0
	v_mov_b32_e32 v71, 0
	v_mov_b32_e32 v70, 0
	v_mov_b32_e32 v69, 0
	v_mov_b32_e32 v68, 0
	v_mov_b32_e32 v75, 0
	v_mov_b32_e32 v74, 0
	v_mov_b32_e32 v73, 0
	v_mov_b32_e32 v72, 0
	v_mov_b32_e32 v79, 0
	v_mov_b32_e32 v78, 0
	v_mov_b32_e32 v77, 0
	v_mov_b32_e32 v76, 0
	v_mov_b32_e32 v83, 0
	v_mov_b32_e32 v82, 0
	v_mov_b32_e32 v81, 0
	v_mov_b32_e32 v80, 0
	v_mov_b32_e32 v87, 0
	v_mov_b32_e32 v86, 0
	v_mov_b32_e32 v85, 0
	v_mov_b32_e32 v84, 0
	v_mov_b32_e32 v91, 0
	v_mov_b32_e32 v90, 0
	v_mov_b32_e32 v89, 0
	v_mov_b32_e32 v88, 0
	v_mov_b32_e32 v95, 0
	v_mov_b32_e32 v94, 0
	v_mov_b32_e32 v93, 0
	v_mov_b32_e32 v92, 0
	v_mov_b32_e32 v99, 0
	v_mov_b32_e32 v98, 0
	v_mov_b32_e32 v97, 0
	v_mov_b32_e32 v96, 0
	v_mov_b32_e32 v103, 0
	v_mov_b32_e32 v102, 0
	v_mov_b32_e32 v101, 0
	v_mov_b32_e32 v100, 0
	v_mov_b32_e32 v107, 0
	v_mov_b32_e32 v106, 0
	v_mov_b32_e32 v105, 0
	v_mov_b32_e32 v104, 0
	v_mov_b32_e32 v111, 0
	v_mov_b32_e32 v110, 0
	v_mov_b32_e32 v109, 0
	v_mov_b32_e32 v108, 0
	v_mov_b32_e32 v115, 0
	v_mov_b32_e32 v114, 0
	v_mov_b32_e32 v113, 0
	v_mov_b32_e32 v112, 0
	v_mov_b32_e32 v119, 0
	v_mov_b32_e32 v118, 0
	v_mov_b32_e32 v117, 0
	v_mov_b32_e32 v116, 0
	v_mov_b32_e32 v123, 0
	v_mov_b32_e32 v122, 0
	v_mov_b32_e32 v121, 0
	v_mov_b32_e32 v120, 0
	v_mov_b32_e32 v127, 0
	v_mov_b32_e32 v126, 0
	v_mov_b32_e32 v125, 0
	v_mov_b32_e32 v124, 0
	s_and_saveexec_b64 s[26:27], vcc
	s_cbranch_execz .LBB0_1009
	s_mul_i32 s28, s20, s35
	s_mul_hi_u32 s29, s20, s34
	s_add_i32 s28, s29, s28
	s_mul_i32 s21, s21, s34
	s_add_i32 s29, s28, s21
	s_mul_i32 s28, s20, s34
	s_lshl_b64 s[28:29], s[28:29], 2
	s_add_u32 s21, s22, s28
	s_addc_u32 s28, s23, s29
	s_ashr_i32 s31, s30, 31
	s_lshl_b64 s[22:23], s[30:31], 2
	s_add_u32 s22, s21, s22
	s_addc_u32 s23, s28, s23
	v_mul_hi_i32_i24_e32 v65, s20, v132
	v_mul_i32_i24_e32 v64, s20, v132
	v_lshl_add_u64 v[64:65], v[64:65], 2, s[22:23]
	v_lshlrev_b32_e32 v120, 2, v128
	v_mov_b32_e32 v121, v167
	v_lshl_add_u64 v[72:73], v[64:65], 0, v[120:121]
	v_mul_hi_i32_i24_e32 v65, s20, v134
	v_mul_i32_i24_e32 v64, s20, v134
	v_lshl_add_u64 v[64:65], v[64:65], 2, s[22:23]
	v_lshl_add_u64 v[74:75], v[64:65], 0, v[120:121]
	global_load_dwordx4 v[64:67], v[72:73], off nt
	global_load_dwordx4 v[68:71], v[74:75], off nt
	v_mul_hi_i32_i24_e32 v73, s20, v136
	v_mul_i32_i24_e32 v72, s20, v136
	v_lshl_add_u64 v[72:73], v[72:73], 2, s[22:23]
	v_lshl_add_u64 v[80:81], v[72:73], 0, v[120:121]
	v_mul_hi_i32_i24_e32 v73, s20, v138
	v_mul_i32_i24_e32 v72, s20, v138
	v_lshl_add_u64 v[72:73], v[72:73], 2, s[22:23]
	v_lshl_add_u64 v[82:83], v[72:73], 0, v[120:121]
	global_load_dwordx4 v[72:75], v[80:81], off nt
	global_load_dwordx4 v[76:79], v[82:83], off nt
	v_mul_hi_i32_i24_e32 v81, s20, v140
	v_mul_i32_i24_e32 v80, s20, v140
	v_mul_hi_i32_i24_e32 v83, s20, v142
	v_mul_i32_i24_e32 v82, s20, v142
	v_mul_hi_i32_i24_e32 v89, s20, v144
	v_mul_i32_i24_e32 v88, s20, v144
	v_mul_hi_i32_i24_e32 v91, s20, v146
	v_mul_i32_i24_e32 v90, s20, v146
	v_mul_hi_i32_i24_e32 v97, s20, v148
	v_mul_i32_i24_e32 v96, s20, v148
	v_mul_hi_i32_i24_e32 v99, s20, v150
	v_mul_i32_i24_e32 v98, s20, v150
	v_mul_hi_i32_i24_e32 v105, s20, v152
	v_mul_i32_i24_e32 v104, s20, v152
	v_mul_hi_i32_i24_e32 v107, s20, v154
	v_mul_i32_i24_e32 v106, s20, v154
	v_mul_hi_i32_i24_e32 v113, s20, v156
	v_mul_i32_i24_e32 v112, s20, v156
	v_mul_hi_i32_i24_e32 v115, s20, v158
	v_mul_i32_i24_e32 v114, s20, v158
	v_mul_hi_i32_i24_e32 v123, s20, v160
	v_mul_i32_i24_e32 v122, s20, v160
	v_mul_hi_i32_i24_e32 v125, s20, v162
	v_mul_i32_i24_e32 v124, s20, v162
	v_lshl_add_u64 v[80:81], v[80:81], 2, s[22:23]
	v_lshl_add_u64 v[82:83], v[82:83], 2, s[22:23]
	v_lshl_add_u64 v[88:89], v[88:89], 2, s[22:23]
	v_lshl_add_u64 v[90:91], v[90:91], 2, s[22:23]
	v_lshl_add_u64 v[96:97], v[96:97], 2, s[22:23]
	v_lshl_add_u64 v[98:99], v[98:99], 2, s[22:23]
	v_lshl_add_u64 v[104:105], v[104:105], 2, s[22:23]
	v_lshl_add_u64 v[106:107], v[106:107], 2, s[22:23]
	v_lshl_add_u64 v[112:113], v[112:113], 2, s[22:23]
	v_lshl_add_u64 v[114:115], v[114:115], 2, s[22:23]
	v_lshl_add_u64 v[122:123], v[122:123], 2, s[22:23]
	v_lshl_add_u64 v[124:125], v[124:125], 2, s[22:23]
	v_lshl_add_u64 v[80:81], v[80:81], 0, v[120:121]
	v_lshl_add_u64 v[84:85], v[82:83], 0, v[120:121]
	v_lshl_add_u64 v[88:89], v[88:89], 0, v[120:121]
	v_lshl_add_u64 v[92:93], v[90:91], 0, v[120:121]
	v_lshl_add_u64 v[96:97], v[96:97], 0, v[120:121]
	v_lshl_add_u64 v[100:101], v[98:99], 0, v[120:121]
	v_lshl_add_u64 v[104:105], v[104:105], 0, v[120:121]
	v_lshl_add_u64 v[108:109], v[106:107], 0, v[120:121]
	v_lshl_add_u64 v[112:113], v[112:113], 0, v[120:121]
	v_lshl_add_u64 v[116:117], v[114:115], 0, v[120:121]
	v_lshl_add_u64 v[122:123], v[122:123], 0, v[120:121]
	v_lshl_add_u64 v[124:125], v[124:125], 0, v[120:121]
	global_load_dwordx4 v[80:83], v[80:81], off nt
	s_nop 0
	global_load_dwordx4 v[84:87], v[84:85], off nt
	s_nop 0
	global_load_dwordx4 v[88:91], v[88:89], off nt
	s_nop 0
	global_load_dwordx4 v[92:95], v[92:93], off nt
	s_nop 0
	global_load_dwordx4 v[96:99], v[96:97], off nt
	s_nop 0
	global_load_dwordx4 v[100:103], v[100:101], off nt
	s_nop 0
	global_load_dwordx4 v[104:107], v[104:105], off nt
	s_nop 0
	global_load_dwordx4 v[108:111], v[108:109], off nt
	s_nop 0
	global_load_dwordx4 v[112:115], v[112:113], off nt
	s_nop 0
	global_load_dwordx4 v[116:119], v[116:117], off nt
	s_nop 0
	global_load_dwordx4 v[120:123], v[122:123], off nt
	s_nop 0
	global_load_dwordx4 v[124:127], v[124:125], off nt

.LBB0_1080:
	s_waitcnt lgkmcnt(0)
	s_add_u32 s26, s8, s24
	s_addc_u32 s27, s9, s25
	s_add_i32 s30, s30, s48
	s_cmpk_lt_i32 s30, 0x400
	s_cselect_b64 s[24:25], -1, 0
	s_lshl_b32 s34, s31, 6
	s_ashr_i32 s35, s34, 31
	s_lshl_b64 s[8:9], s[34:35], 2
	s_add_u32 s8, s10, s8
	s_addc_u32 s9, s11, s9
	s_cmp_lg_u64 s[10:11], 0
	s_cselect_b32 s9, s9, 0
	s_cselect_b32 s8, s8, 0
	s_ashr_i32 s31, s33, 31
	s_and_b64 s[10:11], s[28:29], exec
	s_cselect_b32 s10, 0, s33
	s_cselect_b32 s11, 0, s31
	s_mul_i32 s11, s11, s37
	s_mul_hi_u32 s28, s10, s37
	s_add_i32 s11, s28, s11
	s_mul_i32 s10, s10, s37
	s_lshl_b64 s[10:11], s[10:11], 1
	s_add_u32 s26, s26, s10
	s_addc_u32 s27, s27, s11
	s_lshl_b64 s[10:11], s[34:35], 1
	v_mov_b32_e32 v2, v167
	v_mov_b32_e32 v3, v167
	s_add_u32 s10, s26, s10
	v_mov_b32_e32 v0, v167
	v_mov_b32_e32 v1, v167
	v_mov_b64_e32 v[6:7], v[2:3]
	v_mov_b64_e32 v[10:11], v[2:3]
	v_mov_b64_e32 v[14:15], v[2:3]
	v_mov_b64_e32 v[18:19], v[2:3]
	v_mov_b64_e32 v[22:23], v[2:3]
	v_mov_b64_e32 v[26:27], v[2:3]
	v_mov_b64_e32 v[30:31], v[2:3]
	v_mov_b64_e32 v[38:39], v[2:3]
	v_mov_b64_e32 v[42:43], v[2:3]
	v_mov_b64_e32 v[46:47], v[2:3]
	v_mov_b64_e32 v[50:51], v[2:3]
	v_mov_b64_e32 v[54:55], v[2:3]
	v_mov_b64_e32 v[58:59], v[2:3]
	v_mov_b64_e32 v[34:35], v[2:3]
	v_mov_b64_e32 v[62:63], v[2:3]
	s_addc_u32 s11, s27, s11
	v_cmp_gt_u32_e32 vcc, s39, v128
	v_mov_b64_e32 v[4:5], v[0:1]
	v_mov_b64_e32 v[8:9], v[0:1]
	v_mov_b64_e32 v[12:13], v[0:1]
	v_mov_b64_e32 v[16:17], v[0:1]
	v_mov_b64_e32 v[20:21], v[0:1]
	v_mov_b64_e32 v[24:25], v[0:1]
	v_mov_b64_e32 v[28:29], v[0:1]
	v_mov_b64_e32 v[36:37], v[0:1]
	v_mov_b64_e32 v[40:41], v[0:1]
	v_mov_b64_e32 v[44:45], v[0:1]
	v_mov_b64_e32 v[48:49], v[0:1]
	v_mov_b64_e32 v[52:53], v[0:1]
	v_mov_b64_e32 v[56:57], v[0:1]
	v_mov_b64_e32 v[32:33], v[0:1]
	v_mov_b64_e32 v[60:61], v[0:1]
	s_and_saveexec_b64 s[26:27], vcc
	s_cbranch_execz .LBB0_1082
	s_mul_i32 s28, s20, s35
	s_mul_hi_u32 s29, s20, s34
	s_add_i32 s28, s29, s28
	s_mul_i32 s21, s21, s34
	s_add_i32 s29, s28, s21
	s_mul_i32 s28, s20, s34
	s_lshl_b64 s[28:29], s[28:29], 2
	s_add_u32 s21, s22, s28
	s_addc_u32 s28, s23, s29
	s_ashr_i32 s31, s30, 31
	s_lshl_b64 s[22:23], s[30:31], 2
	s_add_u32 s22, s21, s22
	s_addc_u32 s23, s28, s23
	v_mul_hi_i32_i24_e32 v1, s20, v132
	v_mul_i32_i24_e32 v0, s20, v132
	v_lshl_add_u64 v[0:1], v[0:1], 2, s[22:23]
	v_lshlrev_b32_e32 v32, 2, v128
	v_mov_b32_e32 v33, v167
	v_lshl_add_u64 v[8:9], v[0:1], 0, v[32:33]
	v_mul_hi_i32_i24_e32 v1, s20, v134
	v_mul_i32_i24_e32 v0, s20, v134
	v_lshl_add_u64 v[0:1], v[0:1], 2, s[22:23]
	v_lshl_add_u64 v[10:11], v[0:1], 0, v[32:33]
	global_load_dwordx4 v[0:3], v[8:9], off nt
	global_load_dwordx4 v[4:7], v[10:11], off nt
	v_mul_hi_i32_i24_e32 v9, s20, v136
	v_mul_i32_i24_e32 v8, s20, v136
	v_lshl_add_u64 v[8:9], v[8:9], 2, s[22:23]
	v_lshl_add_u64 v[16:17], v[8:9], 0, v[32:33]
	v_mul_hi_i32_i24_e32 v9, s20, v138
	v_mul_i32_i24_e32 v8, s20, v138
	v_lshl_add_u64 v[8:9], v[8:9], 2, s[22:23]
	v_lshl_add_u64 v[18:19], v[8:9], 0, v[32:33]
	global_load_dwordx4 v[8:11], v[16:17], off nt
	global_load_dwordx4 v[12:15], v[18:19], off nt
	v_mul_hi_i32_i24_e32 v17, s20, v140
	v_mul_i32_i24_e32 v16, s20, v140
	v_mul_hi_i32_i24_e32 v19, s20, v142
	v_mul_i32_i24_e32 v18, s20, v142
	v_mul_hi_i32_i24_e32 v25, s20, v144
	v_mul_i32_i24_e32 v24, s20, v144
	v_mul_hi_i32_i24_e32 v27, s20, v146
	v_mul_i32_i24_e32 v26, s20, v146
	v_mul_hi_i32_i24_e32 v35, s20, v148
	v_mul_i32_i24_e32 v34, s20, v148
	v_mul_hi_i32_i24_e32 v37, s20, v150
	v_mul_i32_i24_e32 v36, s20, v150
	v_lshl_add_u64 v[16:17], v[16:17], 2, s[22:23]
	v_lshl_add_u64 v[18:19], v[18:19], 2, s[22:23]
	v_lshl_add_u64 v[24:25], v[24:25], 2, s[22:23]
	v_lshl_add_u64 v[26:27], v[26:27], 2, s[22:23]
	v_lshl_add_u64 v[34:35], v[34:35], 2, s[22:23]
	v_lshl_add_u64 v[36:37], v[36:37], 2, s[22:23]
	v_lshl_add_u64 v[16:17], v[16:17], 0, v[32:33]
	v_lshl_add_u64 v[20:21], v[18:19], 0, v[32:33]
	v_lshl_add_u64 v[24:25], v[24:25], 0, v[32:33]
	v_lshl_add_u64 v[28:29], v[26:27], 0, v[32:33]
	v_lshl_add_u64 v[34:35], v[34:35], 0, v[32:33]
	v_lshl_add_u64 v[40:41], v[36:37], 0, v[32:33]
	global_load_dwordx4 v[16:19], v[16:17], off nt
	s_nop 0
	global_load_dwordx4 v[20:23], v[20:21], off nt
	s_nop 0
	global_load_dwordx4 v[24:27], v[24:25], off nt
	s_nop 0
	global_load_dwordx4 v[28:31], v[28:29], off nt
	s_nop 0
	global_load_dwordx4 v[36:39], v[34:35], off nt
	s_nop 0
	global_load_dwordx4 v[40:43], v[40:41], off nt
	v_mul_hi_i32_i24_e32 v35, s20, v152
	v_mul_i32_i24_e32 v34, s20, v152
	v_mul_hi_i32_i24_e32 v45, s20, v154
	v_mul_i32_i24_e32 v44, s20, v154
	v_lshl_add_u64 v[34:35], v[34:35], 2, s[22:23]
	v_lshl_add_u64 v[44:45], v[44:45], 2, s[22:23]
	v_lshl_add_u64 v[34:35], v[34:35], 0, v[32:33]
	v_lshl_add_u64 v[48:49], v[44:45], 0, v[32:33]
	global_load_dwordx4 v[44:47], v[34:35], off nt
	s_nop 0
	global_load_dwordx4 v[48:51], v[48:49], off nt
	v_mul_hi_i32_i24_e32 v35, s20, v156
	v_mul_i32_i24_e32 v34, s20, v156
	v_mul_hi_i32_i24_e32 v53, s20, v158
	v_mul_i32_i24_e32 v52, s20, v158
	v_lshl_add_u64 v[34:35], v[34:35], 2, s[22:23]
	v_lshl_add_u64 v[52:53], v[52:53], 2, s[22:23]
	v_lshl_add_u64 v[34:35], v[34:35], 0, v[32:33]
	v_lshl_add_u64 v[56:57], v[52:53], 0, v[32:33]
	global_load_dwordx4 v[52:55], v[34:35], off nt
	s_nop 0
	global_load_dwordx4 v[56:59], v[56:57], off nt
	v_mul_hi_i32_i24_e32 v35, s20, v160
	v_mul_i32_i24_e32 v34, s20, v160
	v_mul_hi_i32_i24_e32 v61, s20, v162
	v_mul_i32_i24_e32 v60, s20, v162
	v_lshl_add_u64 v[34:35], v[34:35], 2, s[22:23]
	v_lshl_add_u64 v[60:61], v[60:61], 2, s[22:23]
	v_lshl_add_u64 v[34:35], v[34:35], 0, v[32:33]
	v_lshl_add_u64 v[60:61], v[60:61], 0, v[32:33]
	global_load_dwordx4 v[32:35], v[34:35], off nt
	s_nop 0
	global_load_dwordx4 v[60:63], v[60:61], off nt

.LBB0_1187:
	ds_read_b128 v[152:155], v161
	ds_read_b128 v[166:169], v161 offset:1024
	ds_read_b128 v[170:173], v161 offset:2048
	ds_read_b128 v[174:177], v161 offset:3072
	ds_read_b128 v[178:181], v162
	ds_read_b128 v[182:185], v162 offset:1024
	ds_read_b128 v[186:189], v162 offset:2048
	ds_read_b128 v[194:197], v162 offset:3072
	s_add_u32 s30, s28, 0x100
	s_addc_u32 s31, s29, 0
	s_cmpk_eq_i32 s68, 0x54
	s_cselect_b32 s37, s11, s31
	s_cselect_b32 s36, s10, s30
	s_cselect_b32 s35, s27, s67
	s_cselect_b32 s34, s26, s66
	v_lshl_add_u64 v[156:157], s[28:29], 0, v[136:137]
	s_add_i32 m0, s43, 0xc000
	ds_read_b128 v[198:201], v163
	ds_read_b128 v[202:205], v163 offset:1024
	ds_read_b128 v[206:209], v163 offset:2048
	ds_read_b128 v[210:213], v163 offset:3072
	ds_read_b128 v[214:217], v163 offset:4096
	ds_read_b128 v[218:221], v163 offset:5120
	ds_read_b128 v[222:225], v163 offset:6144
	ds_read_b128 v[226:229], v163 offset:7168
	global_load_lds_dwordx4 v[156:157], off
	v_lshl_add_u64 v[156:157], s[28:29], 0, v[138:139]
	s_add_i32 m0, s43, 0xe000
	s_nop 0
	global_load_lds_dwordx4 v[156:157], off
	s_waitcnt vmcnt(8)
	s_waitcnt lgkmcnt(0)
	s_barrier
	s_setprio 1
	s_waitcnt lgkmcnt(0)
	v_mfma_f32_16x16x32_bf16 v[124:127], v[152:155], v[198:201], v[124:127]
	v_mfma_f32_16x16x32_bf16 v[120:123], v[170:173], v[198:201], v[120:123]
	v_mfma_f32_16x16x32_bf16 v[108:111], v[152:155], v[206:209], v[108:111]
	v_mfma_f32_16x16x32_bf16 v[104:107], v[170:173], v[206:209], v[104:107]
	v_mfma_f32_16x16x32_bf16 v[92:95], v[152:155], v[214:217], v[92:95]
	v_mfma_f32_16x16x32_bf16 v[88:91], v[170:173], v[214:217], v[88:91]
	v_mfma_f32_16x16x32_bf16 v[76:79], v[152:155], v[222:225], v[76:79]
	v_mfma_f32_16x16x32_bf16 v[72:75], v[170:173], v[222:225], v[72:75]
	v_mfma_f32_16x16x32_bf16 v[124:127], v[166:169], v[202:205], v[124:127]
	v_mfma_f32_16x16x32_bf16 v[120:123], v[174:177], v[202:205], v[120:123]
	v_mfma_f32_16x16x32_bf16 v[108:111], v[166:169], v[210:213], v[108:111]
	v_mfma_f32_16x16x32_bf16 v[104:107], v[174:177], v[210:213], v[104:107]
	v_mfma_f32_16x16x32_bf16 v[92:95], v[166:169], v[218:221], v[92:95]
	v_mfma_f32_16x16x32_bf16 v[88:91], v[174:177], v[218:221], v[88:91]
	v_mfma_f32_16x16x32_bf16 v[76:79], v[166:169], v[226:229], v[76:79]
	v_mfma_f32_16x16x32_bf16 v[72:75], v[174:177], v[226:229], v[72:75]
	s_setprio 0
	s_setprio 1
	v_mfma_f32_16x16x32_bf16 v[116:119], v[178:181], v[198:201], v[116:119]
	v_mfma_f32_16x16x32_bf16 v[112:115], v[186:189], v[198:201], v[112:115]
	v_mfma_f32_16x16x32_bf16 v[100:103], v[178:181], v[206:209], v[100:103]
	v_mfma_f32_16x16x32_bf16 v[96:99], v[186:189], v[206:209], v[96:99]
	v_mfma_f32_16x16x32_bf16 v[84:87], v[178:181], v[214:217], v[84:87]
	v_mfma_f32_16x16x32_bf16 v[80:83], v[186:189], v[214:217], v[80:83]
	v_mfma_f32_16x16x32_bf16 v[68:71], v[178:181], v[222:225], v[68:71]
	v_mfma_f32_16x16x32_bf16 v[64:67], v[186:189], v[222:225], v[64:67]
	v_mfma_f32_16x16x32_bf16 v[116:119], v[182:185], v[202:205], v[116:119]
	v_mfma_f32_16x16x32_bf16 v[112:115], v[194:197], v[202:205], v[112:115]
	v_mfma_f32_16x16x32_bf16 v[100:103], v[182:185], v[210:213], v[100:103]
	v_mfma_f32_16x16x32_bf16 v[96:99], v[194:197], v[210:213], v[96:99]
	v_mfma_f32_16x16x32_bf16 v[84:87], v[182:185], v[218:221], v[84:87]
	v_mfma_f32_16x16x32_bf16 v[80:83], v[194:197], v[218:221], v[80:83]
	v_mfma_f32_16x16x32_bf16 v[68:71], v[182:185], v[226:229], v[68:71]
	v_mfma_f32_16x16x32_bf16 v[64:67], v[194:197], v[226:229], v[64:67]
	s_setprio 0
	s_barrier
	s_add_i32 s28, s60, s42
	v_lshl_add_u64 v[156:157], s[34:35], 0, v[130:131]
	s_mov_b32 m0, s28
	ds_read_b128 v[198:201], v163 offset:16384
	ds_read_b128 v[202:205], v163 offset:17408
	ds_read_b128 v[206:209], v163 offset:18432
	ds_read_b128 v[210:213], v163 offset:19456
	ds_read_b128 v[214:217], v163 offset:20480
	ds_read_b128 v[218:221], v163 offset:21504
	ds_read_b128 v[222:225], v163 offset:22528
	ds_read_b128 v[226:229], v163 offset:23552
	global_load_lds_dwordx4 v[156:157], off
	s_add_i32 m0, s28, 0x2000
	s_add_u32 s28, s34, 0x160000
	v_lshl_add_u64 v[190:191], s[34:35], 0, v[134:135]
	s_addc_u32 s29, s35, 0
	s_add_i32 s33, s61, s42
	global_load_lds_dwordx4 v[190:191], off
	v_lshl_add_u64 v[230:231], s[28:29], 0, v[130:131]
	s_mov_b32 m0, s33
	v_lshl_add_u64 v[232:233], s[36:37], 0, v[132:133]
	global_load_lds_dwordx4 v[230:231], off
	v_lshl_add_u64 v[230:231], s[28:29], 0, v[134:135]
	s_add_i32 m0, s33, 0x2000
	s_nop 0
	global_load_lds_dwordx4 v[230:231], off
	v_lshl_add_u64 v[230:231], s[36:37], 0, v[128:129]
	s_mov_b32 m0, s43
	s_nop 0
	global_load_lds_dwordx4 v[230:231], off
	s_mov_b32 m0, s48
	s_nop 0
	global_load_lds_dwordx4 v[232:233], off
	s_waitcnt vmcnt(8)
	s_waitcnt lgkmcnt(0)
	s_barrier
	s_setprio 1
	s_waitcnt lgkmcnt(0)
	v_mfma_f32_16x16x32_bf16 v[60:63], v[152:155], v[198:201], v[60:63]
	v_mfma_f32_16x16x32_bf16 v[56:59], v[170:173], v[198:201], v[56:59]
	v_mfma_f32_16x16x32_bf16 v[44:47], v[152:155], v[206:209], v[44:47]
	v_mfma_f32_16x16x32_bf16 v[40:43], v[170:173], v[206:209], v[40:43]
	v_mfma_f32_16x16x32_bf16 v[28:31], v[152:155], v[214:217], v[28:31]
	v_mfma_f32_16x16x32_bf16 v[24:27], v[170:173], v[214:217], v[24:27]
	v_mfma_f32_16x16x32_bf16 v[12:15], v[152:155], v[222:225], v[12:15]
	v_mfma_f32_16x16x32_bf16 v[8:11], v[170:173], v[222:225], v[8:11]
	v_mfma_f32_16x16x32_bf16 v[60:63], v[166:169], v[202:205], v[60:63]
	v_mfma_f32_16x16x32_bf16 v[56:59], v[174:177], v[202:205], v[56:59]
	v_mfma_f32_16x16x32_bf16 v[44:47], v[166:169], v[210:213], v[44:47]
	v_mfma_f32_16x16x32_bf16 v[40:43], v[174:177], v[210:213], v[40:43]
	v_mfma_f32_16x16x32_bf16 v[28:31], v[166:169], v[218:221], v[28:31]
	v_mfma_f32_16x16x32_bf16 v[24:27], v[174:177], v[218:221], v[24:27]
	v_mfma_f32_16x16x32_bf16 v[12:15], v[166:169], v[226:229], v[12:15]
	v_mfma_f32_16x16x32_bf16 v[8:11], v[174:177], v[226:229], v[8:11]
	s_setprio 0
	s_setprio 1
	v_mfma_f32_16x16x32_bf16 v[52:55], v[178:181], v[198:201], v[52:55]
	v_mfma_f32_16x16x32_bf16 v[48:51], v[186:189], v[198:201], v[48:51]
	v_mfma_f32_16x16x32_bf16 v[36:39], v[178:181], v[206:209], v[36:39]
	v_mfma_f32_16x16x32_bf16 v[32:35], v[186:189], v[206:209], v[32:35]
	v_mfma_f32_16x16x32_bf16 v[20:23], v[178:181], v[214:217], v[20:23]
	v_mfma_f32_16x16x32_bf16 v[16:19], v[186:189], v[214:217], v[16:19]
	v_mfma_f32_16x16x32_bf16 v[4:7], v[178:181], v[222:225], v[4:7]
	v_mfma_f32_16x16x32_bf16 v[0:3], v[186:189], v[222:225], v[0:3]
	v_mfma_f32_16x16x32_bf16 v[52:55], v[182:185], v[202:205], v[52:55]
	v_mfma_f32_16x16x32_bf16 v[48:51], v[194:197], v[202:205], v[48:51]
	v_mfma_f32_16x16x32_bf16 v[36:39], v[182:185], v[210:213], v[36:39]
	v_mfma_f32_16x16x32_bf16 v[32:35], v[194:197], v[210:213], v[32:35]
	v_mfma_f32_16x16x32_bf16 v[20:23], v[182:185], v[218:221], v[20:23]
	v_mfma_f32_16x16x32_bf16 v[16:19], v[194:197], v[218:221], v[16:19]
	v_mfma_f32_16x16x32_bf16 v[4:7], v[182:185], v[226:229], v[4:7]
	v_mfma_f32_16x16x32_bf16 v[0:3], v[194:197], v[226:229], v[0:3]
	s_setprio 0
	s_barrier
	s_add_i32 s33, 0, 0x18000
	v_add_u32_e32 v165, s33, v159
	s_add_i32 s54, 0, 0x1c000
	ds_read_b128 v[152:155], v165
	ds_read_b128 v[166:169], v165 offset:1024
	ds_read_b128 v[170:173], v165 offset:2048
	ds_read_b128 v[174:177], v165 offset:3072
	v_add_u32_e32 v165, s54, v159
	ds_read_b128 v[178:181], v165
	ds_read_b128 v[182:185], v165 offset:1024
	ds_read_b128 v[186:189], v165 offset:2048
	ds_read_b128 v[194:197], v165 offset:3072
	s_add_u32 s28, s36, 0x160000
	s_addc_u32 s29, s37, 0
	s_mov_b32 m0, s49
	v_lshl_add_u64 v[234:235], s[28:29], 0, v[128:129]
	ds_read_b128 v[198:201], v163 offset:32768
	ds_read_b128 v[202:205], v163 offset:33792
	ds_read_b128 v[206:209], v163 offset:34816
	ds_read_b128 v[210:213], v163 offset:35840
	ds_read_b128 v[214:217], v163 offset:36864
	ds_read_b128 v[218:221], v163 offset:37888
	ds_read_b128 v[222:225], v163 offset:38912
	ds_read_b128 v[226:229], v163 offset:39936
	global_load_lds_dwordx4 v[234:235], off
	v_lshl_add_u64 v[234:235], s[28:29], 0, v[132:133]
	s_mov_b32 m0, s50
	s_nop 0
	global_load_lds_dwordx4 v[234:235], off
	s_waitcnt vmcnt(8)
	s_waitcnt lgkmcnt(0)
	s_barrier
	s_setprio 1
	s_waitcnt lgkmcnt(0)
	v_mfma_f32_16x16x32_bf16 v[124:127], v[152:155], v[198:201], v[124:127]
	v_mfma_f32_16x16x32_bf16 v[120:123], v[170:173], v[198:201], v[120:123]
	v_mfma_f32_16x16x32_bf16 v[108:111], v[152:155], v[206:209], v[108:111]
	v_mfma_f32_16x16x32_bf16 v[104:107], v[170:173], v[206:209], v[104:107]
	v_mfma_f32_16x16x32_bf16 v[92:95], v[152:155], v[214:217], v[92:95]
	v_mfma_f32_16x16x32_bf16 v[88:91], v[170:173], v[214:217], v[88:91]
	v_mfma_f32_16x16x32_bf16 v[76:79], v[152:155], v[222:225], v[76:79]
	v_mfma_f32_16x16x32_bf16 v[72:75], v[170:173], v[222:225], v[72:75]
	v_mfma_f32_16x16x32_bf16 v[124:127], v[166:169], v[202:205], v[124:127]
	v_mfma_f32_16x16x32_bf16 v[120:123], v[174:177], v[202:205], v[120:123]
	v_mfma_f32_16x16x32_bf16 v[108:111], v[166:169], v[210:213], v[108:111]
	v_mfma_f32_16x16x32_bf16 v[104:107], v[174:177], v[210:213], v[104:107]
	v_mfma_f32_16x16x32_bf16 v[92:95], v[166:169], v[218:221], v[92:95]
	v_mfma_f32_16x16x32_bf16 v[88:91], v[174:177], v[218:221], v[88:91]
	v_mfma_f32_16x16x32_bf16 v[76:79], v[166:169], v[226:229], v[76:79]
	v_mfma_f32_16x16x32_bf16 v[72:75], v[174:177], v[226:229], v[72:75]
	s_setprio 0
	s_setprio 1
	v_mfma_f32_16x16x32_bf16 v[116:119], v[178:181], v[198:201], v[116:119]
	v_mfma_f32_16x16x32_bf16 v[112:115], v[186:189], v[198:201], v[112:115]
	v_mfma_f32_16x16x32_bf16 v[100:103], v[178:181], v[206:209], v[100:103]
	v_mfma_f32_16x16x32_bf16 v[96:99], v[186:189], v[206:209], v[96:99]
	v_mfma_f32_16x16x32_bf16 v[84:87], v[178:181], v[214:217], v[84:87]
	v_mfma_f32_16x16x32_bf16 v[80:83], v[186:189], v[214:217], v[80:83]
	v_mfma_f32_16x16x32_bf16 v[68:71], v[178:181], v[222:225], v[68:71]
	v_mfma_f32_16x16x32_bf16 v[64:67], v[186:189], v[222:225], v[64:67]
	v_mfma_f32_16x16x32_bf16 v[116:119], v[182:185], v[202:205], v[116:119]
	v_mfma_f32_16x16x32_bf16 v[112:115], v[194:197], v[202:205], v[112:115]
	v_mfma_f32_16x16x32_bf16 v[100:103], v[182:185], v[210:213], v[100:103]
	v_mfma_f32_16x16x32_bf16 v[96:99], v[194:197], v[210:213], v[96:99]
	v_mfma_f32_16x16x32_bf16 v[84:87], v[182:185], v[218:221], v[84:87]
	v_mfma_f32_16x16x32_bf16 v[80:83], v[194:197], v[218:221], v[80:83]
	v_mfma_f32_16x16x32_bf16 v[68:71], v[182:185], v[226:229], v[68:71]
	v_mfma_f32_16x16x32_bf16 v[64:67], v[194:197], v[226:229], v[64:67]
	s_setprio 0
	s_barrier
	s_add_i32 s28, s33, s42
	v_lshl_add_u64 v[156:157], v[156:157], 0, s[22:23]
	s_mov_b32 m0, s28
	ds_read_b128 v[198:201], v163 offset:49152
	ds_read_b128 v[202:205], v163 offset:50176
	ds_read_b128 v[206:209], v163 offset:51200
	ds_read_b128 v[210:213], v163 offset:52224
	ds_read_b128 v[214:217], v163 offset:53248
	ds_read_b128 v[218:221], v163 offset:54272
	ds_read_b128 v[222:225], v163 offset:55296
	ds_read_b128 v[226:229], v163 offset:56320
	global_load_lds_dwordx4 v[156:157], off
	s_add_i32 m0, s28, 0x2000
	s_add_u32 s28, s34, 0x160080
	v_lshl_add_u64 v[156:157], v[190:191], 0, s[22:23]
	s_addc_u32 s29, s35, 0
	s_add_i32 s33, s54, s42
	global_load_lds_dwordx4 v[156:157], off
	v_lshl_add_u64 v[156:157], s[28:29], 0, v[130:131]
	s_mov_b32 m0, s33
	s_nop 0
	global_load_lds_dwordx4 v[156:157], off
	v_lshl_add_u64 v[156:157], s[28:29], 0, v[134:135]
	s_add_i32 m0, s33, 0x2000
	s_nop 0
	global_load_lds_dwordx4 v[156:157], off
	v_lshl_add_u64 v[156:157], v[230:231], 0, s[22:23]
	s_mov_b32 m0, s58
	s_nop 0
	global_load_lds_dwordx4 v[156:157], off
	v_lshl_add_u64 v[156:157], v[232:233], 0, s[22:23]
	s_mov_b32 m0, s59
	s_nop 0
	global_load_lds_dwordx4 v[156:157], off
	s_waitcnt vmcnt(8)
	s_waitcnt lgkmcnt(0)
	s_barrier
	s_setprio 1
	s_waitcnt lgkmcnt(0)
	v_mfma_f32_16x16x32_bf16 v[60:63], v[152:155], v[198:201], v[60:63]
	v_mfma_f32_16x16x32_bf16 v[56:59], v[170:173], v[198:201], v[56:59]
	v_mfma_f32_16x16x32_bf16 v[44:47], v[152:155], v[206:209], v[44:47]
	v_mfma_f32_16x16x32_bf16 v[40:43], v[170:173], v[206:209], v[40:43]
	v_mfma_f32_16x16x32_bf16 v[28:31], v[152:155], v[214:217], v[28:31]
	v_mfma_f32_16x16x32_bf16 v[24:27], v[170:173], v[214:217], v[24:27]
	v_mfma_f32_16x16x32_bf16 v[12:15], v[152:155], v[222:225], v[12:15]
	v_mfma_f32_16x16x32_bf16 v[8:11], v[170:173], v[222:225], v[8:11]
	v_mfma_f32_16x16x32_bf16 v[60:63], v[166:169], v[202:205], v[60:63]
	v_mfma_f32_16x16x32_bf16 v[56:59], v[174:177], v[202:205], v[56:59]
	v_mfma_f32_16x16x32_bf16 v[44:47], v[166:169], v[210:213], v[44:47]
	v_mfma_f32_16x16x32_bf16 v[40:43], v[174:177], v[210:213], v[40:43]
	v_mfma_f32_16x16x32_bf16 v[28:31], v[166:169], v[218:221], v[28:31]
	v_mfma_f32_16x16x32_bf16 v[24:27], v[174:177], v[218:221], v[24:27]
	v_mfma_f32_16x16x32_bf16 v[12:15], v[166:169], v[226:229], v[12:15]
	v_mfma_f32_16x16x32_bf16 v[8:11], v[174:177], v[226:229], v[8:11]
	s_setprio 0
	s_setprio 1
	v_mfma_f32_16x16x32_bf16 v[52:55], v[178:181], v[198:201], v[52:55]
	v_mfma_f32_16x16x32_bf16 v[48:51], v[186:189], v[198:201], v[48:51]
	v_mfma_f32_16x16x32_bf16 v[36:39], v[178:181], v[206:209], v[36:39]
	v_mfma_f32_16x16x32_bf16 v[32:35], v[186:189], v[206:209], v[32:35]
	v_mfma_f32_16x16x32_bf16 v[20:23], v[178:181], v[214:217], v[20:23]
	v_mfma_f32_16x16x32_bf16 v[16:19], v[186:189], v[214:217], v[16:19]
	v_mfma_f32_16x16x32_bf16 v[4:7], v[178:181], v[222:225], v[4:7]
	v_mfma_f32_16x16x32_bf16 v[0:3], v[186:189], v[222:225], v[0:3]
	v_mfma_f32_16x16x32_bf16 v[52:55], v[182:185], v[202:205], v[52:55]
	v_mfma_f32_16x16x32_bf16 v[48:51], v[194:197], v[202:205], v[48:51]
	v_mfma_f32_16x16x32_bf16 v[36:39], v[182:185], v[210:213], v[36:39]
	v_mfma_f32_16x16x32_bf16 v[32:35], v[194:197], v[210:213], v[32:35]
	v_mfma_f32_16x16x32_bf16 v[20:23], v[182:185], v[218:221], v[20:23]
	v_mfma_f32_16x16x32_bf16 v[16:19], v[194:197], v[218:221], v[16:19]
	v_mfma_f32_16x16x32_bf16 v[4:7], v[182:185], v[226:229], v[4:7]
	v_mfma_f32_16x16x32_bf16 v[0:3], v[194:197], v[226:229], v[0:3]
	s_setprio 0
	s_barrier
	s_add_i32 s68, s68, 2
	s_add_u32 s66, s66, 0x100
	s_addc_u32 s67, s67, 0
	s_cmpk_gt_u32 s68, 0x55
	s_mov_b64 s[28:29], s[30:31]
	s_cbranch_scc0 .LBB0_1187
	v_lshl_add_u32 v156, s64, 8, v158
	v_lshl_or_b32 v154, s65, 8, v160
	v_ashrrev_i32_e32 v157, 31, v156
	v_ashrrev_i32_e32 v155, 31, v154
	v_lshlrev_b64 v[152:153], 11, v[156:157]
	v_lshl_add_u64 v[152:153], v[152:153], 0, v[154:155]
	v_lshlrev_b64 v[170:171], 1, v[152:153]
	v_lshl_add_u64 v[172:173], s[16:17], 0, v[170:171]
	global_load_dwordx4 v[180:183], v[172:173], off
	global_load_dwordx4 v[184:187], v[172:173], off offset:256
	v_add_co_u32_e32 v252, vcc, 0x10000, v172
	s_nop 1
	v_addc_co_u32_e32 v253, vcc, 0, v173, vcc
	global_load_dwordx4 v[188:191], v[252:253], off
	global_load_dwordx4 v[194:197], v[252:253], off offset:256
	v_add_co_u32_e32 v254, vcc, 0x20000, v172
	s_nop 1
	v_addc_co_u32_e32 v255, vcc, 0, v173, vcc
	global_load_dwordx4 v[198:201], v[254:255], off
	global_load_dwordx4 v[202:205], v[254:255], off offset:256
	v_add_co_u32_e32 v252, vcc, 0x30000, v172
	s_nop 1
	v_addc_co_u32_e32 v253, vcc, 0, v173, vcc
	global_load_dwordx4 v[206:209], v[252:253], off
	global_load_dwordx4 v[210:213], v[252:253], off offset:256
	v_add_co_u32_e32 v254, vcc, 0x80000, v172
	s_nop 1
	v_addc_co_u32_e32 v255, vcc, 0, v173, vcc
	global_load_dwordx4 v[214:217], v[254:255], off
	global_load_dwordx4 v[218:221], v[254:255], off offset:256
	v_add_co_u32_e32 v252, vcc, 0x90000, v172
	s_nop 1
	v_addc_co_u32_e32 v253, vcc, 0, v173, vcc
	global_load_dwordx4 v[222:225], v[252:253], off
	global_load_dwordx4 v[226:229], v[252:253], off offset:256
	v_add_co_u32_e32 v254, vcc, 0xa0000, v172
	s_nop 1
	v_addc_co_u32_e32 v255, vcc, 0, v173, vcc
	global_load_dwordx4 v[230:233], v[254:255], off
	global_load_dwordx4 v[234:237], v[254:255], off offset:256
	v_add_co_u32_e32 v252, vcc, 0xb0000, v172
	s_nop 1
	v_addc_co_u32_e32 v253, vcc, 0, v173, vcc
	global_load_dwordx4 v[238:241], v[252:253], off
	global_load_dwordx4 v[242:245], v[252:253], off offset:256
	s_and_b64 vcc, exec, s[24:25]
	s_cbranch_vccz .LBB0_1190
	s_barrier
.LBB0_1190:
	s_waitcnt vmcnt(15)
	v_mov_b32_e32 v166, v180
	v_mov_b32_e32 v167, v181
	v_mov_b32_e32 v168, v182
	v_mov_b32_e32 v169, v183
	v_xor_b32_e32 v165, 32, v164
	v_lshlrev_b32_e32 v174, 16, v166
	v_and_b32_e32 v175, 0xffff0000, v166
	v_lshlrev_b32_e32 v166, 16, v167
	v_and_b32_e32 v167, 0xffff0000, v167
	v_lshlrev_b32_e32 v176, 16, v168
	v_and_b32_e32 v177, 0xffff0000, v168
	v_lshlrev_b32_e32 v168, 16, v169
	v_and_b32_e32 v169, 0xffff0000, v169
	v_pk_add_f32 v[126:127], v[126:127], v[166:167]
	v_pk_add_f32 v[174:175], v[124:125], v[174:175]
	v_pk_add_f32 v[178:179], v[122:123], v[168:169]
	v_pk_add_f32 v[176:177], v[120:121], v[176:177]
	v_cvt_pk_bf16_f32 v122, v174, v175
	v_cvt_pk_bf16_f32 v123, v126, v127
	v_and_b32_e32 v121, 64, v164
	v_cvt_pk_bf16_f32 v124, v176, v177
	v_cvt_pk_bf16_f32 v125, v178, v179
	s_waitcnt vmcnt(14)
	v_mov_b32_e32 v166, v184
	v_mov_b32_e32 v167, v185
	v_mov_b32_e32 v168, v186
	v_mov_b32_e32 v169, v187
	v_xor_b32_e32 v120, 16, v164
	v_add_u32_e32 v121, 64, v121
	v_cmp_lt_i32_e32 vcc, v120, v121
	v_mul_f32_e32 v127, v127, v127
	v_mul_f32_e32 v172, v177, v177
	v_cndmask_b32_e32 v120, v164, v120, vcc
	v_cmp_lt_i32_e32 vcc, v165, v121
	v_fmac_f32_e32 v127, v126, v126
	v_mul_f32_e32 v173, v179, v179
	v_cndmask_b32_e32 v121, v164, v165, vcc
	v_mul_f32_e32 v165, v175, v175
	v_fmac_f32_e32 v165, v174, v174
	v_fmac_f32_e32 v172, v176, v176
	v_add_f32_e32 v126, v165, v127
	v_fmac_f32_e32 v173, v178, v178
	v_add_f32_e32 v126, v172, v126
	v_add_f32_e32 v165, v173, v126
	v_lshlrev_b32_e32 v120, 2, v120
	v_lshlrev_b32_e32 v126, 16, v166
	v_and_b32_e32 v127, 0xffff0000, v166
	v_lshlrev_b32_e32 v166, 16, v167
	v_and_b32_e32 v167, 0xffff0000, v167
	v_lshlrev_b32_e32 v172, 16, v168
	v_and_b32_e32 v173, 0xffff0000, v168
	v_lshlrev_b32_e32 v168, 16, v169
	v_and_b32_e32 v169, 0xffff0000, v169
	v_pk_add_f32 v[118:119], v[118:119], v[166:167]
	v_pk_add_f32 v[116:117], v[116:117], v[126:127]
	v_pk_add_f32 v[126:127], v[114:115], v[168:169]
	v_pk_add_f32 v[112:113], v[112:113], v[172:173]
	v_mul_f32_e32 v114, v117, v117
	v_mul_f32_e32 v115, v119, v119
	v_mul_f32_e32 v166, v113, v113
	v_fmac_f32_e32 v114, v116, v116
	v_fmac_f32_e32 v115, v118, v118
	v_mul_f32_e32 v167, v127, v127
	v_fmac_f32_e32 v166, v112, v112
	v_add_f32_e32 v114, v114, v115
	v_fmac_f32_e32 v167, v126, v126
	v_add_f32_e32 v114, v166, v114
	v_add_f32_e32 v114, v167, v114
	v_add_f32_e32 v114, v165, v114
	ds_bpermute_b32 v115, v120, v114
	v_lshl_add_u64 v[166:167], s[18:19], 0, v[170:171]
	global_store_dwordx4 v[166:167], v[122:125], off
	s_waitcnt lgkmcnt(0)
	v_add_f32_e32 v115, v114, v115
	v_lshlrev_b32_e32 v114, 2, v121
	v_cvt_pk_bf16_f32 v122, v116, v117
	ds_bpermute_b32 v116, v114, v115
	v_cvt_pk_bf16_f32 v123, v118, v119
	v_cvt_pk_bf16_f32 v124, v112, v113
	v_lshl_add_u64 v[112:113], v[156:157], 2, s[20:21]
	v_cvt_pk_bf16_f32 v125, v126, v127
	global_store_dwordx4 v[166:167], v[122:125], off offset:256
	s_and_saveexec_b64 s[28:29], s[6:7]
	s_cbranch_execz .LBB0_1192
	s_waitcnt lgkmcnt(0)
	v_add_f32_e32 v115, v115, v116
	global_atomic_add_f32 v[112:113], v115, off
.LBB0_1192:
	s_or_b64 exec, exec, s[28:29]
	s_waitcnt lgkmcnt(0)
	v_or_b32_e32 v116, 16, v156
	v_ashrrev_i32_e32 v117, 31, v116
	v_lshlrev_b64 v[116:117], 11, v[116:117]
	v_lshl_add_u64 v[116:117], v[116:117], 0, v[154:155]
	v_lshlrev_b64 v[122:123], 1, v[116:117]
	v_lshl_add_u64 v[124:125], s[16:17], 0, v[122:123]
	s_waitcnt vmcnt(15)
	v_mov_b32_e32 v116, v188
	v_mov_b32_e32 v117, v189
	v_mov_b32_e32 v118, v190
	v_mov_b32_e32 v119, v191
	v_lshlrev_b32_e32 v126, 16, v116
	v_and_b32_e32 v127, 0xffff0000, v116
	v_lshlrev_b32_e32 v116, 16, v117
	v_and_b32_e32 v117, 0xffff0000, v117
	v_lshlrev_b32_e32 v166, 16, v118
	v_and_b32_e32 v167, 0xffff0000, v118
	v_lshlrev_b32_e32 v118, 16, v119
	v_and_b32_e32 v119, 0xffff0000, v119
	v_pk_add_f32 v[116:117], v[110:111], v[116:117]
	v_pk_add_f32 v[126:127], v[108:109], v[126:127]
	v_pk_add_f32 v[118:119], v[106:107], v[118:119]
	v_pk_add_f32 v[166:167], v[104:105], v[166:167]
	v_cvt_pk_bf16_f32 v104, v126, v127
	v_cvt_pk_bf16_f32 v105, v116, v117
	v_mul_f32_e32 v115, v127, v127
	v_cvt_pk_bf16_f32 v106, v166, v167
	v_cvt_pk_bf16_f32 v107, v118, v119
	s_waitcnt vmcnt(14)
	v_mov_b32_e32 v108, v194
	v_mov_b32_e32 v109, v195
	v_mov_b32_e32 v110, v196
	v_mov_b32_e32 v111, v197
	v_mul_f32_e32 v117, v117, v117
	v_mul_f32_e32 v121, v167, v167
	v_fmac_f32_e32 v115, v126, v126
	v_fmac_f32_e32 v117, v116, v116
	v_mul_f32_e32 v119, v119, v119
	v_fmac_f32_e32 v121, v166, v166
	v_add_f32_e32 v115, v115, v117
	v_fmac_f32_e32 v119, v118, v118
	v_add_f32_e32 v115, v121, v115
	v_add_f32_e32 v115, v119, v115
	v_lshlrev_b32_e32 v116, 16, v108
	v_and_b32_e32 v117, 0xffff0000, v108
	v_lshlrev_b32_e32 v108, 16, v109
	v_and_b32_e32 v109, 0xffff0000, v109
	v_lshlrev_b32_e32 v118, 16, v110
	v_and_b32_e32 v119, 0xffff0000, v110
	v_lshlrev_b32_e32 v110, 16, v111
	v_and_b32_e32 v111, 0xffff0000, v111
	v_pk_add_f32 v[102:103], v[102:103], v[108:109]
	v_pk_add_f32 v[100:101], v[100:101], v[116:117]
	v_pk_add_f32 v[108:109], v[98:99], v[110:111]
	v_pk_add_f32 v[110:111], v[96:97], v[118:119]
	v_mul_f32_e32 v96, v101, v101
	v_mul_f32_e32 v97, v103, v103
	v_mul_f32_e32 v98, v111, v111
	v_fmac_f32_e32 v96, v100, v100
	v_fmac_f32_e32 v97, v102, v102
	v_mul_f32_e32 v99, v109, v109
	v_fmac_f32_e32 v98, v110, v110
	v_add_f32_e32 v96, v96, v97
	v_add_f32_e32 v96, v98, v96
	v_fmac_f32_e32 v99, v108, v108
	v_add_f32_e32 v96, v99, v96
	v_add_f32_e32 v96, v115, v96
	ds_bpermute_b32 v97, v120, v96
	v_lshl_add_u64 v[116:117], s[18:19], 0, v[122:123]
	global_store_dwordx4 v[116:117], v[104:107], off
	v_cvt_pk_bf16_f32 v98, v100, v101
	v_cvt_pk_bf16_f32 v99, v102, v103
	s_waitcnt lgkmcnt(0)
	v_add_f32_e32 v96, v96, v97
	ds_bpermute_b32 v97, v114, v96
	v_cvt_pk_bf16_f32 v100, v110, v111
	v_cvt_pk_bf16_f32 v101, v108, v109
	global_store_dwordx4 v[116:117], v[98:101], off offset:256
	s_and_saveexec_b64 s[28:29], s[6:7]
	s_cbranch_execz .LBB0_1194
	s_waitcnt lgkmcnt(0)
	v_add_f32_e32 v96, v96, v97
	global_atomic_add_f32 v[112:113], v96, off offset:64
.LBB0_1194:
	s_or_b64 exec, exec, s[28:29]
	v_or_b32_e32 v96, 32, v156
	s_waitcnt lgkmcnt(0)
	v_ashrrev_i32_e32 v97, 31, v96
	v_lshlrev_b64 v[96:97], 11, v[96:97]
	v_lshl_add_u64 v[96:97], v[96:97], 0, v[154:155]
	v_lshlrev_b64 v[100:101], 1, v[96:97]
	v_lshl_add_u64 v[102:103], s[16:17], 0, v[100:101]
	s_waitcnt vmcnt(15)
	v_mov_b32_e32 v96, v198
	v_mov_b32_e32 v97, v199
	v_mov_b32_e32 v98, v200
	v_mov_b32_e32 v99, v201
	v_lshlrev_b32_e32 v104, 16, v96
	v_and_b32_e32 v105, 0xffff0000, v96
	v_lshlrev_b32_e32 v96, 16, v97
	v_and_b32_e32 v97, 0xffff0000, v97
	v_lshlrev_b32_e32 v106, 16, v98
	v_and_b32_e32 v107, 0xffff0000, v98
	v_lshlrev_b32_e32 v98, 16, v99
	v_and_b32_e32 v99, 0xffff0000, v99
	v_pk_add_f32 v[96:97], v[94:95], v[96:97]
	v_pk_add_f32 v[104:105], v[92:93], v[104:105]
	v_pk_add_f32 v[98:99], v[90:91], v[98:99]
	v_pk_add_f32 v[106:107], v[88:89], v[106:107]
	v_cvt_pk_bf16_f32 v88, v104, v105
	v_cvt_pk_bf16_f32 v89, v96, v97
	v_mul_f32_e32 v97, v97, v97
	v_cvt_pk_bf16_f32 v90, v106, v107
	v_cvt_pk_bf16_f32 v91, v98, v99
	s_waitcnt vmcnt(14)
	v_mov_b32_e32 v92, v202
	v_mov_b32_e32 v93, v203
	v_mov_b32_e32 v94, v204
	v_mov_b32_e32 v95, v205
	v_mul_f32_e32 v102, v105, v105
	v_mul_f32_e32 v103, v107, v107
	v_fmac_f32_e32 v102, v104, v104
	v_fmac_f32_e32 v97, v96, v96
	v_mul_f32_e32 v99, v99, v99
	v_fmac_f32_e32 v103, v106, v106
	v_add_f32_e32 v96, v102, v97
	v_fmac_f32_e32 v99, v98, v98
	v_add_f32_e32 v96, v103, v96
	v_add_f32_e32 v102, v99, v96
	v_lshlrev_b32_e32 v96, 16, v92
	v_and_b32_e32 v97, 0xffff0000, v92
	v_lshlrev_b32_e32 v92, 16, v93
	v_and_b32_e32 v93, 0xffff0000, v93
	v_lshlrev_b32_e32 v98, 16, v94
	v_and_b32_e32 v99, 0xffff0000, v94
	v_lshlrev_b32_e32 v94, 16, v95
	v_and_b32_e32 v95, 0xffff0000, v95
	v_pk_add_f32 v[86:87], v[86:87], v[92:93]
	v_pk_add_f32 v[84:85], v[84:85], v[96:97]
	v_pk_add_f32 v[92:93], v[82:83], v[94:95]
	v_pk_add_f32 v[94:95], v[80:81], v[98:99]
	v_mul_f32_e32 v80, v85, v85
	v_mul_f32_e32 v81, v87, v87
	v_mul_f32_e32 v82, v95, v95
	v_fmac_f32_e32 v80, v84, v84
	v_fmac_f32_e32 v81, v86, v86
	v_mul_f32_e32 v83, v93, v93
	v_fmac_f32_e32 v82, v94, v94
	v_add_f32_e32 v80, v80, v81
	v_add_f32_e32 v80, v82, v80
	v_fmac_f32_e32 v83, v92, v92
	v_add_f32_e32 v80, v83, v80
	v_add_f32_e32 v80, v102, v80
	ds_bpermute_b32 v81, v120, v80
	v_lshl_add_u64 v[96:97], s[18:19], 0, v[100:101]
	global_store_dwordx4 v[96:97], v[88:91], off
	v_cvt_pk_bf16_f32 v82, v84, v85
	v_cvt_pk_bf16_f32 v83, v86, v87
	s_waitcnt lgkmcnt(0)
	v_add_f32_e32 v80, v80, v81
	ds_bpermute_b32 v81, v114, v80
	v_cvt_pk_bf16_f32 v84, v94, v95
	v_cvt_pk_bf16_f32 v85, v92, v93
	global_store_dwordx4 v[96:97], v[82:85], off offset:256
	s_and_saveexec_b64 s[28:29], s[6:7]
	s_cbranch_execz .LBB0_1196
	s_waitcnt lgkmcnt(0)
	v_add_f32_e32 v80, v80, v81
	global_atomic_add_f32 v[112:113], v80, off offset:128
.LBB0_1196:
	s_or_b64 exec, exec, s[28:29]
	v_or_b32_e32 v80, 48, v156
	s_waitcnt lgkmcnt(0)
	v_ashrrev_i32_e32 v81, 31, v80
	v_lshlrev_b64 v[80:81], 11, v[80:81]
	v_lshl_add_u64 v[80:81], v[80:81], 0, v[154:155]
	v_lshlrev_b64 v[84:85], 1, v[80:81]
	v_lshl_add_u64 v[86:87], s[16:17], 0, v[84:85]
	s_waitcnt vmcnt(15)
	v_mov_b32_e32 v80, v206
	v_mov_b32_e32 v81, v207
	v_mov_b32_e32 v82, v208
	v_mov_b32_e32 v83, v209
	v_lshlrev_b32_e32 v88, 16, v80
	v_and_b32_e32 v89, 0xffff0000, v80
	v_lshlrev_b32_e32 v80, 16, v81
	v_and_b32_e32 v81, 0xffff0000, v81
	v_lshlrev_b32_e32 v90, 16, v82
	v_and_b32_e32 v91, 0xffff0000, v82
	v_lshlrev_b32_e32 v82, 16, v83
	v_and_b32_e32 v83, 0xffff0000, v83
	v_pk_add_f32 v[80:81], v[78:79], v[80:81]
	v_pk_add_f32 v[88:89], v[76:77], v[88:89]
	v_pk_add_f32 v[82:83], v[74:75], v[82:83]
	v_pk_add_f32 v[90:91], v[72:73], v[90:91]
	v_cvt_pk_bf16_f32 v72, v88, v89
	v_cvt_pk_bf16_f32 v73, v80, v81
	v_mul_f32_e32 v81, v81, v81
	v_cvt_pk_bf16_f32 v74, v90, v91
	v_cvt_pk_bf16_f32 v75, v82, v83
	s_waitcnt vmcnt(14)
	v_mov_b32_e32 v76, v210
	v_mov_b32_e32 v77, v211
	v_mov_b32_e32 v78, v212
	v_mov_b32_e32 v79, v213
	v_mul_f32_e32 v86, v89, v89
	v_mul_f32_e32 v87, v91, v91
	v_fmac_f32_e32 v86, v88, v88
	v_fmac_f32_e32 v81, v80, v80
	v_mul_f32_e32 v83, v83, v83
	v_fmac_f32_e32 v87, v90, v90
	v_add_f32_e32 v80, v86, v81
	v_fmac_f32_e32 v83, v82, v82
	v_add_f32_e32 v80, v87, v80
	v_add_f32_e32 v86, v83, v80
	v_lshlrev_b32_e32 v80, 16, v76
	v_and_b32_e32 v81, 0xffff0000, v76
	v_lshlrev_b32_e32 v76, 16, v77
	v_and_b32_e32 v77, 0xffff0000, v77
	v_lshlrev_b32_e32 v82, 16, v78
	v_and_b32_e32 v83, 0xffff0000, v78
	v_lshlrev_b32_e32 v78, 16, v79
	v_and_b32_e32 v79, 0xffff0000, v79
	v_pk_add_f32 v[70:71], v[70:71], v[76:77]
	v_pk_add_f32 v[68:69], v[68:69], v[80:81]
	v_pk_add_f32 v[76:77], v[66:67], v[78:79]
	v_pk_add_f32 v[78:79], v[64:65], v[82:83]
	v_mul_f32_e32 v64, v69, v69
	v_mul_f32_e32 v65, v71, v71
	v_mul_f32_e32 v66, v79, v79
	v_fmac_f32_e32 v64, v68, v68
	v_fmac_f32_e32 v65, v70, v70
	v_mul_f32_e32 v67, v77, v77
	v_fmac_f32_e32 v66, v78, v78
	v_add_f32_e32 v64, v64, v65
	v_add_f32_e32 v64, v66, v64
	v_fmac_f32_e32 v67, v76, v76
	v_add_f32_e32 v64, v67, v64
	v_add_f32_e32 v64, v86, v64
	ds_bpermute_b32 v65, v120, v64
	v_lshl_add_u64 v[80:81], s[18:19], 0, v[84:85]
	global_store_dwordx4 v[80:81], v[72:75], off
	v_cvt_pk_bf16_f32 v66, v68, v69
	v_cvt_pk_bf16_f32 v67, v70, v71
	s_waitcnt lgkmcnt(0)
	v_add_f32_e32 v64, v64, v65
	ds_bpermute_b32 v65, v114, v64
	v_cvt_pk_bf16_f32 v68, v78, v79
	v_cvt_pk_bf16_f32 v69, v76, v77
	global_store_dwordx4 v[80:81], v[66:69], off offset:256
	s_and_saveexec_b64 s[28:29], s[6:7]
	s_cbranch_execz .LBB0_1198
	s_waitcnt lgkmcnt(0)
	v_add_f32_e32 v64, v64, v65
	global_atomic_add_f32 v[112:113], v64, off offset:192
.LBB0_1198:
	s_or_b64 exec, exec, s[28:29]
	v_lshl_add_u64 v[68:69], v[152:153], 1, v[144:145]
	v_lshl_add_u64 v[70:71], s[16:17], 0, v[68:69]
	s_waitcnt lgkmcnt(0)
	s_waitcnt vmcnt(15)
	v_mov_b32_e32 v64, v214
	v_mov_b32_e32 v65, v215
	v_mov_b32_e32 v66, v216
	v_mov_b32_e32 v67, v217
	v_lshlrev_b32_e32 v72, 16, v64
	v_and_b32_e32 v73, 0xffff0000, v64
	v_lshlrev_b32_e32 v64, 16, v65
	v_and_b32_e32 v65, 0xffff0000, v65
	v_lshlrev_b32_e32 v74, 16, v66
	v_and_b32_e32 v75, 0xffff0000, v66
	v_lshlrev_b32_e32 v66, 16, v67
	v_and_b32_e32 v67, 0xffff0000, v67
	v_pk_add_f32 v[64:65], v[62:63], v[64:65]
	v_pk_add_f32 v[72:73], v[60:61], v[72:73]
	v_pk_add_f32 v[66:67], v[58:59], v[66:67]
	v_pk_add_f32 v[74:75], v[56:57], v[74:75]
	v_cvt_pk_bf16_f32 v56, v72, v73
	v_cvt_pk_bf16_f32 v57, v64, v65
	v_mul_f32_e32 v65, v65, v65
	v_cvt_pk_bf16_f32 v58, v74, v75
	v_cvt_pk_bf16_f32 v59, v66, v67
	s_waitcnt vmcnt(14)
	v_mov_b32_e32 v60, v218
	v_mov_b32_e32 v61, v219
	v_mov_b32_e32 v62, v220
	v_mov_b32_e32 v63, v221
	v_mul_f32_e32 v70, v73, v73
	v_mul_f32_e32 v71, v75, v75
	v_fmac_f32_e32 v70, v72, v72
	v_fmac_f32_e32 v65, v64, v64
	v_mul_f32_e32 v67, v67, v67
	v_fmac_f32_e32 v71, v74, v74
	v_add_f32_e32 v64, v70, v65
	v_fmac_f32_e32 v67, v66, v66
	v_add_f32_e32 v64, v71, v64
	v_add_f32_e32 v70, v67, v64
	v_lshlrev_b32_e32 v64, 16, v60
	v_and_b32_e32 v65, 0xffff0000, v60
	v_lshlrev_b32_e32 v60, 16, v61
	v_and_b32_e32 v61, 0xffff0000, v61
	v_lshlrev_b32_e32 v66, 16, v62
	v_and_b32_e32 v67, 0xffff0000, v62
	v_lshlrev_b32_e32 v62, 16, v63
	v_and_b32_e32 v63, 0xffff0000, v63
	v_pk_add_f32 v[54:55], v[54:55], v[60:61]
	v_pk_add_f32 v[52:53], v[52:53], v[64:65]
	v_pk_add_f32 v[60:61], v[50:51], v[62:63]
	v_pk_add_f32 v[62:63], v[48:49], v[66:67]
	v_mul_f32_e32 v48, v53, v53
	v_mul_f32_e32 v49, v55, v55
	v_mul_f32_e32 v50, v63, v63
	v_fmac_f32_e32 v48, v52, v52
	v_fmac_f32_e32 v49, v54, v54
	v_mul_f32_e32 v51, v61, v61
	v_fmac_f32_e32 v50, v62, v62
	v_add_f32_e32 v48, v48, v49
	v_add_f32_e32 v48, v50, v48
	v_fmac_f32_e32 v51, v60, v60
	v_add_f32_e32 v48, v51, v48
	v_add_f32_e32 v48, v70, v48
	ds_bpermute_b32 v49, v120, v48
	v_lshl_add_u64 v[64:65], s[18:19], 0, v[68:69]
	global_store_dwordx4 v[64:65], v[56:59], off
	v_cvt_pk_bf16_f32 v50, v52, v53
	v_cvt_pk_bf16_f32 v51, v54, v55
	s_waitcnt lgkmcnt(0)
	v_add_f32_e32 v48, v48, v49
	ds_bpermute_b32 v49, v114, v48
	v_cvt_pk_bf16_f32 v52, v62, v63
	v_cvt_pk_bf16_f32 v53, v60, v61
	global_store_dwordx4 v[64:65], v[50:53], off offset:256
	s_and_saveexec_b64 s[28:29], s[6:7]
	s_cbranch_execz .LBB0_1200
	s_waitcnt lgkmcnt(0)
	v_add_f32_e32 v48, v48, v49
	global_atomic_add_f32 v[112:113], v48, off offset:512
.LBB0_1200:
	s_or_b64 exec, exec, s[28:29]
	v_lshl_add_u64 v[52:53], v[152:153], 1, v[146:147]
	v_lshl_add_u64 v[54:55], s[16:17], 0, v[52:53]
	s_waitcnt lgkmcnt(0)
	s_waitcnt vmcnt(15)
	v_mov_b32_e32 v48, v222
	v_mov_b32_e32 v49, v223
	v_mov_b32_e32 v50, v224
	v_mov_b32_e32 v51, v225
	v_lshlrev_b32_e32 v56, 16, v48
	v_and_b32_e32 v57, 0xffff0000, v48
	v_lshlrev_b32_e32 v48, 16, v49
	v_and_b32_e32 v49, 0xffff0000, v49
	v_lshlrev_b32_e32 v58, 16, v50
	v_and_b32_e32 v59, 0xffff0000, v50
	v_lshlrev_b32_e32 v50, 16, v51
	v_and_b32_e32 v51, 0xffff0000, v51
	v_pk_add_f32 v[48:49], v[46:47], v[48:49]
	v_pk_add_f32 v[56:57], v[44:45], v[56:57]
	v_pk_add_f32 v[50:51], v[42:43], v[50:51]
	v_pk_add_f32 v[58:59], v[40:41], v[58:59]
	v_cvt_pk_bf16_f32 v40, v56, v57
	v_cvt_pk_bf16_f32 v41, v48, v49
	v_mul_f32_e32 v49, v49, v49
	v_cvt_pk_bf16_f32 v42, v58, v59
	v_cvt_pk_bf16_f32 v43, v50, v51
	s_waitcnt vmcnt(14)
	v_mov_b32_e32 v44, v226
	v_mov_b32_e32 v45, v227
	v_mov_b32_e32 v46, v228
	v_mov_b32_e32 v47, v229
	v_mul_f32_e32 v54, v57, v57
	v_mul_f32_e32 v55, v59, v59
	v_fmac_f32_e32 v54, v56, v56
	v_fmac_f32_e32 v49, v48, v48
	v_mul_f32_e32 v51, v51, v51
	v_fmac_f32_e32 v55, v58, v58
	v_add_f32_e32 v48, v54, v49
	v_fmac_f32_e32 v51, v50, v50
	v_add_f32_e32 v48, v55, v48
	v_add_f32_e32 v54, v51, v48
	v_lshlrev_b32_e32 v48, 16, v44
	v_and_b32_e32 v49, 0xffff0000, v44
	v_lshlrev_b32_e32 v44, 16, v45
	v_and_b32_e32 v45, 0xffff0000, v45
	v_lshlrev_b32_e32 v50, 16, v46
	v_and_b32_e32 v51, 0xffff0000, v46
	v_lshlrev_b32_e32 v46, 16, v47
	v_and_b32_e32 v47, 0xffff0000, v47
	v_pk_add_f32 v[38:39], v[38:39], v[44:45]
	v_pk_add_f32 v[36:37], v[36:37], v[48:49]
	v_pk_add_f32 v[44:45], v[34:35], v[46:47]
	v_pk_add_f32 v[46:47], v[32:33], v[50:51]
	v_mul_f32_e32 v32, v37, v37
	v_mul_f32_e32 v33, v39, v39
	v_mul_f32_e32 v34, v47, v47
	v_fmac_f32_e32 v32, v36, v36
	v_fmac_f32_e32 v33, v38, v38
	v_mul_f32_e32 v35, v45, v45
	v_fmac_f32_e32 v34, v46, v46
	v_add_f32_e32 v32, v32, v33
	v_add_f32_e32 v32, v34, v32
	v_fmac_f32_e32 v35, v44, v44
	v_add_f32_e32 v32, v35, v32
	v_add_f32_e32 v32, v54, v32
	ds_bpermute_b32 v33, v120, v32
	v_lshl_add_u64 v[48:49], s[18:19], 0, v[52:53]
	global_store_dwordx4 v[48:49], v[40:43], off
	v_cvt_pk_bf16_f32 v34, v36, v37
	v_cvt_pk_bf16_f32 v35, v38, v39
	s_waitcnt lgkmcnt(0)
	v_add_f32_e32 v32, v32, v33
	ds_bpermute_b32 v33, v114, v32
	v_cvt_pk_bf16_f32 v36, v46, v47
	v_cvt_pk_bf16_f32 v37, v44, v45
	global_store_dwordx4 v[48:49], v[34:37], off offset:256
	s_and_saveexec_b64 s[28:29], s[6:7]
	s_cbranch_execz .LBB0_1202
	s_waitcnt lgkmcnt(0)
	v_add_f32_e32 v32, v32, v33
	global_atomic_add_f32 v[112:113], v32, off offset:576
.LBB0_1202:
	s_or_b64 exec, exec, s[28:29]
	v_lshl_add_u64 v[36:37], v[152:153], 1, v[148:149]
	v_lshl_add_u64 v[38:39], s[16:17], 0, v[36:37]
	s_waitcnt lgkmcnt(0)
	s_waitcnt vmcnt(15)
	v_mov_b32_e32 v32, v230
	v_mov_b32_e32 v33, v231
	v_mov_b32_e32 v34, v232
	v_mov_b32_e32 v35, v233
	v_lshlrev_b32_e32 v40, 16, v32
	v_and_b32_e32 v41, 0xffff0000, v32
	v_lshlrev_b32_e32 v32, 16, v33
	v_and_b32_e32 v33, 0xffff0000, v33
	v_lshlrev_b32_e32 v42, 16, v34
	v_and_b32_e32 v43, 0xffff0000, v34
	v_lshlrev_b32_e32 v34, 16, v35
	v_and_b32_e32 v35, 0xffff0000, v35
	v_pk_add_f32 v[32:33], v[30:31], v[32:33]
	v_pk_add_f32 v[40:41], v[28:29], v[40:41]
	v_pk_add_f32 v[34:35], v[26:27], v[34:35]
	v_pk_add_f32 v[42:43], v[24:25], v[42:43]
	v_cvt_pk_bf16_f32 v24, v40, v41
	v_cvt_pk_bf16_f32 v25, v32, v33
	v_mul_f32_e32 v33, v33, v33
	v_cvt_pk_bf16_f32 v26, v42, v43
	v_cvt_pk_bf16_f32 v27, v34, v35
	s_waitcnt vmcnt(14)
	v_mov_b32_e32 v28, v234
	v_mov_b32_e32 v29, v235
	v_mov_b32_e32 v30, v236
	v_mov_b32_e32 v31, v237
	v_mul_f32_e32 v38, v41, v41
	v_mul_f32_e32 v39, v43, v43
	v_fmac_f32_e32 v38, v40, v40
	v_fmac_f32_e32 v33, v32, v32
	v_mul_f32_e32 v35, v35, v35
	v_fmac_f32_e32 v39, v42, v42
	v_add_f32_e32 v32, v38, v33
	v_fmac_f32_e32 v35, v34, v34
	v_add_f32_e32 v32, v39, v32
	v_add_f32_e32 v38, v35, v32
	v_lshlrev_b32_e32 v32, 16, v28
	v_and_b32_e32 v33, 0xffff0000, v28
	v_lshlrev_b32_e32 v28, 16, v29
	v_and_b32_e32 v29, 0xffff0000, v29
	v_lshlrev_b32_e32 v34, 16, v30
	v_and_b32_e32 v35, 0xffff0000, v30
	v_lshlrev_b32_e32 v30, 16, v31
	v_and_b32_e32 v31, 0xffff0000, v31
	v_pk_add_f32 v[22:23], v[22:23], v[28:29]
	v_pk_add_f32 v[20:21], v[20:21], v[32:33]
	v_pk_add_f32 v[28:29], v[18:19], v[30:31]
	v_pk_add_f32 v[30:31], v[16:17], v[34:35]
	v_mul_f32_e32 v16, v21, v21
	v_mul_f32_e32 v17, v23, v23
	v_mul_f32_e32 v18, v31, v31
	v_fmac_f32_e32 v16, v20, v20
	v_fmac_f32_e32 v17, v22, v22
	v_mul_f32_e32 v19, v29, v29
	v_fmac_f32_e32 v18, v30, v30
	v_add_f32_e32 v16, v16, v17
	v_add_f32_e32 v16, v18, v16
	v_fmac_f32_e32 v19, v28, v28
	v_add_f32_e32 v16, v19, v16
	v_add_f32_e32 v16, v38, v16
	ds_bpermute_b32 v17, v120, v16
	v_lshl_add_u64 v[32:33], s[18:19], 0, v[36:37]
	global_store_dwordx4 v[32:33], v[24:27], off
	v_cvt_pk_bf16_f32 v18, v20, v21
	v_cvt_pk_bf16_f32 v19, v22, v23
	s_waitcnt lgkmcnt(0)
	v_add_f32_e32 v16, v16, v17
	ds_bpermute_b32 v17, v114, v16
	v_cvt_pk_bf16_f32 v20, v30, v31
	v_cvt_pk_bf16_f32 v21, v28, v29
	global_store_dwordx4 v[32:33], v[18:21], off offset:256
	s_and_saveexec_b64 s[28:29], s[6:7]
	s_cbranch_execz .LBB0_1204
	s_waitcnt lgkmcnt(0)
	v_add_f32_e32 v16, v16, v17
	global_atomic_add_f32 v[112:113], v16, off offset:640
.LBB0_1204:
	s_or_b64 exec, exec, s[28:29]
	v_lshl_add_u64 v[20:21], v[152:153], 1, v[150:151]
	v_lshl_add_u64 v[22:23], s[16:17], 0, v[20:21]
	s_waitcnt lgkmcnt(0)
	s_waitcnt vmcnt(15)
	v_mov_b32_e32 v16, v238
	v_mov_b32_e32 v17, v239
	v_mov_b32_e32 v18, v240
	v_mov_b32_e32 v19, v241
	v_lshlrev_b32_e32 v24, 16, v16
	v_and_b32_e32 v25, 0xffff0000, v16
	v_lshlrev_b32_e32 v16, 16, v17
	v_and_b32_e32 v17, 0xffff0000, v17
	v_lshlrev_b32_e32 v26, 16, v18
	v_and_b32_e32 v27, 0xffff0000, v18
	v_lshlrev_b32_e32 v18, 16, v19
	v_and_b32_e32 v19, 0xffff0000, v19
	v_pk_add_f32 v[16:17], v[14:15], v[16:17]
	v_pk_add_f32 v[24:25], v[12:13], v[24:25]
	v_pk_add_f32 v[18:19], v[10:11], v[18:19]
	v_pk_add_f32 v[26:27], v[8:9], v[26:27]
	v_cvt_pk_bf16_f32 v8, v24, v25
	v_cvt_pk_bf16_f32 v9, v16, v17
	v_mul_f32_e32 v17, v17, v17
	v_cvt_pk_bf16_f32 v10, v26, v27
	v_cvt_pk_bf16_f32 v11, v18, v19
	s_waitcnt vmcnt(14)
	v_mov_b32_e32 v12, v242
	v_mov_b32_e32 v13, v243
	v_mov_b32_e32 v14, v244
	v_mov_b32_e32 v15, v245
	v_mul_f32_e32 v22, v25, v25
	v_mul_f32_e32 v23, v27, v27
	v_fmac_f32_e32 v22, v24, v24
	v_fmac_f32_e32 v17, v16, v16
	v_mul_f32_e32 v19, v19, v19
	v_fmac_f32_e32 v23, v26, v26
	v_add_f32_e32 v16, v22, v17
	v_fmac_f32_e32 v19, v18, v18
	v_add_f32_e32 v16, v23, v16
	v_add_f32_e32 v22, v19, v16
	v_lshlrev_b32_e32 v16, 16, v12
	v_and_b32_e32 v17, 0xffff0000, v12
	v_lshlrev_b32_e32 v12, 16, v13
	v_and_b32_e32 v13, 0xffff0000, v13
	v_lshlrev_b32_e32 v18, 16, v14
	v_and_b32_e32 v19, 0xffff0000, v14
	v_lshlrev_b32_e32 v14, 16, v15
	v_and_b32_e32 v15, 0xffff0000, v15
	v_pk_add_f32 v[6:7], v[6:7], v[12:13]
	v_pk_add_f32 v[4:5], v[4:5], v[16:17]
	v_pk_add_f32 v[12:13], v[2:3], v[14:15]
	v_pk_add_f32 v[14:15], v[0:1], v[18:19]
	v_mul_f32_e32 v0, v5, v5
	v_mul_f32_e32 v1, v7, v7
	v_mul_f32_e32 v2, v15, v15
	v_fmac_f32_e32 v0, v4, v4
	v_fmac_f32_e32 v1, v6, v6
	v_mul_f32_e32 v3, v13, v13
	v_fmac_f32_e32 v2, v14, v14
	v_add_f32_e32 v0, v0, v1
	v_add_f32_e32 v0, v2, v0
	v_fmac_f32_e32 v3, v12, v12
	v_add_f32_e32 v0, v3, v0
	v_add_f32_e32 v0, v22, v0
	ds_bpermute_b32 v1, v120, v0
	v_lshl_add_u64 v[16:17], s[18:19], 0, v[20:21]
	global_store_dwordx4 v[16:17], v[8:11], off
	v_cvt_pk_bf16_f32 v2, v4, v5
	v_cvt_pk_bf16_f32 v3, v6, v7
	s_waitcnt lgkmcnt(0)
	v_add_f32_e32 v0, v0, v1
	ds_bpermute_b32 v1, v114, v0
	v_cvt_pk_bf16_f32 v4, v14, v15
	v_cvt_pk_bf16_f32 v5, v12, v13
	global_store_dwordx4 v[16:17], v[2:5], off offset:256
	s_and_saveexec_b64 s[28:29], s[6:7]
	s_cbranch_execz .LBB0_1206
	s_waitcnt lgkmcnt(0)
	v_add_f32_e32 v0, v0, v1
	global_atomic_add_f32 v[112:113], v0, off offset:704

.LBB0_1271:
	ds_read_b128 v[144:147], v155
	ds_read_b128 v[148:151], v155 offset:1024
	ds_read_b128 v[160:163], v155 offset:2048
	ds_read_b128 v[164:167], v155 offset:3072
	ds_read_b128 v[168:171], v156
	ds_read_b128 v[172:175], v156 offset:1024
	ds_read_b128 v[176:179], v156 offset:2048
	ds_read_b128 v[180:183], v156 offset:3072
	s_add_u32 s33, s30, 0xfff80080
	s_addc_u32 s34, s31, -1
	s_cmp_eq_u32 s67, 28
	s_cselect_b32 s37, s25, s34
	s_cselect_b32 s36, s63, s33
	s_cselect_b32 s35, s23, s66
	s_cselect_b32 s34, s64, s65
	v_lshl_add_u64 v[218:219], s[30:31], 0, v[136:137]
	s_add_i32 m0, s48, 0xc000
	ds_read_b128 v[184:187], v157
	ds_read_b128 v[188:191], v157 offset:1024
	ds_read_b128 v[194:197], v157 offset:2048
	ds_read_b128 v[198:201], v157 offset:3072
	ds_read_b128 v[202:205], v157 offset:4096
	ds_read_b128 v[206:209], v157 offset:5120
	ds_read_b128 v[210:213], v157 offset:6144
	ds_read_b128 v[214:217], v157 offset:7168
	global_load_lds_dwordx4 v[218:219], off
	v_lshl_add_u64 v[218:219], s[30:31], 0, v[138:139]
	s_add_i32 m0, s48, 0xe000
	s_nop 0
	global_load_lds_dwordx4 v[218:219], off
	s_waitcnt vmcnt(8)
	s_waitcnt lgkmcnt(0)
	s_barrier
	s_setprio 1
	s_waitcnt lgkmcnt(0)
	v_mfma_f32_16x16x32_bf16 v[124:127], v[144:147], v[184:187], v[124:127]
	v_mfma_f32_16x16x32_bf16 v[120:123], v[160:163], v[184:187], v[120:123]
	v_mfma_f32_16x16x32_bf16 v[108:111], v[144:147], v[194:197], v[108:111]
	v_mfma_f32_16x16x32_bf16 v[104:107], v[160:163], v[194:197], v[104:107]
	v_mfma_f32_16x16x32_bf16 v[92:95], v[144:147], v[202:205], v[92:95]
	v_mfma_f32_16x16x32_bf16 v[88:91], v[160:163], v[202:205], v[88:91]
	v_mfma_f32_16x16x32_bf16 v[76:79], v[144:147], v[210:213], v[76:79]
	v_mfma_f32_16x16x32_bf16 v[72:75], v[160:163], v[210:213], v[72:75]
	v_mfma_f32_16x16x32_bf16 v[124:127], v[148:151], v[188:191], v[124:127]
	v_mfma_f32_16x16x32_bf16 v[120:123], v[164:167], v[188:191], v[120:123]
	v_mfma_f32_16x16x32_bf16 v[108:111], v[148:151], v[198:201], v[108:111]
	v_mfma_f32_16x16x32_bf16 v[104:107], v[164:167], v[198:201], v[104:107]
	v_mfma_f32_16x16x32_bf16 v[92:95], v[148:151], v[206:209], v[92:95]
	v_mfma_f32_16x16x32_bf16 v[88:91], v[164:167], v[206:209], v[88:91]
	v_mfma_f32_16x16x32_bf16 v[76:79], v[148:151], v[214:217], v[76:79]
	v_mfma_f32_16x16x32_bf16 v[72:75], v[164:167], v[214:217], v[72:75]
	s_setprio 0
	s_setprio 1
	v_mfma_f32_16x16x32_bf16 v[116:119], v[168:171], v[184:187], v[116:119]
	v_mfma_f32_16x16x32_bf16 v[112:115], v[176:179], v[184:187], v[112:115]
	v_mfma_f32_16x16x32_bf16 v[100:103], v[168:171], v[194:197], v[100:103]
	v_mfma_f32_16x16x32_bf16 v[96:99], v[176:179], v[194:197], v[96:99]
	v_mfma_f32_16x16x32_bf16 v[84:87], v[168:171], v[202:205], v[84:87]
	v_mfma_f32_16x16x32_bf16 v[80:83], v[176:179], v[202:205], v[80:83]
	v_mfma_f32_16x16x32_bf16 v[68:71], v[168:171], v[210:213], v[68:71]
	v_mfma_f32_16x16x32_bf16 v[64:67], v[176:179], v[210:213], v[64:67]
	v_mfma_f32_16x16x32_bf16 v[116:119], v[172:175], v[188:191], v[116:119]
	v_mfma_f32_16x16x32_bf16 v[112:115], v[180:183], v[188:191], v[112:115]
	v_mfma_f32_16x16x32_bf16 v[100:103], v[172:175], v[198:201], v[100:103]
	v_mfma_f32_16x16x32_bf16 v[96:99], v[180:183], v[198:201], v[96:99]
	v_mfma_f32_16x16x32_bf16 v[84:87], v[172:175], v[206:209], v[84:87]
	v_mfma_f32_16x16x32_bf16 v[80:83], v[180:183], v[206:209], v[80:83]
	v_mfma_f32_16x16x32_bf16 v[68:71], v[172:175], v[214:217], v[68:71]
	v_mfma_f32_16x16x32_bf16 v[64:67], v[180:183], v[214:217], v[64:67]
	s_setprio 0
	s_barrier
	s_add_i32 s33, s59, s42
	v_lshl_add_u64 v[218:219], s[34:35], 0, v[132:133]
	s_mov_b32 m0, s33
	ds_read_b128 v[184:187], v157 offset:16384
	ds_read_b128 v[188:191], v157 offset:17408
	ds_read_b128 v[194:197], v157 offset:18432
	ds_read_b128 v[198:201], v157 offset:19456
	ds_read_b128 v[202:205], v157 offset:20480
	ds_read_b128 v[206:209], v157 offset:21504
	ds_read_b128 v[210:213], v157 offset:22528
	ds_read_b128 v[214:217], v157 offset:23552
	global_load_lds_dwordx4 v[218:219], off
	s_add_i32 m0, s33, 0x2000
	s_add_u32 s54, s34, 0x80000
	v_lshl_add_u64 v[220:221], s[34:35], 0, v[128:129]
	s_addc_u32 s55, s35, 0
	s_add_i32 s33, s60, s42
	global_load_lds_dwordx4 v[220:221], off
	v_lshl_add_u64 v[222:223], s[54:55], 0, v[132:133]
	s_mov_b32 m0, s33
	v_lshl_add_u64 v[224:225], s[36:37], 0, v[130:131]
	global_load_lds_dwordx4 v[222:223], off
	v_lshl_add_u64 v[222:223], s[54:55], 0, v[128:129]
	s_add_i32 m0, s33, 0x2000
	s_nop 0
	global_load_lds_dwordx4 v[222:223], off
	v_lshl_add_u64 v[222:223], s[36:37], 0, v[134:135]
	s_mov_b32 m0, s48
	s_nop 0
	global_load_lds_dwordx4 v[222:223], off
	s_mov_b32 m0, s49
	s_nop 0
	global_load_lds_dwordx4 v[224:225], off
	s_waitcnt vmcnt(8)
	s_waitcnt lgkmcnt(0)
	s_barrier
	s_setprio 1
	s_waitcnt lgkmcnt(0)
	v_mfma_f32_16x16x32_bf16 v[60:63], v[144:147], v[184:187], v[60:63]
	v_mfma_f32_16x16x32_bf16 v[56:59], v[160:163], v[184:187], v[56:59]
	v_mfma_f32_16x16x32_bf16 v[44:47], v[144:147], v[194:197], v[44:47]
	v_mfma_f32_16x16x32_bf16 v[40:43], v[160:163], v[194:197], v[40:43]
	v_mfma_f32_16x16x32_bf16 v[28:31], v[144:147], v[202:205], v[28:31]
	v_mfma_f32_16x16x32_bf16 v[24:27], v[160:163], v[202:205], v[24:27]
	v_mfma_f32_16x16x32_bf16 v[12:15], v[144:147], v[210:213], v[12:15]
	v_mfma_f32_16x16x32_bf16 v[8:11], v[160:163], v[210:213], v[8:11]
	v_mfma_f32_16x16x32_bf16 v[60:63], v[148:151], v[188:191], v[60:63]
	v_mfma_f32_16x16x32_bf16 v[56:59], v[164:167], v[188:191], v[56:59]
	v_mfma_f32_16x16x32_bf16 v[44:47], v[148:151], v[198:201], v[44:47]
	v_mfma_f32_16x16x32_bf16 v[40:43], v[164:167], v[198:201], v[40:43]
	v_mfma_f32_16x16x32_bf16 v[28:31], v[148:151], v[206:209], v[28:31]
	v_mfma_f32_16x16x32_bf16 v[24:27], v[164:167], v[206:209], v[24:27]
	v_mfma_f32_16x16x32_bf16 v[12:15], v[148:151], v[214:217], v[12:15]
	v_mfma_f32_16x16x32_bf16 v[8:11], v[164:167], v[214:217], v[8:11]
	s_setprio 0
	s_setprio 1
	v_mfma_f32_16x16x32_bf16 v[52:55], v[168:171], v[184:187], v[52:55]
	v_mfma_f32_16x16x32_bf16 v[48:51], v[176:179], v[184:187], v[48:51]
	v_mfma_f32_16x16x32_bf16 v[36:39], v[168:171], v[194:197], v[36:39]
	v_mfma_f32_16x16x32_bf16 v[32:35], v[176:179], v[194:197], v[32:35]
	v_mfma_f32_16x16x32_bf16 v[20:23], v[168:171], v[202:205], v[20:23]
	v_mfma_f32_16x16x32_bf16 v[16:19], v[176:179], v[202:205], v[16:19]
	v_mfma_f32_16x16x32_bf16 v[4:7], v[168:171], v[210:213], v[4:7]
	v_mfma_f32_16x16x32_bf16 v[0:3], v[176:179], v[210:213], v[0:3]
	v_mfma_f32_16x16x32_bf16 v[52:55], v[172:175], v[188:191], v[52:55]
	v_mfma_f32_16x16x32_bf16 v[48:51], v[180:183], v[188:191], v[48:51]
	v_mfma_f32_16x16x32_bf16 v[36:39], v[172:175], v[198:201], v[36:39]
	v_mfma_f32_16x16x32_bf16 v[32:35], v[180:183], v[198:201], v[32:35]
	v_mfma_f32_16x16x32_bf16 v[20:23], v[172:175], v[206:209], v[20:23]
	v_mfma_f32_16x16x32_bf16 v[16:19], v[180:183], v[206:209], v[16:19]
	v_mfma_f32_16x16x32_bf16 v[4:7], v[172:175], v[214:217], v[4:7]
	v_mfma_f32_16x16x32_bf16 v[0:3], v[180:183], v[214:217], v[0:3]
	s_setprio 0
	s_barrier
	s_add_i32 s33, 0, 0x18000
	s_add_i32 s54, 0, 0x1c000
	v_add_u32_e32 v164, s33, v153
	v_add_u32_e32 v180, s54, v153
	ds_read_b128 v[144:147], v164
	ds_read_b128 v[148:151], v164 offset:1024
	ds_read_b128 v[160:163], v164 offset:2048
	ds_read_b128 v[164:167], v164 offset:3072
	ds_read_b128 v[168:171], v180
	ds_read_b128 v[172:175], v180 offset:1024
	ds_read_b128 v[176:179], v180 offset:2048
	ds_read_b128 v[180:183], v180 offset:3072
	s_add_u32 s36, s36, 0x80000
	s_addc_u32 s37, s37, 0
	s_mov_b32 m0, s50
	v_lshl_add_u64 v[226:227], s[36:37], 0, v[134:135]
	ds_read_b128 v[184:187], v157 offset:32768
	ds_read_b128 v[188:191], v157 offset:33792
	ds_read_b128 v[194:197], v157 offset:34816
	ds_read_b128 v[198:201], v157 offset:35840
	ds_read_b128 v[202:205], v157 offset:36864
	ds_read_b128 v[206:209], v157 offset:37888
	ds_read_b128 v[210:213], v157 offset:38912
	ds_read_b128 v[214:217], v157 offset:39936
	global_load_lds_dwordx4 v[226:227], off
	v_lshl_add_u64 v[226:227], s[36:37], 0, v[130:131]
	s_mov_b32 m0, s51
	s_nop 0
	global_load_lds_dwordx4 v[226:227], off
	s_waitcnt vmcnt(8)
	s_waitcnt lgkmcnt(0)
	s_barrier
	s_setprio 1
	s_waitcnt lgkmcnt(0)
	v_mfma_f32_16x16x32_bf16 v[124:127], v[144:147], v[184:187], v[124:127]
	v_mfma_f32_16x16x32_bf16 v[120:123], v[160:163], v[184:187], v[120:123]
	v_mfma_f32_16x16x32_bf16 v[108:111], v[144:147], v[194:197], v[108:111]
	v_mfma_f32_16x16x32_bf16 v[104:107], v[160:163], v[194:197], v[104:107]
	v_mfma_f32_16x16x32_bf16 v[92:95], v[144:147], v[202:205], v[92:95]
	v_mfma_f32_16x16x32_bf16 v[88:91], v[160:163], v[202:205], v[88:91]
	v_mfma_f32_16x16x32_bf16 v[76:79], v[144:147], v[210:213], v[76:79]
	v_mfma_f32_16x16x32_bf16 v[72:75], v[160:163], v[210:213], v[72:75]
	v_mfma_f32_16x16x32_bf16 v[124:127], v[148:151], v[188:191], v[124:127]
	v_mfma_f32_16x16x32_bf16 v[120:123], v[164:167], v[188:191], v[120:123]
	v_mfma_f32_16x16x32_bf16 v[108:111], v[148:151], v[198:201], v[108:111]
	v_mfma_f32_16x16x32_bf16 v[104:107], v[164:167], v[198:201], v[104:107]
	v_mfma_f32_16x16x32_bf16 v[92:95], v[148:151], v[206:209], v[92:95]
	v_mfma_f32_16x16x32_bf16 v[88:91], v[164:167], v[206:209], v[88:91]
	v_mfma_f32_16x16x32_bf16 v[76:79], v[148:151], v[214:217], v[76:79]
	v_mfma_f32_16x16x32_bf16 v[72:75], v[164:167], v[214:217], v[72:75]
	s_setprio 0
	s_setprio 1
	v_mfma_f32_16x16x32_bf16 v[116:119], v[168:171], v[184:187], v[116:119]
	v_mfma_f32_16x16x32_bf16 v[112:115], v[176:179], v[184:187], v[112:115]
	v_mfma_f32_16x16x32_bf16 v[100:103], v[168:171], v[194:197], v[100:103]
	v_mfma_f32_16x16x32_bf16 v[96:99], v[176:179], v[194:197], v[96:99]
	v_mfma_f32_16x16x32_bf16 v[84:87], v[168:171], v[202:205], v[84:87]
	v_mfma_f32_16x16x32_bf16 v[80:83], v[176:179], v[202:205], v[80:83]
	v_mfma_f32_16x16x32_bf16 v[68:71], v[168:171], v[210:213], v[68:71]
	v_mfma_f32_16x16x32_bf16 v[64:67], v[176:179], v[210:213], v[64:67]
	v_mfma_f32_16x16x32_bf16 v[116:119], v[172:175], v[188:191], v[116:119]
	v_mfma_f32_16x16x32_bf16 v[112:115], v[180:183], v[188:191], v[112:115]
	v_mfma_f32_16x16x32_bf16 v[100:103], v[172:175], v[198:201], v[100:103]
	v_mfma_f32_16x16x32_bf16 v[96:99], v[180:183], v[198:201], v[96:99]
	v_mfma_f32_16x16x32_bf16 v[84:87], v[172:175], v[206:209], v[84:87]
	v_mfma_f32_16x16x32_bf16 v[80:83], v[180:183], v[206:209], v[80:83]
	v_mfma_f32_16x16x32_bf16 v[68:71], v[172:175], v[214:217], v[68:71]
	v_mfma_f32_16x16x32_bf16 v[64:67], v[180:183], v[214:217], v[64:67]
	s_setprio 0
	s_barrier
	s_add_i32 s33, s33, s42
	v_lshl_add_u64 v[218:219], v[218:219], 0, s[18:19]
	s_mov_b32 m0, s33
	ds_read_b128 v[184:187], v157 offset:49152
	ds_read_b128 v[188:191], v157 offset:50176
	ds_read_b128 v[194:197], v157 offset:51200
	ds_read_b128 v[198:201], v157 offset:52224
	ds_read_b128 v[202:205], v157 offset:53248
	ds_read_b128 v[206:209], v157 offset:54272
	ds_read_b128 v[210:213], v157 offset:55296
	ds_read_b128 v[214:217], v157 offset:56320
	global_load_lds_dwordx4 v[218:219], off
	s_add_i32 m0, s33, 0x2000
	s_add_u32 s34, s34, 0x80080
	v_lshl_add_u64 v[218:219], v[220:221], 0, s[18:19]
	s_addc_u32 s35, s35, 0
	s_add_i32 s33, s54, s42
	global_load_lds_dwordx4 v[218:219], off
	v_lshl_add_u64 v[218:219], s[34:35], 0, v[132:133]
	s_mov_b32 m0, s33
	s_nop 0
	global_load_lds_dwordx4 v[218:219], off
	v_lshl_add_u64 v[218:219], s[34:35], 0, v[128:129]
	s_add_i32 m0, s33, 0x2000
	s_nop 0
	global_load_lds_dwordx4 v[218:219], off
	v_lshl_add_u64 v[218:219], v[222:223], 0, s[18:19]
	s_mov_b32 m0, s57
	s_nop 0
	global_load_lds_dwordx4 v[218:219], off
	v_lshl_add_u64 v[218:219], v[224:225], 0, s[18:19]
	s_mov_b32 m0, s58
	s_nop 0
	global_load_lds_dwordx4 v[218:219], off
	s_waitcnt vmcnt(8)
	s_waitcnt lgkmcnt(0)
	s_barrier
	s_setprio 1
	s_waitcnt lgkmcnt(0)
	v_mfma_f32_16x16x32_bf16 v[60:63], v[144:147], v[184:187], v[60:63]
	v_mfma_f32_16x16x32_bf16 v[56:59], v[160:163], v[184:187], v[56:59]
	v_mfma_f32_16x16x32_bf16 v[44:47], v[144:147], v[194:197], v[44:47]
	v_mfma_f32_16x16x32_bf16 v[40:43], v[160:163], v[194:197], v[40:43]
	v_mfma_f32_16x16x32_bf16 v[28:31], v[144:147], v[202:205], v[28:31]
	v_mfma_f32_16x16x32_bf16 v[24:27], v[160:163], v[202:205], v[24:27]
	v_mfma_f32_16x16x32_bf16 v[12:15], v[144:147], v[210:213], v[12:15]
	v_mfma_f32_16x16x32_bf16 v[8:11], v[160:163], v[210:213], v[8:11]
	v_mfma_f32_16x16x32_bf16 v[60:63], v[148:151], v[188:191], v[60:63]
	v_mfma_f32_16x16x32_bf16 v[56:59], v[164:167], v[188:191], v[56:59]
	v_mfma_f32_16x16x32_bf16 v[44:47], v[148:151], v[198:201], v[44:47]
	v_mfma_f32_16x16x32_bf16 v[40:43], v[164:167], v[198:201], v[40:43]
	v_mfma_f32_16x16x32_bf16 v[28:31], v[148:151], v[206:209], v[28:31]
	v_mfma_f32_16x16x32_bf16 v[24:27], v[164:167], v[206:209], v[24:27]
	v_mfma_f32_16x16x32_bf16 v[12:15], v[148:151], v[214:217], v[12:15]
	v_mfma_f32_16x16x32_bf16 v[8:11], v[164:167], v[214:217], v[8:11]
	s_setprio 0
	s_setprio 1
	v_mfma_f32_16x16x32_bf16 v[52:55], v[168:171], v[184:187], v[52:55]
	v_mfma_f32_16x16x32_bf16 v[48:51], v[176:179], v[184:187], v[48:51]
	v_mfma_f32_16x16x32_bf16 v[36:39], v[168:171], v[194:197], v[36:39]
	v_mfma_f32_16x16x32_bf16 v[32:35], v[176:179], v[194:197], v[32:35]
	v_mfma_f32_16x16x32_bf16 v[20:23], v[168:171], v[202:205], v[20:23]
	v_mfma_f32_16x16x32_bf16 v[16:19], v[176:179], v[202:205], v[16:19]
	v_mfma_f32_16x16x32_bf16 v[4:7], v[168:171], v[210:213], v[4:7]
	v_mfma_f32_16x16x32_bf16 v[0:3], v[176:179], v[210:213], v[0:3]
	v_mfma_f32_16x16x32_bf16 v[52:55], v[172:175], v[188:191], v[52:55]
	v_mfma_f32_16x16x32_bf16 v[48:51], v[180:183], v[188:191], v[48:51]
	v_mfma_f32_16x16x32_bf16 v[36:39], v[172:175], v[198:201], v[36:39]
	v_mfma_f32_16x16x32_bf16 v[32:35], v[180:183], v[198:201], v[32:35]
	v_mfma_f32_16x16x32_bf16 v[20:23], v[172:175], v[206:209], v[20:23]
	v_mfma_f32_16x16x32_bf16 v[16:19], v[180:183], v[206:209], v[16:19]
	v_mfma_f32_16x16x32_bf16 v[4:7], v[172:175], v[214:217], v[4:7]
	v_mfma_f32_16x16x32_bf16 v[0:3], v[180:183], v[214:217], v[0:3]
	s_setprio 0
	s_barrier
	s_add_i32 s67, s67, 2
	s_add_u32 s30, s30, 0x100
	s_addc_u32 s31, s31, 0
	s_add_u32 s65, s65, 0x100
	s_addc_u32 s66, s66, 0
	s_cmp_gt_u32 s67, 29
	s_cbranch_scc0 .LBB0_1271
	v_lshl_add_u32 v144, s8, 8, v152
	v_ashrrev_i32_e32 v145, 31, v144
	v_lshl_add_u64 v[150:151], v[144:145], 2, s[16:17]
	global_load_dword v172, v[150:151], off
	global_load_dword v173, v[150:151], off offset:64
	global_load_dword v174, v[150:151], off offset:128
	global_load_dword v175, v[150:151], off offset:192
	global_load_dword v176, v[150:151], off offset:512
	global_load_dword v177, v[150:151], off offset:576
	global_load_dword v178, v[150:151], off offset:640
	global_load_dword v179, v[150:151], off offset:704
	s_and_b64 vcc, exec, s[20:21]
	s_cbranch_vccz .LBB0_1274
	s_barrier
.LBB0_1274:
	s_nop 0
	v_mov_b64_e32 v[146:147], s[12:13]
	v_lshl_or_b32 v148, s9, 8, v154
	v_mad_i64_i32 v[160:161], s[8:9], v144, s61, v[146:147]
	v_or_b32_e32 v162, 16, v144
	v_ashrrev_i32_e32 v149, 31, v148
	v_lshlrev_b64 v[148:149], 1, v[148:149]
	v_lshl_add_u64 v[160:161], v[160:161], 0, v[148:149]
	s_waitcnt vmcnt(7)
	v_mov_b32_e32 v145, v172
	v_fmamk_f32 v145, v145, 0x3a000000, v158
	v_mul_f32_e32 v163, 0x4f800000, v145
	v_cmp_gt_f32_e32 vcc, s62, v145
	s_nop 1
	v_cndmask_b32_e32 v145, v145, v163, vcc
	v_sqrt_f32_e32 v164, v145
	v_ashrrev_i32_e32 v163, 31, v162
	v_add_u32_e32 v165, -1, v164
	v_add_u32_e32 v166, 1, v164
	v_fma_f32 v167, -v165, v164, v145
	v_fma_f32 v168, -v166, v164, v145
	v_cmp_ge_f32_e64 s[8:9], 0, v167
	s_nop 1
	v_cndmask_b32_e64 v164, v164, v165, s[8:9]
	v_cmp_lt_f32_e64 s[8:9], 0, v168
	s_nop 1
	v_cndmask_b32_e64 v164, v164, v166, s[8:9]
	v_mul_f32_e32 v165, 0x37800000, v164
	v_cndmask_b32_e32 v164, v164, v165, vcc
	v_cmp_class_f32_e32 vcc, v145, v159
	s_nop 1
	v_cndmask_b32_e32 v145, v164, v145, vcc
	v_div_scale_f32 v166, s[8:9], v145, v145, 1.0
	v_rcp_f32_e32 v167, v166
	v_lshl_add_u64 v[164:165], v[162:163], 2, s[16:17]
	v_div_scale_f32 v163, vcc, 1.0, v145, 1.0
	v_fma_f32 v168, -v166, v167, 1.0
	v_fmac_f32_e32 v167, v168, v167
	v_mul_f32_e32 v168, v163, v167
	v_fma_f32 v169, -v166, v168, v163
	v_fmac_f32_e32 v168, v169, v167
	v_fma_f32 v163, -v166, v168, v163
	v_div_fmas_f32 v163, v163, v167, v168
	v_div_fixup_f32 v166, v163, v145, 1.0
	v_pk_mul_f32 v[126:127], v[126:127], v[166:167] op_sel_hi:[1,0]
	v_pk_mul_f32 v[124:125], v[124:125], v[166:167] op_sel_hi:[1,0]
	v_pk_mul_f32 v[122:123], v[122:123], v[166:167] op_sel_hi:[1,0]
	v_pk_mul_f32 v[120:121], v[120:121], v[166:167] op_sel_hi:[1,0]
	v_pk_mul_f32 v[118:119], v[118:119], v[166:167] op_sel_hi:[1,0]
	v_pk_mul_f32 v[116:117], v[116:117], v[166:167] op_sel_hi:[1,0]
	v_pk_mul_f32 v[168:169], v[114:115], v[166:167] op_sel_hi:[1,0]
	v_pk_mul_f32 v[166:167], v[112:113], v[166:167] op_sel_hi:[1,0]
	v_cvt_pk_bf16_f32 v112, v124, v125
	v_cvt_pk_bf16_f32 v113, v126, v127
	v_cvt_pk_bf16_f32 v114, v120, v121
	v_cvt_pk_bf16_f32 v115, v122, v123
	global_store_dwordx4 v[160:161], v[112:115], off
	s_nop 1
	v_cvt_pk_bf16_f32 v112, v116, v117
	v_cvt_pk_bf16_f32 v113, v118, v119
	v_cvt_pk_bf16_f32 v114, v166, v167
	v_cvt_pk_bf16_f32 v115, v168, v169
	global_store_dwordx4 v[160:161], v[112:115], off offset:256
	s_nop 0
	s_nop 0
	v_or_b32_e32 v112, 32, v144
	s_waitcnt vmcnt(7)
	v_mov_b32_e32 v113, v173
	v_fmamk_f32 v113, v113, 0x3a000000, v158
	v_mul_f32_e32 v114, 0x4f800000, v113
	v_cmp_gt_f32_e32 vcc, s62, v113
	s_nop 1
	v_cndmask_b32_e32 v116, v113, v114, vcc
	v_sqrt_f32_e32 v117, v116
	v_mad_i64_i32 v[114:115], s[8:9], v162, s61, v[146:147]
	v_ashrrev_i32_e32 v113, 31, v112
	v_add_u32_e32 v118, -1, v117
	v_add_u32_e32 v119, 1, v117
	v_fma_f32 v120, -v118, v117, v116
	v_fma_f32 v121, -v119, v117, v116
	v_cmp_ge_f32_e64 s[8:9], 0, v120
	v_lshl_add_u64 v[114:115], v[114:115], 0, v[148:149]
	s_nop 0
	v_cndmask_b32_e64 v117, v117, v118, s[8:9]
	v_cmp_lt_f32_e64 s[8:9], 0, v121
	s_nop 1
	v_cndmask_b32_e64 v117, v117, v119, s[8:9]
	v_mul_f32_e32 v118, 0x37800000, v117
	v_cndmask_b32_e32 v117, v117, v118, vcc
	v_cmp_class_f32_e32 vcc, v116, v159
	s_nop 1
	v_cndmask_b32_e32 v118, v117, v116, vcc
	v_div_scale_f32 v119, s[8:9], v118, v118, 1.0
	v_rcp_f32_e32 v120, v119
	v_lshl_add_u64 v[116:117], v[112:113], 2, s[16:17]
	v_div_scale_f32 v113, vcc, 1.0, v118, 1.0
	v_fma_f32 v121, -v119, v120, 1.0
	v_fmac_f32_e32 v120, v121, v120
	v_mul_f32_e32 v121, v113, v120
	v_fma_f32 v122, -v119, v121, v113
	v_fmac_f32_e32 v121, v122, v120
	v_fma_f32 v113, -v119, v121, v113
	v_div_fmas_f32 v113, v113, v120, v121
	v_div_fixup_f32 v118, v113, v118, 1.0
	v_pk_mul_f32 v[110:111], v[110:111], v[118:119] op_sel_hi:[1,0]
	v_pk_mul_f32 v[108:109], v[108:109], v[118:119] op_sel_hi:[1,0]
	v_pk_mul_f32 v[106:107], v[106:107], v[118:119] op_sel_hi:[1,0]
	v_pk_mul_f32 v[104:105], v[104:105], v[118:119] op_sel_hi:[1,0]
	v_pk_mul_f32 v[102:103], v[102:103], v[118:119] op_sel_hi:[1,0]
	v_pk_mul_f32 v[100:101], v[100:101], v[118:119] op_sel_hi:[1,0]
	v_pk_mul_f32 v[120:121], v[98:99], v[118:119] op_sel_hi:[1,0]
	v_pk_mul_f32 v[118:119], v[96:97], v[118:119] op_sel_hi:[1,0]
	v_cvt_pk_bf16_f32 v96, v108, v109
	v_cvt_pk_bf16_f32 v97, v110, v111
	v_cvt_pk_bf16_f32 v98, v104, v105
	v_cvt_pk_bf16_f32 v99, v106, v107
	global_store_dwordx4 v[114:115], v[96:99], off
	s_nop 1
	v_cvt_pk_bf16_f32 v96, v100, v101
	v_cvt_pk_bf16_f32 v97, v102, v103
	v_cvt_pk_bf16_f32 v98, v118, v119
	v_cvt_pk_bf16_f32 v99, v120, v121
	global_store_dwordx4 v[114:115], v[96:99], off offset:256
	s_nop 0
	s_nop 0
	v_or_b32_e32 v96, 48, v144
	s_waitcnt vmcnt(7)
	v_mov_b32_e32 v97, v174
	v_fmamk_f32 v97, v97, 0x3a000000, v158
	v_mul_f32_e32 v98, 0x4f800000, v97
	v_cmp_gt_f32_e32 vcc, s62, v97
	s_nop 1
	v_cndmask_b32_e32 v100, v97, v98, vcc
	v_sqrt_f32_e32 v101, v100
	v_mad_i64_i32 v[98:99], s[8:9], v112, s61, v[146:147]
	v_ashrrev_i32_e32 v97, 31, v96
	v_add_u32_e32 v102, -1, v101
	v_add_u32_e32 v103, 1, v101
	v_fma_f32 v104, -v102, v101, v100
	v_fma_f32 v105, -v103, v101, v100
	v_cmp_ge_f32_e64 s[8:9], 0, v104
	v_lshl_add_u64 v[98:99], v[98:99], 0, v[148:149]
	s_nop 0
	v_cndmask_b32_e64 v101, v101, v102, s[8:9]
	v_cmp_lt_f32_e64 s[8:9], 0, v105
	s_nop 1
	v_cndmask_b32_e64 v101, v101, v103, s[8:9]
	v_mul_f32_e32 v102, 0x37800000, v101
	v_cndmask_b32_e32 v101, v101, v102, vcc
	v_cmp_class_f32_e32 vcc, v100, v159
	s_nop 1
	v_cndmask_b32_e32 v102, v101, v100, vcc
	v_div_scale_f32 v103, s[8:9], v102, v102, 1.0
	v_rcp_f32_e32 v104, v103
	v_lshl_add_u64 v[100:101], v[96:97], 2, s[16:17]
	v_div_scale_f32 v97, vcc, 1.0, v102, 1.0
	v_fma_f32 v105, -v103, v104, 1.0
	v_fmac_f32_e32 v104, v105, v104
	v_mul_f32_e32 v105, v97, v104
	v_fma_f32 v106, -v103, v105, v97
	v_fmac_f32_e32 v105, v106, v104
	v_fma_f32 v97, -v103, v105, v97
	v_div_fmas_f32 v97, v97, v104, v105
	v_div_fixup_f32 v102, v97, v102, 1.0
	v_pk_mul_f32 v[94:95], v[94:95], v[102:103] op_sel_hi:[1,0]
	v_pk_mul_f32 v[92:93], v[92:93], v[102:103] op_sel_hi:[1,0]
	v_pk_mul_f32 v[90:91], v[90:91], v[102:103] op_sel_hi:[1,0]
	v_pk_mul_f32 v[88:89], v[88:89], v[102:103] op_sel_hi:[1,0]
	v_pk_mul_f32 v[86:87], v[86:87], v[102:103] op_sel_hi:[1,0]
	v_pk_mul_f32 v[84:85], v[84:85], v[102:103] op_sel_hi:[1,0]
	v_pk_mul_f32 v[104:105], v[82:83], v[102:103] op_sel_hi:[1,0]
	v_pk_mul_f32 v[102:103], v[80:81], v[102:103] op_sel_hi:[1,0]
	v_cvt_pk_bf16_f32 v80, v92, v93
	v_cvt_pk_bf16_f32 v81, v94, v95
	v_cvt_pk_bf16_f32 v82, v88, v89
	v_cvt_pk_bf16_f32 v83, v90, v91
	global_store_dwordx4 v[98:99], v[80:83], off
	s_nop 1
	v_cvt_pk_bf16_f32 v80, v84, v85
	v_cvt_pk_bf16_f32 v81, v86, v87
	v_cvt_pk_bf16_f32 v82, v102, v103
	v_cvt_pk_bf16_f32 v83, v104, v105
	global_store_dwordx4 v[98:99], v[80:83], off offset:256
	s_nop 0
	s_waitcnt vmcnt(7)
	v_mov_b32_e32 v80, v175
	v_fmamk_f32 v80, v80, 0x3a000000, v158
	v_mul_f32_e32 v81, 0x4f800000, v80
	v_cmp_gt_f32_e32 vcc, s62, v80
	s_nop 1
	v_cndmask_b32_e32 v82, v80, v81, vcc
	v_sqrt_f32_e32 v83, v82
	v_mad_i64_i32 v[80:81], s[8:9], v96, s61, v[146:147]
	v_lshl_add_u64 v[80:81], v[80:81], 0, v[148:149]
	v_add_u32_e32 v84, -1, v83
	v_add_u32_e32 v85, 1, v83
	v_fma_f32 v86, -v84, v83, v82
	v_fma_f32 v87, -v85, v83, v82
	v_cmp_ge_f32_e64 s[8:9], 0, v86
	s_nop 1
	v_cndmask_b32_e64 v83, v83, v84, s[8:9]
	v_cmp_lt_f32_e64 s[8:9], 0, v87
	s_nop 1
	v_cndmask_b32_e64 v83, v83, v85, s[8:9]
	v_mul_f32_e32 v84, 0x37800000, v83
	v_cndmask_b32_e32 v83, v83, v84, vcc
	v_cmp_class_f32_e32 vcc, v82, v159
	s_nop 1
	v_cndmask_b32_e32 v82, v83, v82, vcc
	v_div_scale_f32 v83, s[8:9], v82, v82, 1.0
	v_rcp_f32_e32 v84, v83
	v_div_scale_f32 v85, vcc, 1.0, v82, 1.0
	v_fma_f32 v86, -v83, v84, 1.0
	v_fmac_f32_e32 v84, v86, v84
	v_mul_f32_e32 v86, v85, v84
	v_fma_f32 v87, -v83, v86, v85
	v_fmac_f32_e32 v86, v87, v84
	v_fma_f32 v83, -v83, v86, v85
	v_div_fmas_f32 v83, v83, v84, v86
	v_div_fixup_f32 v82, v83, v82, 1.0
	v_pk_mul_f32 v[78:79], v[78:79], v[82:83] op_sel_hi:[1,0]
	v_pk_mul_f32 v[76:77], v[76:77], v[82:83] op_sel_hi:[1,0]
	v_pk_mul_f32 v[74:75], v[74:75], v[82:83] op_sel_hi:[1,0]
	v_pk_mul_f32 v[72:73], v[72:73], v[82:83] op_sel_hi:[1,0]
	v_pk_mul_f32 v[70:71], v[70:71], v[82:83] op_sel_hi:[1,0]
	v_pk_mul_f32 v[68:69], v[68:69], v[82:83] op_sel_hi:[1,0]
	v_pk_mul_f32 v[84:85], v[66:67], v[82:83] op_sel_hi:[1,0]
	v_pk_mul_f32 v[82:83], v[64:65], v[82:83] op_sel_hi:[1,0]
	v_cvt_pk_bf16_f32 v64, v76, v77
	v_cvt_pk_bf16_f32 v65, v78, v79
	v_cvt_pk_bf16_f32 v66, v72, v73
	v_cvt_pk_bf16_f32 v67, v74, v75
	global_store_dwordx4 v[80:81], v[64:67], off
	s_nop 1
	v_cvt_pk_bf16_f32 v64, v68, v69
	v_cvt_pk_bf16_f32 v65, v70, v71
	v_cvt_pk_bf16_f32 v66, v82, v83
	v_cvt_pk_bf16_f32 v67, v84, v85
	global_store_dwordx4 v[80:81], v[64:67], off offset:256
	s_nop 0
	s_waitcnt vmcnt(7)
	v_mov_b32_e32 v64, v176
	v_fmamk_f32 v64, v64, 0x3a000000, v158
	v_mul_f32_e32 v65, 0x4f800000, v64
	v_cmp_gt_f32_e32 vcc, s62, v64
	s_nop 1
	v_cndmask_b32_e32 v66, v64, v65, vcc
	v_sqrt_f32_e32 v67, v66
	v_add_u32_e32 v64, 0x80, v144
	v_mad_i64_i32 v[64:65], s[8:9], v64, s61, v[146:147]
	v_add_u32_e32 v68, -1, v67
	v_add_u32_e32 v69, 1, v67
	v_fma_f32 v70, -v68, v67, v66
	v_fma_f32 v71, -v69, v67, v66
	v_cmp_ge_f32_e64 s[8:9], 0, v70
	v_lshl_add_u64 v[64:65], v[64:65], 0, v[148:149]
	s_nop 0
	v_cndmask_b32_e64 v67, v67, v68, s[8:9]
	v_cmp_lt_f32_e64 s[8:9], 0, v71
	s_nop 1
	v_cndmask_b32_e64 v67, v67, v69, s[8:9]
	v_mul_f32_e32 v68, 0x37800000, v67
	v_cndmask_b32_e32 v67, v67, v68, vcc
	v_cmp_class_f32_e32 vcc, v66, v159
	s_nop 1
	v_cndmask_b32_e32 v66, v67, v66, vcc
	v_div_scale_f32 v67, s[8:9], v66, v66, 1.0
	v_rcp_f32_e32 v68, v67
	v_div_scale_f32 v69, vcc, 1.0, v66, 1.0
	v_fma_f32 v70, -v67, v68, 1.0
	v_fmac_f32_e32 v68, v70, v68
	v_mul_f32_e32 v70, v69, v68
	v_fma_f32 v71, -v67, v70, v69
	v_fmac_f32_e32 v70, v71, v68
	v_fma_f32 v67, -v67, v70, v69
	v_div_fmas_f32 v67, v67, v68, v70
	v_div_fixup_f32 v66, v67, v66, 1.0
	v_pk_mul_f32 v[62:63], v[62:63], v[66:67] op_sel_hi:[1,0]
	v_pk_mul_f32 v[60:61], v[60:61], v[66:67] op_sel_hi:[1,0]
	v_pk_mul_f32 v[58:59], v[58:59], v[66:67] op_sel_hi:[1,0]
	v_pk_mul_f32 v[56:57], v[56:57], v[66:67] op_sel_hi:[1,0]
	v_pk_mul_f32 v[54:55], v[54:55], v[66:67] op_sel_hi:[1,0]
	v_pk_mul_f32 v[52:53], v[52:53], v[66:67] op_sel_hi:[1,0]
	v_pk_mul_f32 v[68:69], v[50:51], v[66:67] op_sel_hi:[1,0]
	v_pk_mul_f32 v[66:67], v[48:49], v[66:67] op_sel_hi:[1,0]
	v_cvt_pk_bf16_f32 v48, v60, v61
	v_cvt_pk_bf16_f32 v49, v62, v63
	v_cvt_pk_bf16_f32 v50, v56, v57
	v_cvt_pk_bf16_f32 v51, v58, v59
	global_store_dwordx4 v[64:65], v[48:51], off
	s_nop 1
	v_cvt_pk_bf16_f32 v48, v52, v53
	v_cvt_pk_bf16_f32 v49, v54, v55
	v_cvt_pk_bf16_f32 v50, v66, v67
	v_cvt_pk_bf16_f32 v51, v68, v69
	global_store_dwordx4 v[64:65], v[48:51], off offset:256
	s_nop 0
	s_waitcnt vmcnt(7)
	v_mov_b32_e32 v48, v177
	v_fmamk_f32 v48, v48, 0x3a000000, v158
	v_mul_f32_e32 v49, 0x4f800000, v48
	v_cmp_gt_f32_e32 vcc, s62, v48
	s_nop 1
	v_cndmask_b32_e32 v50, v48, v49, vcc
	v_sqrt_f32_e32 v51, v50
	v_add_u32_e32 v48, 0x90, v144
	v_mad_i64_i32 v[48:49], s[8:9], v48, s61, v[146:147]
	v_add_u32_e32 v52, -1, v51
	v_add_u32_e32 v53, 1, v51
	v_fma_f32 v54, -v52, v51, v50
	v_fma_f32 v55, -v53, v51, v50
	v_cmp_ge_f32_e64 s[8:9], 0, v54
	v_lshl_add_u64 v[48:49], v[48:49], 0, v[148:149]
	s_nop 0
	v_cndmask_b32_e64 v51, v51, v52, s[8:9]
	v_cmp_lt_f32_e64 s[8:9], 0, v55
	s_nop 1
	v_cndmask_b32_e64 v51, v51, v53, s[8:9]
	v_mul_f32_e32 v52, 0x37800000, v51
	v_cndmask_b32_e32 v51, v51, v52, vcc
	v_cmp_class_f32_e32 vcc, v50, v159
	s_nop 1
	v_cndmask_b32_e32 v50, v51, v50, vcc
	v_div_scale_f32 v51, s[8:9], v50, v50, 1.0
	v_rcp_f32_e32 v52, v51
	v_div_scale_f32 v53, vcc, 1.0, v50, 1.0
	v_fma_f32 v54, -v51, v52, 1.0
	v_fmac_f32_e32 v52, v54, v52
	v_mul_f32_e32 v54, v53, v52
	v_fma_f32 v55, -v51, v54, v53
	v_fmac_f32_e32 v54, v55, v52
	v_fma_f32 v51, -v51, v54, v53
	v_div_fmas_f32 v51, v51, v52, v54
	v_div_fixup_f32 v50, v51, v50, 1.0
	v_pk_mul_f32 v[46:47], v[46:47], v[50:51] op_sel_hi:[1,0]
	v_pk_mul_f32 v[44:45], v[44:45], v[50:51] op_sel_hi:[1,0]
	v_pk_mul_f32 v[42:43], v[42:43], v[50:51] op_sel_hi:[1,0]
	v_pk_mul_f32 v[40:41], v[40:41], v[50:51] op_sel_hi:[1,0]
	v_pk_mul_f32 v[38:39], v[38:39], v[50:51] op_sel_hi:[1,0]
	v_pk_mul_f32 v[36:37], v[36:37], v[50:51] op_sel_hi:[1,0]
	v_pk_mul_f32 v[52:53], v[34:35], v[50:51] op_sel_hi:[1,0]
	v_pk_mul_f32 v[50:51], v[32:33], v[50:51] op_sel_hi:[1,0]
	v_cvt_pk_bf16_f32 v32, v44, v45
	v_cvt_pk_bf16_f32 v33, v46, v47
	v_cvt_pk_bf16_f32 v34, v40, v41
	v_cvt_pk_bf16_f32 v35, v42, v43
	global_store_dwordx4 v[48:49], v[32:35], off
	s_nop 1
	v_cvt_pk_bf16_f32 v32, v36, v37
	v_cvt_pk_bf16_f32 v33, v38, v39
	v_cvt_pk_bf16_f32 v34, v50, v51
	v_cvt_pk_bf16_f32 v35, v52, v53
	global_store_dwordx4 v[48:49], v[32:35], off offset:256
	s_nop 0
	s_waitcnt vmcnt(7)
	v_mov_b32_e32 v32, v178
	v_fmamk_f32 v32, v32, 0x3a000000, v158
	v_mul_f32_e32 v33, 0x4f800000, v32
	v_cmp_gt_f32_e32 vcc, s62, v32
	s_nop 1
	v_cndmask_b32_e32 v34, v32, v33, vcc
	v_sqrt_f32_e32 v35, v34
	v_add_u32_e32 v32, 0xa0, v144
	v_mad_i64_i32 v[32:33], s[8:9], v32, s61, v[146:147]
	v_add_u32_e32 v36, -1, v35
	v_add_u32_e32 v37, 1, v35
	v_fma_f32 v38, -v36, v35, v34
	v_fma_f32 v39, -v37, v35, v34
	v_cmp_ge_f32_e64 s[8:9], 0, v38
	v_lshl_add_u64 v[32:33], v[32:33], 0, v[148:149]
	s_nop 0
	v_cndmask_b32_e64 v35, v35, v36, s[8:9]
	v_cmp_lt_f32_e64 s[8:9], 0, v39
	s_nop 1
	v_cndmask_b32_e64 v35, v35, v37, s[8:9]
	v_mul_f32_e32 v36, 0x37800000, v35
	v_cndmask_b32_e32 v35, v35, v36, vcc
	v_cmp_class_f32_e32 vcc, v34, v159
	s_nop 1
	v_cndmask_b32_e32 v34, v35, v34, vcc
	v_div_scale_f32 v35, s[8:9], v34, v34, 1.0
	v_rcp_f32_e32 v36, v35
	v_div_scale_f32 v37, vcc, 1.0, v34, 1.0
	v_fma_f32 v38, -v35, v36, 1.0
	v_fmac_f32_e32 v36, v38, v36
	v_mul_f32_e32 v38, v37, v36
	v_fma_f32 v39, -v35, v38, v37
	v_fmac_f32_e32 v38, v39, v36
	v_fma_f32 v35, -v35, v38, v37
	v_div_fmas_f32 v35, v35, v36, v38
	v_div_fixup_f32 v34, v35, v34, 1.0
	v_pk_mul_f32 v[30:31], v[30:31], v[34:35] op_sel_hi:[1,0]
	v_pk_mul_f32 v[28:29], v[28:29], v[34:35] op_sel_hi:[1,0]
	v_pk_mul_f32 v[26:27], v[26:27], v[34:35] op_sel_hi:[1,0]
	v_pk_mul_f32 v[24:25], v[24:25], v[34:35] op_sel_hi:[1,0]
	v_pk_mul_f32 v[22:23], v[22:23], v[34:35] op_sel_hi:[1,0]
	v_pk_mul_f32 v[20:21], v[20:21], v[34:35] op_sel_hi:[1,0]
	v_pk_mul_f32 v[36:37], v[18:19], v[34:35] op_sel_hi:[1,0]
	v_pk_mul_f32 v[34:35], v[16:17], v[34:35] op_sel_hi:[1,0]
	v_cvt_pk_bf16_f32 v16, v28, v29
	v_cvt_pk_bf16_f32 v17, v30, v31
	v_cvt_pk_bf16_f32 v18, v24, v25
	v_cvt_pk_bf16_f32 v19, v26, v27
	global_store_dwordx4 v[32:33], v[16:19], off
	s_nop 1
	v_cvt_pk_bf16_f32 v16, v20, v21
	v_cvt_pk_bf16_f32 v17, v22, v23
	v_cvt_pk_bf16_f32 v18, v34, v35
	v_cvt_pk_bf16_f32 v19, v36, v37
	global_store_dwordx4 v[32:33], v[16:19], off offset:256
	s_nop 0
	s_nop 0
	v_add_u32_e32 v17, 0xb0, v144
	s_waitcnt vmcnt(7)
	v_mov_b32_e32 v16, v179
	v_fmamk_f32 v16, v16, 0x3a000000, v158
	v_mul_f32_e32 v18, 0x4f800000, v16
	v_cmp_gt_f32_e32 vcc, s62, v16
	s_nop 1
	v_cndmask_b32_e32 v18, v16, v18, vcc
	v_sqrt_f32_e32 v19, v18
	v_mad_i64_i32 v[16:17], s[8:9], v17, s61, v[146:147]
	v_lshl_add_u64 v[16:17], v[16:17], 0, v[148:149]
	v_add_u32_e32 v20, -1, v19
	v_add_u32_e32 v21, 1, v19
	v_fma_f32 v22, -v20, v19, v18
	v_fma_f32 v23, -v21, v19, v18
	v_cmp_ge_f32_e64 s[8:9], 0, v22
	s_nop 1
	v_cndmask_b32_e64 v19, v19, v20, s[8:9]
	v_cmp_lt_f32_e64 s[8:9], 0, v23
	s_nop 1
	v_cndmask_b32_e64 v19, v19, v21, s[8:9]
	v_mul_f32_e32 v20, 0x37800000, v19
	v_cndmask_b32_e32 v19, v19, v20, vcc
	v_cmp_class_f32_e32 vcc, v18, v159
	s_nop 1
	v_cndmask_b32_e32 v18, v19, v18, vcc
	v_div_scale_f32 v19, s[8:9], v18, v18, 1.0
	v_rcp_f32_e32 v20, v19
	v_div_scale_f32 v21, vcc, 1.0, v18, 1.0
	v_fma_f32 v22, -v19, v20, 1.0
	v_fmac_f32_e32 v20, v22, v20
	v_mul_f32_e32 v22, v21, v20
	v_fma_f32 v23, -v19, v22, v21
	v_fmac_f32_e32 v22, v23, v20
	v_fma_f32 v19, -v19, v22, v21
	v_div_fmas_f32 v19, v19, v20, v22
	v_div_fixup_f32 v18, v19, v18, 1.0
	s_andn2_b64 vcc, exec, s[6:7]
	v_pk_mul_f32 v[14:15], v[14:15], v[18:19] op_sel_hi:[1,0]
	v_pk_mul_f32 v[12:13], v[12:13], v[18:19] op_sel_hi:[1,0]
	v_pk_mul_f32 v[10:11], v[10:11], v[18:19] op_sel_hi:[1,0]
	v_pk_mul_f32 v[8:9], v[8:9], v[18:19] op_sel_hi:[1,0]
	v_pk_mul_f32 v[6:7], v[6:7], v[18:19] op_sel_hi:[1,0]
	v_pk_mul_f32 v[4:5], v[4:5], v[18:19] op_sel_hi:[1,0]
	v_pk_mul_f32 v[20:21], v[2:3], v[18:19] op_sel_hi:[1,0]
	v_pk_mul_f32 v[18:19], v[0:1], v[18:19] op_sel_hi:[1,0]
	v_cvt_pk_bf16_f32 v0, v12, v13
	v_cvt_pk_bf16_f32 v1, v14, v15
	v_cvt_pk_bf16_f32 v2, v8, v9
	v_cvt_pk_bf16_f32 v3, v10, v11
	s_mov_b64 s[6:7], -1
	global_store_dwordx4 v[16:17], v[0:3], off
	s_nop 1
	v_cvt_pk_bf16_f32 v0, v4, v5
	v_cvt_pk_bf16_f32 v1, v6, v7
	v_cvt_pk_bf16_f32 v2, v18, v19
	v_cvt_pk_bf16_f32 v3, v20, v21
	global_store_dwordx4 v[16:17], v[0:3], off offset:256
	s_cbranch_vccnz .LBB0_1267
	s_andn2_b64 vcc, exec, s[10:11]
	s_cbranch_vccnz .LBB0_1266
	s_barrier
	s_branch .LBB0_1266

.LBB0_1420:
	ds_read_b128 v[152:155], v161
	ds_read_b128 v[166:169], v161 offset:1024
	ds_read_b128 v[170:173], v161 offset:2048
	ds_read_b128 v[174:177], v161 offset:3072
	ds_read_b128 v[178:181], v162
	ds_read_b128 v[182:185], v162 offset:1024
	ds_read_b128 v[186:189], v162 offset:2048
	ds_read_b128 v[194:197], v162 offset:3072
	s_add_u32 s33, s38, 0xfff80080
	s_addc_u32 s40, s39, -1
	s_cmp_eq_u32 s68, 28
	s_cselect_b32 s43, s27, s40
	s_cselect_b32 s42, s35, s33
	s_cselect_b32 s41, s25, s67
	s_cselect_b32 s40, s65, s66
	v_lshl_add_u64 v[156:157], s[38:39], 0, v[136:137]
	s_add_i32 m0, s37, 0xc000
	ds_read_b128 v[198:201], v163
	ds_read_b128 v[202:205], v163 offset:1024
	ds_read_b128 v[206:209], v163 offset:2048
	ds_read_b128 v[210:213], v163 offset:3072
	ds_read_b128 v[214:217], v163 offset:4096
	ds_read_b128 v[218:221], v163 offset:5120
	ds_read_b128 v[222:225], v163 offset:6144
	ds_read_b128 v[226:229], v163 offset:7168
	global_load_lds_dwordx4 v[156:157], off
	v_lshl_add_u64 v[156:157], s[38:39], 0, v[138:139]
	s_add_i32 m0, s37, 0xe000
	s_nop 0
	global_load_lds_dwordx4 v[156:157], off
	s_waitcnt vmcnt(8)
	s_waitcnt lgkmcnt(0)
	s_barrier
	s_setprio 1
	s_waitcnt lgkmcnt(0)
	v_mfma_f32_16x16x32_bf16 v[124:127], v[152:155], v[198:201], v[124:127]
	v_mfma_f32_16x16x32_bf16 v[120:123], v[170:173], v[198:201], v[120:123]
	v_mfma_f32_16x16x32_bf16 v[108:111], v[152:155], v[206:209], v[108:111]
	v_mfma_f32_16x16x32_bf16 v[104:107], v[170:173], v[206:209], v[104:107]
	v_mfma_f32_16x16x32_bf16 v[92:95], v[152:155], v[214:217], v[92:95]
	v_mfma_f32_16x16x32_bf16 v[88:91], v[170:173], v[214:217], v[88:91]
	v_mfma_f32_16x16x32_bf16 v[76:79], v[152:155], v[222:225], v[76:79]
	v_mfma_f32_16x16x32_bf16 v[72:75], v[170:173], v[222:225], v[72:75]
	v_mfma_f32_16x16x32_bf16 v[124:127], v[166:169], v[202:205], v[124:127]
	v_mfma_f32_16x16x32_bf16 v[120:123], v[174:177], v[202:205], v[120:123]
	v_mfma_f32_16x16x32_bf16 v[108:111], v[166:169], v[210:213], v[108:111]
	v_mfma_f32_16x16x32_bf16 v[104:107], v[174:177], v[210:213], v[104:107]
	v_mfma_f32_16x16x32_bf16 v[92:95], v[166:169], v[218:221], v[92:95]
	v_mfma_f32_16x16x32_bf16 v[88:91], v[174:177], v[218:221], v[88:91]
	v_mfma_f32_16x16x32_bf16 v[76:79], v[166:169], v[226:229], v[76:79]
	v_mfma_f32_16x16x32_bf16 v[72:75], v[174:177], v[226:229], v[72:75]
	s_setprio 0
	s_setprio 1
	v_mfma_f32_16x16x32_bf16 v[116:119], v[178:181], v[198:201], v[116:119]
	v_mfma_f32_16x16x32_bf16 v[112:115], v[186:189], v[198:201], v[112:115]
	v_mfma_f32_16x16x32_bf16 v[100:103], v[178:181], v[206:209], v[100:103]
	v_mfma_f32_16x16x32_bf16 v[96:99], v[186:189], v[206:209], v[96:99]
	v_mfma_f32_16x16x32_bf16 v[84:87], v[178:181], v[214:217], v[84:87]
	v_mfma_f32_16x16x32_bf16 v[80:83], v[186:189], v[214:217], v[80:83]
	v_mfma_f32_16x16x32_bf16 v[68:71], v[178:181], v[222:225], v[68:71]
	v_mfma_f32_16x16x32_bf16 v[64:67], v[186:189], v[222:225], v[64:67]
	v_mfma_f32_16x16x32_bf16 v[116:119], v[182:185], v[202:205], v[116:119]
	v_mfma_f32_16x16x32_bf16 v[112:115], v[194:197], v[202:205], v[112:115]
	v_mfma_f32_16x16x32_bf16 v[100:103], v[182:185], v[210:213], v[100:103]
	v_mfma_f32_16x16x32_bf16 v[96:99], v[194:197], v[210:213], v[96:99]
	v_mfma_f32_16x16x32_bf16 v[84:87], v[182:185], v[218:221], v[84:87]
	v_mfma_f32_16x16x32_bf16 v[80:83], v[194:197], v[218:221], v[80:83]
	v_mfma_f32_16x16x32_bf16 v[68:71], v[182:185], v[226:229], v[68:71]
	v_mfma_f32_16x16x32_bf16 v[64:67], v[194:197], v[226:229], v[64:67]
	s_setprio 0
	s_barrier
	s_add_i32 s33, s63, s56
	v_lshl_add_u64 v[156:157], s[40:41], 0, v[130:131]
	s_mov_b32 m0, s33
	ds_read_b128 v[198:201], v163 offset:16384
	ds_read_b128 v[202:205], v163 offset:17408
	ds_read_b128 v[206:209], v163 offset:18432
	ds_read_b128 v[210:213], v163 offset:19456
	ds_read_b128 v[214:217], v163 offset:20480
	ds_read_b128 v[218:221], v163 offset:21504
	ds_read_b128 v[222:225], v163 offset:22528
	ds_read_b128 v[226:229], v163 offset:23552
	global_load_lds_dwordx4 v[156:157], off
	s_add_i32 m0, s33, 0x2000
	s_add_u32 s54, s40, 0x80000
	v_lshl_add_u64 v[190:191], s[40:41], 0, v[134:135]
	s_addc_u32 s55, s41, 0
	s_add_i32 s33, s64, s56
	global_load_lds_dwordx4 v[190:191], off
	v_lshl_add_u64 v[230:231], s[54:55], 0, v[130:131]
	s_mov_b32 m0, s33
	v_lshl_add_u64 v[232:233], s[42:43], 0, v[132:133]
	global_load_lds_dwordx4 v[230:231], off
	v_lshl_add_u64 v[230:231], s[54:55], 0, v[134:135]
	s_add_i32 m0, s33, 0x2000
	s_nop 0
	global_load_lds_dwordx4 v[230:231], off
	v_lshl_add_u64 v[230:231], s[42:43], 0, v[128:129]
	s_mov_b32 m0, s37
	s_nop 0
	global_load_lds_dwordx4 v[230:231], off
	s_mov_b32 m0, s57
	s_nop 0
	global_load_lds_dwordx4 v[232:233], off
	s_waitcnt vmcnt(8)
	s_waitcnt lgkmcnt(0)
	s_barrier
	s_setprio 1
	s_waitcnt lgkmcnt(0)
	v_mfma_f32_16x16x32_bf16 v[60:63], v[152:155], v[198:201], v[60:63]
	v_mfma_f32_16x16x32_bf16 v[56:59], v[170:173], v[198:201], v[56:59]
	v_mfma_f32_16x16x32_bf16 v[44:47], v[152:155], v[206:209], v[44:47]
	v_mfma_f32_16x16x32_bf16 v[40:43], v[170:173], v[206:209], v[40:43]
	v_mfma_f32_16x16x32_bf16 v[28:31], v[152:155], v[214:217], v[28:31]
	v_mfma_f32_16x16x32_bf16 v[24:27], v[170:173], v[214:217], v[24:27]
	v_mfma_f32_16x16x32_bf16 v[12:15], v[152:155], v[222:225], v[12:15]
	v_mfma_f32_16x16x32_bf16 v[8:11], v[170:173], v[222:225], v[8:11]
	v_mfma_f32_16x16x32_bf16 v[60:63], v[166:169], v[202:205], v[60:63]
	v_mfma_f32_16x16x32_bf16 v[56:59], v[174:177], v[202:205], v[56:59]
	v_mfma_f32_16x16x32_bf16 v[44:47], v[166:169], v[210:213], v[44:47]
	v_mfma_f32_16x16x32_bf16 v[40:43], v[174:177], v[210:213], v[40:43]
	v_mfma_f32_16x16x32_bf16 v[28:31], v[166:169], v[218:221], v[28:31]
	v_mfma_f32_16x16x32_bf16 v[24:27], v[174:177], v[218:221], v[24:27]
	v_mfma_f32_16x16x32_bf16 v[12:15], v[166:169], v[226:229], v[12:15]
	v_mfma_f32_16x16x32_bf16 v[8:11], v[174:177], v[226:229], v[8:11]
	s_setprio 0
	s_setprio 1
	v_mfma_f32_16x16x32_bf16 v[52:55], v[178:181], v[198:201], v[52:55]
	v_mfma_f32_16x16x32_bf16 v[48:51], v[186:189], v[198:201], v[48:51]
	v_mfma_f32_16x16x32_bf16 v[36:39], v[178:181], v[206:209], v[36:39]
	v_mfma_f32_16x16x32_bf16 v[32:35], v[186:189], v[206:209], v[32:35]
	v_mfma_f32_16x16x32_bf16 v[20:23], v[178:181], v[214:217], v[20:23]
	v_mfma_f32_16x16x32_bf16 v[16:19], v[186:189], v[214:217], v[16:19]
	v_mfma_f32_16x16x32_bf16 v[4:7], v[178:181], v[222:225], v[4:7]
	v_mfma_f32_16x16x32_bf16 v[0:3], v[186:189], v[222:225], v[0:3]
	v_mfma_f32_16x16x32_bf16 v[52:55], v[182:185], v[202:205], v[52:55]
	v_mfma_f32_16x16x32_bf16 v[48:51], v[194:197], v[202:205], v[48:51]
	v_mfma_f32_16x16x32_bf16 v[36:39], v[182:185], v[210:213], v[36:39]
	v_mfma_f32_16x16x32_bf16 v[32:35], v[194:197], v[210:213], v[32:35]
	v_mfma_f32_16x16x32_bf16 v[20:23], v[182:185], v[218:221], v[20:23]
	v_mfma_f32_16x16x32_bf16 v[16:19], v[194:197], v[218:221], v[16:19]
	v_mfma_f32_16x16x32_bf16 v[4:7], v[182:185], v[226:229], v[4:7]
	v_mfma_f32_16x16x32_bf16 v[0:3], v[194:197], v[226:229], v[0:3]
	s_setprio 0
	s_barrier
	s_add_i32 s33, 0, 0x18000
	v_add_u32_e32 v165, s33, v159
	s_add_i32 s54, 0, 0x1c000
	ds_read_b128 v[152:155], v165
	ds_read_b128 v[166:169], v165 offset:1024
	ds_read_b128 v[170:173], v165 offset:2048
	ds_read_b128 v[174:177], v165 offset:3072
	v_add_u32_e32 v165, s54, v159
	ds_read_b128 v[178:181], v165
	ds_read_b128 v[182:185], v165 offset:1024
	ds_read_b128 v[186:189], v165 offset:2048
	ds_read_b128 v[194:197], v165 offset:3072
	s_add_u32 s42, s42, 0x80000
	s_addc_u32 s43, s43, 0
	s_mov_b32 m0, s58
	v_lshl_add_u64 v[234:235], s[42:43], 0, v[128:129]
	ds_read_b128 v[198:201], v163 offset:32768
	ds_read_b128 v[202:205], v163 offset:33792
	ds_read_b128 v[206:209], v163 offset:34816
	ds_read_b128 v[210:213], v163 offset:35840
	ds_read_b128 v[214:217], v163 offset:36864
	ds_read_b128 v[218:221], v163 offset:37888
	ds_read_b128 v[222:225], v163 offset:38912
	ds_read_b128 v[226:229], v163 offset:39936
	global_load_lds_dwordx4 v[234:235], off
	v_lshl_add_u64 v[234:235], s[42:43], 0, v[132:133]
	s_mov_b32 m0, s59
	s_nop 0
	global_load_lds_dwordx4 v[234:235], off
	s_waitcnt vmcnt(8)
	s_waitcnt lgkmcnt(0)
	s_barrier
	s_setprio 1
	s_waitcnt lgkmcnt(0)
	v_mfma_f32_16x16x32_bf16 v[124:127], v[152:155], v[198:201], v[124:127]
	v_mfma_f32_16x16x32_bf16 v[120:123], v[170:173], v[198:201], v[120:123]
	v_mfma_f32_16x16x32_bf16 v[108:111], v[152:155], v[206:209], v[108:111]
	v_mfma_f32_16x16x32_bf16 v[104:107], v[170:173], v[206:209], v[104:107]
	v_mfma_f32_16x16x32_bf16 v[92:95], v[152:155], v[214:217], v[92:95]
	v_mfma_f32_16x16x32_bf16 v[88:91], v[170:173], v[214:217], v[88:91]
	v_mfma_f32_16x16x32_bf16 v[76:79], v[152:155], v[222:225], v[76:79]
	v_mfma_f32_16x16x32_bf16 v[72:75], v[170:173], v[222:225], v[72:75]
	v_mfma_f32_16x16x32_bf16 v[124:127], v[166:169], v[202:205], v[124:127]
	v_mfma_f32_16x16x32_bf16 v[120:123], v[174:177], v[202:205], v[120:123]
	v_mfma_f32_16x16x32_bf16 v[108:111], v[166:169], v[210:213], v[108:111]
	v_mfma_f32_16x16x32_bf16 v[104:107], v[174:177], v[210:213], v[104:107]
	v_mfma_f32_16x16x32_bf16 v[92:95], v[166:169], v[218:221], v[92:95]
	v_mfma_f32_16x16x32_bf16 v[88:91], v[174:177], v[218:221], v[88:91]
	v_mfma_f32_16x16x32_bf16 v[76:79], v[166:169], v[226:229], v[76:79]
	v_mfma_f32_16x16x32_bf16 v[72:75], v[174:177], v[226:229], v[72:75]
	s_setprio 0
	s_setprio 1
	v_mfma_f32_16x16x32_bf16 v[116:119], v[178:181], v[198:201], v[116:119]
	v_mfma_f32_16x16x32_bf16 v[112:115], v[186:189], v[198:201], v[112:115]
	v_mfma_f32_16x16x32_bf16 v[100:103], v[178:181], v[206:209], v[100:103]
	v_mfma_f32_16x16x32_bf16 v[96:99], v[186:189], v[206:209], v[96:99]
	v_mfma_f32_16x16x32_bf16 v[84:87], v[178:181], v[214:217], v[84:87]
	v_mfma_f32_16x16x32_bf16 v[80:83], v[186:189], v[214:217], v[80:83]
	v_mfma_f32_16x16x32_bf16 v[68:71], v[178:181], v[222:225], v[68:71]
	v_mfma_f32_16x16x32_bf16 v[64:67], v[186:189], v[222:225], v[64:67]
	v_mfma_f32_16x16x32_bf16 v[116:119], v[182:185], v[202:205], v[116:119]
	v_mfma_f32_16x16x32_bf16 v[112:115], v[194:197], v[202:205], v[112:115]
	v_mfma_f32_16x16x32_bf16 v[100:103], v[182:185], v[210:213], v[100:103]
	v_mfma_f32_16x16x32_bf16 v[96:99], v[194:197], v[210:213], v[96:99]
	v_mfma_f32_16x16x32_bf16 v[84:87], v[182:185], v[218:221], v[84:87]
	v_mfma_f32_16x16x32_bf16 v[80:83], v[194:197], v[218:221], v[80:83]
	v_mfma_f32_16x16x32_bf16 v[68:71], v[182:185], v[226:229], v[68:71]
	v_mfma_f32_16x16x32_bf16 v[64:67], v[194:197], v[226:229], v[64:67]
	s_setprio 0
	s_barrier
	s_add_i32 s33, s33, s56
	v_lshl_add_u64 v[156:157], v[156:157], 0, s[20:21]
	s_mov_b32 m0, s33
	ds_read_b128 v[198:201], v163 offset:49152
	ds_read_b128 v[202:205], v163 offset:50176
	ds_read_b128 v[206:209], v163 offset:51200
	ds_read_b128 v[210:213], v163 offset:52224
	ds_read_b128 v[214:217], v163 offset:53248
	ds_read_b128 v[218:221], v163 offset:54272
	ds_read_b128 v[222:225], v163 offset:55296
	ds_read_b128 v[226:229], v163 offset:56320
	global_load_lds_dwordx4 v[156:157], off
	s_add_i32 m0, s33, 0x2000
	s_add_u32 s40, s40, 0x80080
	v_lshl_add_u64 v[156:157], v[190:191], 0, s[20:21]
	s_addc_u32 s41, s41, 0
	s_add_i32 s33, s54, s56
	global_load_lds_dwordx4 v[156:157], off
	v_lshl_add_u64 v[156:157], s[40:41], 0, v[130:131]
	s_mov_b32 m0, s33
	s_nop 0
	global_load_lds_dwordx4 v[156:157], off
	v_lshl_add_u64 v[156:157], s[40:41], 0, v[134:135]
	s_add_i32 m0, s33, 0x2000
	s_nop 0
	global_load_lds_dwordx4 v[156:157], off
	v_lshl_add_u64 v[156:157], v[230:231], 0, s[20:21]
	s_mov_b32 m0, s61
	s_nop 0
	global_load_lds_dwordx4 v[156:157], off
	v_lshl_add_u64 v[156:157], v[232:233], 0, s[20:21]
	s_mov_b32 m0, s62
	s_nop 0
	global_load_lds_dwordx4 v[156:157], off
	s_waitcnt vmcnt(8)
	s_waitcnt lgkmcnt(0)
	s_barrier
	s_setprio 1
	s_waitcnt lgkmcnt(0)
	v_mfma_f32_16x16x32_bf16 v[60:63], v[152:155], v[198:201], v[60:63]
	v_mfma_f32_16x16x32_bf16 v[56:59], v[170:173], v[198:201], v[56:59]
	v_mfma_f32_16x16x32_bf16 v[44:47], v[152:155], v[206:209], v[44:47]
	v_mfma_f32_16x16x32_bf16 v[40:43], v[170:173], v[206:209], v[40:43]
	v_mfma_f32_16x16x32_bf16 v[28:31], v[152:155], v[214:217], v[28:31]
	v_mfma_f32_16x16x32_bf16 v[24:27], v[170:173], v[214:217], v[24:27]
	v_mfma_f32_16x16x32_bf16 v[12:15], v[152:155], v[222:225], v[12:15]
	v_mfma_f32_16x16x32_bf16 v[8:11], v[170:173], v[222:225], v[8:11]
	v_mfma_f32_16x16x32_bf16 v[60:63], v[166:169], v[202:205], v[60:63]
	v_mfma_f32_16x16x32_bf16 v[56:59], v[174:177], v[202:205], v[56:59]
	v_mfma_f32_16x16x32_bf16 v[44:47], v[166:169], v[210:213], v[44:47]
	v_mfma_f32_16x16x32_bf16 v[40:43], v[174:177], v[210:213], v[40:43]
	v_mfma_f32_16x16x32_bf16 v[28:31], v[166:169], v[218:221], v[28:31]
	v_mfma_f32_16x16x32_bf16 v[24:27], v[174:177], v[218:221], v[24:27]
	v_mfma_f32_16x16x32_bf16 v[12:15], v[166:169], v[226:229], v[12:15]
	v_mfma_f32_16x16x32_bf16 v[8:11], v[174:177], v[226:229], v[8:11]
	s_setprio 0
	s_setprio 1
	v_mfma_f32_16x16x32_bf16 v[52:55], v[178:181], v[198:201], v[52:55]
	v_mfma_f32_16x16x32_bf16 v[48:51], v[186:189], v[198:201], v[48:51]
	v_mfma_f32_16x16x32_bf16 v[36:39], v[178:181], v[206:209], v[36:39]
	v_mfma_f32_16x16x32_bf16 v[32:35], v[186:189], v[206:209], v[32:35]
	v_mfma_f32_16x16x32_bf16 v[20:23], v[178:181], v[214:217], v[20:23]
	v_mfma_f32_16x16x32_bf16 v[16:19], v[186:189], v[214:217], v[16:19]
	v_mfma_f32_16x16x32_bf16 v[4:7], v[178:181], v[222:225], v[4:7]
	v_mfma_f32_16x16x32_bf16 v[0:3], v[186:189], v[222:225], v[0:3]
	v_mfma_f32_16x16x32_bf16 v[52:55], v[182:185], v[202:205], v[52:55]
	v_mfma_f32_16x16x32_bf16 v[48:51], v[194:197], v[202:205], v[48:51]
	v_mfma_f32_16x16x32_bf16 v[36:39], v[182:185], v[210:213], v[36:39]
	v_mfma_f32_16x16x32_bf16 v[32:35], v[194:197], v[210:213], v[32:35]
	v_mfma_f32_16x16x32_bf16 v[20:23], v[182:185], v[218:221], v[20:23]
	v_mfma_f32_16x16x32_bf16 v[16:19], v[194:197], v[218:221], v[16:19]
	v_mfma_f32_16x16x32_bf16 v[4:7], v[182:185], v[226:229], v[4:7]
	v_mfma_f32_16x16x32_bf16 v[0:3], v[194:197], v[226:229], v[0:3]
	s_setprio 0
	s_barrier
	s_add_i32 s68, s68, 2
	s_add_u32 s38, s38, 0x100
	s_addc_u32 s39, s39, 0
	s_add_u32 s66, s66, 0x100
	s_addc_u32 s67, s67, 0
	s_cmp_gt_u32 s68, 29
	s_cbranch_scc0 .LBB0_1420
	v_lshl_add_u32 v156, s34, 8, v158
	v_lshl_or_b32 v154, s36, 8, v160
	v_ashrrev_i32_e32 v157, 31, v156
	v_ashrrev_i32_e32 v155, 31, v154
	v_lshlrev_b64 v[152:153], 11, v[156:157]
	v_lshl_add_u64 v[152:153], v[152:153], 0, v[154:155]
	v_lshlrev_b64 v[170:171], 1, v[152:153]
	v_lshl_add_u64 v[172:173], s[12:13], 0, v[170:171]
	global_load_dwordx4 v[180:183], v[172:173], off
	global_load_dwordx4 v[184:187], v[172:173], off offset:256
	v_add_co_u32_e32 v252, vcc, 0x10000, v172
	s_nop 1
	v_addc_co_u32_e32 v253, vcc, 0, v173, vcc
	global_load_dwordx4 v[188:191], v[252:253], off
	global_load_dwordx4 v[194:197], v[252:253], off offset:256
	v_add_co_u32_e32 v254, vcc, 0x20000, v172
	s_nop 1
	v_addc_co_u32_e32 v255, vcc, 0, v173, vcc
	global_load_dwordx4 v[198:201], v[254:255], off
	global_load_dwordx4 v[202:205], v[254:255], off offset:256
	v_add_co_u32_e32 v252, vcc, 0x30000, v172
	s_nop 1
	v_addc_co_u32_e32 v253, vcc, 0, v173, vcc
	global_load_dwordx4 v[206:209], v[252:253], off
	global_load_dwordx4 v[210:213], v[252:253], off offset:256
	v_add_co_u32_e32 v254, vcc, 0x80000, v172
	s_nop 1
	v_addc_co_u32_e32 v255, vcc, 0, v173, vcc
	global_load_dwordx4 v[214:217], v[254:255], off
	global_load_dwordx4 v[218:221], v[254:255], off offset:256
	v_add_co_u32_e32 v252, vcc, 0x90000, v172
	s_nop 1
	v_addc_co_u32_e32 v253, vcc, 0, v173, vcc
	global_load_dwordx4 v[222:225], v[252:253], off
	global_load_dwordx4 v[226:229], v[252:253], off offset:256
	v_add_co_u32_e32 v254, vcc, 0xa0000, v172
	s_nop 1
	v_addc_co_u32_e32 v255, vcc, 0, v173, vcc
	global_load_dwordx4 v[230:233], v[254:255], off
	global_load_dwordx4 v[234:237], v[254:255], off offset:256
	v_add_co_u32_e32 v252, vcc, 0xb0000, v172
	s_nop 1
	v_addc_co_u32_e32 v253, vcc, 0, v173, vcc
	global_load_dwordx4 v[238:241], v[252:253], off
	global_load_dwordx4 v[242:245], v[252:253], off offset:256
	s_and_b64 vcc, exec, s[22:23]
	s_cbranch_vccz .LBB0_1423
	s_barrier
.LBB0_1423:
	s_waitcnt vmcnt(15)
	v_mov_b32_e32 v166, v180
	v_mov_b32_e32 v167, v181
	v_mov_b32_e32 v168, v182
	v_mov_b32_e32 v169, v183
	v_xor_b32_e32 v165, 32, v164
	v_lshlrev_b32_e32 v174, 16, v166
	v_and_b32_e32 v175, 0xffff0000, v166
	v_lshlrev_b32_e32 v166, 16, v167
	v_and_b32_e32 v167, 0xffff0000, v167
	v_lshlrev_b32_e32 v176, 16, v168
	v_and_b32_e32 v177, 0xffff0000, v168
	v_lshlrev_b32_e32 v168, 16, v169
	v_and_b32_e32 v169, 0xffff0000, v169
	v_pk_add_f32 v[126:127], v[126:127], v[166:167]
	v_pk_add_f32 v[174:175], v[124:125], v[174:175]
	v_pk_add_f32 v[178:179], v[122:123], v[168:169]
	v_pk_add_f32 v[176:177], v[120:121], v[176:177]
	v_cvt_pk_bf16_f32 v122, v174, v175
	v_cvt_pk_bf16_f32 v123, v126, v127
	v_and_b32_e32 v121, 64, v164
	v_cvt_pk_bf16_f32 v124, v176, v177
	v_cvt_pk_bf16_f32 v125, v178, v179
	s_waitcnt vmcnt(14)
	v_mov_b32_e32 v166, v184
	v_mov_b32_e32 v167, v185
	v_mov_b32_e32 v168, v186
	v_mov_b32_e32 v169, v187
	v_xor_b32_e32 v120, 16, v164
	v_add_u32_e32 v121, 64, v121
	v_cmp_lt_i32_e32 vcc, v120, v121
	v_mul_f32_e32 v127, v127, v127
	v_mul_f32_e32 v172, v177, v177
	v_cndmask_b32_e32 v120, v164, v120, vcc
	v_cmp_lt_i32_e32 vcc, v165, v121
	v_fmac_f32_e32 v127, v126, v126
	v_mul_f32_e32 v173, v179, v179
	v_cndmask_b32_e32 v121, v164, v165, vcc
	v_mul_f32_e32 v165, v175, v175
	v_fmac_f32_e32 v165, v174, v174
	v_fmac_f32_e32 v172, v176, v176
	v_add_f32_e32 v126, v165, v127
	v_fmac_f32_e32 v173, v178, v178
	v_add_f32_e32 v126, v172, v126
	v_add_f32_e32 v165, v173, v126
	v_lshlrev_b32_e32 v120, 2, v120
	v_lshlrev_b32_e32 v126, 16, v166
	v_and_b32_e32 v127, 0xffff0000, v166
	v_lshlrev_b32_e32 v166, 16, v167
	v_and_b32_e32 v167, 0xffff0000, v167
	v_lshlrev_b32_e32 v172, 16, v168
	v_and_b32_e32 v173, 0xffff0000, v168
	v_lshlrev_b32_e32 v168, 16, v169
	v_and_b32_e32 v169, 0xffff0000, v169
	v_pk_add_f32 v[118:119], v[118:119], v[166:167]
	v_pk_add_f32 v[116:117], v[116:117], v[126:127]
	v_pk_add_f32 v[126:127], v[114:115], v[168:169]
	v_pk_add_f32 v[112:113], v[112:113], v[172:173]
	v_mul_f32_e32 v114, v117, v117
	v_mul_f32_e32 v115, v119, v119
	v_mul_f32_e32 v166, v113, v113
	v_fmac_f32_e32 v114, v116, v116
	v_fmac_f32_e32 v115, v118, v118
	v_mul_f32_e32 v167, v127, v127
	v_fmac_f32_e32 v166, v112, v112
	v_add_f32_e32 v114, v114, v115
	v_fmac_f32_e32 v167, v126, v126
	v_add_f32_e32 v114, v166, v114
	v_add_f32_e32 v114, v167, v114
	v_add_f32_e32 v114, v165, v114
	ds_bpermute_b32 v115, v120, v114
	v_lshl_add_u64 v[166:167], s[16:17], 0, v[170:171]
	global_store_dwordx4 v[166:167], v[122:125], off
	s_waitcnt lgkmcnt(0)
	v_add_f32_e32 v115, v114, v115
	v_lshlrev_b32_e32 v114, 2, v121
	v_cvt_pk_bf16_f32 v122, v116, v117
	ds_bpermute_b32 v116, v114, v115
	v_cvt_pk_bf16_f32 v123, v118, v119
	v_cvt_pk_bf16_f32 v124, v112, v113
	v_lshl_add_u64 v[112:113], v[156:157], 2, s[18:19]
	v_cvt_pk_bf16_f32 v125, v126, v127
	global_store_dwordx4 v[166:167], v[122:125], off offset:256
	s_and_saveexec_b64 s[34:35], s[6:7]
	s_cbranch_execz .LBB0_1425
	s_waitcnt lgkmcnt(0)
	v_add_f32_e32 v115, v115, v116
	global_atomic_add_f32 v[112:113], v115, off
.LBB0_1425:
	s_or_b64 exec, exec, s[34:35]
	s_waitcnt lgkmcnt(0)
	v_or_b32_e32 v116, 16, v156
	v_ashrrev_i32_e32 v117, 31, v116
	v_lshlrev_b64 v[116:117], 11, v[116:117]
	v_lshl_add_u64 v[116:117], v[116:117], 0, v[154:155]
	v_lshlrev_b64 v[122:123], 1, v[116:117]
	v_lshl_add_u64 v[124:125], s[12:13], 0, v[122:123]
	s_waitcnt vmcnt(15)
	v_mov_b32_e32 v116, v188
	v_mov_b32_e32 v117, v189
	v_mov_b32_e32 v118, v190
	v_mov_b32_e32 v119, v191
	v_lshlrev_b32_e32 v126, 16, v116
	v_and_b32_e32 v127, 0xffff0000, v116
	v_lshlrev_b32_e32 v116, 16, v117
	v_and_b32_e32 v117, 0xffff0000, v117
	v_lshlrev_b32_e32 v166, 16, v118
	v_and_b32_e32 v167, 0xffff0000, v118
	v_lshlrev_b32_e32 v118, 16, v119
	v_and_b32_e32 v119, 0xffff0000, v119
	v_pk_add_f32 v[116:117], v[110:111], v[116:117]
	v_pk_add_f32 v[126:127], v[108:109], v[126:127]
	v_pk_add_f32 v[118:119], v[106:107], v[118:119]
	v_pk_add_f32 v[166:167], v[104:105], v[166:167]
	v_cvt_pk_bf16_f32 v104, v126, v127
	v_cvt_pk_bf16_f32 v105, v116, v117
	v_mul_f32_e32 v115, v127, v127
	v_cvt_pk_bf16_f32 v106, v166, v167
	v_cvt_pk_bf16_f32 v107, v118, v119
	s_waitcnt vmcnt(14)
	v_mov_b32_e32 v108, v194
	v_mov_b32_e32 v109, v195
	v_mov_b32_e32 v110, v196
	v_mov_b32_e32 v111, v197
	v_mul_f32_e32 v117, v117, v117
	v_mul_f32_e32 v121, v167, v167
	v_fmac_f32_e32 v115, v126, v126
	v_fmac_f32_e32 v117, v116, v116
	v_mul_f32_e32 v119, v119, v119
	v_fmac_f32_e32 v121, v166, v166
	v_add_f32_e32 v115, v115, v117
	v_fmac_f32_e32 v119, v118, v118
	v_add_f32_e32 v115, v121, v115
	v_add_f32_e32 v115, v119, v115
	v_lshlrev_b32_e32 v116, 16, v108
	v_and_b32_e32 v117, 0xffff0000, v108
	v_lshlrev_b32_e32 v108, 16, v109
	v_and_b32_e32 v109, 0xffff0000, v109
	v_lshlrev_b32_e32 v118, 16, v110
	v_and_b32_e32 v119, 0xffff0000, v110
	v_lshlrev_b32_e32 v110, 16, v111
	v_and_b32_e32 v111, 0xffff0000, v111
	v_pk_add_f32 v[102:103], v[102:103], v[108:109]
	v_pk_add_f32 v[100:101], v[100:101], v[116:117]
	v_pk_add_f32 v[108:109], v[98:99], v[110:111]
	v_pk_add_f32 v[110:111], v[96:97], v[118:119]
	v_mul_f32_e32 v96, v101, v101
	v_mul_f32_e32 v97, v103, v103
	v_mul_f32_e32 v98, v111, v111
	v_fmac_f32_e32 v96, v100, v100
	v_fmac_f32_e32 v97, v102, v102
	v_mul_f32_e32 v99, v109, v109
	v_fmac_f32_e32 v98, v110, v110
	v_add_f32_e32 v96, v96, v97
	v_add_f32_e32 v96, v98, v96
	v_fmac_f32_e32 v99, v108, v108
	v_add_f32_e32 v96, v99, v96
	v_add_f32_e32 v96, v115, v96
	ds_bpermute_b32 v97, v120, v96
	v_lshl_add_u64 v[116:117], s[16:17], 0, v[122:123]
	global_store_dwordx4 v[116:117], v[104:107], off
	v_cvt_pk_bf16_f32 v98, v100, v101
	v_cvt_pk_bf16_f32 v99, v102, v103
	s_waitcnt lgkmcnt(0)
	v_add_f32_e32 v96, v96, v97
	ds_bpermute_b32 v97, v114, v96
	v_cvt_pk_bf16_f32 v100, v110, v111
	v_cvt_pk_bf16_f32 v101, v108, v109
	global_store_dwordx4 v[116:117], v[98:101], off offset:256
	s_and_saveexec_b64 s[34:35], s[6:7]
	s_cbranch_execz .LBB0_1427
	s_waitcnt lgkmcnt(0)
	v_add_f32_e32 v96, v96, v97
	global_atomic_add_f32 v[112:113], v96, off offset:64
.LBB0_1427:
	s_or_b64 exec, exec, s[34:35]
	v_or_b32_e32 v96, 32, v156
	s_waitcnt lgkmcnt(0)
	v_ashrrev_i32_e32 v97, 31, v96
	v_lshlrev_b64 v[96:97], 11, v[96:97]
	v_lshl_add_u64 v[96:97], v[96:97], 0, v[154:155]
	v_lshlrev_b64 v[100:101], 1, v[96:97]
	v_lshl_add_u64 v[102:103], s[12:13], 0, v[100:101]
	s_waitcnt vmcnt(15)
	v_mov_b32_e32 v96, v198
	v_mov_b32_e32 v97, v199
	v_mov_b32_e32 v98, v200
	v_mov_b32_e32 v99, v201
	v_lshlrev_b32_e32 v104, 16, v96
	v_and_b32_e32 v105, 0xffff0000, v96
	v_lshlrev_b32_e32 v96, 16, v97
	v_and_b32_e32 v97, 0xffff0000, v97
	v_lshlrev_b32_e32 v106, 16, v98
	v_and_b32_e32 v107, 0xffff0000, v98
	v_lshlrev_b32_e32 v98, 16, v99
	v_and_b32_e32 v99, 0xffff0000, v99
	v_pk_add_f32 v[96:97], v[94:95], v[96:97]
	v_pk_add_f32 v[104:105], v[92:93], v[104:105]
	v_pk_add_f32 v[98:99], v[90:91], v[98:99]
	v_pk_add_f32 v[106:107], v[88:89], v[106:107]
	v_cvt_pk_bf16_f32 v88, v104, v105
	v_cvt_pk_bf16_f32 v89, v96, v97
	v_mul_f32_e32 v97, v97, v97
	v_cvt_pk_bf16_f32 v90, v106, v107
	v_cvt_pk_bf16_f32 v91, v98, v99
	s_waitcnt vmcnt(14)
	v_mov_b32_e32 v92, v202
	v_mov_b32_e32 v93, v203
	v_mov_b32_e32 v94, v204
	v_mov_b32_e32 v95, v205
	v_mul_f32_e32 v102, v105, v105
	v_mul_f32_e32 v103, v107, v107
	v_fmac_f32_e32 v102, v104, v104
	v_fmac_f32_e32 v97, v96, v96
	v_mul_f32_e32 v99, v99, v99
	v_fmac_f32_e32 v103, v106, v106
	v_add_f32_e32 v96, v102, v97
	v_fmac_f32_e32 v99, v98, v98
	v_add_f32_e32 v96, v103, v96
	v_add_f32_e32 v102, v99, v96
	v_lshlrev_b32_e32 v96, 16, v92
	v_and_b32_e32 v97, 0xffff0000, v92
	v_lshlrev_b32_e32 v92, 16, v93
	v_and_b32_e32 v93, 0xffff0000, v93
	v_lshlrev_b32_e32 v98, 16, v94
	v_and_b32_e32 v99, 0xffff0000, v94
	v_lshlrev_b32_e32 v94, 16, v95
	v_and_b32_e32 v95, 0xffff0000, v95
	v_pk_add_f32 v[86:87], v[86:87], v[92:93]
	v_pk_add_f32 v[84:85], v[84:85], v[96:97]
	v_pk_add_f32 v[92:93], v[82:83], v[94:95]
	v_pk_add_f32 v[94:95], v[80:81], v[98:99]
	v_mul_f32_e32 v80, v85, v85
	v_mul_f32_e32 v81, v87, v87
	v_mul_f32_e32 v82, v95, v95
	v_fmac_f32_e32 v80, v84, v84
	v_fmac_f32_e32 v81, v86, v86
	v_mul_f32_e32 v83, v93, v93
	v_fmac_f32_e32 v82, v94, v94
	v_add_f32_e32 v80, v80, v81
	v_add_f32_e32 v80, v82, v80
	v_fmac_f32_e32 v83, v92, v92
	v_add_f32_e32 v80, v83, v80
	v_add_f32_e32 v80, v102, v80
	ds_bpermute_b32 v81, v120, v80
	v_lshl_add_u64 v[96:97], s[16:17], 0, v[100:101]
	global_store_dwordx4 v[96:97], v[88:91], off
	v_cvt_pk_bf16_f32 v82, v84, v85
	v_cvt_pk_bf16_f32 v83, v86, v87
	s_waitcnt lgkmcnt(0)
	v_add_f32_e32 v80, v80, v81
	ds_bpermute_b32 v81, v114, v80
	v_cvt_pk_bf16_f32 v84, v94, v95
	v_cvt_pk_bf16_f32 v85, v92, v93
	global_store_dwordx4 v[96:97], v[82:85], off offset:256
	s_and_saveexec_b64 s[34:35], s[6:7]
	s_cbranch_execz .LBB0_1429
	s_waitcnt lgkmcnt(0)
	v_add_f32_e32 v80, v80, v81
	global_atomic_add_f32 v[112:113], v80, off offset:128
.LBB0_1429:
	s_or_b64 exec, exec, s[34:35]
	v_or_b32_e32 v80, 48, v156
	s_waitcnt lgkmcnt(0)
	v_ashrrev_i32_e32 v81, 31, v80
	v_lshlrev_b64 v[80:81], 11, v[80:81]
	v_lshl_add_u64 v[80:81], v[80:81], 0, v[154:155]
	v_lshlrev_b64 v[84:85], 1, v[80:81]
	v_lshl_add_u64 v[86:87], s[12:13], 0, v[84:85]
	s_waitcnt vmcnt(15)
	v_mov_b32_e32 v80, v206
	v_mov_b32_e32 v81, v207
	v_mov_b32_e32 v82, v208
	v_mov_b32_e32 v83, v209
	v_lshlrev_b32_e32 v88, 16, v80
	v_and_b32_e32 v89, 0xffff0000, v80
	v_lshlrev_b32_e32 v80, 16, v81
	v_and_b32_e32 v81, 0xffff0000, v81
	v_lshlrev_b32_e32 v90, 16, v82
	v_and_b32_e32 v91, 0xffff0000, v82
	v_lshlrev_b32_e32 v82, 16, v83
	v_and_b32_e32 v83, 0xffff0000, v83
	v_pk_add_f32 v[80:81], v[78:79], v[80:81]
	v_pk_add_f32 v[88:89], v[76:77], v[88:89]
	v_pk_add_f32 v[82:83], v[74:75], v[82:83]
	v_pk_add_f32 v[90:91], v[72:73], v[90:91]
	v_cvt_pk_bf16_f32 v72, v88, v89
	v_cvt_pk_bf16_f32 v73, v80, v81
	v_mul_f32_e32 v81, v81, v81
	v_cvt_pk_bf16_f32 v74, v90, v91
	v_cvt_pk_bf16_f32 v75, v82, v83
	s_waitcnt vmcnt(14)
	v_mov_b32_e32 v76, v210
	v_mov_b32_e32 v77, v211
	v_mov_b32_e32 v78, v212
	v_mov_b32_e32 v79, v213
	v_mul_f32_e32 v86, v89, v89
	v_mul_f32_e32 v87, v91, v91
	v_fmac_f32_e32 v86, v88, v88
	v_fmac_f32_e32 v81, v80, v80
	v_mul_f32_e32 v83, v83, v83
	v_fmac_f32_e32 v87, v90, v90
	v_add_f32_e32 v80, v86, v81
	v_fmac_f32_e32 v83, v82, v82
	v_add_f32_e32 v80, v87, v80
	v_add_f32_e32 v86, v83, v80
	v_lshlrev_b32_e32 v80, 16, v76
	v_and_b32_e32 v81, 0xffff0000, v76
	v_lshlrev_b32_e32 v76, 16, v77
	v_and_b32_e32 v77, 0xffff0000, v77
	v_lshlrev_b32_e32 v82, 16, v78
	v_and_b32_e32 v83, 0xffff0000, v78
	v_lshlrev_b32_e32 v78, 16, v79
	v_and_b32_e32 v79, 0xffff0000, v79
	v_pk_add_f32 v[70:71], v[70:71], v[76:77]
	v_pk_add_f32 v[68:69], v[68:69], v[80:81]
	v_pk_add_f32 v[76:77], v[66:67], v[78:79]
	v_pk_add_f32 v[78:79], v[64:65], v[82:83]
	v_mul_f32_e32 v64, v69, v69
	v_mul_f32_e32 v65, v71, v71
	v_mul_f32_e32 v66, v79, v79
	v_fmac_f32_e32 v64, v68, v68
	v_fmac_f32_e32 v65, v70, v70
	v_mul_f32_e32 v67, v77, v77
	v_fmac_f32_e32 v66, v78, v78
	v_add_f32_e32 v64, v64, v65
	v_add_f32_e32 v64, v66, v64
	v_fmac_f32_e32 v67, v76, v76
	v_add_f32_e32 v64, v67, v64
	v_add_f32_e32 v64, v86, v64
	ds_bpermute_b32 v65, v120, v64
	v_lshl_add_u64 v[80:81], s[16:17], 0, v[84:85]
	global_store_dwordx4 v[80:81], v[72:75], off
	v_cvt_pk_bf16_f32 v66, v68, v69
	v_cvt_pk_bf16_f32 v67, v70, v71
	s_waitcnt lgkmcnt(0)
	v_add_f32_e32 v64, v64, v65
	ds_bpermute_b32 v65, v114, v64
	v_cvt_pk_bf16_f32 v68, v78, v79
	v_cvt_pk_bf16_f32 v69, v76, v77
	global_store_dwordx4 v[80:81], v[66:69], off offset:256
	s_and_saveexec_b64 s[34:35], s[6:7]
	s_cbranch_execz .LBB0_1431
	s_waitcnt lgkmcnt(0)
	v_add_f32_e32 v64, v64, v65
	global_atomic_add_f32 v[112:113], v64, off offset:192
.LBB0_1431:
	s_or_b64 exec, exec, s[34:35]
	v_lshl_add_u64 v[68:69], v[152:153], 1, v[144:145]
	v_lshl_add_u64 v[70:71], s[12:13], 0, v[68:69]
	s_waitcnt lgkmcnt(0)
	s_waitcnt vmcnt(15)
	v_mov_b32_e32 v64, v214
	v_mov_b32_e32 v65, v215
	v_mov_b32_e32 v66, v216
	v_mov_b32_e32 v67, v217
	v_lshlrev_b32_e32 v72, 16, v64
	v_and_b32_e32 v73, 0xffff0000, v64
	v_lshlrev_b32_e32 v64, 16, v65
	v_and_b32_e32 v65, 0xffff0000, v65
	v_lshlrev_b32_e32 v74, 16, v66
	v_and_b32_e32 v75, 0xffff0000, v66
	v_lshlrev_b32_e32 v66, 16, v67
	v_and_b32_e32 v67, 0xffff0000, v67
	v_pk_add_f32 v[64:65], v[62:63], v[64:65]
	v_pk_add_f32 v[72:73], v[60:61], v[72:73]
	v_pk_add_f32 v[66:67], v[58:59], v[66:67]
	v_pk_add_f32 v[74:75], v[56:57], v[74:75]
	v_cvt_pk_bf16_f32 v56, v72, v73
	v_cvt_pk_bf16_f32 v57, v64, v65
	v_mul_f32_e32 v65, v65, v65
	v_cvt_pk_bf16_f32 v58, v74, v75
	v_cvt_pk_bf16_f32 v59, v66, v67
	s_waitcnt vmcnt(14)
	v_mov_b32_e32 v60, v218
	v_mov_b32_e32 v61, v219
	v_mov_b32_e32 v62, v220
	v_mov_b32_e32 v63, v221
	v_mul_f32_e32 v70, v73, v73
	v_mul_f32_e32 v71, v75, v75
	v_fmac_f32_e32 v70, v72, v72
	v_fmac_f32_e32 v65, v64, v64
	v_mul_f32_e32 v67, v67, v67
	v_fmac_f32_e32 v71, v74, v74
	v_add_f32_e32 v64, v70, v65
	v_fmac_f32_e32 v67, v66, v66
	v_add_f32_e32 v64, v71, v64
	v_add_f32_e32 v70, v67, v64
	v_lshlrev_b32_e32 v64, 16, v60
	v_and_b32_e32 v65, 0xffff0000, v60
	v_lshlrev_b32_e32 v60, 16, v61
	v_and_b32_e32 v61, 0xffff0000, v61
	v_lshlrev_b32_e32 v66, 16, v62
	v_and_b32_e32 v67, 0xffff0000, v62
	v_lshlrev_b32_e32 v62, 16, v63
	v_and_b32_e32 v63, 0xffff0000, v63
	v_pk_add_f32 v[54:55], v[54:55], v[60:61]
	v_pk_add_f32 v[52:53], v[52:53], v[64:65]
	v_pk_add_f32 v[60:61], v[50:51], v[62:63]
	v_pk_add_f32 v[62:63], v[48:49], v[66:67]
	v_mul_f32_e32 v48, v53, v53
	v_mul_f32_e32 v49, v55, v55
	v_mul_f32_e32 v50, v63, v63
	v_fmac_f32_e32 v48, v52, v52
	v_fmac_f32_e32 v49, v54, v54
	v_mul_f32_e32 v51, v61, v61
	v_fmac_f32_e32 v50, v62, v62
	v_add_f32_e32 v48, v48, v49
	v_add_f32_e32 v48, v50, v48
	v_fmac_f32_e32 v51, v60, v60
	v_add_f32_e32 v48, v51, v48
	v_add_f32_e32 v48, v70, v48
	ds_bpermute_b32 v49, v120, v48
	v_lshl_add_u64 v[64:65], s[16:17], 0, v[68:69]
	global_store_dwordx4 v[64:65], v[56:59], off
	v_cvt_pk_bf16_f32 v50, v52, v53
	v_cvt_pk_bf16_f32 v51, v54, v55
	s_waitcnt lgkmcnt(0)
	v_add_f32_e32 v48, v48, v49
	ds_bpermute_b32 v49, v114, v48
	v_cvt_pk_bf16_f32 v52, v62, v63
	v_cvt_pk_bf16_f32 v53, v60, v61
	global_store_dwordx4 v[64:65], v[50:53], off offset:256
	s_and_saveexec_b64 s[34:35], s[6:7]
	s_cbranch_execz .LBB0_1433
	s_waitcnt lgkmcnt(0)
	v_add_f32_e32 v48, v48, v49
	global_atomic_add_f32 v[112:113], v48, off offset:512
.LBB0_1433:
	s_or_b64 exec, exec, s[34:35]
	v_lshl_add_u64 v[52:53], v[152:153], 1, v[146:147]
	v_lshl_add_u64 v[54:55], s[12:13], 0, v[52:53]
	s_waitcnt lgkmcnt(0)
	s_waitcnt vmcnt(15)
	v_mov_b32_e32 v48, v222
	v_mov_b32_e32 v49, v223
	v_mov_b32_e32 v50, v224
	v_mov_b32_e32 v51, v225
	v_lshlrev_b32_e32 v56, 16, v48
	v_and_b32_e32 v57, 0xffff0000, v48
	v_lshlrev_b32_e32 v48, 16, v49
	v_and_b32_e32 v49, 0xffff0000, v49
	v_lshlrev_b32_e32 v58, 16, v50
	v_and_b32_e32 v59, 0xffff0000, v50
	v_lshlrev_b32_e32 v50, 16, v51
	v_and_b32_e32 v51, 0xffff0000, v51
	v_pk_add_f32 v[48:49], v[46:47], v[48:49]
	v_pk_add_f32 v[56:57], v[44:45], v[56:57]
	v_pk_add_f32 v[50:51], v[42:43], v[50:51]
	v_pk_add_f32 v[58:59], v[40:41], v[58:59]
	v_cvt_pk_bf16_f32 v40, v56, v57
	v_cvt_pk_bf16_f32 v41, v48, v49
	v_mul_f32_e32 v49, v49, v49
	v_cvt_pk_bf16_f32 v42, v58, v59
	v_cvt_pk_bf16_f32 v43, v50, v51
	s_waitcnt vmcnt(14)
	v_mov_b32_e32 v44, v226
	v_mov_b32_e32 v45, v227
	v_mov_b32_e32 v46, v228
	v_mov_b32_e32 v47, v229
	v_mul_f32_e32 v54, v57, v57
	v_mul_f32_e32 v55, v59, v59
	v_fmac_f32_e32 v54, v56, v56
	v_fmac_f32_e32 v49, v48, v48
	v_mul_f32_e32 v51, v51, v51
	v_fmac_f32_e32 v55, v58, v58
	v_add_f32_e32 v48, v54, v49
	v_fmac_f32_e32 v51, v50, v50
	v_add_f32_e32 v48, v55, v48
	v_add_f32_e32 v54, v51, v48
	v_lshlrev_b32_e32 v48, 16, v44
	v_and_b32_e32 v49, 0xffff0000, v44
	v_lshlrev_b32_e32 v44, 16, v45
	v_and_b32_e32 v45, 0xffff0000, v45
	v_lshlrev_b32_e32 v50, 16, v46
	v_and_b32_e32 v51, 0xffff0000, v46
	v_lshlrev_b32_e32 v46, 16, v47
	v_and_b32_e32 v47, 0xffff0000, v47
	v_pk_add_f32 v[38:39], v[38:39], v[44:45]
	v_pk_add_f32 v[36:37], v[36:37], v[48:49]
	v_pk_add_f32 v[44:45], v[34:35], v[46:47]
	v_pk_add_f32 v[46:47], v[32:33], v[50:51]
	v_mul_f32_e32 v32, v37, v37
	v_mul_f32_e32 v33, v39, v39
	v_mul_f32_e32 v34, v47, v47
	v_fmac_f32_e32 v32, v36, v36
	v_fmac_f32_e32 v33, v38, v38
	v_mul_f32_e32 v35, v45, v45
	v_fmac_f32_e32 v34, v46, v46
	v_add_f32_e32 v32, v32, v33
	v_add_f32_e32 v32, v34, v32
	v_fmac_f32_e32 v35, v44, v44
	v_add_f32_e32 v32, v35, v32
	v_add_f32_e32 v32, v54, v32
	ds_bpermute_b32 v33, v120, v32
	v_lshl_add_u64 v[48:49], s[16:17], 0, v[52:53]
	global_store_dwordx4 v[48:49], v[40:43], off
	v_cvt_pk_bf16_f32 v34, v36, v37
	v_cvt_pk_bf16_f32 v35, v38, v39
	s_waitcnt lgkmcnt(0)
	v_add_f32_e32 v32, v32, v33
	ds_bpermute_b32 v33, v114, v32
	v_cvt_pk_bf16_f32 v36, v46, v47
	v_cvt_pk_bf16_f32 v37, v44, v45
	global_store_dwordx4 v[48:49], v[34:37], off offset:256
	s_and_saveexec_b64 s[34:35], s[6:7]
	s_cbranch_execz .LBB0_1435
	s_waitcnt lgkmcnt(0)
	v_add_f32_e32 v32, v32, v33
	global_atomic_add_f32 v[112:113], v32, off offset:576
.LBB0_1435:
	s_or_b64 exec, exec, s[34:35]
	v_lshl_add_u64 v[36:37], v[152:153], 1, v[148:149]
	v_lshl_add_u64 v[38:39], s[12:13], 0, v[36:37]
	s_waitcnt lgkmcnt(0)
	s_waitcnt vmcnt(15)
	v_mov_b32_e32 v32, v230
	v_mov_b32_e32 v33, v231
	v_mov_b32_e32 v34, v232
	v_mov_b32_e32 v35, v233
	v_lshlrev_b32_e32 v40, 16, v32
	v_and_b32_e32 v41, 0xffff0000, v32
	v_lshlrev_b32_e32 v32, 16, v33
	v_and_b32_e32 v33, 0xffff0000, v33
	v_lshlrev_b32_e32 v42, 16, v34
	v_and_b32_e32 v43, 0xffff0000, v34
	v_lshlrev_b32_e32 v34, 16, v35
	v_and_b32_e32 v35, 0xffff0000, v35
	v_pk_add_f32 v[32:33], v[30:31], v[32:33]
	v_pk_add_f32 v[40:41], v[28:29], v[40:41]
	v_pk_add_f32 v[34:35], v[26:27], v[34:35]
	v_pk_add_f32 v[42:43], v[24:25], v[42:43]
	v_cvt_pk_bf16_f32 v24, v40, v41
	v_cvt_pk_bf16_f32 v25, v32, v33
	v_mul_f32_e32 v33, v33, v33
	v_cvt_pk_bf16_f32 v26, v42, v43
	v_cvt_pk_bf16_f32 v27, v34, v35
	s_waitcnt vmcnt(14)
	v_mov_b32_e32 v28, v234
	v_mov_b32_e32 v29, v235
	v_mov_b32_e32 v30, v236
	v_mov_b32_e32 v31, v237
	v_mul_f32_e32 v38, v41, v41
	v_mul_f32_e32 v39, v43, v43
	v_fmac_f32_e32 v38, v40, v40
	v_fmac_f32_e32 v33, v32, v32
	v_mul_f32_e32 v35, v35, v35
	v_fmac_f32_e32 v39, v42, v42
	v_add_f32_e32 v32, v38, v33
	v_fmac_f32_e32 v35, v34, v34
	v_add_f32_e32 v32, v39, v32
	v_add_f32_e32 v38, v35, v32
	v_lshlrev_b32_e32 v32, 16, v28
	v_and_b32_e32 v33, 0xffff0000, v28
	v_lshlrev_b32_e32 v28, 16, v29
	v_and_b32_e32 v29, 0xffff0000, v29
	v_lshlrev_b32_e32 v34, 16, v30
	v_and_b32_e32 v35, 0xffff0000, v30
	v_lshlrev_b32_e32 v30, 16, v31
	v_and_b32_e32 v31, 0xffff0000, v31
	v_pk_add_f32 v[22:23], v[22:23], v[28:29]
	v_pk_add_f32 v[20:21], v[20:21], v[32:33]
	v_pk_add_f32 v[28:29], v[18:19], v[30:31]
	v_pk_add_f32 v[30:31], v[16:17], v[34:35]
	v_mul_f32_e32 v16, v21, v21
	v_mul_f32_e32 v17, v23, v23
	v_mul_f32_e32 v18, v31, v31
	v_fmac_f32_e32 v16, v20, v20
	v_fmac_f32_e32 v17, v22, v22
	v_mul_f32_e32 v19, v29, v29
	v_fmac_f32_e32 v18, v30, v30
	v_add_f32_e32 v16, v16, v17
	v_add_f32_e32 v16, v18, v16
	v_fmac_f32_e32 v19, v28, v28
	v_add_f32_e32 v16, v19, v16
	v_add_f32_e32 v16, v38, v16
	ds_bpermute_b32 v17, v120, v16
	v_lshl_add_u64 v[32:33], s[16:17], 0, v[36:37]
	global_store_dwordx4 v[32:33], v[24:27], off
	v_cvt_pk_bf16_f32 v18, v20, v21
	v_cvt_pk_bf16_f32 v19, v22, v23
	s_waitcnt lgkmcnt(0)
	v_add_f32_e32 v16, v16, v17
	ds_bpermute_b32 v17, v114, v16
	v_cvt_pk_bf16_f32 v20, v30, v31
	v_cvt_pk_bf16_f32 v21, v28, v29
	global_store_dwordx4 v[32:33], v[18:21], off offset:256
	s_and_saveexec_b64 s[34:35], s[6:7]
	s_cbranch_execz .LBB0_1437
	s_waitcnt lgkmcnt(0)
	v_add_f32_e32 v16, v16, v17
	global_atomic_add_f32 v[112:113], v16, off offset:640
.LBB0_1437:
	s_or_b64 exec, exec, s[34:35]
	v_lshl_add_u64 v[20:21], v[152:153], 1, v[150:151]
	v_lshl_add_u64 v[22:23], s[12:13], 0, v[20:21]
	s_waitcnt lgkmcnt(0)
	s_waitcnt vmcnt(15)
	v_mov_b32_e32 v16, v238
	v_mov_b32_e32 v17, v239
	v_mov_b32_e32 v18, v240
	v_mov_b32_e32 v19, v241
	v_lshlrev_b32_e32 v24, 16, v16
	v_and_b32_e32 v25, 0xffff0000, v16
	v_lshlrev_b32_e32 v16, 16, v17
	v_and_b32_e32 v17, 0xffff0000, v17
	v_lshlrev_b32_e32 v26, 16, v18
	v_and_b32_e32 v27, 0xffff0000, v18
	v_lshlrev_b32_e32 v18, 16, v19
	v_and_b32_e32 v19, 0xffff0000, v19
	v_pk_add_f32 v[16:17], v[14:15], v[16:17]
	v_pk_add_f32 v[24:25], v[12:13], v[24:25]
	v_pk_add_f32 v[18:19], v[10:11], v[18:19]
	v_pk_add_f32 v[26:27], v[8:9], v[26:27]
	v_cvt_pk_bf16_f32 v8, v24, v25
	v_cvt_pk_bf16_f32 v9, v16, v17
	v_mul_f32_e32 v17, v17, v17
	v_cvt_pk_bf16_f32 v10, v26, v27
	v_cvt_pk_bf16_f32 v11, v18, v19
	s_waitcnt vmcnt(14)
	v_mov_b32_e32 v12, v242
	v_mov_b32_e32 v13, v243
	v_mov_b32_e32 v14, v244
	v_mov_b32_e32 v15, v245
	v_mul_f32_e32 v22, v25, v25
	v_mul_f32_e32 v23, v27, v27
	v_fmac_f32_e32 v22, v24, v24
	v_fmac_f32_e32 v17, v16, v16
	v_mul_f32_e32 v19, v19, v19
	v_fmac_f32_e32 v23, v26, v26
	v_add_f32_e32 v16, v22, v17
	v_fmac_f32_e32 v19, v18, v18
	v_add_f32_e32 v16, v23, v16
	v_add_f32_e32 v22, v19, v16
	v_lshlrev_b32_e32 v16, 16, v12
	v_and_b32_e32 v17, 0xffff0000, v12
	v_lshlrev_b32_e32 v12, 16, v13
	v_and_b32_e32 v13, 0xffff0000, v13
	v_lshlrev_b32_e32 v18, 16, v14
	v_and_b32_e32 v19, 0xffff0000, v14
	v_lshlrev_b32_e32 v14, 16, v15
	v_and_b32_e32 v15, 0xffff0000, v15
	v_pk_add_f32 v[6:7], v[6:7], v[12:13]
	v_pk_add_f32 v[4:5], v[4:5], v[16:17]
	v_pk_add_f32 v[12:13], v[2:3], v[14:15]
	v_pk_add_f32 v[14:15], v[0:1], v[18:19]
	v_mul_f32_e32 v0, v5, v5
	v_mul_f32_e32 v1, v7, v7
	v_mul_f32_e32 v2, v15, v15
	v_fmac_f32_e32 v0, v4, v4
	v_fmac_f32_e32 v1, v6, v6
	v_mul_f32_e32 v3, v13, v13
	v_fmac_f32_e32 v2, v14, v14
	v_add_f32_e32 v0, v0, v1
	v_add_f32_e32 v0, v2, v0
	v_fmac_f32_e32 v3, v12, v12
	v_add_f32_e32 v0, v3, v0
	v_add_f32_e32 v0, v22, v0
	ds_bpermute_b32 v1, v120, v0
	v_lshl_add_u64 v[16:17], s[16:17], 0, v[20:21]
	global_store_dwordx4 v[16:17], v[8:11], off
	v_cvt_pk_bf16_f32 v2, v4, v5
	v_cvt_pk_bf16_f32 v3, v6, v7
	s_waitcnt lgkmcnt(0)
	v_add_f32_e32 v0, v0, v1
	ds_bpermute_b32 v1, v114, v0
	v_cvt_pk_bf16_f32 v4, v14, v15
	v_cvt_pk_bf16_f32 v5, v12, v13
	global_store_dwordx4 v[16:17], v[2:5], off offset:256
	s_and_saveexec_b64 s[34:35], s[6:7]
	s_cbranch_execz .LBB0_1439
	s_waitcnt lgkmcnt(0)
	v_add_f32_e32 v0, v0, v1
	global_atomic_add_f32 v[112:113], v0, off offset:704

.LBB0_1504:
	ds_read_b128 v[144:147], v153
	ds_read_b128 v[158:161], v153 offset:1024
	ds_read_b128 v[162:165], v153 offset:2048
	ds_read_b128 v[166:169], v153 offset:3072
	ds_read_b128 v[170:173], v154
	ds_read_b128 v[174:177], v154 offset:1024
	ds_read_b128 v[178:181], v154 offset:2048
	ds_read_b128 v[182:185], v154 offset:3072
	s_add_u32 s30, s28, 0xfff80080
	s_addc_u32 s31, s29, -1
	s_cmp_eq_u32 s65, 28
	s_cselect_b32 s35, s23, s31
	s_cselect_b32 s34, s61, s30
	s_cselect_b32 s31, s21, s64
	s_cselect_b32 s30, s62, s63
	v_lshl_add_u64 v[148:149], s[28:29], 0, v[136:137]
	s_add_i32 m0, s42, 0xc000
	ds_read_b128 v[186:189], v155
	ds_read_b128 v[194:197], v155 offset:1024
	ds_read_b128 v[198:201], v155 offset:2048
	ds_read_b128 v[202:205], v155 offset:3072
	ds_read_b128 v[206:209], v155 offset:4096
	ds_read_b128 v[210:213], v155 offset:5120
	ds_read_b128 v[214:217], v155 offset:6144
	ds_read_b128 v[218:221], v155 offset:7168
	global_load_lds_dwordx4 v[148:149], off
	v_lshl_add_u64 v[148:149], s[28:29], 0, v[138:139]
	s_add_i32 m0, s42, 0xe000
	s_nop 0
	global_load_lds_dwordx4 v[148:149], off
	s_waitcnt vmcnt(8)
	s_waitcnt lgkmcnt(0)
	s_barrier
	s_setprio 1
	s_waitcnt lgkmcnt(0)
	v_mfma_f32_16x16x32_bf16 v[116:119], v[144:147], v[186:189], v[116:119]
	v_mfma_f32_16x16x32_bf16 v[112:115], v[162:165], v[186:189], v[112:115]
	v_mfma_f32_16x16x32_bf16 v[100:103], v[144:147], v[198:201], v[100:103]
	v_mfma_f32_16x16x32_bf16 v[96:99], v[162:165], v[198:201], v[96:99]
	v_mfma_f32_16x16x32_bf16 v[84:87], v[144:147], v[206:209], v[84:87]
	v_mfma_f32_16x16x32_bf16 v[80:83], v[162:165], v[206:209], v[80:83]
	v_mfma_f32_16x16x32_bf16 v[68:71], v[144:147], v[214:217], v[68:71]
	v_mfma_f32_16x16x32_bf16 v[64:67], v[162:165], v[214:217], v[64:67]
	v_mfma_f32_16x16x32_bf16 v[116:119], v[158:161], v[194:197], v[116:119]
	v_mfma_f32_16x16x32_bf16 v[112:115], v[166:169], v[194:197], v[112:115]
	v_mfma_f32_16x16x32_bf16 v[100:103], v[158:161], v[202:205], v[100:103]
	v_mfma_f32_16x16x32_bf16 v[96:99], v[166:169], v[202:205], v[96:99]
	v_mfma_f32_16x16x32_bf16 v[84:87], v[158:161], v[210:213], v[84:87]
	v_mfma_f32_16x16x32_bf16 v[80:83], v[166:169], v[210:213], v[80:83]
	v_mfma_f32_16x16x32_bf16 v[68:71], v[158:161], v[218:221], v[68:71]
	v_mfma_f32_16x16x32_bf16 v[64:67], v[166:169], v[218:221], v[64:67]
	s_setprio 0
	s_setprio 1
	v_mfma_f32_16x16x32_bf16 v[124:127], v[170:173], v[186:189], v[124:127]
	v_mfma_f32_16x16x32_bf16 v[120:123], v[178:181], v[186:189], v[120:123]
	v_mfma_f32_16x16x32_bf16 v[108:111], v[170:173], v[198:201], v[108:111]
	v_mfma_f32_16x16x32_bf16 v[104:107], v[178:181], v[198:201], v[104:107]
	v_mfma_f32_16x16x32_bf16 v[92:95], v[170:173], v[206:209], v[92:95]
	v_mfma_f32_16x16x32_bf16 v[88:91], v[178:181], v[206:209], v[88:91]
	v_mfma_f32_16x16x32_bf16 v[76:79], v[170:173], v[214:217], v[76:79]
	v_mfma_f32_16x16x32_bf16 v[72:75], v[178:181], v[214:217], v[72:75]
	v_mfma_f32_16x16x32_bf16 v[124:127], v[174:177], v[194:197], v[124:127]
	v_mfma_f32_16x16x32_bf16 v[120:123], v[182:185], v[194:197], v[120:123]
	v_mfma_f32_16x16x32_bf16 v[108:111], v[174:177], v[202:205], v[108:111]
	v_mfma_f32_16x16x32_bf16 v[104:107], v[182:185], v[202:205], v[104:107]
	v_mfma_f32_16x16x32_bf16 v[92:95], v[174:177], v[210:213], v[92:95]
	v_mfma_f32_16x16x32_bf16 v[88:91], v[182:185], v[210:213], v[88:91]
	v_mfma_f32_16x16x32_bf16 v[76:79], v[174:177], v[218:221], v[76:79]
	v_mfma_f32_16x16x32_bf16 v[72:75], v[182:185], v[218:221], v[72:75]
	s_setprio 0
	s_barrier
	s_add_i32 s33, s57, s40
	v_lshl_add_u64 v[148:149], s[30:31], 0, v[132:133]
	s_mov_b32 m0, s33
	ds_read_b128 v[186:189], v155 offset:16384
	ds_read_b128 v[194:197], v155 offset:17408
	ds_read_b128 v[198:201], v155 offset:18432
	ds_read_b128 v[202:205], v155 offset:19456
	ds_read_b128 v[206:209], v155 offset:20480
	ds_read_b128 v[210:213], v155 offset:21504
	ds_read_b128 v[214:217], v155 offset:22528
	ds_read_b128 v[218:221], v155 offset:23552
	global_load_lds_dwordx4 v[148:149], off
	s_add_i32 m0, s33, 0x2000
	s_add_u32 s54, s30, 0x80000
	v_lshl_add_u64 v[190:191], s[30:31], 0, v[128:129]
	s_addc_u32 s55, s31, 0
	s_add_i32 s33, s58, s40
	global_load_lds_dwordx4 v[190:191], off
	v_lshl_add_u64 v[222:223], s[54:55], 0, v[132:133]
	s_mov_b32 m0, s33
	v_lshl_add_u64 v[224:225], s[34:35], 0, v[130:131]
	global_load_lds_dwordx4 v[222:223], off
	v_lshl_add_u64 v[222:223], s[54:55], 0, v[128:129]
	s_add_i32 m0, s33, 0x2000
	s_nop 0
	global_load_lds_dwordx4 v[222:223], off
	v_lshl_add_u64 v[222:223], s[34:35], 0, v[134:135]
	s_mov_b32 m0, s42
	s_nop 0
	global_load_lds_dwordx4 v[222:223], off
	s_mov_b32 m0, s43
	s_nop 0
	global_load_lds_dwordx4 v[224:225], off
	s_waitcnt vmcnt(8)
	s_waitcnt lgkmcnt(0)
	s_barrier
	s_setprio 1
	s_waitcnt lgkmcnt(0)
	v_mfma_f32_16x16x32_bf16 v[52:55], v[144:147], v[186:189], v[52:55]
	v_mfma_f32_16x16x32_bf16 v[48:51], v[162:165], v[186:189], v[48:51]
	v_mfma_f32_16x16x32_bf16 v[36:39], v[144:147], v[198:201], v[36:39]
	v_mfma_f32_16x16x32_bf16 v[32:35], v[162:165], v[198:201], v[32:35]
	v_mfma_f32_16x16x32_bf16 v[20:23], v[144:147], v[206:209], v[20:23]
	v_mfma_f32_16x16x32_bf16 v[16:19], v[162:165], v[206:209], v[16:19]
	v_mfma_f32_16x16x32_bf16 v[4:7], v[144:147], v[214:217], v[4:7]
	v_mfma_f32_16x16x32_bf16 v[0:3], v[162:165], v[214:217], v[0:3]
	v_mfma_f32_16x16x32_bf16 v[52:55], v[158:161], v[194:197], v[52:55]
	v_mfma_f32_16x16x32_bf16 v[48:51], v[166:169], v[194:197], v[48:51]
	v_mfma_f32_16x16x32_bf16 v[36:39], v[158:161], v[202:205], v[36:39]
	v_mfma_f32_16x16x32_bf16 v[32:35], v[166:169], v[202:205], v[32:35]
	v_mfma_f32_16x16x32_bf16 v[20:23], v[158:161], v[210:213], v[20:23]
	v_mfma_f32_16x16x32_bf16 v[16:19], v[166:169], v[210:213], v[16:19]
	v_mfma_f32_16x16x32_bf16 v[4:7], v[158:161], v[218:221], v[4:7]
	v_mfma_f32_16x16x32_bf16 v[0:3], v[166:169], v[218:221], v[0:3]
	s_setprio 0
	s_setprio 1
	v_mfma_f32_16x16x32_bf16 v[60:63], v[170:173], v[186:189], v[60:63]
	v_mfma_f32_16x16x32_bf16 v[56:59], v[178:181], v[186:189], v[56:59]
	v_mfma_f32_16x16x32_bf16 v[44:47], v[170:173], v[198:201], v[44:47]
	v_mfma_f32_16x16x32_bf16 v[40:43], v[178:181], v[198:201], v[40:43]
	v_mfma_f32_16x16x32_bf16 v[28:31], v[170:173], v[206:209], v[28:31]
	v_mfma_f32_16x16x32_bf16 v[24:27], v[178:181], v[206:209], v[24:27]
	v_mfma_f32_16x16x32_bf16 v[12:15], v[170:173], v[214:217], v[12:15]
	v_mfma_f32_16x16x32_bf16 v[8:11], v[178:181], v[214:217], v[8:11]
	v_mfma_f32_16x16x32_bf16 v[60:63], v[174:177], v[194:197], v[60:63]
	v_mfma_f32_16x16x32_bf16 v[56:59], v[182:185], v[194:197], v[56:59]
	v_mfma_f32_16x16x32_bf16 v[44:47], v[174:177], v[202:205], v[44:47]
	v_mfma_f32_16x16x32_bf16 v[40:43], v[182:185], v[202:205], v[40:43]
	v_mfma_f32_16x16x32_bf16 v[28:31], v[174:177], v[210:213], v[28:31]
	v_mfma_f32_16x16x32_bf16 v[24:27], v[182:185], v[210:213], v[24:27]
	v_mfma_f32_16x16x32_bf16 v[12:15], v[174:177], v[218:221], v[12:15]
	v_mfma_f32_16x16x32_bf16 v[8:11], v[182:185], v[218:221], v[8:11]
	s_setprio 0
	s_barrier
	s_add_i32 s33, 0, 0x18000
	s_add_i32 s54, 0, 0x1c000
	v_add_u32_e32 v166, s33, v151
	v_add_u32_e32 v182, s54, v151
	ds_read_b128 v[144:147], v166
	ds_read_b128 v[158:161], v166 offset:1024
	ds_read_b128 v[162:165], v166 offset:2048
	ds_read_b128 v[166:169], v166 offset:3072
	ds_read_b128 v[170:173], v182
	ds_read_b128 v[174:177], v182 offset:1024
	ds_read_b128 v[178:181], v182 offset:2048
	ds_read_b128 v[182:185], v182 offset:3072
	s_add_u32 s34, s34, 0x80000
	s_addc_u32 s35, s35, 0
	s_mov_b32 m0, s48
	v_lshl_add_u64 v[226:227], s[34:35], 0, v[134:135]
	ds_read_b128 v[186:189], v155 offset:32768
	ds_read_b128 v[194:197], v155 offset:33792
	ds_read_b128 v[198:201], v155 offset:34816
	ds_read_b128 v[202:205], v155 offset:35840
	ds_read_b128 v[206:209], v155 offset:36864
	ds_read_b128 v[210:213], v155 offset:37888
	ds_read_b128 v[214:217], v155 offset:38912
	ds_read_b128 v[218:221], v155 offset:39936
	global_load_lds_dwordx4 v[226:227], off
	v_lshl_add_u64 v[226:227], s[34:35], 0, v[130:131]
	s_mov_b32 m0, s49
	s_nop 0
	global_load_lds_dwordx4 v[226:227], off
	s_waitcnt vmcnt(8)
	s_waitcnt lgkmcnt(0)
	s_barrier
	s_setprio 1
	s_waitcnt lgkmcnt(0)
	v_mfma_f32_16x16x32_bf16 v[116:119], v[144:147], v[186:189], v[116:119]
	v_mfma_f32_16x16x32_bf16 v[112:115], v[162:165], v[186:189], v[112:115]
	v_mfma_f32_16x16x32_bf16 v[100:103], v[144:147], v[198:201], v[100:103]
	v_mfma_f32_16x16x32_bf16 v[96:99], v[162:165], v[198:201], v[96:99]
	v_mfma_f32_16x16x32_bf16 v[84:87], v[144:147], v[206:209], v[84:87]
	v_mfma_f32_16x16x32_bf16 v[80:83], v[162:165], v[206:209], v[80:83]
	v_mfma_f32_16x16x32_bf16 v[68:71], v[144:147], v[214:217], v[68:71]
	v_mfma_f32_16x16x32_bf16 v[64:67], v[162:165], v[214:217], v[64:67]
	v_mfma_f32_16x16x32_bf16 v[116:119], v[158:161], v[194:197], v[116:119]
	v_mfma_f32_16x16x32_bf16 v[112:115], v[166:169], v[194:197], v[112:115]
	v_mfma_f32_16x16x32_bf16 v[100:103], v[158:161], v[202:205], v[100:103]
	v_mfma_f32_16x16x32_bf16 v[96:99], v[166:169], v[202:205], v[96:99]
	v_mfma_f32_16x16x32_bf16 v[84:87], v[158:161], v[210:213], v[84:87]
	v_mfma_f32_16x16x32_bf16 v[80:83], v[166:169], v[210:213], v[80:83]
	v_mfma_f32_16x16x32_bf16 v[68:71], v[158:161], v[218:221], v[68:71]
	v_mfma_f32_16x16x32_bf16 v[64:67], v[166:169], v[218:221], v[64:67]
	s_setprio 0
	s_setprio 1
	v_mfma_f32_16x16x32_bf16 v[124:127], v[170:173], v[186:189], v[124:127]
	v_mfma_f32_16x16x32_bf16 v[120:123], v[178:181], v[186:189], v[120:123]
	v_mfma_f32_16x16x32_bf16 v[108:111], v[170:173], v[198:201], v[108:111]
	v_mfma_f32_16x16x32_bf16 v[104:107], v[178:181], v[198:201], v[104:107]
	v_mfma_f32_16x16x32_bf16 v[92:95], v[170:173], v[206:209], v[92:95]
	v_mfma_f32_16x16x32_bf16 v[88:91], v[178:181], v[206:209], v[88:91]
	v_mfma_f32_16x16x32_bf16 v[76:79], v[170:173], v[214:217], v[76:79]
	v_mfma_f32_16x16x32_bf16 v[72:75], v[178:181], v[214:217], v[72:75]
	v_mfma_f32_16x16x32_bf16 v[124:127], v[174:177], v[194:197], v[124:127]
	v_mfma_f32_16x16x32_bf16 v[120:123], v[182:185], v[194:197], v[120:123]
	v_mfma_f32_16x16x32_bf16 v[108:111], v[174:177], v[202:205], v[108:111]
	v_mfma_f32_16x16x32_bf16 v[104:107], v[182:185], v[202:205], v[104:107]
	v_mfma_f32_16x16x32_bf16 v[92:95], v[174:177], v[210:213], v[92:95]
	v_mfma_f32_16x16x32_bf16 v[88:91], v[182:185], v[210:213], v[88:91]
	v_mfma_f32_16x16x32_bf16 v[76:79], v[174:177], v[218:221], v[76:79]
	v_mfma_f32_16x16x32_bf16 v[72:75], v[182:185], v[218:221], v[72:75]
	s_setprio 0
	s_barrier
	s_add_i32 s33, s33, s40
	v_lshl_add_u64 v[148:149], v[148:149], 0, s[16:17]
	s_mov_b32 m0, s33
	ds_read_b128 v[186:189], v155 offset:49152
	ds_read_b128 v[194:197], v155 offset:50176
	ds_read_b128 v[198:201], v155 offset:51200
	ds_read_b128 v[202:205], v155 offset:52224
	ds_read_b128 v[206:209], v155 offset:53248
	ds_read_b128 v[210:213], v155 offset:54272
	ds_read_b128 v[214:217], v155 offset:55296
	ds_read_b128 v[218:221], v155 offset:56320
	global_load_lds_dwordx4 v[148:149], off
	s_add_i32 m0, s33, 0x2000
	s_add_u32 s30, s30, 0x80080
	v_lshl_add_u64 v[148:149], v[190:191], 0, s[16:17]
	s_addc_u32 s31, s31, 0
	s_add_i32 s33, s54, s40
	global_load_lds_dwordx4 v[148:149], off
	v_lshl_add_u64 v[148:149], s[30:31], 0, v[132:133]
	s_mov_b32 m0, s33
	s_nop 0
	global_load_lds_dwordx4 v[148:149], off
	v_lshl_add_u64 v[148:149], s[30:31], 0, v[128:129]
	s_add_i32 m0, s33, 0x2000
	s_nop 0
	global_load_lds_dwordx4 v[148:149], off
	v_lshl_add_u64 v[148:149], v[222:223], 0, s[16:17]
	s_mov_b32 m0, s51
	s_nop 0
	global_load_lds_dwordx4 v[148:149], off
	v_lshl_add_u64 v[148:149], v[224:225], 0, s[16:17]
	s_mov_b32 m0, s56
	s_nop 0
	global_load_lds_dwordx4 v[148:149], off
	s_waitcnt vmcnt(8)
	s_waitcnt lgkmcnt(0)
	s_barrier
	s_setprio 1
	s_waitcnt lgkmcnt(0)
	v_mfma_f32_16x16x32_bf16 v[52:55], v[144:147], v[186:189], v[52:55]
	v_mfma_f32_16x16x32_bf16 v[48:51], v[162:165], v[186:189], v[48:51]
	v_mfma_f32_16x16x32_bf16 v[36:39], v[144:147], v[198:201], v[36:39]
	v_mfma_f32_16x16x32_bf16 v[32:35], v[162:165], v[198:201], v[32:35]
	v_mfma_f32_16x16x32_bf16 v[20:23], v[144:147], v[206:209], v[20:23]
	v_mfma_f32_16x16x32_bf16 v[16:19], v[162:165], v[206:209], v[16:19]
	v_mfma_f32_16x16x32_bf16 v[4:7], v[144:147], v[214:217], v[4:7]
	v_mfma_f32_16x16x32_bf16 v[0:3], v[162:165], v[214:217], v[0:3]
	v_mfma_f32_16x16x32_bf16 v[52:55], v[158:161], v[194:197], v[52:55]
	v_mfma_f32_16x16x32_bf16 v[48:51], v[166:169], v[194:197], v[48:51]
	v_mfma_f32_16x16x32_bf16 v[36:39], v[158:161], v[202:205], v[36:39]
	v_mfma_f32_16x16x32_bf16 v[32:35], v[166:169], v[202:205], v[32:35]
	v_mfma_f32_16x16x32_bf16 v[20:23], v[158:161], v[210:213], v[20:23]
	v_mfma_f32_16x16x32_bf16 v[16:19], v[166:169], v[210:213], v[16:19]
	v_mfma_f32_16x16x32_bf16 v[4:7], v[158:161], v[218:221], v[4:7]
	v_mfma_f32_16x16x32_bf16 v[0:3], v[166:169], v[218:221], v[0:3]
	s_setprio 0
	s_setprio 1
	v_mfma_f32_16x16x32_bf16 v[60:63], v[170:173], v[186:189], v[60:63]
	v_mfma_f32_16x16x32_bf16 v[56:59], v[178:181], v[186:189], v[56:59]
	v_mfma_f32_16x16x32_bf16 v[44:47], v[170:173], v[198:201], v[44:47]
	v_mfma_f32_16x16x32_bf16 v[40:43], v[178:181], v[198:201], v[40:43]
	v_mfma_f32_16x16x32_bf16 v[28:31], v[170:173], v[206:209], v[28:31]
	v_mfma_f32_16x16x32_bf16 v[24:27], v[178:181], v[206:209], v[24:27]
	v_mfma_f32_16x16x32_bf16 v[12:15], v[170:173], v[214:217], v[12:15]
	v_mfma_f32_16x16x32_bf16 v[8:11], v[178:181], v[214:217], v[8:11]
	v_mfma_f32_16x16x32_bf16 v[60:63], v[174:177], v[194:197], v[60:63]
	v_mfma_f32_16x16x32_bf16 v[56:59], v[182:185], v[194:197], v[56:59]
	v_mfma_f32_16x16x32_bf16 v[44:47], v[174:177], v[202:205], v[44:47]
	v_mfma_f32_16x16x32_bf16 v[40:43], v[182:185], v[202:205], v[40:43]
	v_mfma_f32_16x16x32_bf16 v[28:31], v[174:177], v[210:213], v[28:31]
	v_mfma_f32_16x16x32_bf16 v[24:27], v[182:185], v[210:213], v[24:27]
	v_mfma_f32_16x16x32_bf16 v[12:15], v[174:177], v[218:221], v[12:15]
	v_mfma_f32_16x16x32_bf16 v[8:11], v[182:185], v[218:221], v[8:11]
	s_setprio 0
	s_barrier
	s_add_i32 s65, s65, 2
	s_add_u32 s28, s28, 0x100
	s_addc_u32 s29, s29, 0
	s_add_u32 s63, s63, 0x100
	s_addc_u32 s64, s64, 0
	s_cmp_gt_u32 s65, 29
	s_cbranch_scc0 .LBB0_1504
	v_lshl_add_u32 v144, s8, 8, v150
	v_ashrrev_i32_e32 v145, 31, v144
	v_lshl_add_u64 v[148:149], v[144:145], 2, s[14:15]
	global_load_dword v172, v[148:149], off
	global_load_dword v173, v[148:149], off offset:64
	global_load_dword v174, v[148:149], off offset:128
	global_load_dword v175, v[148:149], off offset:192
	global_load_dword v176, v[148:149], off offset:512
	global_load_dword v177, v[148:149], off offset:576
	global_load_dword v178, v[148:149], off offset:640
	global_load_dword v179, v[148:149], off offset:704
	s_and_b64 vcc, exec, s[18:19]
	s_cbranch_vccz .LBB0_1507
	s_barrier
.LBB0_1507:
	s_nop 0
	v_mov_b32_e32 v160, v124
	v_mov_b32_e32 v124, v126
	v_mov_b32_e32 v126, v120
	v_mov_b32_e32 v161, v116
	v_mov_b32_e32 v116, v125
	v_mov_b32_e32 v125, v118
	v_mov_b32_e32 v118, v127
	v_mov_b32_e32 v127, v112
	v_mov_b32_e32 v112, v121
	v_lshl_or_b32 v158, s9, 7, v152
	v_ashrrev_i32_e32 v159, 31, v158
	v_mov_b64_e32 v[146:147], s[12:13]
	v_mov_b32_e32 v162, v122
	v_mov_b32_e32 v163, v114
	v_mov_b32_e32 v114, v123
	v_mad_i64_i32 v[122:123], s[8:9], v144, s59, v[146:147]
	v_or_b32_e32 v164, 16, v144
	v_ashrrev_i32_e32 v165, 31, v164
	s_waitcnt vmcnt(7)
	v_mov_b32_e32 v145, v172
	v_fmamk_f32 v120, v145, 0x3a000000, v156
	v_mul_f32_e32 v121, 0x4f800000, v120
	v_cmp_gt_f32_e32 vcc, s60, v120
	s_nop 1
	v_cndmask_b32_e32 v145, v120, v121, vcc
	v_sqrt_f32_e32 v166, v145
	v_lshlrev_b64 v[120:121], 1, v[158:159]
	v_lshl_add_u64 v[122:123], v[122:123], 0, v[120:121]
	v_add_u32_e32 v158, -1, v166
	v_add_u32_e32 v159, 1, v166
	v_fma_f32 v167, -v158, v166, v145
	v_fma_f32 v168, -v159, v166, v145
	v_cmp_ge_f32_e64 s[8:9], 0, v167
	s_nop 1
	v_cndmask_b32_e64 v158, v166, v158, s[8:9]
	v_cmp_lt_f32_e64 s[8:9], 0, v168
	s_nop 1
	v_cndmask_b32_e64 v158, v158, v159, s[8:9]
	v_mul_f32_e32 v159, 0x37800000, v158
	v_cndmask_b32_e32 v158, v158, v159, vcc
	v_cmp_class_f32_e32 vcc, v145, v157
	s_nop 1
	v_cndmask_b32_e32 v145, v158, v145, vcc
	v_div_scale_f32 v166, s[8:9], v145, v145, 1.0
	v_rcp_f32_e32 v167, v166
	v_lshl_add_u64 v[158:159], v[164:165], 2, s[14:15]
	v_div_scale_f32 v165, vcc, 1.0, v145, 1.0
	v_fma_f32 v168, -v166, v167, 1.0
	v_fmac_f32_e32 v167, v168, v167
	v_mul_f32_e32 v168, v165, v167
	v_fma_f32 v169, -v166, v168, v165
	v_fmac_f32_e32 v168, v169, v167
	v_fma_f32 v165, -v166, v168, v165
	v_div_fmas_f32 v165, v165, v167, v168
	v_div_fixup_f32 v166, v165, v145, 1.0
	v_pk_mul_f32 v[114:115], v[114:115], v[166:167] op_sel_hi:[1,0]
	v_pk_mul_f32 v[160:161], v[160:161], v[166:167] op_sel_hi:[1,0]
	v_pk_mul_f32 v[116:117], v[116:117], v[166:167] op_sel_hi:[1,0]
	v_pk_mul_f32 v[124:125], v[124:125], v[166:167] op_sel_hi:[1,0]
	v_pk_mul_f32 v[118:119], v[118:119], v[166:167] op_sel_hi:[1,0]
	v_pk_mul_f32 v[126:127], v[126:127], v[166:167] op_sel_hi:[1,0]
	v_pk_mul_f32 v[112:113], v[112:113], v[166:167] op_sel_hi:[1,0]
	v_pk_mul_f32 v[162:163], v[162:163], v[166:167] op_sel_hi:[1,0]
	v_mul_f32_e32 v171, 0xbfb8aa3b, v115
	v_mul_f32_e32 v145, 0xbfb8aa3b, v161
	v_mul_f32_e32 v165, 0xbfb8aa3b, v117
	v_mul_f32_e32 v166, 0xbfb8aa3b, v125
	v_mul_f32_e32 v167, 0xbfb8aa3b, v119
	v_mul_f32_e32 v168, 0xbfb8aa3b, v127
	v_mul_f32_e32 v169, 0xbfb8aa3b, v113
	v_mul_f32_e32 v170, 0xbfb8aa3b, v163
	v_exp_f32_e32 v171, v171
	v_exp_f32_e32 v145, v145
	v_exp_f32_e32 v165, v165
	v_exp_f32_e32 v166, v166
	v_exp_f32_e32 v167, v167
	v_exp_f32_e32 v168, v168
	v_exp_f32_e32 v169, v169
	v_exp_f32_e32 v170, v170
	v_add_f32_e32 v171, 1.0, v171
	v_add_f32_e32 v145, 1.0, v145
	v_add_f32_e32 v165, 1.0, v165
	v_add_f32_e32 v166, 1.0, v166
	v_add_f32_e32 v167, 1.0, v167
	v_add_f32_e32 v168, 1.0, v168
	v_add_f32_e32 v169, 1.0, v169
	v_add_f32_e32 v170, 1.0, v170
	v_rcp_f32_e32 v171, v171
	v_rcp_f32_e32 v145, v145
	v_rcp_f32_e32 v165, v165
	v_rcp_f32_e32 v166, v166
	v_rcp_f32_e32 v167, v167
	v_rcp_f32_e32 v168, v168
	v_rcp_f32_e32 v169, v169
	v_rcp_f32_e32 v170, v170
	v_mul_f32_e32 v115, v115, v171
	v_mul_f32_e32 v145, v161, v145
	v_mul_f32_e32 v117, v117, v165
	v_mul_f32_e32 v125, v125, v166
	v_mul_f32_e32 v119, v119, v167
	v_mul_f32_e32 v127, v127, v168
	v_mul_f32_e32 v113, v113, v169
	v_mul_f32_e32 v161, v163, v170
	v_mul_f32_e32 v115, v114, v115
	v_mul_f32_e32 v145, v160, v145
	v_mul_f32_e32 v116, v116, v117
	v_mul_f32_e32 v117, v124, v125
	v_mul_f32_e32 v118, v118, v119
	v_mul_f32_e32 v119, v126, v127
	v_mul_f32_e32 v124, v112, v113
	v_mul_f32_e32 v125, v162, v161
	v_cvt_pk_bf16_f32 v112, v145, v116
	v_cvt_pk_bf16_f32 v113, v117, v118
	v_cvt_pk_bf16_f32 v114, v119, v124
	v_cvt_pk_bf16_f32 v115, v125, v115
	global_store_dwordx4 v[122:123], v[112:115], off
	s_nop 0
	s_nop 0
	v_mov_b32_e32 v113, v100
	v_mov_b32_e32 v100, v109
	v_mov_b32_e32 v109, v102
	v_mov_b32_e32 v102, v111
	v_mov_b32_e32 v111, v96
	v_mov_b32_e32 v96, v105
	v_mov_b32_e32 v105, v98
	v_mov_b32_e32 v98, v107
	v_mov_b32_e32 v112, v108
	v_mov_b32_e32 v108, v110
	v_mov_b32_e32 v110, v104
	v_mov_b32_e32 v104, v106
	v_or_b32_e32 v106, 32, v144
	s_waitcnt vmcnt(7)
	v_mov_b32_e32 v114, v173
	v_fmamk_f32 v107, v114, 0x3a000000, v156
	v_mul_f32_e32 v114, 0x4f800000, v107
	v_cmp_gt_f32_e32 vcc, s60, v107
	s_nop 1
	v_cndmask_b32_e32 v116, v107, v114, vcc
	v_sqrt_f32_e32 v117, v116
	v_mad_i64_i32 v[114:115], s[8:9], v164, s59, v[146:147]
	v_ashrrev_i32_e32 v107, 31, v106
	v_add_u32_e32 v118, -1, v117
	v_add_u32_e32 v119, 1, v117
	v_fma_f32 v122, -v118, v117, v116
	v_fma_f32 v123, -v119, v117, v116
	v_cmp_ge_f32_e64 s[8:9], 0, v122
	v_lshl_add_u64 v[114:115], v[114:115], 0, v[120:121]
	s_nop 0
	v_cndmask_b32_e64 v117, v117, v118, s[8:9]
	v_cmp_lt_f32_e64 s[8:9], 0, v123
	s_nop 1
	v_cndmask_b32_e64 v117, v117, v119, s[8:9]
	v_mul_f32_e32 v118, 0x37800000, v117
	v_cndmask_b32_e32 v117, v117, v118, vcc
	v_cmp_class_f32_e32 vcc, v116, v157
	s_nop 1
	v_cndmask_b32_e32 v118, v117, v116, vcc
	v_div_scale_f32 v119, s[8:9], v118, v118, 1.0
	v_rcp_f32_e32 v122, v119
	v_lshl_add_u64 v[116:117], v[106:107], 2, s[14:15]
	v_div_scale_f32 v107, vcc, 1.0, v118, 1.0
	v_fma_f32 v123, -v119, v122, 1.0
	v_fmac_f32_e32 v122, v123, v122
	v_mul_f32_e32 v123, v107, v122
	v_fma_f32 v124, -v119, v123, v107
	v_fmac_f32_e32 v123, v124, v122
	v_fma_f32 v107, -v119, v123, v107
	v_div_fmas_f32 v107, v107, v122, v123
	v_div_fixup_f32 v118, v107, v118, 1.0
	v_pk_mul_f32 v[98:99], v[98:99], v[118:119] op_sel_hi:[1,0]
	v_pk_mul_f32 v[112:113], v[112:113], v[118:119] op_sel_hi:[1,0]
	v_pk_mul_f32 v[100:101], v[100:101], v[118:119] op_sel_hi:[1,0]
	v_pk_mul_f32 v[108:109], v[108:109], v[118:119] op_sel_hi:[1,0]
	v_pk_mul_f32 v[102:103], v[102:103], v[118:119] op_sel_hi:[1,0]
	v_pk_mul_f32 v[110:111], v[110:111], v[118:119] op_sel_hi:[1,0]
	v_pk_mul_f32 v[96:97], v[96:97], v[118:119] op_sel_hi:[1,0]
	v_pk_mul_f32 v[104:105], v[104:105], v[118:119] op_sel_hi:[1,0]
	v_mul_f32_e32 v126, 0xbfb8aa3b, v99
	v_mul_f32_e32 v107, 0xbfb8aa3b, v113
	v_mul_f32_e32 v118, 0xbfb8aa3b, v101
	v_mul_f32_e32 v119, 0xbfb8aa3b, v109
	v_mul_f32_e32 v122, 0xbfb8aa3b, v103
	v_mul_f32_e32 v123, 0xbfb8aa3b, v111
	v_mul_f32_e32 v124, 0xbfb8aa3b, v97
	v_mul_f32_e32 v125, 0xbfb8aa3b, v105
	v_exp_f32_e32 v126, v126
	v_exp_f32_e32 v107, v107
	v_exp_f32_e32 v118, v118
	v_exp_f32_e32 v119, v119
	v_exp_f32_e32 v122, v122
	v_exp_f32_e32 v123, v123
	v_exp_f32_e32 v124, v124
	v_exp_f32_e32 v125, v125
	v_add_f32_e32 v126, 1.0, v126
	v_add_f32_e32 v107, 1.0, v107
	v_add_f32_e32 v118, 1.0, v118
	v_add_f32_e32 v119, 1.0, v119
	v_add_f32_e32 v122, 1.0, v122
	v_add_f32_e32 v123, 1.0, v123
	v_add_f32_e32 v124, 1.0, v124
	v_add_f32_e32 v125, 1.0, v125
	v_rcp_f32_e32 v126, v126
	v_rcp_f32_e32 v107, v107
	v_rcp_f32_e32 v118, v118
	v_rcp_f32_e32 v119, v119
	v_rcp_f32_e32 v122, v122
	v_rcp_f32_e32 v123, v123
	v_rcp_f32_e32 v124, v124
	v_rcp_f32_e32 v125, v125
	v_mul_f32_e32 v99, v99, v126
	v_mul_f32_e32 v107, v113, v107
	v_mul_f32_e32 v101, v101, v118
	v_mul_f32_e32 v109, v109, v119
	v_mul_f32_e32 v103, v103, v122
	v_mul_f32_e32 v111, v111, v123
	v_mul_f32_e32 v97, v97, v124
	v_mul_f32_e32 v105, v105, v125
	v_mul_f32_e32 v99, v98, v99
	v_mul_f32_e32 v107, v112, v107
	v_mul_f32_e32 v100, v100, v101
	v_mul_f32_e32 v101, v108, v109
	v_mul_f32_e32 v102, v102, v103
	v_mul_f32_e32 v103, v110, v111
	v_mul_f32_e32 v108, v96, v97
	v_mul_f32_e32 v104, v104, v105
	v_cvt_pk_bf16_f32 v96, v107, v100
	v_cvt_pk_bf16_f32 v97, v101, v102
	v_cvt_pk_bf16_f32 v98, v103, v108
	v_cvt_pk_bf16_f32 v99, v104, v99
	global_store_dwordx4 v[114:115], v[96:99], off
	s_nop 0
	s_nop 0
	v_mov_b32_e32 v97, v84
	v_mov_b32_e32 v84, v93
	v_mov_b32_e32 v93, v86
	v_mov_b32_e32 v86, v95
	v_mov_b32_e32 v95, v80
	v_mov_b32_e32 v80, v89
	v_mov_b32_e32 v89, v82
	v_mov_b32_e32 v82, v91
	v_mov_b32_e32 v96, v92
	v_mov_b32_e32 v92, v94
	v_mov_b32_e32 v94, v88
	v_mov_b32_e32 v88, v90
	v_or_b32_e32 v90, 48, v144
	s_waitcnt vmcnt(7)
	v_mov_b32_e32 v98, v174
	v_fmamk_f32 v91, v98, 0x3a000000, v156
	v_mul_f32_e32 v98, 0x4f800000, v91
	v_cmp_gt_f32_e32 vcc, s60, v91
	s_nop 1
	v_cndmask_b32_e32 v100, v91, v98, vcc
	v_sqrt_f32_e32 v101, v100
	v_mad_i64_i32 v[98:99], s[8:9], v106, s59, v[146:147]
	v_ashrrev_i32_e32 v91, 31, v90
	v_add_u32_e32 v102, -1, v101
	v_add_u32_e32 v103, 1, v101
	v_fma_f32 v104, -v102, v101, v100
	v_fma_f32 v105, -v103, v101, v100
	v_cmp_ge_f32_e64 s[8:9], 0, v104
	v_lshl_add_u64 v[98:99], v[98:99], 0, v[120:121]
	s_nop 0
	v_cndmask_b32_e64 v101, v101, v102, s[8:9]
	v_cmp_lt_f32_e64 s[8:9], 0, v105
	s_nop 1
	v_cndmask_b32_e64 v101, v101, v103, s[8:9]
	v_mul_f32_e32 v102, 0x37800000, v101
	v_cndmask_b32_e32 v101, v101, v102, vcc
	v_cmp_class_f32_e32 vcc, v100, v157
	s_nop 1
	v_cndmask_b32_e32 v102, v101, v100, vcc
	v_div_scale_f32 v103, s[8:9], v102, v102, 1.0
	v_rcp_f32_e32 v104, v103
	v_lshl_add_u64 v[100:101], v[90:91], 2, s[14:15]
	v_div_scale_f32 v91, vcc, 1.0, v102, 1.0
	v_fma_f32 v105, -v103, v104, 1.0
	v_fmac_f32_e32 v104, v105, v104
	v_mul_f32_e32 v105, v91, v104
	v_fma_f32 v106, -v103, v105, v91
	v_fmac_f32_e32 v105, v106, v104
	v_fma_f32 v91, -v103, v105, v91
	v_div_fmas_f32 v91, v91, v104, v105
	v_div_fixup_f32 v102, v91, v102, 1.0
	v_pk_mul_f32 v[82:83], v[82:83], v[102:103] op_sel_hi:[1,0]
	v_pk_mul_f32 v[96:97], v[96:97], v[102:103] op_sel_hi:[1,0]
	v_pk_mul_f32 v[84:85], v[84:85], v[102:103] op_sel_hi:[1,0]
	v_pk_mul_f32 v[92:93], v[92:93], v[102:103] op_sel_hi:[1,0]
	v_pk_mul_f32 v[86:87], v[86:87], v[102:103] op_sel_hi:[1,0]
	v_pk_mul_f32 v[94:95], v[94:95], v[102:103] op_sel_hi:[1,0]
	v_pk_mul_f32 v[80:81], v[80:81], v[102:103] op_sel_hi:[1,0]
	v_pk_mul_f32 v[88:89], v[88:89], v[102:103] op_sel_hi:[1,0]
	v_mul_f32_e32 v108, 0xbfb8aa3b, v83
	v_mul_f32_e32 v91, 0xbfb8aa3b, v97
	v_mul_f32_e32 v102, 0xbfb8aa3b, v85
	v_mul_f32_e32 v103, 0xbfb8aa3b, v93
	v_mul_f32_e32 v104, 0xbfb8aa3b, v87
	v_mul_f32_e32 v105, 0xbfb8aa3b, v95
	v_mul_f32_e32 v106, 0xbfb8aa3b, v81
	v_mul_f32_e32 v107, 0xbfb8aa3b, v89
	v_exp_f32_e32 v108, v108
	v_exp_f32_e32 v91, v91
	v_exp_f32_e32 v102, v102
	v_exp_f32_e32 v103, v103
	v_exp_f32_e32 v104, v104
	v_exp_f32_e32 v105, v105
	v_exp_f32_e32 v106, v106
	v_exp_f32_e32 v107, v107
	v_add_f32_e32 v108, 1.0, v108
	v_add_f32_e32 v91, 1.0, v91
	v_add_f32_e32 v102, 1.0, v102
	v_add_f32_e32 v103, 1.0, v103
	v_add_f32_e32 v104, 1.0, v104
	v_add_f32_e32 v105, 1.0, v105
	v_add_f32_e32 v106, 1.0, v106
	v_add_f32_e32 v107, 1.0, v107
	v_rcp_f32_e32 v108, v108
	v_rcp_f32_e32 v91, v91
	v_rcp_f32_e32 v102, v102
	v_rcp_f32_e32 v103, v103
	v_rcp_f32_e32 v104, v104
	v_rcp_f32_e32 v105, v105
	v_rcp_f32_e32 v106, v106
	v_rcp_f32_e32 v107, v107
	v_mul_f32_e32 v83, v83, v108
	v_mul_f32_e32 v91, v97, v91
	v_mul_f32_e32 v85, v85, v102
	v_mul_f32_e32 v93, v93, v103
	v_mul_f32_e32 v87, v87, v104
	v_mul_f32_e32 v95, v95, v105
	v_mul_f32_e32 v81, v81, v106
	v_mul_f32_e32 v89, v89, v107
	v_mul_f32_e32 v83, v82, v83
	v_mul_f32_e32 v91, v96, v91
	v_mul_f32_e32 v84, v84, v85
	v_mul_f32_e32 v85, v92, v93
	v_mul_f32_e32 v86, v86, v87
	v_mul_f32_e32 v87, v94, v95
	v_mul_f32_e32 v92, v80, v81
	v_mul_f32_e32 v88, v88, v89
	v_cvt_pk_bf16_f32 v80, v91, v84
	v_cvt_pk_bf16_f32 v81, v85, v86
	v_cvt_pk_bf16_f32 v82, v87, v92
	v_cvt_pk_bf16_f32 v83, v88, v83
	global_store_dwordx4 v[98:99], v[80:83], off
	s_nop 0
	s_nop 0
	v_mov_b32_e32 v81, v68
	v_mov_b32_e32 v68, v77
	v_mov_b32_e32 v77, v70
	v_mov_b32_e32 v70, v79
	v_mov_b32_e32 v79, v64
	v_mov_b32_e32 v64, v73
	v_mov_b32_e32 v73, v66
	v_mov_b32_e32 v80, v76
	v_mov_b32_e32 v76, v78
	v_mov_b32_e32 v78, v72
	v_mov_b32_e32 v72, v74
	s_waitcnt vmcnt(7)
	v_mov_b32_e32 v82, v175
	v_fmamk_f32 v66, v82, 0x3a000000, v156
	v_mul_f32_e32 v74, 0x4f800000, v66
	v_cmp_gt_f32_e32 vcc, s60, v66
	s_nop 1
	v_cndmask_b32_e32 v82, v66, v74, vcc
	v_sqrt_f32_e32 v83, v82
	v_mov_b32_e32 v66, v75
	v_mad_i64_i32 v[74:75], s[8:9], v90, s59, v[146:147]
	v_add_u32_e32 v84, -1, v83
	v_add_u32_e32 v85, 1, v83
	v_fma_f32 v86, -v84, v83, v82
	v_fma_f32 v87, -v85, v83, v82
	v_cmp_ge_f32_e64 s[8:9], 0, v86
	v_lshl_add_u64 v[74:75], v[74:75], 0, v[120:121]
	s_nop 0
	v_cndmask_b32_e64 v83, v83, v84, s[8:9]
	v_cmp_lt_f32_e64 s[8:9], 0, v87
	s_nop 1
	v_cndmask_b32_e64 v83, v83, v85, s[8:9]
	v_mul_f32_e32 v84, 0x37800000, v83
	v_cndmask_b32_e32 v83, v83, v84, vcc
	v_cmp_class_f32_e32 vcc, v82, v157
	s_nop 1
	v_cndmask_b32_e32 v82, v83, v82, vcc
	v_div_scale_f32 v83, s[8:9], v82, v82, 1.0
	v_rcp_f32_e32 v84, v83
	v_div_scale_f32 v85, vcc, 1.0, v82, 1.0
	v_fma_f32 v86, -v83, v84, 1.0
	v_fmac_f32_e32 v84, v86, v84
	v_mul_f32_e32 v86, v85, v84
	v_fma_f32 v87, -v83, v86, v85
	v_fmac_f32_e32 v86, v87, v84
	v_fma_f32 v83, -v83, v86, v85
	v_div_fmas_f32 v83, v83, v84, v86
	v_div_fixup_f32 v82, v83, v82, 1.0
	v_pk_mul_f32 v[66:67], v[66:67], v[82:83] op_sel_hi:[1,0]
	v_pk_mul_f32 v[80:81], v[80:81], v[82:83] op_sel_hi:[1,0]
	v_pk_mul_f32 v[68:69], v[68:69], v[82:83] op_sel_hi:[1,0]
	v_pk_mul_f32 v[76:77], v[76:77], v[82:83] op_sel_hi:[1,0]
	v_pk_mul_f32 v[70:71], v[70:71], v[82:83] op_sel_hi:[1,0]
	v_pk_mul_f32 v[78:79], v[78:79], v[82:83] op_sel_hi:[1,0]
	v_pk_mul_f32 v[64:65], v[64:65], v[82:83] op_sel_hi:[1,0]
	v_pk_mul_f32 v[72:73], v[72:73], v[82:83] op_sel_hi:[1,0]
	v_mul_f32_e32 v89, 0xbfb8aa3b, v67
	v_mul_f32_e32 v82, 0xbfb8aa3b, v81
	v_mul_f32_e32 v83, 0xbfb8aa3b, v69
	v_mul_f32_e32 v84, 0xbfb8aa3b, v77
	v_mul_f32_e32 v85, 0xbfb8aa3b, v71
	v_mul_f32_e32 v86, 0xbfb8aa3b, v79
	v_mul_f32_e32 v87, 0xbfb8aa3b, v65
	v_mul_f32_e32 v88, 0xbfb8aa3b, v73
	v_exp_f32_e32 v89, v89
	v_exp_f32_e32 v82, v82
	v_exp_f32_e32 v83, v83
	v_exp_f32_e32 v84, v84
	v_exp_f32_e32 v85, v85
	v_exp_f32_e32 v86, v86
	v_exp_f32_e32 v87, v87
	v_exp_f32_e32 v88, v88
	v_add_f32_e32 v89, 1.0, v89
	v_add_f32_e32 v82, 1.0, v82
	v_add_f32_e32 v83, 1.0, v83
	v_add_f32_e32 v84, 1.0, v84
	v_add_f32_e32 v85, 1.0, v85
	v_add_f32_e32 v86, 1.0, v86
	v_add_f32_e32 v87, 1.0, v87
	v_add_f32_e32 v88, 1.0, v88
	v_rcp_f32_e32 v89, v89
	v_rcp_f32_e32 v82, v82
	v_rcp_f32_e32 v83, v83
	v_rcp_f32_e32 v84, v84
	v_rcp_f32_e32 v85, v85
	v_rcp_f32_e32 v86, v86
	v_rcp_f32_e32 v87, v87
	v_rcp_f32_e32 v88, v88
	v_mul_f32_e32 v67, v67, v89
	v_mul_f32_e32 v81, v81, v82
	v_mul_f32_e32 v69, v69, v83
	v_mul_f32_e32 v77, v77, v84
	v_mul_f32_e32 v71, v71, v85
	v_mul_f32_e32 v79, v79, v86
	v_mul_f32_e32 v65, v65, v87
	v_mul_f32_e32 v73, v73, v88
	v_mul_f32_e32 v67, v66, v67
	v_mul_f32_e32 v80, v80, v81
	v_mul_f32_e32 v68, v68, v69
	v_mul_f32_e32 v69, v76, v77
	v_mul_f32_e32 v70, v70, v71
	v_mul_f32_e32 v71, v78, v79
	v_mul_f32_e32 v76, v64, v65
	v_mul_f32_e32 v72, v72, v73
	v_cvt_pk_bf16_f32 v64, v80, v68
	v_cvt_pk_bf16_f32 v65, v69, v70
	v_cvt_pk_bf16_f32 v66, v71, v76
	v_cvt_pk_bf16_f32 v67, v72, v67
	global_store_dwordx4 v[74:75], v[64:67], off
	s_nop 0
	s_nop 0
	v_mov_b32_e32 v64, v60
	v_mov_b32_e32 v60, v62
	v_mov_b32_e32 v62, v56
	v_mov_b32_e32 v56, v58
	v_mov_b32_e32 v65, v52
	v_mov_b32_e32 v52, v61
	v_mov_b32_e32 v61, v54
	v_mov_b32_e32 v54, v63
	v_mov_b32_e32 v63, v48
	v_mov_b32_e32 v48, v57
	v_mov_b32_e32 v57, v50
	v_mov_b32_e32 v50, v59
	s_waitcnt vmcnt(7)
	v_mov_b32_e32 v66, v176
	v_fmamk_f32 v58, v66, 0x3a000000, v156
	v_mul_f32_e32 v59, 0x4f800000, v58
	v_cmp_gt_f32_e32 vcc, s60, v58
	s_nop 1
	v_cndmask_b32_e32 v66, v58, v59, vcc
	v_sqrt_f32_e32 v67, v66
	v_add_u32_e32 v58, 0x80, v144
	v_mad_i64_i32 v[58:59], s[8:9], v58, s59, v[146:147]
	v_add_u32_e32 v68, -1, v67
	v_add_u32_e32 v69, 1, v67
	v_fma_f32 v70, -v68, v67, v66
	v_fma_f32 v71, -v69, v67, v66
	v_cmp_ge_f32_e64 s[8:9], 0, v70
	v_lshl_add_u64 v[58:59], v[58:59], 0, v[120:121]
	s_nop 0
	v_cndmask_b32_e64 v67, v67, v68, s[8:9]
	v_cmp_lt_f32_e64 s[8:9], 0, v71
	s_nop 1
	v_cndmask_b32_e64 v67, v67, v69, s[8:9]
	v_mul_f32_e32 v68, 0x37800000, v67
	v_cndmask_b32_e32 v67, v67, v68, vcc
	v_cmp_class_f32_e32 vcc, v66, v157
	s_nop 1
	v_cndmask_b32_e32 v66, v67, v66, vcc
	v_div_scale_f32 v67, s[8:9], v66, v66, 1.0
	v_rcp_f32_e32 v68, v67
	v_div_scale_f32 v69, vcc, 1.0, v66, 1.0
	v_fma_f32 v70, -v67, v68, 1.0
	v_fmac_f32_e32 v68, v70, v68
	v_mul_f32_e32 v70, v69, v68
	v_fma_f32 v71, -v67, v70, v69
	v_fmac_f32_e32 v70, v71, v68
	v_fma_f32 v67, -v67, v70, v69
	v_div_fmas_f32 v67, v67, v68, v70
	v_div_fixup_f32 v66, v67, v66, 1.0
	v_pk_mul_f32 v[50:51], v[50:51], v[66:67] op_sel_hi:[1,0]
	v_pk_mul_f32 v[64:65], v[64:65], v[66:67] op_sel_hi:[1,0]
	v_pk_mul_f32 v[52:53], v[52:53], v[66:67] op_sel_hi:[1,0]
	v_pk_mul_f32 v[60:61], v[60:61], v[66:67] op_sel_hi:[1,0]
	v_pk_mul_f32 v[54:55], v[54:55], v[66:67] op_sel_hi:[1,0]
	v_pk_mul_f32 v[62:63], v[62:63], v[66:67] op_sel_hi:[1,0]
	v_pk_mul_f32 v[48:49], v[48:49], v[66:67] op_sel_hi:[1,0]
	v_pk_mul_f32 v[56:57], v[56:57], v[66:67] op_sel_hi:[1,0]
	v_mul_f32_e32 v73, 0xbfb8aa3b, v51
	v_mul_f32_e32 v66, 0xbfb8aa3b, v65
	v_mul_f32_e32 v67, 0xbfb8aa3b, v53
	v_mul_f32_e32 v68, 0xbfb8aa3b, v61
	v_mul_f32_e32 v69, 0xbfb8aa3b, v55
	v_mul_f32_e32 v70, 0xbfb8aa3b, v63
	v_mul_f32_e32 v71, 0xbfb8aa3b, v49
	v_mul_f32_e32 v72, 0xbfb8aa3b, v57
	v_exp_f32_e32 v73, v73
	v_exp_f32_e32 v66, v66
	v_exp_f32_e32 v67, v67
	v_exp_f32_e32 v68, v68
	v_exp_f32_e32 v69, v69
	v_exp_f32_e32 v70, v70
	v_exp_f32_e32 v71, v71
	v_exp_f32_e32 v72, v72
	v_add_f32_e32 v73, 1.0, v73
	v_add_f32_e32 v66, 1.0, v66
	v_add_f32_e32 v67, 1.0, v67
	v_add_f32_e32 v68, 1.0, v68
	v_add_f32_e32 v69, 1.0, v69
	v_add_f32_e32 v70, 1.0, v70
	v_add_f32_e32 v71, 1.0, v71
	v_add_f32_e32 v72, 1.0, v72
	v_rcp_f32_e32 v73, v73
	v_rcp_f32_e32 v66, v66
	v_rcp_f32_e32 v67, v67
	v_rcp_f32_e32 v68, v68
	v_rcp_f32_e32 v69, v69
	v_rcp_f32_e32 v70, v70
	v_rcp_f32_e32 v71, v71
	v_rcp_f32_e32 v72, v72
	v_mul_f32_e32 v51, v51, v73
	v_mul_f32_e32 v65, v65, v66
	v_mul_f32_e32 v53, v53, v67
	v_mul_f32_e32 v61, v61, v68
	v_mul_f32_e32 v55, v55, v69
	v_mul_f32_e32 v63, v63, v70
	v_mul_f32_e32 v49, v49, v71
	v_mul_f32_e32 v57, v57, v72
	v_mul_f32_e32 v51, v50, v51
	v_mul_f32_e32 v64, v64, v65
	v_mul_f32_e32 v52, v52, v53
	v_mul_f32_e32 v53, v60, v61
	v_mul_f32_e32 v54, v54, v55
	v_mul_f32_e32 v55, v62, v63
	v_mul_f32_e32 v60, v48, v49
	v_mul_f32_e32 v56, v56, v57
	v_cvt_pk_bf16_f32 v48, v64, v52
	v_cvt_pk_bf16_f32 v49, v53, v54
	v_cvt_pk_bf16_f32 v50, v55, v60
	v_cvt_pk_bf16_f32 v51, v56, v51
	global_store_dwordx4 v[58:59], v[48:51], off
	s_nop 0
	s_nop 0
	v_mov_b32_e32 v48, v44
	v_mov_b32_e32 v44, v46
	v_mov_b32_e32 v46, v40
	v_mov_b32_e32 v40, v42
	v_mov_b32_e32 v49, v36
	v_mov_b32_e32 v36, v45
	v_mov_b32_e32 v45, v38
	v_mov_b32_e32 v38, v47
	v_mov_b32_e32 v47, v32
	v_mov_b32_e32 v32, v41
	v_mov_b32_e32 v41, v34
	v_mov_b32_e32 v34, v43
	s_waitcnt vmcnt(7)
	v_mov_b32_e32 v50, v177
	v_fmamk_f32 v42, v50, 0x3a000000, v156
	v_mul_f32_e32 v43, 0x4f800000, v42
	v_cmp_gt_f32_e32 vcc, s60, v42
	s_nop 1
	v_cndmask_b32_e32 v50, v42, v43, vcc
	v_sqrt_f32_e32 v51, v50
	v_add_u32_e32 v42, 0x90, v144
	v_mad_i64_i32 v[42:43], s[8:9], v42, s59, v[146:147]
	v_add_u32_e32 v52, -1, v51
	v_add_u32_e32 v53, 1, v51
	v_fma_f32 v54, -v52, v51, v50
	v_fma_f32 v55, -v53, v51, v50
	v_cmp_ge_f32_e64 s[8:9], 0, v54
	v_lshl_add_u64 v[42:43], v[42:43], 0, v[120:121]
	s_nop 0
	v_cndmask_b32_e64 v51, v51, v52, s[8:9]
	v_cmp_lt_f32_e64 s[8:9], 0, v55
	s_nop 1
	v_cndmask_b32_e64 v51, v51, v53, s[8:9]
	v_mul_f32_e32 v52, 0x37800000, v51
	v_cndmask_b32_e32 v51, v51, v52, vcc
	v_cmp_class_f32_e32 vcc, v50, v157
	s_nop 1
	v_cndmask_b32_e32 v50, v51, v50, vcc
	v_div_scale_f32 v51, s[8:9], v50, v50, 1.0
	v_rcp_f32_e32 v52, v51
	v_div_scale_f32 v53, vcc, 1.0, v50, 1.0
	v_fma_f32 v54, -v51, v52, 1.0
	v_fmac_f32_e32 v52, v54, v52
	v_mul_f32_e32 v54, v53, v52
	v_fma_f32 v55, -v51, v54, v53
	v_fmac_f32_e32 v54, v55, v52
	v_fma_f32 v51, -v51, v54, v53
	v_div_fmas_f32 v51, v51, v52, v54
	v_div_fixup_f32 v50, v51, v50, 1.0
	v_pk_mul_f32 v[34:35], v[34:35], v[50:51] op_sel_hi:[1,0]
	v_pk_mul_f32 v[48:49], v[48:49], v[50:51] op_sel_hi:[1,0]
	v_pk_mul_f32 v[36:37], v[36:37], v[50:51] op_sel_hi:[1,0]
	v_pk_mul_f32 v[44:45], v[44:45], v[50:51] op_sel_hi:[1,0]
	v_pk_mul_f32 v[38:39], v[38:39], v[50:51] op_sel_hi:[1,0]
	v_pk_mul_f32 v[46:47], v[46:47], v[50:51] op_sel_hi:[1,0]
	v_pk_mul_f32 v[32:33], v[32:33], v[50:51] op_sel_hi:[1,0]
	v_pk_mul_f32 v[40:41], v[40:41], v[50:51] op_sel_hi:[1,0]
	v_mul_f32_e32 v57, 0xbfb8aa3b, v35
	v_mul_f32_e32 v50, 0xbfb8aa3b, v49
	v_mul_f32_e32 v51, 0xbfb8aa3b, v37
	v_mul_f32_e32 v52, 0xbfb8aa3b, v45
	v_mul_f32_e32 v53, 0xbfb8aa3b, v39
	v_mul_f32_e32 v54, 0xbfb8aa3b, v47
	v_mul_f32_e32 v55, 0xbfb8aa3b, v33
	v_mul_f32_e32 v56, 0xbfb8aa3b, v41
	v_exp_f32_e32 v57, v57
	v_exp_f32_e32 v50, v50
	v_exp_f32_e32 v51, v51
	v_exp_f32_e32 v52, v52
	v_exp_f32_e32 v53, v53
	v_exp_f32_e32 v54, v54
	v_exp_f32_e32 v55, v55
	v_exp_f32_e32 v56, v56
	v_add_f32_e32 v57, 1.0, v57
	v_add_f32_e32 v50, 1.0, v50
	v_add_f32_e32 v51, 1.0, v51
	v_add_f32_e32 v52, 1.0, v52
	v_add_f32_e32 v53, 1.0, v53
	v_add_f32_e32 v54, 1.0, v54
	v_add_f32_e32 v55, 1.0, v55
	v_add_f32_e32 v56, 1.0, v56
	v_rcp_f32_e32 v57, v57
	v_rcp_f32_e32 v50, v50
	v_rcp_f32_e32 v51, v51
	v_rcp_f32_e32 v52, v52
	v_rcp_f32_e32 v53, v53
	v_rcp_f32_e32 v54, v54
	v_rcp_f32_e32 v55, v55
	v_rcp_f32_e32 v56, v56
	v_mul_f32_e32 v35, v35, v57
	v_mul_f32_e32 v49, v49, v50
	v_mul_f32_e32 v37, v37, v51
	v_mul_f32_e32 v45, v45, v52
	v_mul_f32_e32 v39, v39, v53
	v_mul_f32_e32 v47, v47, v54
	v_mul_f32_e32 v33, v33, v55
	v_mul_f32_e32 v41, v41, v56
	v_mul_f32_e32 v35, v34, v35
	v_mul_f32_e32 v48, v48, v49
	v_mul_f32_e32 v36, v36, v37
	v_mul_f32_e32 v37, v44, v45
	v_mul_f32_e32 v38, v38, v39
	v_mul_f32_e32 v39, v46, v47
	v_mul_f32_e32 v44, v32, v33
	v_mul_f32_e32 v40, v40, v41
	v_cvt_pk_bf16_f32 v32, v48, v36
	v_cvt_pk_bf16_f32 v33, v37, v38
	v_cvt_pk_bf16_f32 v34, v39, v44
	v_cvt_pk_bf16_f32 v35, v40, v35
	global_store_dwordx4 v[42:43], v[32:35], off
	s_nop 0
	s_nop 0
	v_mov_b32_e32 v32, v28
	v_mov_b32_e32 v28, v30
	v_mov_b32_e32 v30, v24
	v_mov_b32_e32 v24, v26
	v_mov_b32_e32 v33, v20
	v_mov_b32_e32 v20, v29
	v_mov_b32_e32 v29, v22
	v_mov_b32_e32 v22, v31
	v_mov_b32_e32 v31, v16
	v_mov_b32_e32 v16, v25
	v_mov_b32_e32 v25, v18
	v_mov_b32_e32 v18, v27
	s_waitcnt vmcnt(7)
	v_mov_b32_e32 v34, v178
	v_fmamk_f32 v26, v34, 0x3a000000, v156
	v_mul_f32_e32 v27, 0x4f800000, v26
	v_cmp_gt_f32_e32 vcc, s60, v26
	s_nop 1
	v_cndmask_b32_e32 v34, v26, v27, vcc
	v_sqrt_f32_e32 v35, v34
	v_add_u32_e32 v26, 0xa0, v144
	v_mad_i64_i32 v[26:27], s[8:9], v26, s59, v[146:147]
	v_add_u32_e32 v36, -1, v35
	v_add_u32_e32 v37, 1, v35
	v_fma_f32 v38, -v36, v35, v34
	v_fma_f32 v39, -v37, v35, v34
	v_cmp_ge_f32_e64 s[8:9], 0, v38
	v_lshl_add_u64 v[26:27], v[26:27], 0, v[120:121]
	s_nop 0
	v_cndmask_b32_e64 v35, v35, v36, s[8:9]
	v_cmp_lt_f32_e64 s[8:9], 0, v39
	s_nop 1
	v_cndmask_b32_e64 v35, v35, v37, s[8:9]
	v_mul_f32_e32 v36, 0x37800000, v35
	v_cndmask_b32_e32 v35, v35, v36, vcc
	v_cmp_class_f32_e32 vcc, v34, v157
	s_nop 1
	v_cndmask_b32_e32 v34, v35, v34, vcc
	v_div_scale_f32 v35, s[8:9], v34, v34, 1.0
	v_rcp_f32_e32 v36, v35
	v_div_scale_f32 v37, vcc, 1.0, v34, 1.0
	v_fma_f32 v38, -v35, v36, 1.0
	v_fmac_f32_e32 v36, v38, v36
	v_mul_f32_e32 v38, v37, v36
	v_fma_f32 v39, -v35, v38, v37
	v_fmac_f32_e32 v38, v39, v36
	v_fma_f32 v35, -v35, v38, v37
	v_div_fmas_f32 v35, v35, v36, v38
	v_div_fixup_f32 v34, v35, v34, 1.0
	v_pk_mul_f32 v[18:19], v[18:19], v[34:35] op_sel_hi:[1,0]
	v_pk_mul_f32 v[32:33], v[32:33], v[34:35] op_sel_hi:[1,0]
	v_pk_mul_f32 v[20:21], v[20:21], v[34:35] op_sel_hi:[1,0]
	v_pk_mul_f32 v[28:29], v[28:29], v[34:35] op_sel_hi:[1,0]
	v_pk_mul_f32 v[22:23], v[22:23], v[34:35] op_sel_hi:[1,0]
	v_pk_mul_f32 v[30:31], v[30:31], v[34:35] op_sel_hi:[1,0]
	v_pk_mul_f32 v[16:17], v[16:17], v[34:35] op_sel_hi:[1,0]
	v_pk_mul_f32 v[24:25], v[24:25], v[34:35] op_sel_hi:[1,0]
	v_mul_f32_e32 v41, 0xbfb8aa3b, v19
	v_mul_f32_e32 v34, 0xbfb8aa3b, v33
	v_mul_f32_e32 v35, 0xbfb8aa3b, v21
	v_mul_f32_e32 v36, 0xbfb8aa3b, v29
	v_mul_f32_e32 v37, 0xbfb8aa3b, v23
	v_mul_f32_e32 v38, 0xbfb8aa3b, v31
	v_mul_f32_e32 v39, 0xbfb8aa3b, v17
	v_mul_f32_e32 v40, 0xbfb8aa3b, v25
	v_exp_f32_e32 v41, v41
	v_exp_f32_e32 v34, v34
	v_exp_f32_e32 v35, v35
	v_exp_f32_e32 v36, v36
	v_exp_f32_e32 v37, v37
	v_exp_f32_e32 v38, v38
	v_exp_f32_e32 v39, v39
	v_exp_f32_e32 v40, v40
	v_add_f32_e32 v41, 1.0, v41
	v_add_f32_e32 v34, 1.0, v34
	v_add_f32_e32 v35, 1.0, v35
	v_add_f32_e32 v36, 1.0, v36
	v_add_f32_e32 v37, 1.0, v37
	v_add_f32_e32 v38, 1.0, v38
	v_add_f32_e32 v39, 1.0, v39
	v_add_f32_e32 v40, 1.0, v40
	v_rcp_f32_e32 v41, v41
	v_rcp_f32_e32 v34, v34
	v_rcp_f32_e32 v35, v35
	v_rcp_f32_e32 v36, v36
	v_rcp_f32_e32 v37, v37
	v_rcp_f32_e32 v38, v38
	v_rcp_f32_e32 v39, v39
	v_rcp_f32_e32 v40, v40
	v_mul_f32_e32 v19, v19, v41
	v_mul_f32_e32 v33, v33, v34
	v_mul_f32_e32 v21, v21, v35
	v_mul_f32_e32 v29, v29, v36
	v_mul_f32_e32 v23, v23, v37
	v_mul_f32_e32 v31, v31, v38
	v_mul_f32_e32 v17, v17, v39
	v_mul_f32_e32 v25, v25, v40
	v_mul_f32_e32 v19, v18, v19
	v_mul_f32_e32 v32, v32, v33
	v_mul_f32_e32 v20, v20, v21
	v_mul_f32_e32 v21, v28, v29
	v_mul_f32_e32 v22, v22, v23
	v_mul_f32_e32 v23, v30, v31
	v_mul_f32_e32 v28, v16, v17
	v_mul_f32_e32 v24, v24, v25
	v_cvt_pk_bf16_f32 v16, v32, v20
	v_cvt_pk_bf16_f32 v17, v21, v22
	v_cvt_pk_bf16_f32 v18, v23, v28
	v_cvt_pk_bf16_f32 v19, v24, v19
	global_store_dwordx4 v[26:27], v[16:19], off
	s_nop 0
	s_nop 0
	v_mov_b32_e32 v17, v4
	v_mov_b32_e32 v4, v13
	v_mov_b32_e32 v13, v6
	v_mov_b32_e32 v6, v15
	v_mov_b32_e32 v15, v0
	v_mov_b32_e32 v0, v9
	v_mov_b32_e32 v9, v2
	v_mov_b32_e32 v2, v11
	v_mov_b32_e32 v16, v12
	v_mov_b32_e32 v12, v14
	v_mov_b32_e32 v14, v8
	v_mov_b32_e32 v8, v10
	v_add_u32_e32 v10, 0xb0, v144
	s_waitcnt vmcnt(7)
	v_mov_b32_e32 v18, v179
	v_fmamk_f32 v11, v18, 0x3a000000, v156
	v_mul_f32_e32 v18, 0x4f800000, v11
	v_cmp_gt_f32_e32 vcc, s60, v11
	s_nop 1
	v_cndmask_b32_e32 v18, v11, v18, vcc
	v_sqrt_f32_e32 v19, v18
	v_mad_i64_i32 v[10:11], s[8:9], v10, s59, v[146:147]
	v_lshl_add_u64 v[10:11], v[10:11], 0, v[120:121]
	v_add_u32_e32 v20, -1, v19
	v_add_u32_e32 v21, 1, v19
	v_fma_f32 v22, -v20, v19, v18
	v_fma_f32 v23, -v21, v19, v18
	v_cmp_ge_f32_e64 s[8:9], 0, v22
	s_nop 1
	v_cndmask_b32_e64 v19, v19, v20, s[8:9]
	v_cmp_lt_f32_e64 s[8:9], 0, v23
	s_nop 1
	v_cndmask_b32_e64 v19, v19, v21, s[8:9]
	v_mul_f32_e32 v20, 0x37800000, v19
	v_cndmask_b32_e32 v19, v19, v20, vcc
	v_cmp_class_f32_e32 vcc, v18, v157
	s_nop 1
	v_cndmask_b32_e32 v18, v19, v18, vcc
	v_div_scale_f32 v19, s[8:9], v18, v18, 1.0
	v_rcp_f32_e32 v20, v19
	v_div_scale_f32 v21, vcc, 1.0, v18, 1.0
	v_fma_f32 v22, -v19, v20, 1.0
	v_fmac_f32_e32 v20, v22, v20
	v_mul_f32_e32 v22, v21, v20
	v_fma_f32 v23, -v19, v22, v21
	v_fmac_f32_e32 v22, v23, v20
	v_fma_f32 v19, -v19, v22, v21
	v_div_fmas_f32 v19, v19, v20, v22
	v_div_fixup_f32 v18, v19, v18, 1.0
	v_pk_mul_f32 v[2:3], v[2:3], v[18:19] op_sel_hi:[1,0]
	v_pk_mul_f32 v[16:17], v[16:17], v[18:19] op_sel_hi:[1,0]
	v_pk_mul_f32 v[4:5], v[4:5], v[18:19] op_sel_hi:[1,0]
	v_pk_mul_f32 v[12:13], v[12:13], v[18:19] op_sel_hi:[1,0]
	v_pk_mul_f32 v[6:7], v[6:7], v[18:19] op_sel_hi:[1,0]
	v_pk_mul_f32 v[14:15], v[14:15], v[18:19] op_sel_hi:[1,0]
	v_pk_mul_f32 v[0:1], v[0:1], v[18:19] op_sel_hi:[1,0]
	v_pk_mul_f32 v[8:9], v[8:9], v[18:19] op_sel_hi:[1,0]
	v_mul_f32_e32 v25, 0xbfb8aa3b, v3
	v_mul_f32_e32 v18, 0xbfb8aa3b, v17
	v_mul_f32_e32 v19, 0xbfb8aa3b, v5
	v_mul_f32_e32 v20, 0xbfb8aa3b, v13
	v_mul_f32_e32 v21, 0xbfb8aa3b, v7
	v_mul_f32_e32 v22, 0xbfb8aa3b, v15
	v_mul_f32_e32 v23, 0xbfb8aa3b, v1
	v_mul_f32_e32 v24, 0xbfb8aa3b, v9
	v_exp_f32_e32 v25, v25
	v_exp_f32_e32 v18, v18
	v_exp_f32_e32 v19, v19
	v_exp_f32_e32 v20, v20
	v_exp_f32_e32 v21, v21
	v_exp_f32_e32 v22, v22
	v_exp_f32_e32 v23, v23
	v_exp_f32_e32 v24, v24
	v_add_f32_e32 v25, 1.0, v25
	v_add_f32_e32 v18, 1.0, v18
	v_add_f32_e32 v19, 1.0, v19
	v_add_f32_e32 v20, 1.0, v20
	v_add_f32_e32 v21, 1.0, v21
	v_add_f32_e32 v22, 1.0, v22
	v_add_f32_e32 v23, 1.0, v23
	v_add_f32_e32 v24, 1.0, v24
	v_rcp_f32_e32 v25, v25
	v_rcp_f32_e32 v18, v18
	v_rcp_f32_e32 v19, v19
	v_rcp_f32_e32 v20, v20
	v_rcp_f32_e32 v21, v21
	v_rcp_f32_e32 v22, v22
	v_rcp_f32_e32 v23, v23
	v_rcp_f32_e32 v24, v24
	v_mul_f32_e32 v3, v3, v25
	s_andn2_b64 vcc, exec, s[6:7]
	v_mul_f32_e32 v17, v17, v18
	v_mul_f32_e32 v5, v5, v19
	v_mul_f32_e32 v13, v13, v20
	v_mul_f32_e32 v7, v7, v21
	v_mul_f32_e32 v15, v15, v22
	v_mul_f32_e32 v1, v1, v23
	v_mul_f32_e32 v9, v9, v24
	v_mul_f32_e32 v3, v2, v3
	s_mov_b64 s[6:7], -1
	v_mul_f32_e32 v16, v16, v17
	v_mul_f32_e32 v4, v4, v5
	v_mul_f32_e32 v5, v12, v13
	v_mul_f32_e32 v6, v6, v7
	v_mul_f32_e32 v7, v14, v15
	v_mul_f32_e32 v12, v0, v1
	v_mul_f32_e32 v8, v8, v9
	v_cvt_pk_bf16_f32 v0, v16, v4
	v_cvt_pk_bf16_f32 v1, v5, v6
	v_cvt_pk_bf16_f32 v2, v7, v12
	v_cvt_pk_bf16_f32 v3, v8, v3
	global_store_dwordx4 v[10:11], v[0:3], off
	s_cbranch_vccnz .LBB0_1500
	s_andn2_b64 vcc, exec, s[10:11]
	s_cbranch_vccnz .LBB0_1499
	s_barrier
	s_branch .LBB0_1499

.LBB0_1536:
	s_or_saveexec_b64 s[24:25], s[22:23]
	v_mov_b32_e32 v33, v32
	v_mov_b32_e32 v34, v32
	v_mov_b32_e32 v35, v32
	v_mov_b64_e32 v[58:59], v[34:35]
	v_mov_b64_e32 v[54:55], v[34:35]
	v_mov_b64_e32 v[50:51], v[34:35]
	v_mov_b64_e32 v[46:47], v[34:35]
	v_mov_b64_e32 v[42:43], v[34:35]
	v_mov_b64_e32 v[38:39], v[34:35]
	v_mov_b64_e32 v[28:29], v[32:33]
	v_mov_b64_e32 v[24:25], v[32:33]
	v_mov_b64_e32 v[20:21], v[32:33]
	v_mov_b64_e32 v[16:17], v[32:33]
	v_mov_b64_e32 v[12:13], v[32:33]
	v_mov_b64_e32 v[8:9], v[32:33]
	v_mov_b64_e32 v[4:5], v[32:33]
	v_mov_b64_e32 v[0:1], v[32:33]
	s_waitcnt vmcnt(2)
	v_mov_b64_e32 v[62:63], v[34:35]
	s_add_i32 s22, s30, s29
	v_mov_b64_e32 v[56:57], v[32:33]
	v_mov_b64_e32 v[52:53], v[32:33]
	v_mov_b64_e32 v[48:49], v[32:33]
	v_mov_b64_e32 v[44:45], v[32:33]
	v_mov_b64_e32 v[40:41], v[32:33]
	v_mov_b64_e32 v[36:37], v[32:33]
	v_mov_b64_e32 v[30:31], v[34:35]
	v_mov_b64_e32 v[26:27], v[34:35]
	v_mov_b64_e32 v[22:23], v[34:35]
	v_mov_b64_e32 v[18:19], v[34:35]
	v_mov_b64_e32 v[14:15], v[34:35]
	v_mov_b64_e32 v[10:11], v[34:35]
	v_mov_b64_e32 v[6:7], v[34:35]
	v_mov_b64_e32 v[2:3], v[34:35]
	v_mov_b64_e32 v[60:61], v[32:33]
	s_xor_b64 exec, exec, s[24:25]
	s_cbranch_execz .LBB0_1538
	s_mul_i32 s23, s14, s21
	s_mul_hi_u32 s28, s14, s20
	s_add_i32 s23, s28, s23
	s_mul_i32 s15, s15, s20
	s_add_i32 s29, s23, s15
	s_mul_i32 s28, s14, s20
	s_lshl_b64 s[28:29], s[28:29], 2
	s_waitcnt lgkmcnt(0)
	s_add_u32 s15, s16, s28
	s_addc_u32 s28, s17, s29
	s_ashr_i32 s23, s22, 31
	v_lshrrev_b32_e32 v130, 3, v131
	s_lshl_b64 s[16:17], s[22:23], 2
	v_and_b32_e32 v132, 6, v130
	s_add_u32 s16, s15, s16
	v_mul_u32_u24_e32 v0, s14, v132
	s_addc_u32 s17, s28, s17
	v_mov_b32_e32 v33, 0
	v_lshlrev_b32_e32 v32, 2, v0
	v_lshl_add_u64 v[0:1], s[16:17], 0, v[32:33]
	v_lshlrev_b32_e32 v32, 2, v128
	v_or_b32_e32 v134, 1, v130
	v_lshl_add_u64 v[8:9], v[0:1], 0, v[32:33]
	v_mul_u32_u24_e32 v0, s14, v134
	v_lshlrev_b32_e32 v0, 2, v0
	v_mov_b32_e32 v1, v33
	v_lshl_add_u64 v[0:1], s[16:17], 0, v[0:1]
	v_or_b32_e32 v136, 8, v132
	v_lshl_add_u64 v[10:11], v[0:1], 0, v[32:33]
	global_load_dwordx4 v[0:3], v[8:9], off nt
	global_load_dwordx4 v[4:7], v[10:11], off nt
	v_mul_u32_u24_e32 v8, s14, v136
	v_lshlrev_b32_e32 v8, 2, v8
	v_mov_b32_e32 v9, v33
	v_lshl_add_u64 v[8:9], s[16:17], 0, v[8:9]
	v_or_b32_e32 v138, 9, v130
	v_lshl_add_u64 v[16:17], v[8:9], 0, v[32:33]
	v_mul_u32_u24_e32 v8, s14, v138
	v_lshlrev_b32_e32 v8, 2, v8
	v_mov_b32_e32 v9, v33
	v_lshl_add_u64 v[8:9], s[16:17], 0, v[8:9]
	v_or_b32_e32 v140, 16, v132
	v_lshl_add_u64 v[18:19], v[8:9], 0, v[32:33]
	global_load_dwordx4 v[8:11], v[16:17], off nt
	global_load_dwordx4 v[12:15], v[18:19], off nt
	v_mul_u32_u24_e32 v16, s14, v140
	v_lshlrev_b32_e32 v16, 2, v16
	v_mov_b32_e32 v17, v33
	v_lshl_add_u64 v[16:17], s[16:17], 0, v[16:17]
	v_or_b32_e32 v142, 17, v130
	v_lshl_add_u64 v[24:25], v[16:17], 0, v[32:33]
	v_mul_u32_u24_e32 v16, s14, v142
	v_lshlrev_b32_e32 v16, 2, v16
	v_mov_b32_e32 v17, v33
	v_lshl_add_u64 v[16:17], s[16:17], 0, v[16:17]
	v_or_b32_e32 v144, 24, v132
	v_lshl_add_u64 v[26:27], v[16:17], 0, v[32:33]
	global_load_dwordx4 v[16:19], v[24:25], off nt
	global_load_dwordx4 v[20:23], v[26:27], off nt
	v_mul_u32_u24_e32 v24, s14, v144
	v_lshlrev_b32_e32 v24, 2, v24
	v_mov_b32_e32 v25, v33
	v_lshl_add_u64 v[24:25], s[16:17], 0, v[24:25]
	v_or_b32_e32 v146, 25, v130
	v_lshl_add_u64 v[34:35], v[24:25], 0, v[32:33]
	v_mul_u32_u24_e32 v24, s14, v146
	v_lshlrev_b32_e32 v24, 2, v24
	v_mov_b32_e32 v25, v33
	v_lshl_add_u64 v[24:25], s[16:17], 0, v[24:25]
	v_or_b32_e32 v148, 32, v132
	v_lshl_add_u64 v[36:37], v[24:25], 0, v[32:33]
	global_load_dwordx4 v[24:27], v[34:35], off nt
	global_load_dwordx4 v[28:31], v[36:37], off nt
	v_mul_u32_u24_e32 v34, s14, v148
	v_or_b32_e32 v150, 33, v130
	v_lshlrev_b32_e32 v34, 2, v34
	v_mov_b32_e32 v35, v33
	v_mul_u32_u24_e32 v36, s14, v150
	v_lshl_add_u64 v[34:35], s[16:17], 0, v[34:35]
	v_lshlrev_b32_e32 v36, 2, v36
	v_mov_b32_e32 v37, v33
	v_lshl_add_u64 v[34:35], v[34:35], 0, v[32:33]
	v_lshl_add_u64 v[36:37], s[16:17], 0, v[36:37]
	v_or_b32_e32 v152, 40, v132
	v_lshl_add_u64 v[44:45], v[36:37], 0, v[32:33]
	global_load_dwordx4 v[36:39], v[34:35], off nt
	global_load_dwordx4 v[40:43], v[44:45], off nt
	v_mul_u32_u24_e32 v34, s14, v152
	v_or_b32_e32 v154, 41, v130
	v_lshlrev_b32_e32 v34, 2, v34
	v_mov_b32_e32 v35, v33
	v_mul_u32_u24_e32 v44, s14, v154
	v_lshl_add_u64 v[34:35], s[16:17], 0, v[34:35]
	v_lshlrev_b32_e32 v44, 2, v44
	v_mov_b32_e32 v45, v33
	v_lshl_add_u64 v[34:35], v[34:35], 0, v[32:33]
	v_lshl_add_u64 v[44:45], s[16:17], 0, v[44:45]
	v_or_b32_e32 v156, 48, v132
	v_lshl_add_u64 v[52:53], v[44:45], 0, v[32:33]
	global_load_dwordx4 v[44:47], v[34:35], off nt
	global_load_dwordx4 v[48:51], v[52:53], off nt
	v_mul_u32_u24_e32 v34, s14, v156
	v_or_b32_e32 v158, 49, v130
	v_lshlrev_b32_e32 v34, 2, v34
	v_mov_b32_e32 v35, v33
	v_mul_u32_u24_e32 v52, s14, v158
	v_lshl_add_u64 v[34:35], s[16:17], 0, v[34:35]
	v_lshlrev_b32_e32 v52, 2, v52
	v_mov_b32_e32 v53, v33
	v_lshl_add_u64 v[34:35], v[34:35], 0, v[32:33]
	v_lshl_add_u64 v[52:53], s[16:17], 0, v[52:53]
	v_or_b32_e32 v160, 56, v132
	v_lshl_add_u64 v[60:61], v[52:53], 0, v[32:33]
	global_load_dwordx4 v[52:55], v[34:35], off nt
	global_load_dwordx4 v[56:59], v[60:61], off nt
	v_mul_u32_u24_e32 v34, s14, v160
	v_lshlrev_b32_e32 v34, 2, v34
	v_mov_b32_e32 v35, v33
	v_lshl_add_u64 v[34:35], s[16:17], 0, v[34:35]
	v_or_b32_e32 v162, 57, v130
	v_lshl_add_u64 v[64:65], v[34:35], 0, v[32:33]
	v_mul_u32_u24_e32 v34, s14, v162
	v_lshlrev_b32_e32 v34, 2, v34
	v_mov_b32_e32 v35, v33
	v_lshl_add_u64 v[34:35], s[16:17], 0, v[34:35]
	v_lshl_add_u64 v[66:67], v[34:35], 0, v[32:33]
	global_load_dwordx4 v[32:35], v[64:65], off nt
	global_load_dwordx4 v[60:63], v[66:67], off nt

.LBB0_1584:
	s_waitcnt lgkmcnt(0)
	s_add_u32 s24, s12, s22
	s_addc_u32 s25, s13, s23
	s_add_i32 s28, s28, s42
	s_cmpk_lt_i32 s28, 0x400
	s_cselect_b64 s[22:23], -1, 0
	s_lshl_b32 s30, s29, 6
	s_ashr_i32 s31, s30, 31
	s_lshl_b64 s[12:13], s[30:31], 2
	s_add_u32 s12, s14, s12
	s_addc_u32 s13, s15, s13
	s_cmp_lg_u64 s[14:15], 0
	s_cselect_b32 s13, s13, 0
	s_cselect_b32 s12, s12, 0
	s_ashr_i32 s29, s43, 31
	s_and_b64 s[14:15], s[26:27], exec
	s_cselect_b32 s14, 0, s43
	s_cselect_b32 s15, 0, s29
	s_mul_i32 s15, s15, s38
	s_mul_hi_u32 s26, s14, s38
	s_add_i32 s15, s26, s15
	s_mul_i32 s14, s14, s38
	s_lshl_b64 s[14:15], s[14:15], 1
	s_add_u32 s24, s24, s14
	s_addc_u32 s25, s25, s15
	s_lshl_b64 s[14:15], s[30:31], 1
	s_add_u32 s14, s24, s14
	s_addc_u32 s15, s25, s15
	v_cmp_gt_u32_e32 vcc, s40, v128
	v_mov_b32_e32 v67, 0
	v_mov_b32_e32 v66, 0
	v_mov_b32_e32 v65, 0
	v_mov_b32_e32 v64, 0
	v_mov_b32_e32 v71, 0
	v_mov_b32_e32 v70, 0
	v_mov_b32_e32 v69, 0
	v_mov_b32_e32 v68, 0
	v_mov_b32_e32 v75, 0
	v_mov_b32_e32 v74, 0
	v_mov_b32_e32 v73, 0
	v_mov_b32_e32 v72, 0
	v_mov_b32_e32 v79, 0
	v_mov_b32_e32 v78, 0
	v_mov_b32_e32 v77, 0
	v_mov_b32_e32 v76, 0
	v_mov_b32_e32 v83, 0
	v_mov_b32_e32 v82, 0
	v_mov_b32_e32 v81, 0
	v_mov_b32_e32 v80, 0
	v_mov_b32_e32 v87, 0
	v_mov_b32_e32 v86, 0
	v_mov_b32_e32 v85, 0
	v_mov_b32_e32 v84, 0
	v_mov_b32_e32 v91, 0
	v_mov_b32_e32 v90, 0
	v_mov_b32_e32 v89, 0
	v_mov_b32_e32 v88, 0
	v_mov_b32_e32 v95, 0
	v_mov_b32_e32 v94, 0
	v_mov_b32_e32 v93, 0
	v_mov_b32_e32 v92, 0
	v_mov_b32_e32 v99, 0
	v_mov_b32_e32 v98, 0
	v_mov_b32_e32 v97, 0
	v_mov_b32_e32 v96, 0
	v_mov_b32_e32 v103, 0
	v_mov_b32_e32 v102, 0
	v_mov_b32_e32 v101, 0
	v_mov_b32_e32 v100, 0
	v_mov_b32_e32 v107, 0
	v_mov_b32_e32 v106, 0
	v_mov_b32_e32 v105, 0
	v_mov_b32_e32 v104, 0
	v_mov_b32_e32 v111, 0
	v_mov_b32_e32 v110, 0
	v_mov_b32_e32 v109, 0
	v_mov_b32_e32 v108, 0
	v_mov_b32_e32 v115, 0
	v_mov_b32_e32 v114, 0
	v_mov_b32_e32 v113, 0
	v_mov_b32_e32 v112, 0
	v_mov_b32_e32 v119, 0
	v_mov_b32_e32 v118, 0
	v_mov_b32_e32 v117, 0
	v_mov_b32_e32 v116, 0
	v_mov_b32_e32 v123, 0
	v_mov_b32_e32 v122, 0
	v_mov_b32_e32 v121, 0
	v_mov_b32_e32 v120, 0
	v_mov_b32_e32 v127, 0
	v_mov_b32_e32 v126, 0
	v_mov_b32_e32 v125, 0
	v_mov_b32_e32 v124, 0
	s_and_saveexec_b64 s[24:25], vcc
	s_cbranch_execz .LBB0_1586
	s_mul_i32 s26, s20, s31
	s_mul_hi_u32 s27, s20, s30
	s_add_i32 s26, s27, s26
	s_mul_i32 s21, s21, s30
	s_add_i32 s27, s26, s21
	s_mul_i32 s26, s20, s30
	s_lshl_b64 s[26:27], s[26:27], 2
	s_add_u32 s21, s18, s26
	s_addc_u32 s26, s19, s27
	s_ashr_i32 s29, s28, 31
	s_lshl_b64 s[18:19], s[28:29], 2
	s_add_u32 s18, s21, s18
	s_addc_u32 s19, s26, s19
	v_mul_hi_i32_i24_e32 v65, s20, v132
	v_mul_i32_i24_e32 v64, s20, v132
	v_lshl_add_u64 v[64:65], v[64:65], 2, s[18:19]
	v_lshlrev_b32_e32 v120, 2, v128
	v_mov_b32_e32 v121, v167
	v_lshl_add_u64 v[72:73], v[64:65], 0, v[120:121]
	v_mul_hi_i32_i24_e32 v65, s20, v134
	v_mul_i32_i24_e32 v64, s20, v134
	v_lshl_add_u64 v[64:65], v[64:65], 2, s[18:19]
	v_lshl_add_u64 v[74:75], v[64:65], 0, v[120:121]
	global_load_dwordx4 v[64:67], v[72:73], off nt
	global_load_dwordx4 v[68:71], v[74:75], off nt
	v_mul_hi_i32_i24_e32 v73, s20, v136
	v_mul_i32_i24_e32 v72, s20, v136
	v_mul_hi_i32_i24_e32 v75, s20, v138
	v_mul_i32_i24_e32 v74, s20, v138
	v_mul_hi_i32_i24_e32 v81, s20, v140
	v_mul_i32_i24_e32 v80, s20, v140
	v_mul_hi_i32_i24_e32 v83, s20, v142
	v_mul_i32_i24_e32 v82, s20, v142
	v_mul_hi_i32_i24_e32 v89, s20, v144
	v_mul_i32_i24_e32 v88, s20, v144
	v_mul_hi_i32_i24_e32 v91, s20, v146
	v_mul_i32_i24_e32 v90, s20, v146
	v_mul_hi_i32_i24_e32 v97, s20, v148
	v_mul_i32_i24_e32 v96, s20, v148
	v_mul_hi_i32_i24_e32 v99, s20, v150
	v_mul_i32_i24_e32 v98, s20, v150
	v_mul_hi_i32_i24_e32 v105, s20, v152
	v_mul_i32_i24_e32 v104, s20, v152
	v_mul_hi_i32_i24_e32 v107, s20, v154
	v_mul_i32_i24_e32 v106, s20, v154
	v_mul_hi_i32_i24_e32 v113, s20, v156
	v_mul_i32_i24_e32 v112, s20, v156
	v_mul_hi_i32_i24_e32 v115, s20, v158
	v_mul_i32_i24_e32 v114, s20, v158
	v_mul_hi_i32_i24_e32 v123, s20, v160
	v_mul_i32_i24_e32 v122, s20, v160
	v_mul_hi_i32_i24_e32 v125, s20, v162
	v_mul_i32_i24_e32 v124, s20, v162
	v_lshl_add_u64 v[72:73], v[72:73], 2, s[18:19]
	v_lshl_add_u64 v[74:75], v[74:75], 2, s[18:19]
	v_lshl_add_u64 v[80:81], v[80:81], 2, s[18:19]
	v_lshl_add_u64 v[82:83], v[82:83], 2, s[18:19]
	v_lshl_add_u64 v[88:89], v[88:89], 2, s[18:19]
	v_lshl_add_u64 v[90:91], v[90:91], 2, s[18:19]
	v_lshl_add_u64 v[96:97], v[96:97], 2, s[18:19]
	v_lshl_add_u64 v[98:99], v[98:99], 2, s[18:19]
	v_lshl_add_u64 v[104:105], v[104:105], 2, s[18:19]
	v_lshl_add_u64 v[106:107], v[106:107], 2, s[18:19]
	v_lshl_add_u64 v[112:113], v[112:113], 2, s[18:19]
	v_lshl_add_u64 v[114:115], v[114:115], 2, s[18:19]
	v_lshl_add_u64 v[122:123], v[122:123], 2, s[18:19]
	v_lshl_add_u64 v[124:125], v[124:125], 2, s[18:19]
	v_lshl_add_u64 v[72:73], v[72:73], 0, v[120:121]
	v_lshl_add_u64 v[76:77], v[74:75], 0, v[120:121]
	v_lshl_add_u64 v[80:81], v[80:81], 0, v[120:121]
	v_lshl_add_u64 v[84:85], v[82:83], 0, v[120:121]
	v_lshl_add_u64 v[88:89], v[88:89], 0, v[120:121]
	v_lshl_add_u64 v[92:93], v[90:91], 0, v[120:121]
	v_lshl_add_u64 v[96:97], v[96:97], 0, v[120:121]
	v_lshl_add_u64 v[100:101], v[98:99], 0, v[120:121]
	v_lshl_add_u64 v[104:105], v[104:105], 0, v[120:121]
	v_lshl_add_u64 v[108:109], v[106:107], 0, v[120:121]
	v_lshl_add_u64 v[112:113], v[112:113], 0, v[120:121]
	v_lshl_add_u64 v[116:117], v[114:115], 0, v[120:121]
	v_lshl_add_u64 v[122:123], v[122:123], 0, v[120:121]
	v_lshl_add_u64 v[124:125], v[124:125], 0, v[120:121]
	global_load_dwordx4 v[72:75], v[72:73], off nt
	s_nop 0
	global_load_dwordx4 v[76:79], v[76:77], off nt
	s_nop 0
	global_load_dwordx4 v[80:83], v[80:81], off nt
	s_nop 0
	global_load_dwordx4 v[84:87], v[84:85], off nt
	s_nop 0
	global_load_dwordx4 v[88:91], v[88:89], off nt
	s_nop 0
	global_load_dwordx4 v[92:95], v[92:93], off nt
	s_nop 0
	global_load_dwordx4 v[96:99], v[96:97], off nt
	s_nop 0
	global_load_dwordx4 v[100:103], v[100:101], off nt
	s_nop 0
	global_load_dwordx4 v[104:107], v[104:105], off nt
	s_nop 0
	global_load_dwordx4 v[108:111], v[108:109], off nt
	s_nop 0
	global_load_dwordx4 v[112:115], v[112:113], off nt
	s_nop 0
	global_load_dwordx4 v[116:119], v[116:117], off nt
	s_nop 0
	global_load_dwordx4 v[120:123], v[122:123], off nt
	s_nop 0
	global_load_dwordx4 v[124:127], v[124:125], off nt

.LBB0_1660:
	s_waitcnt lgkmcnt(0)
	s_add_u32 s24, s8, s22
	s_addc_u32 s25, s9, s23
	s_add_i32 s28, s28, s42
	s_cmpk_lt_i32 s28, 0x400
	s_cselect_b64 s[22:23], -1, 0
	s_lshl_b32 s30, s29, 6
	s_ashr_i32 s31, s30, 31
	s_lshl_b64 s[8:9], s[30:31], 2
	s_add_u32 s8, s10, s8
	s_addc_u32 s9, s11, s9
	s_cmp_lg_u64 s[10:11], 0
	s_cselect_b32 s9, s9, 0
	s_cselect_b32 s8, s8, 0
	s_ashr_i32 s29, s43, 31
	s_and_b64 s[10:11], s[26:27], exec
	s_cselect_b32 s10, 0, s43
	s_cselect_b32 s11, 0, s29
	s_mul_i32 s11, s11, s35
	s_mul_hi_u32 s26, s10, s35
	s_add_i32 s11, s26, s11
	s_mul_i32 s10, s10, s35
	s_lshl_b64 s[10:11], s[10:11], 1
	s_add_u32 s24, s24, s10
	s_addc_u32 s25, s25, s11
	s_lshl_b64 s[10:11], s[30:31], 1
	v_mov_b32_e32 v2, v167
	v_mov_b32_e32 v3, v167
	s_add_u32 s10, s24, s10
	v_mov_b32_e32 v0, v167
	v_mov_b32_e32 v1, v167
	v_mov_b64_e32 v[6:7], v[2:3]
	v_mov_b64_e32 v[10:11], v[2:3]
	v_mov_b64_e32 v[14:15], v[2:3]
	v_mov_b64_e32 v[18:19], v[2:3]
	v_mov_b64_e32 v[22:23], v[2:3]
	v_mov_b64_e32 v[26:27], v[2:3]
	v_mov_b64_e32 v[30:31], v[2:3]
	v_mov_b64_e32 v[38:39], v[2:3]
	v_mov_b64_e32 v[42:43], v[2:3]
	v_mov_b64_e32 v[46:47], v[2:3]
	v_mov_b64_e32 v[50:51], v[2:3]
	v_mov_b64_e32 v[54:55], v[2:3]
	v_mov_b64_e32 v[58:59], v[2:3]
	v_mov_b64_e32 v[34:35], v[2:3]
	v_mov_b64_e32 v[62:63], v[2:3]
	s_addc_u32 s11, s25, s11
	v_cmp_gt_u32_e32 vcc, s36, v128
	v_mov_b64_e32 v[4:5], v[0:1]
	v_mov_b64_e32 v[8:9], v[0:1]
	v_mov_b64_e32 v[12:13], v[0:1]
	v_mov_b64_e32 v[16:17], v[0:1]
	v_mov_b64_e32 v[20:21], v[0:1]
	v_mov_b64_e32 v[24:25], v[0:1]
	v_mov_b64_e32 v[28:29], v[0:1]
	v_mov_b64_e32 v[36:37], v[0:1]
	v_mov_b64_e32 v[40:41], v[0:1]
	v_mov_b64_e32 v[44:45], v[0:1]
	v_mov_b64_e32 v[48:49], v[0:1]
	v_mov_b64_e32 v[52:53], v[0:1]
	v_mov_b64_e32 v[56:57], v[0:1]
	v_mov_b64_e32 v[32:33], v[0:1]
	v_mov_b64_e32 v[60:61], v[0:1]
	s_and_saveexec_b64 s[24:25], vcc
	s_cbranch_execz .LBB0_1662
	s_mul_i32 s26, s20, s31
	s_mul_hi_u32 s27, s20, s30
	s_add_i32 s26, s27, s26
	s_mul_i32 s21, s21, s30
	s_add_i32 s27, s26, s21
	s_mul_i32 s26, s20, s30
	s_lshl_b64 s[26:27], s[26:27], 2
	s_add_u32 s21, s18, s26
	s_addc_u32 s26, s19, s27
	s_ashr_i32 s29, s28, 31
	s_lshl_b64 s[18:19], s[28:29], 2
	s_add_u32 s18, s21, s18
	s_addc_u32 s19, s26, s19
	v_mul_hi_i32_i24_e32 v1, s20, v132
	v_mul_i32_i24_e32 v0, s20, v132
	v_lshl_add_u64 v[0:1], v[0:1], 2, s[18:19]
	v_lshlrev_b32_e32 v32, 2, v128
	v_mov_b32_e32 v33, v167
	v_lshl_add_u64 v[8:9], v[0:1], 0, v[32:33]
	v_mul_hi_i32_i24_e32 v1, s20, v134
	v_mul_i32_i24_e32 v0, s20, v134
	v_lshl_add_u64 v[0:1], v[0:1], 2, s[18:19]
	v_lshl_add_u64 v[10:11], v[0:1], 0, v[32:33]
	global_load_dwordx4 v[0:3], v[8:9], off nt
	global_load_dwordx4 v[4:7], v[10:11], off nt
	v_mul_hi_i32_i24_e32 v9, s20, v136
	v_mul_i32_i24_e32 v8, s20, v136
	v_mul_hi_i32_i24_e32 v11, s20, v138
	v_mul_i32_i24_e32 v10, s20, v138
	v_mul_hi_i32_i24_e32 v17, s20, v140
	v_mul_i32_i24_e32 v16, s20, v140
	v_mul_hi_i32_i24_e32 v19, s20, v142
	v_mul_i32_i24_e32 v18, s20, v142
	v_mul_hi_i32_i24_e32 v25, s20, v144
	v_mul_i32_i24_e32 v24, s20, v144
	v_mul_hi_i32_i24_e32 v27, s20, v146
	v_mul_i32_i24_e32 v26, s20, v146
	v_mul_hi_i32_i24_e32 v35, s20, v148
	v_mul_i32_i24_e32 v34, s20, v148
	v_mul_hi_i32_i24_e32 v37, s20, v150
	v_mul_i32_i24_e32 v36, s20, v150
	v_lshl_add_u64 v[8:9], v[8:9], 2, s[18:19]
	v_lshl_add_u64 v[10:11], v[10:11], 2, s[18:19]
	v_lshl_add_u64 v[16:17], v[16:17], 2, s[18:19]
	v_lshl_add_u64 v[18:19], v[18:19], 2, s[18:19]
	v_lshl_add_u64 v[24:25], v[24:25], 2, s[18:19]
	v_lshl_add_u64 v[26:27], v[26:27], 2, s[18:19]
	v_lshl_add_u64 v[34:35], v[34:35], 2, s[18:19]
	v_lshl_add_u64 v[36:37], v[36:37], 2, s[18:19]
	v_lshl_add_u64 v[8:9], v[8:9], 0, v[32:33]
	v_lshl_add_u64 v[12:13], v[10:11], 0, v[32:33]
	v_lshl_add_u64 v[16:17], v[16:17], 0, v[32:33]
	v_lshl_add_u64 v[20:21], v[18:19], 0, v[32:33]
	v_lshl_add_u64 v[24:25], v[24:25], 0, v[32:33]
	v_lshl_add_u64 v[28:29], v[26:27], 0, v[32:33]
	v_lshl_add_u64 v[34:35], v[34:35], 0, v[32:33]
	v_lshl_add_u64 v[40:41], v[36:37], 0, v[32:33]
	global_load_dwordx4 v[8:11], v[8:9], off nt
	s_nop 0
	global_load_dwordx4 v[12:15], v[12:13], off nt
	s_nop 0
	global_load_dwordx4 v[16:19], v[16:17], off nt
	s_nop 0
	global_load_dwordx4 v[20:23], v[20:21], off nt
	s_nop 0
	global_load_dwordx4 v[24:27], v[24:25], off nt
	s_nop 0
	global_load_dwordx4 v[28:31], v[28:29], off nt
	s_nop 0
	global_load_dwordx4 v[36:39], v[34:35], off nt
	s_nop 0
	global_load_dwordx4 v[40:43], v[40:41], off nt
	v_mul_hi_i32_i24_e32 v35, s20, v152
	v_mul_i32_i24_e32 v34, s20, v152
	v_mul_hi_i32_i24_e32 v45, s20, v154
	v_mul_i32_i24_e32 v44, s20, v154
	v_lshl_add_u64 v[34:35], v[34:35], 2, s[18:19]
	v_lshl_add_u64 v[44:45], v[44:45], 2, s[18:19]
	v_lshl_add_u64 v[34:35], v[34:35], 0, v[32:33]
	v_lshl_add_u64 v[48:49], v[44:45], 0, v[32:33]
	global_load_dwordx4 v[44:47], v[34:35], off nt
	s_nop 0
	global_load_dwordx4 v[48:51], v[48:49], off nt
	v_mul_hi_i32_i24_e32 v35, s20, v156
	v_mul_i32_i24_e32 v34, s20, v156
	v_mul_hi_i32_i24_e32 v53, s20, v158
	v_mul_i32_i24_e32 v52, s20, v158
	v_lshl_add_u64 v[34:35], v[34:35], 2, s[18:19]
	v_lshl_add_u64 v[52:53], v[52:53], 2, s[18:19]
	v_lshl_add_u64 v[34:35], v[34:35], 0, v[32:33]
	v_lshl_add_u64 v[56:57], v[52:53], 0, v[32:33]
	global_load_dwordx4 v[52:55], v[34:35], off nt
	s_nop 0
	global_load_dwordx4 v[56:59], v[56:57], off nt
	v_mul_hi_i32_i24_e32 v35, s20, v160
	v_mul_i32_i24_e32 v34, s20, v160
	v_mul_hi_i32_i24_e32 v61, s20, v162
	v_mul_i32_i24_e32 v60, s20, v162
	v_lshl_add_u64 v[34:35], v[34:35], 2, s[18:19]
	v_lshl_add_u64 v[60:61], v[60:61], 2, s[18:19]
	v_lshl_add_u64 v[34:35], v[34:35], 0, v[32:33]
	v_lshl_add_u64 v[60:61], v[60:61], 0, v[32:33]
	global_load_dwordx4 v[32:35], v[34:35], off nt
	s_nop 0
	global_load_dwordx4 v[60:63], v[60:61], off nt

.LBB0_1779:
	s_or_saveexec_b64 s[24:25], s[22:23]
	v_mov_b32_e32 v33, v32
	v_mov_b32_e32 v34, v32
	v_mov_b32_e32 v35, v32
	v_mov_b64_e32 v[58:59], v[34:35]
	v_mov_b64_e32 v[54:55], v[34:35]
	v_mov_b64_e32 v[50:51], v[34:35]
	v_mov_b64_e32 v[46:47], v[34:35]
	v_mov_b64_e32 v[42:43], v[34:35]
	v_mov_b64_e32 v[38:39], v[34:35]
	v_mov_b64_e32 v[28:29], v[32:33]
	v_mov_b64_e32 v[24:25], v[32:33]
	v_mov_b64_e32 v[20:21], v[32:33]
	v_mov_b64_e32 v[16:17], v[32:33]
	v_mov_b64_e32 v[12:13], v[32:33]
	v_mov_b64_e32 v[8:9], v[32:33]
	v_mov_b64_e32 v[4:5], v[32:33]
	v_mov_b64_e32 v[0:1], v[32:33]
	s_waitcnt vmcnt(2)
	v_mov_b64_e32 v[62:63], v[34:35]
	s_add_i32 s22, s30, s29
	v_mov_b64_e32 v[56:57], v[32:33]
	v_mov_b64_e32 v[52:53], v[32:33]
	v_mov_b64_e32 v[48:49], v[32:33]
	v_mov_b64_e32 v[44:45], v[32:33]
	v_mov_b64_e32 v[40:41], v[32:33]
	v_mov_b64_e32 v[36:37], v[32:33]
	v_mov_b64_e32 v[30:31], v[34:35]
	v_mov_b64_e32 v[26:27], v[34:35]
	v_mov_b64_e32 v[22:23], v[34:35]
	v_mov_b64_e32 v[18:19], v[34:35]
	v_mov_b64_e32 v[14:15], v[34:35]
	v_mov_b64_e32 v[10:11], v[34:35]
	v_mov_b64_e32 v[6:7], v[34:35]
	v_mov_b64_e32 v[2:3], v[34:35]
	v_mov_b64_e32 v[60:61], v[32:33]
	s_xor_b64 exec, exec, s[24:25]
	s_cbranch_execz .LBB0_1781
	s_mul_i32 s23, s14, s21
	s_mul_hi_u32 s28, s14, s20
	s_add_i32 s23, s28, s23
	s_mul_i32 s15, s15, s20
	s_add_i32 s29, s23, s15
	s_mul_i32 s28, s14, s20
	s_lshl_b64 s[28:29], s[28:29], 2
	s_waitcnt lgkmcnt(0)
	s_add_u32 s15, s16, s28
	s_addc_u32 s28, s17, s29
	s_ashr_i32 s23, s22, 31
	s_lshl_b64 s[16:17], s[22:23], 2
	v_and_b32_e32 v132, 6, v130
	s_add_u32 s16, s15, s16
	v_mul_u32_u24_e32 v0, s14, v132
	s_addc_u32 s17, s28, s17
	v_mov_b32_e32 v33, 0
	v_lshlrev_b32_e32 v32, 2, v0
	v_lshl_add_u64 v[0:1], s[16:17], 0, v[32:33]
	v_lshlrev_b32_e32 v32, 2, v128
	v_or_b32_e32 v134, 1, v130
	v_lshl_add_u64 v[8:9], v[0:1], 0, v[32:33]
	v_mul_u32_u24_e32 v0, s14, v134
	v_lshlrev_b32_e32 v0, 2, v0
	v_mov_b32_e32 v1, v33
	v_lshl_add_u64 v[0:1], s[16:17], 0, v[0:1]
	v_or_b32_e32 v136, 8, v132
	v_lshl_add_u64 v[10:11], v[0:1], 0, v[32:33]
	global_load_dwordx4 v[0:3], v[8:9], off nt
	global_load_dwordx4 v[4:7], v[10:11], off nt
	v_mul_u32_u24_e32 v8, s14, v136
	v_lshlrev_b32_e32 v8, 2, v8
	v_mov_b32_e32 v9, v33
	v_lshl_add_u64 v[8:9], s[16:17], 0, v[8:9]
	v_or_b32_e32 v138, 9, v130
	v_lshl_add_u64 v[16:17], v[8:9], 0, v[32:33]
	v_mul_u32_u24_e32 v8, s14, v138
	v_lshlrev_b32_e32 v8, 2, v8
	v_mov_b32_e32 v9, v33
	v_lshl_add_u64 v[8:9], s[16:17], 0, v[8:9]
	v_or_b32_e32 v140, 16, v132
	v_lshl_add_u64 v[18:19], v[8:9], 0, v[32:33]
	global_load_dwordx4 v[8:11], v[16:17], off nt
	global_load_dwordx4 v[12:15], v[18:19], off nt
	v_mul_u32_u24_e32 v16, s14, v140
	v_lshlrev_b32_e32 v16, 2, v16
	v_mov_b32_e32 v17, v33
	v_lshl_add_u64 v[16:17], s[16:17], 0, v[16:17]
	v_or_b32_e32 v142, 17, v130
	v_lshl_add_u64 v[24:25], v[16:17], 0, v[32:33]
	v_mul_u32_u24_e32 v16, s14, v142
	v_lshlrev_b32_e32 v16, 2, v16
	v_mov_b32_e32 v17, v33
	v_lshl_add_u64 v[16:17], s[16:17], 0, v[16:17]
	v_or_b32_e32 v144, 24, v132
	v_lshl_add_u64 v[26:27], v[16:17], 0, v[32:33]
	global_load_dwordx4 v[16:19], v[24:25], off nt
	global_load_dwordx4 v[20:23], v[26:27], off nt
	v_mul_u32_u24_e32 v24, s14, v144
	v_lshlrev_b32_e32 v24, 2, v24
	v_mov_b32_e32 v25, v33
	v_lshl_add_u64 v[24:25], s[16:17], 0, v[24:25]
	v_or_b32_e32 v146, 25, v130
	v_lshl_add_u64 v[34:35], v[24:25], 0, v[32:33]
	v_mul_u32_u24_e32 v24, s14, v146
	v_lshlrev_b32_e32 v24, 2, v24
	v_mov_b32_e32 v25, v33
	v_lshl_add_u64 v[24:25], s[16:17], 0, v[24:25]
	v_or_b32_e32 v148, 32, v132
	v_lshl_add_u64 v[36:37], v[24:25], 0, v[32:33]
	global_load_dwordx4 v[24:27], v[34:35], off nt
	global_load_dwordx4 v[28:31], v[36:37], off nt
	v_mul_u32_u24_e32 v34, s14, v148
	v_or_b32_e32 v150, 33, v130
	v_lshlrev_b32_e32 v34, 2, v34
	v_mov_b32_e32 v35, v33
	v_mul_u32_u24_e32 v36, s14, v150
	v_lshl_add_u64 v[34:35], s[16:17], 0, v[34:35]
	v_lshlrev_b32_e32 v36, 2, v36
	v_mov_b32_e32 v37, v33
	v_lshl_add_u64 v[34:35], v[34:35], 0, v[32:33]
	v_lshl_add_u64 v[36:37], s[16:17], 0, v[36:37]
	v_or_b32_e32 v152, 40, v132
	v_lshl_add_u64 v[44:45], v[36:37], 0, v[32:33]
	global_load_dwordx4 v[36:39], v[34:35], off nt
	global_load_dwordx4 v[40:43], v[44:45], off nt
	v_mul_u32_u24_e32 v34, s14, v152
	v_or_b32_e32 v154, 41, v130
	v_lshlrev_b32_e32 v34, 2, v34
	v_mov_b32_e32 v35, v33
	v_mul_u32_u24_e32 v44, s14, v154
	v_lshl_add_u64 v[34:35], s[16:17], 0, v[34:35]
	v_lshlrev_b32_e32 v44, 2, v44
	v_mov_b32_e32 v45, v33
	v_lshl_add_u64 v[34:35], v[34:35], 0, v[32:33]
	v_lshl_add_u64 v[44:45], s[16:17], 0, v[44:45]
	v_or_b32_e32 v156, 48, v132
	v_lshl_add_u64 v[52:53], v[44:45], 0, v[32:33]
	global_load_dwordx4 v[44:47], v[34:35], off nt
	global_load_dwordx4 v[48:51], v[52:53], off nt
	v_mul_u32_u24_e32 v34, s14, v156
	v_or_b32_e32 v158, 49, v130
	v_lshlrev_b32_e32 v34, 2, v34
	v_mov_b32_e32 v35, v33
	v_mul_u32_u24_e32 v52, s14, v158
	v_lshl_add_u64 v[34:35], s[16:17], 0, v[34:35]
	v_lshlrev_b32_e32 v52, 2, v52
	v_mov_b32_e32 v53, v33
	v_lshl_add_u64 v[34:35], v[34:35], 0, v[32:33]
	v_lshl_add_u64 v[52:53], s[16:17], 0, v[52:53]
	v_or_b32_e32 v160, 56, v132
	v_lshl_add_u64 v[60:61], v[52:53], 0, v[32:33]
	global_load_dwordx4 v[52:55], v[34:35], off nt
	global_load_dwordx4 v[56:59], v[60:61], off nt
	v_mul_u32_u24_e32 v34, s14, v160
	v_lshlrev_b32_e32 v34, 2, v34
	v_mov_b32_e32 v35, v33
	v_lshl_add_u64 v[34:35], s[16:17], 0, v[34:35]
	v_or_b32_e32 v162, 57, v130
	v_lshl_add_u64 v[64:65], v[34:35], 0, v[32:33]
	v_mul_u32_u24_e32 v34, s14, v162
	v_lshlrev_b32_e32 v34, 2, v34
	v_mov_b32_e32 v35, v33
	v_lshl_add_u64 v[34:35], s[16:17], 0, v[34:35]
	v_lshl_add_u64 v[66:67], v[34:35], 0, v[32:33]
	global_load_dwordx4 v[32:35], v[64:65], off nt
	global_load_dwordx4 v[60:63], v[66:67], off nt

.LBB0_1827:
	s_waitcnt lgkmcnt(0)
	s_add_u32 s24, s12, s22
	s_addc_u32 s25, s13, s23
	s_add_i32 s28, s28, s41
	s_cmpk_lt_i32 s28, 0x400
	s_cselect_b64 s[22:23], -1, 0
	s_lshl_b32 s30, s29, 6
	s_ashr_i32 s31, s30, 31
	s_lshl_b64 s[12:13], s[30:31], 2
	s_add_u32 s12, s14, s12
	s_addc_u32 s13, s15, s13
	s_cmp_lg_u64 s[14:15], 0
	s_cselect_b32 s13, s13, 0
	s_cselect_b32 s12, s12, 0
	s_ashr_i32 s29, s42, 31
	s_and_b64 s[14:15], s[26:27], exec
	s_cselect_b32 s14, 0, s42
	s_cselect_b32 s15, 0, s29
	s_mul_i32 s15, s15, s34
	s_mul_hi_u32 s26, s14, s34
	s_add_i32 s15, s26, s15
	s_mul_i32 s14, s14, s34
	s_lshl_b64 s[14:15], s[14:15], 1
	s_add_u32 s24, s24, s14
	s_addc_u32 s25, s25, s15
	s_lshl_b64 s[14:15], s[30:31], 1
	s_add_u32 s14, s24, s14
	s_addc_u32 s15, s25, s15
	v_cmp_gt_u32_e32 vcc, s39, v128
	v_mov_b32_e32 v67, 0
	v_mov_b32_e32 v66, 0
	v_mov_b32_e32 v65, 0
	v_mov_b32_e32 v64, 0
	v_mov_b32_e32 v71, 0
	v_mov_b32_e32 v70, 0
	v_mov_b32_e32 v69, 0
	v_mov_b32_e32 v68, 0
	v_mov_b32_e32 v75, 0
	v_mov_b32_e32 v74, 0
	v_mov_b32_e32 v73, 0
	v_mov_b32_e32 v72, 0
	v_mov_b32_e32 v79, 0
	v_mov_b32_e32 v78, 0
	v_mov_b32_e32 v77, 0
	v_mov_b32_e32 v76, 0
	v_mov_b32_e32 v83, 0
	v_mov_b32_e32 v82, 0
	v_mov_b32_e32 v81, 0
	v_mov_b32_e32 v80, 0
	v_mov_b32_e32 v87, 0
	v_mov_b32_e32 v86, 0
	v_mov_b32_e32 v85, 0
	v_mov_b32_e32 v84, 0
	v_mov_b32_e32 v91, 0
	v_mov_b32_e32 v90, 0
	v_mov_b32_e32 v89, 0
	v_mov_b32_e32 v88, 0
	v_mov_b32_e32 v95, 0
	v_mov_b32_e32 v94, 0
	v_mov_b32_e32 v93, 0
	v_mov_b32_e32 v92, 0
	v_mov_b32_e32 v99, 0
	v_mov_b32_e32 v98, 0
	v_mov_b32_e32 v97, 0
	v_mov_b32_e32 v96, 0
	v_mov_b32_e32 v103, 0
	v_mov_b32_e32 v102, 0
	v_mov_b32_e32 v101, 0
	v_mov_b32_e32 v100, 0
	v_mov_b32_e32 v107, 0
	v_mov_b32_e32 v106, 0
	v_mov_b32_e32 v105, 0
	v_mov_b32_e32 v104, 0
	v_mov_b32_e32 v111, 0
	v_mov_b32_e32 v110, 0
	v_mov_b32_e32 v109, 0
	v_mov_b32_e32 v108, 0
	v_mov_b32_e32 v115, 0
	v_mov_b32_e32 v114, 0
	v_mov_b32_e32 v113, 0
	v_mov_b32_e32 v112, 0
	v_mov_b32_e32 v119, 0
	v_mov_b32_e32 v118, 0
	v_mov_b32_e32 v117, 0
	v_mov_b32_e32 v116, 0
	v_mov_b32_e32 v123, 0
	v_mov_b32_e32 v122, 0
	v_mov_b32_e32 v121, 0
	v_mov_b32_e32 v120, 0
	v_mov_b32_e32 v127, 0
	v_mov_b32_e32 v126, 0
	v_mov_b32_e32 v125, 0
	v_mov_b32_e32 v124, 0
	s_and_saveexec_b64 s[24:25], vcc
	s_cbranch_execz .LBB0_1829
	s_mul_i32 s26, s18, s31
	s_mul_hi_u32 s27, s18, s30
	s_add_i32 s26, s27, s26
	s_mul_i32 s19, s19, s30
	s_add_i32 s27, s26, s19
	s_mul_i32 s26, s18, s30
	s_lshl_b64 s[26:27], s[26:27], 2
	s_add_u32 s19, s20, s26
	s_addc_u32 s26, s21, s27
	s_ashr_i32 s29, s28, 31
	s_lshl_b64 s[20:21], s[28:29], 2
	s_add_u32 s20, s19, s20
	s_addc_u32 s21, s26, s21
	v_mul_hi_i32_i24_e32 v65, s18, v132
	v_mul_i32_i24_e32 v64, s18, v132
	v_lshl_add_u64 v[64:65], v[64:65], 2, s[20:21]
	v_lshlrev_b32_e32 v120, 2, v128
	v_mov_b32_e32 v121, v167
	v_lshl_add_u64 v[72:73], v[64:65], 0, v[120:121]
	v_mul_hi_i32_i24_e32 v65, s18, v134
	v_mul_i32_i24_e32 v64, s18, v134
	v_lshl_add_u64 v[64:65], v[64:65], 2, s[20:21]
	v_lshl_add_u64 v[74:75], v[64:65], 0, v[120:121]
	global_load_dwordx4 v[64:67], v[72:73], off nt
	global_load_dwordx4 v[68:71], v[74:75], off nt
	v_mul_hi_i32_i24_e32 v73, s18, v136
	v_mul_i32_i24_e32 v72, s18, v136
	v_lshl_add_u64 v[72:73], v[72:73], 2, s[20:21]
	v_lshl_add_u64 v[80:81], v[72:73], 0, v[120:121]
	v_mul_hi_i32_i24_e32 v73, s18, v138
	v_mul_i32_i24_e32 v72, s18, v138
	v_lshl_add_u64 v[72:73], v[72:73], 2, s[20:21]
	v_lshl_add_u64 v[82:83], v[72:73], 0, v[120:121]
	global_load_dwordx4 v[72:75], v[80:81], off nt
	global_load_dwordx4 v[76:79], v[82:83], off nt
	v_mul_hi_i32_i24_e32 v81, s18, v140
	v_mul_i32_i24_e32 v80, s18, v140
	v_mul_hi_i32_i24_e32 v83, s18, v142
	v_mul_i32_i24_e32 v82, s18, v142
	v_mul_hi_i32_i24_e32 v89, s18, v144
	v_mul_i32_i24_e32 v88, s18, v144
	v_mul_hi_i32_i24_e32 v91, s18, v146
	v_mul_i32_i24_e32 v90, s18, v146
	v_mul_hi_i32_i24_e32 v97, s18, v148
	v_mul_i32_i24_e32 v96, s18, v148
	v_mul_hi_i32_i24_e32 v99, s18, v150
	v_mul_i32_i24_e32 v98, s18, v150
	v_mul_hi_i32_i24_e32 v105, s18, v152
	v_mul_i32_i24_e32 v104, s18, v152
	v_mul_hi_i32_i24_e32 v107, s18, v154
	v_mul_i32_i24_e32 v106, s18, v154
	v_mul_hi_i32_i24_e32 v113, s18, v156
	v_mul_i32_i24_e32 v112, s18, v156
	v_mul_hi_i32_i24_e32 v115, s18, v158
	v_mul_i32_i24_e32 v114, s18, v158
	v_mul_hi_i32_i24_e32 v123, s18, v160
	v_mul_i32_i24_e32 v122, s18, v160
	v_mul_hi_i32_i24_e32 v125, s18, v162
	v_mul_i32_i24_e32 v124, s18, v162
	v_lshl_add_u64 v[80:81], v[80:81], 2, s[20:21]
	v_lshl_add_u64 v[82:83], v[82:83], 2, s[20:21]
	v_lshl_add_u64 v[88:89], v[88:89], 2, s[20:21]
	v_lshl_add_u64 v[90:91], v[90:91], 2, s[20:21]
	v_lshl_add_u64 v[96:97], v[96:97], 2, s[20:21]
	v_lshl_add_u64 v[98:99], v[98:99], 2, s[20:21]
	v_lshl_add_u64 v[104:105], v[104:105], 2, s[20:21]
	v_lshl_add_u64 v[106:107], v[106:107], 2, s[20:21]
	v_lshl_add_u64 v[112:113], v[112:113], 2, s[20:21]
	v_lshl_add_u64 v[114:115], v[114:115], 2, s[20:21]
	v_lshl_add_u64 v[122:123], v[122:123], 2, s[20:21]
	v_lshl_add_u64 v[124:125], v[124:125], 2, s[20:21]
	v_lshl_add_u64 v[80:81], v[80:81], 0, v[120:121]
	v_lshl_add_u64 v[84:85], v[82:83], 0, v[120:121]
	v_lshl_add_u64 v[88:89], v[88:89], 0, v[120:121]
	v_lshl_add_u64 v[92:93], v[90:91], 0, v[120:121]
	v_lshl_add_u64 v[96:97], v[96:97], 0, v[120:121]
	v_lshl_add_u64 v[100:101], v[98:99], 0, v[120:121]
	v_lshl_add_u64 v[104:105], v[104:105], 0, v[120:121]
	v_lshl_add_u64 v[108:109], v[106:107], 0, v[120:121]
	v_lshl_add_u64 v[112:113], v[112:113], 0, v[120:121]
	v_lshl_add_u64 v[116:117], v[114:115], 0, v[120:121]
	v_lshl_add_u64 v[122:123], v[122:123], 0, v[120:121]
	v_lshl_add_u64 v[124:125], v[124:125], 0, v[120:121]
	global_load_dwordx4 v[80:83], v[80:81], off nt
	s_nop 0
	global_load_dwordx4 v[84:87], v[84:85], off nt
	s_nop 0
	global_load_dwordx4 v[88:91], v[88:89], off nt
	s_nop 0
	global_load_dwordx4 v[92:95], v[92:93], off nt
	s_nop 0
	global_load_dwordx4 v[96:99], v[96:97], off nt
	s_nop 0
	global_load_dwordx4 v[100:103], v[100:101], off nt
	s_nop 0
	global_load_dwordx4 v[104:107], v[104:105], off nt
	s_nop 0
	global_load_dwordx4 v[108:111], v[108:109], off nt
	s_nop 0
	global_load_dwordx4 v[112:115], v[112:113], off nt
	s_nop 0
	global_load_dwordx4 v[116:119], v[116:117], off nt
	s_nop 0
	global_load_dwordx4 v[120:123], v[122:123], off nt
	s_nop 0
	global_load_dwordx4 v[124:127], v[124:125], off nt

.LBB0_1903:
	s_waitcnt lgkmcnt(0)
	s_add_u32 s24, s8, s22
	s_addc_u32 s25, s9, s23
	s_add_i32 s28, s28, s42
	s_cmpk_lt_i32 s28, 0x400
	s_cselect_b64 s[22:23], -1, 0
	s_lshl_b32 s30, s29, 6
	s_ashr_i32 s31, s30, 31
	s_lshl_b64 s[8:9], s[30:31], 2
	s_add_u32 s8, s10, s8
	s_addc_u32 s9, s11, s9
	s_cmp_lg_u64 s[10:11], 0
	s_cselect_b32 s9, s9, 0
	s_cselect_b32 s8, s8, 0
	s_ashr_i32 s29, s36, 31
	s_and_b64 s[10:11], s[26:27], exec
	s_cselect_b32 s10, 0, s36
	s_cselect_b32 s11, 0, s29
	s_mul_i32 s11, s11, s35
	s_mul_hi_u32 s26, s10, s35
	s_add_i32 s11, s26, s11
	s_mul_i32 s10, s10, s35
	s_lshl_b64 s[10:11], s[10:11], 1
	s_add_u32 s24, s24, s10
	s_addc_u32 s25, s25, s11
	s_lshl_b64 s[10:11], s[30:31], 1
	v_mov_b32_e32 v2, v167
	v_mov_b32_e32 v3, v167
	s_add_u32 s10, s24, s10
	v_mov_b32_e32 v0, v167
	v_mov_b32_e32 v1, v167
	v_mov_b64_e32 v[6:7], v[2:3]
	v_mov_b64_e32 v[10:11], v[2:3]
	v_mov_b64_e32 v[14:15], v[2:3]
	v_mov_b64_e32 v[18:19], v[2:3]
	v_mov_b64_e32 v[22:23], v[2:3]
	v_mov_b64_e32 v[26:27], v[2:3]
	v_mov_b64_e32 v[30:31], v[2:3]
	v_mov_b64_e32 v[38:39], v[2:3]
	v_mov_b64_e32 v[42:43], v[2:3]
	v_mov_b64_e32 v[46:47], v[2:3]
	v_mov_b64_e32 v[50:51], v[2:3]
	v_mov_b64_e32 v[54:55], v[2:3]
	v_mov_b64_e32 v[58:59], v[2:3]
	v_mov_b64_e32 v[34:35], v[2:3]
	v_mov_b64_e32 v[62:63], v[2:3]
	s_addc_u32 s11, s25, s11
	v_cmp_gt_u32_e32 vcc, s37, v128
	v_mov_b64_e32 v[4:5], v[0:1]
	v_mov_b64_e32 v[8:9], v[0:1]
	v_mov_b64_e32 v[12:13], v[0:1]
	v_mov_b64_e32 v[16:17], v[0:1]
	v_mov_b64_e32 v[20:21], v[0:1]
	v_mov_b64_e32 v[24:25], v[0:1]
	v_mov_b64_e32 v[28:29], v[0:1]
	v_mov_b64_e32 v[36:37], v[0:1]
	v_mov_b64_e32 v[40:41], v[0:1]
	v_mov_b64_e32 v[44:45], v[0:1]
	v_mov_b64_e32 v[48:49], v[0:1]
	v_mov_b64_e32 v[52:53], v[0:1]
	v_mov_b64_e32 v[56:57], v[0:1]
	v_mov_b64_e32 v[32:33], v[0:1]
	v_mov_b64_e32 v[60:61], v[0:1]
	s_and_saveexec_b64 s[24:25], vcc
	s_cbranch_execz .LBB0_1905
	s_mul_i32 s26, s18, s31
	s_mul_hi_u32 s27, s18, s30
	s_add_i32 s26, s27, s26
	s_mul_i32 s19, s19, s30
	s_add_i32 s27, s26, s19
	s_mul_i32 s26, s18, s30
	s_lshl_b64 s[26:27], s[26:27], 2
	s_add_u32 s19, s20, s26
	s_addc_u32 s26, s21, s27
	s_ashr_i32 s29, s28, 31
	s_lshl_b64 s[20:21], s[28:29], 2
	s_add_u32 s20, s19, s20
	s_addc_u32 s21, s26, s21
	v_mul_hi_i32_i24_e32 v1, s18, v132
	v_mul_i32_i24_e32 v0, s18, v132
	v_lshl_add_u64 v[0:1], v[0:1], 2, s[20:21]
	v_lshlrev_b32_e32 v32, 2, v128
	v_mov_b32_e32 v33, v167
	v_lshl_add_u64 v[8:9], v[0:1], 0, v[32:33]
	v_mul_hi_i32_i24_e32 v1, s18, v134
	v_mul_i32_i24_e32 v0, s18, v134
	v_lshl_add_u64 v[0:1], v[0:1], 2, s[20:21]
	v_lshl_add_u64 v[10:11], v[0:1], 0, v[32:33]
	global_load_dwordx4 v[0:3], v[8:9], off nt
	global_load_dwordx4 v[4:7], v[10:11], off nt
	v_mul_hi_i32_i24_e32 v9, s18, v136
	v_mul_i32_i24_e32 v8, s18, v136
	v_lshl_add_u64 v[8:9], v[8:9], 2, s[20:21]
	v_lshl_add_u64 v[16:17], v[8:9], 0, v[32:33]
	v_mul_hi_i32_i24_e32 v9, s18, v138
	v_mul_i32_i24_e32 v8, s18, v138
	v_lshl_add_u64 v[8:9], v[8:9], 2, s[20:21]
	v_lshl_add_u64 v[18:19], v[8:9], 0, v[32:33]
	global_load_dwordx4 v[8:11], v[16:17], off nt
	global_load_dwordx4 v[12:15], v[18:19], off nt
	v_mul_hi_i32_i24_e32 v17, s18, v140
	v_mul_i32_i24_e32 v16, s18, v140
	v_mul_hi_i32_i24_e32 v19, s18, v142
	v_mul_i32_i24_e32 v18, s18, v142
	v_mul_hi_i32_i24_e32 v25, s18, v144
	v_mul_i32_i24_e32 v24, s18, v144
	v_mul_hi_i32_i24_e32 v27, s18, v146
	v_mul_i32_i24_e32 v26, s18, v146
	v_mul_hi_i32_i24_e32 v35, s18, v148
	v_mul_i32_i24_e32 v34, s18, v148
	v_mul_hi_i32_i24_e32 v37, s18, v150
	v_mul_i32_i24_e32 v36, s18, v150
	v_lshl_add_u64 v[16:17], v[16:17], 2, s[20:21]
	v_lshl_add_u64 v[18:19], v[18:19], 2, s[20:21]
	v_lshl_add_u64 v[24:25], v[24:25], 2, s[20:21]
	v_lshl_add_u64 v[26:27], v[26:27], 2, s[20:21]
	v_lshl_add_u64 v[34:35], v[34:35], 2, s[20:21]
	v_lshl_add_u64 v[36:37], v[36:37], 2, s[20:21]
	v_lshl_add_u64 v[16:17], v[16:17], 0, v[32:33]
	v_lshl_add_u64 v[20:21], v[18:19], 0, v[32:33]
	v_lshl_add_u64 v[24:25], v[24:25], 0, v[32:33]
	v_lshl_add_u64 v[28:29], v[26:27], 0, v[32:33]
	v_lshl_add_u64 v[34:35], v[34:35], 0, v[32:33]
	v_lshl_add_u64 v[40:41], v[36:37], 0, v[32:33]
	global_load_dwordx4 v[16:19], v[16:17], off nt
	s_nop 0
	global_load_dwordx4 v[20:23], v[20:21], off nt
	s_nop 0
	global_load_dwordx4 v[24:27], v[24:25], off nt
	s_nop 0
	global_load_dwordx4 v[28:31], v[28:29], off nt
	s_nop 0
	global_load_dwordx4 v[36:39], v[34:35], off nt
	s_nop 0
	global_load_dwordx4 v[40:43], v[40:41], off nt
	v_mul_hi_i32_i24_e32 v35, s18, v152
	v_mul_i32_i24_e32 v34, s18, v152
	v_mul_hi_i32_i24_e32 v45, s18, v154
	v_mul_i32_i24_e32 v44, s18, v154
	v_lshl_add_u64 v[34:35], v[34:35], 2, s[20:21]
	v_lshl_add_u64 v[44:45], v[44:45], 2, s[20:21]
	v_lshl_add_u64 v[34:35], v[34:35], 0, v[32:33]
	v_lshl_add_u64 v[48:49], v[44:45], 0, v[32:33]
	global_load_dwordx4 v[44:47], v[34:35], off nt
	s_nop 0
	global_load_dwordx4 v[48:51], v[48:49], off nt
	v_mul_hi_i32_i24_e32 v35, s18, v156
	v_mul_i32_i24_e32 v34, s18, v156
	v_mul_hi_i32_i24_e32 v53, s18, v158
	v_mul_i32_i24_e32 v52, s18, v158
	v_lshl_add_u64 v[34:35], v[34:35], 2, s[20:21]
	v_lshl_add_u64 v[52:53], v[52:53], 2, s[20:21]
	v_lshl_add_u64 v[34:35], v[34:35], 0, v[32:33]
	v_lshl_add_u64 v[56:57], v[52:53], 0, v[32:33]
	global_load_dwordx4 v[52:55], v[34:35], off nt
	s_nop 0
	global_load_dwordx4 v[56:59], v[56:57], off nt
	v_mul_hi_i32_i24_e32 v35, s18, v160
	v_mul_i32_i24_e32 v34, s18, v160
	v_mul_hi_i32_i24_e32 v61, s18, v162
	v_mul_i32_i24_e32 v60, s18, v162
	v_lshl_add_u64 v[34:35], v[34:35], 2, s[20:21]
	v_lshl_add_u64 v[60:61], v[60:61], 2, s[20:21]
	v_lshl_add_u64 v[34:35], v[34:35], 0, v[32:33]
	v_lshl_add_u64 v[60:61], v[60:61], 0, v[32:33]
	global_load_dwordx4 v[32:35], v[34:35], off nt
	s_nop 0
	global_load_dwordx4 v[60:63], v[60:61], off nt

	.amdhsa_kernel _Z8yoco_fwd4Args
		.amdhsa_group_segment_fixed_size 0
		.amdhsa_private_segment_fixed_size 0
		.amdhsa_kernarg_size 392
		.amdhsa_user_sgpr_count 2
		.amdhsa_user_sgpr_dispatch_ptr 0
		.amdhsa_user_sgpr_queue_ptr 0
		.amdhsa_user_sgpr_kernarg_segment_ptr 1
		.amdhsa_user_sgpr_dispatch_id 0
		.amdhsa_user_sgpr_kernarg_preload_length 0
		.amdhsa_user_sgpr_kernarg_preload_offset 0
		.amdhsa_user_sgpr_private_segment_size 0
		.amdhsa_uses_dynamic_stack 0
		.amdhsa_enable_private_segment 0
		.amdhsa_system_sgpr_workgroup_id_x 1
		.amdhsa_system_sgpr_workgroup_id_y 0
		.amdhsa_system_sgpr_workgroup_id_z 0
		.amdhsa_system_sgpr_workgroup_info 0
		.amdhsa_system_vgpr_workitem_id 2
		.amdhsa_next_free_vgpr 256
		.amdhsa_next_free_sgpr 100
		.amdhsa_accum_offset 256
		.amdhsa_reserve_vcc 1
		.amdhsa_float_round_mode_32 0
		.amdhsa_float_round_mode_16_64 0
		.amdhsa_float_denorm_mode_32 3
		.amdhsa_float_denorm_mode_16_64 3
		.amdhsa_dx10_clamp 1
		.amdhsa_ieee_mode 1
		.amdhsa_fp16_overflow 0
		.amdhsa_tg_split 0
		.amdhsa_exception_fp_ieee_invalid_op 0
		.amdhsa_exception_fp_denorm_src 0
		.amdhsa_exception_fp_ieee_div_zero 0
		.amdhsa_exception_fp_ieee_overflow 0
		.amdhsa_exception_fp_ieee_underflow 0
		.amdhsa_exception_fp_ieee_inexact 0
		.amdhsa_exception_int_div_zero 0
	.end_amdhsa_kernel

amdhsa.kernels:
  - .agpr_count:     0
    .args:
      - .offset:         0
        .size:           136
        .value_kind:     by_value
      - .offset:         136
        .size:           4
        .value_kind:     hidden_block_count_x
      - .offset:         140
        .size:           4
        .value_kind:     hidden_block_count_y
      - .offset:         144
        .size:           4
        .value_kind:     hidden_block_count_z
      - .offset:         148
        .size:           2
        .value_kind:     hidden_group_size_x
      - .offset:         150
        .size:           2
        .value_kind:     hidden_group_size_y
      - .offset:         152
        .size:           2
        .value_kind:     hidden_group_size_z
      - .offset:         154
        .size:           2
        .value_kind:     hidden_remainder_x
      - .offset:         156
        .size:           2
        .value_kind:     hidden_remainder_y
      - .offset:         158
        .size:           2
        .value_kind:     hidden_remainder_z
      - .offset:         176
        .size:           8
        .value_kind:     hidden_global_offset_x
      - .offset:         184
        .size:           8
        .value_kind:     hidden_global_offset_y
      - .offset:         192
        .size:           8
        .value_kind:     hidden_global_offset_z
      - .offset:         200
        .size:           2
        .value_kind:     hidden_grid_dims
      - .offset:         224
        .size:           8
        .value_kind:     hidden_multigrid_sync_arg
      - .offset:         256
        .size:           4
        .value_kind:     hidden_dynamic_lds_size
    .group_segment_fixed_size: 0
    .kernarg_segment_align: 8
    .kernarg_segment_size: 392
    .language:       OpenCL C
    .language_version:
      - 2
      - 0
    .max_flat_workgroup_size: 512
    .name:           _Z8yoco_fwd4Args
    .private_segment_fixed_size: 0
    .sgpr_count:     106
    .sgpr_spill_count: 4
    .symbol:         _Z8yoco_fwd4Args.kd
    .uniform_work_group_size: 1
    .uses_dynamic_stack: false
    .vgpr_count:     256
    .vgpr_spill_count: 0
    .wavefront_size: 64
